# GEMM K-loops: pre-MFMA s_barrier moved below the first 2 MFMAs of each block (a block's MFMAs need only the wave's own ds_reads), all 18 K-loops
# speedup vs baseline: 1.0788x; 1.0170x over previous
.LBB0_408:
	ds_read_b128 v[34:37], v196
	ds_read_b128 v[38:41], v196 offset:1024
	ds_read_b128 v[42:45], v196 offset:2048
	ds_read_b128 v[46:49], v196 offset:3072
	ds_read_b128 v[146:149], v197
	ds_read_b128 v[150:153], v197 offset:1024
	ds_read_b128 v[184:187], v197 offset:2048
	ds_read_b128 v[188:191], v197 offset:3072
	s_add_i32 s11, s6, 2
	s_add_u32 s12, s4, 0x80
	s_addc_u32 s7, s5, 0
	s_cmp_eq_u32 s27, s6
	s_cselect_b32 s6, s54, s12
	s_cselect_b32 s7, s55, s7
	s_cselect_b32 s13, s61, s9
	s_cselect_b32 s12, s60, s8
	v_lshl_add_u64 v[192:193], s[4:5], 0, v[174:175]
	s_add_i32 m0, s88, 0xc000
	ds_read_b128 v[200:203], v198
	ds_read_b128 v[204:207], v198 offset:1024
	ds_read_b128 v[208:211], v198 offset:2048
	ds_read_b128 v[212:215], v198 offset:3072
	ds_read_b128 v[216:219], v198 offset:4096
	ds_read_b128 v[220:223], v198 offset:5120
	ds_read_b128 v[224:227], v198 offset:6144
	ds_read_b128 v[228:231], v198 offset:7168
	global_load_lds_dwordx4 v[192:193], off
	v_lshl_add_u64 v[192:193], s[4:5], 0, v[176:177]
	s_add_i32 m0, s88, 0xe000
	s_nop 0
	global_load_lds_dwordx4 v[192:193], off
	s_waitcnt vmcnt(8)
	s_waitcnt lgkmcnt(0)
	s_setprio 1
	s_waitcnt lgkmcnt(0)
	v_mfma_f32_16x16x32_bf16 v[142:145], v[34:37], v[200:203], v[142:145]
	v_mfma_f32_16x16x32_bf16 v[138:141], v[42:45], v[200:203], v[138:141]
	s_barrier
	v_mfma_f32_16x16x32_bf16 v[126:129], v[34:37], v[208:211], v[126:129]
	v_mfma_f32_16x16x32_bf16 v[122:125], v[42:45], v[208:211], v[122:125]
	v_mfma_f32_16x16x32_bf16 v[110:113], v[34:37], v[216:219], v[110:113]
	v_mfma_f32_16x16x32_bf16 v[106:109], v[42:45], v[216:219], v[106:109]
	v_mfma_f32_16x16x32_bf16 v[94:97], v[34:37], v[224:227], v[94:97]
	v_mfma_f32_16x16x32_bf16 v[90:93], v[42:45], v[224:227], v[90:93]
	v_mfma_f32_16x16x32_bf16 v[142:145], v[38:41], v[204:207], v[142:145]
	v_mfma_f32_16x16x32_bf16 v[138:141], v[46:49], v[204:207], v[138:141]
	v_mfma_f32_16x16x32_bf16 v[126:129], v[38:41], v[212:215], v[126:129]
	v_mfma_f32_16x16x32_bf16 v[122:125], v[46:49], v[212:215], v[122:125]
	v_mfma_f32_16x16x32_bf16 v[110:113], v[38:41], v[220:223], v[110:113]
	v_mfma_f32_16x16x32_bf16 v[106:109], v[46:49], v[220:223], v[106:109]
	v_mfma_f32_16x16x32_bf16 v[94:97], v[38:41], v[228:231], v[94:97]
	v_mfma_f32_16x16x32_bf16 v[90:93], v[46:49], v[228:231], v[90:93]
	s_setprio 0
	s_setprio 1
	v_mfma_f32_16x16x32_bf16 v[134:137], v[146:149], v[200:203], v[134:137]
	v_mfma_f32_16x16x32_bf16 v[130:133], v[184:187], v[200:203], v[130:133]
	v_mfma_f32_16x16x32_bf16 v[118:121], v[146:149], v[208:211], v[118:121]
	v_mfma_f32_16x16x32_bf16 v[114:117], v[184:187], v[208:211], v[114:117]
	v_mfma_f32_16x16x32_bf16 v[102:105], v[146:149], v[216:219], v[102:105]
	v_mfma_f32_16x16x32_bf16 v[98:101], v[184:187], v[216:219], v[98:101]
	v_mfma_f32_16x16x32_bf16 v[86:89], v[146:149], v[224:227], v[86:89]
	v_mfma_f32_16x16x32_bf16 v[82:85], v[184:187], v[224:227], v[82:85]
	v_mfma_f32_16x16x32_bf16 v[134:137], v[150:153], v[204:207], v[134:137]
	v_mfma_f32_16x16x32_bf16 v[130:133], v[188:191], v[204:207], v[130:133]
	v_mfma_f32_16x16x32_bf16 v[118:121], v[150:153], v[212:215], v[118:121]
	v_mfma_f32_16x16x32_bf16 v[114:117], v[188:191], v[212:215], v[114:117]
	v_mfma_f32_16x16x32_bf16 v[102:105], v[150:153], v[220:223], v[102:105]
	v_mfma_f32_16x16x32_bf16 v[98:101], v[188:191], v[220:223], v[98:101]
	v_mfma_f32_16x16x32_bf16 v[86:89], v[150:153], v[228:231], v[86:89]
	v_mfma_f32_16x16x32_bf16 v[82:85], v[188:191], v[228:231], v[82:85]
	s_setprio 0
	s_barrier
	s_add_i32 s24, s84, s81
	v_lshl_add_u64 v[192:193], s[12:13], 0, v[156:157]
	s_mov_b32 m0, s24
	ds_read_b128 v[200:203], v198 offset:16384
	ds_read_b128 v[204:207], v198 offset:17408
	ds_read_b128 v[208:211], v198 offset:18432
	ds_read_b128 v[212:215], v198 offset:19456
	ds_read_b128 v[216:219], v198 offset:20480
	ds_read_b128 v[220:223], v198 offset:21504
	ds_read_b128 v[224:227], v198 offset:22528
	ds_read_b128 v[228:231], v198 offset:23552
	global_load_lds_dwordx4 v[192:193], off
	s_add_i32 m0, s24, 0x2000
	v_lshl_add_u64 v[232:233], s[12:13], 0, v[160:161]
	s_add_u32 s12, s12, s20
	s_addc_u32 s13, s13, s21
	s_add_i32 s24, s85, s81
	global_load_lds_dwordx4 v[232:233], off
	v_lshl_add_u64 v[234:235], s[12:13], 0, v[156:157]
	s_mov_b32 m0, s24
	v_lshl_add_u64 v[236:237], s[12:13], 0, v[160:161]
	global_load_lds_dwordx4 v[234:235], off
	s_add_i32 m0, s24, 0x2000
	v_lshl_add_u64 v[238:239], s[6:7], 0, v[154:155]
	global_load_lds_dwordx4 v[236:237], off
	s_mov_b32 m0, s88
	v_lshl_add_u64 v[240:241], s[6:7], 0, v[158:159]
	global_load_lds_dwordx4 v[238:239], off
	s_mov_b32 m0, s90
	s_nop 0
	global_load_lds_dwordx4 v[240:241], off
	s_waitcnt vmcnt(8)
	s_waitcnt lgkmcnt(0)
	s_setprio 1
	s_waitcnt lgkmcnt(0)
	v_mfma_f32_16x16x32_bf16 v[78:81], v[34:37], v[200:203], v[78:81]
	v_mfma_f32_16x16x32_bf16 v[74:77], v[42:45], v[200:203], v[74:77]
	s_barrier
	v_mfma_f32_16x16x32_bf16 v[62:65], v[34:37], v[208:211], v[62:65]
	v_mfma_f32_16x16x32_bf16 v[58:61], v[42:45], v[208:211], v[58:61]
	v_mfma_f32_16x16x32_bf16 v[30:33], v[34:37], v[216:219], v[30:33]
	v_mfma_f32_16x16x32_bf16 v[26:29], v[42:45], v[216:219], v[26:29]
	v_mfma_f32_16x16x32_bf16 v[14:17], v[34:37], v[224:227], v[14:17]
	v_mfma_f32_16x16x32_bf16 v[10:13], v[42:45], v[224:227], v[10:13]
	v_mfma_f32_16x16x32_bf16 v[78:81], v[38:41], v[204:207], v[78:81]
	v_mfma_f32_16x16x32_bf16 v[74:77], v[46:49], v[204:207], v[74:77]
	v_mfma_f32_16x16x32_bf16 v[62:65], v[38:41], v[212:215], v[62:65]
	v_mfma_f32_16x16x32_bf16 v[58:61], v[46:49], v[212:215], v[58:61]
	v_mfma_f32_16x16x32_bf16 v[30:33], v[38:41], v[220:223], v[30:33]
	v_mfma_f32_16x16x32_bf16 v[26:29], v[46:49], v[220:223], v[26:29]
	v_mfma_f32_16x16x32_bf16 v[14:17], v[38:41], v[228:231], v[14:17]
	v_mfma_f32_16x16x32_bf16 v[10:13], v[46:49], v[228:231], v[10:13]
	s_setprio 0
	s_setprio 1
	v_mfma_f32_16x16x32_bf16 v[22:25], v[146:149], v[216:219], v[22:25]
	v_mfma_f32_16x16x32_bf16 v[18:21], v[184:187], v[216:219], v[18:21]
	v_mfma_f32_16x16x32_bf16 v[6:9], v[146:149], v[224:227], v[6:9]
	v_mfma_f32_16x16x32_bf16 v[2:5], v[184:187], v[224:227], v[2:5]
	v_mfma_f32_16x16x32_bf16 v[34:37], v[146:149], v[200:203], v[70:73]
	v_mfma_f32_16x16x32_bf16 v[38:41], v[184:187], v[200:203], v[66:69]
	v_mfma_f32_16x16x32_bf16 v[42:45], v[146:149], v[208:211], v[54:57]
	v_mfma_f32_16x16x32_bf16 v[46:49], v[184:187], v[208:211], v[50:53]
	v_mfma_f32_16x16x32_bf16 v[22:25], v[150:153], v[220:223], v[22:25]
	v_mfma_f32_16x16x32_bf16 v[18:21], v[188:191], v[220:223], v[18:21]
	v_mfma_f32_16x16x32_bf16 v[6:9], v[150:153], v[228:231], v[6:9]
	v_mfma_f32_16x16x32_bf16 v[2:5], v[188:191], v[228:231], v[2:5]
	v_mfma_f32_16x16x32_bf16 v[34:37], v[150:153], v[204:207], v[34:37]
	v_mfma_f32_16x16x32_bf16 v[38:41], v[188:191], v[204:207], v[38:41]
	v_mfma_f32_16x16x32_bf16 v[42:45], v[150:153], v[212:215], v[42:45]
	v_mfma_f32_16x16x32_bf16 v[46:49], v[188:191], v[212:215], v[46:49]
	s_setprio 0
	s_barrier
	s_add_i32 s12, 0, 0x18000
	s_add_i32 s13, 0, 0x1c000
	v_add_u32_e32 v70, s12, v194
	v_add_u32_e32 v162, s13, v194
	ds_read_b128 v[50:53], v70
	ds_read_b128 v[54:57], v70 offset:1024
	ds_read_b128 v[66:69], v70 offset:2048
	ds_read_b128 v[70:73], v70 offset:3072
	ds_read_b128 v[146:149], v162
	ds_read_b128 v[150:153], v162 offset:1024
	ds_read_b128 v[184:187], v162 offset:2048
	ds_read_b128 v[188:191], v162 offset:3072
	s_add_u32 s6, s6, s20
	s_addc_u32 s7, s7, s21
	s_mov_b32 m0, s91
	v_lshl_add_u64 v[242:243], s[6:7], 0, v[154:155]
	ds_read_b128 v[200:203], v198 offset:32768
	ds_read_b128 v[204:207], v198 offset:33792
	ds_read_b128 v[208:211], v198 offset:34816
	ds_read_b128 v[212:215], v198 offset:35840
	ds_read_b128 v[216:219], v198 offset:36864
	ds_read_b128 v[220:223], v198 offset:37888
	ds_read_b128 v[224:227], v198 offset:38912
	ds_read_b128 v[228:231], v198 offset:39936
	global_load_lds_dwordx4 v[242:243], off
	v_lshl_add_u64 v[242:243], s[6:7], 0, v[158:159]
	s_mov_b32 m0, s95
	s_nop 0
	global_load_lds_dwordx4 v[242:243], off
	s_waitcnt vmcnt(8)
	s_waitcnt lgkmcnt(0)
	s_setprio 1
	s_waitcnt lgkmcnt(0)
	v_mfma_f32_16x16x32_bf16 v[142:145], v[50:53], v[200:203], v[142:145]
	v_mfma_f32_16x16x32_bf16 v[138:141], v[66:69], v[200:203], v[138:141]
	s_barrier
	v_mfma_f32_16x16x32_bf16 v[126:129], v[50:53], v[208:211], v[126:129]
	v_mfma_f32_16x16x32_bf16 v[122:125], v[66:69], v[208:211], v[122:125]
	v_mfma_f32_16x16x32_bf16 v[110:113], v[50:53], v[216:219], v[110:113]
	v_mfma_f32_16x16x32_bf16 v[106:109], v[66:69], v[216:219], v[106:109]
	v_mfma_f32_16x16x32_bf16 v[94:97], v[50:53], v[224:227], v[94:97]
	v_mfma_f32_16x16x32_bf16 v[90:93], v[66:69], v[224:227], v[90:93]
	v_mfma_f32_16x16x32_bf16 v[142:145], v[54:57], v[204:207], v[142:145]
	v_mfma_f32_16x16x32_bf16 v[138:141], v[70:73], v[204:207], v[138:141]
	v_mfma_f32_16x16x32_bf16 v[126:129], v[54:57], v[212:215], v[126:129]
	v_mfma_f32_16x16x32_bf16 v[122:125], v[70:73], v[212:215], v[122:125]
	v_mfma_f32_16x16x32_bf16 v[110:113], v[54:57], v[220:223], v[110:113]
	v_mfma_f32_16x16x32_bf16 v[106:109], v[70:73], v[220:223], v[106:109]
	v_mfma_f32_16x16x32_bf16 v[94:97], v[54:57], v[228:231], v[94:97]
	v_mfma_f32_16x16x32_bf16 v[90:93], v[70:73], v[228:231], v[90:93]
	s_setprio 0
	s_setprio 1
	v_mfma_f32_16x16x32_bf16 v[134:137], v[146:149], v[200:203], v[134:137]
	v_mfma_f32_16x16x32_bf16 v[130:133], v[184:187], v[200:203], v[130:133]
	v_mfma_f32_16x16x32_bf16 v[118:121], v[146:149], v[208:211], v[118:121]
	v_mfma_f32_16x16x32_bf16 v[114:117], v[184:187], v[208:211], v[114:117]
	v_mfma_f32_16x16x32_bf16 v[102:105], v[146:149], v[216:219], v[102:105]
	v_mfma_f32_16x16x32_bf16 v[98:101], v[184:187], v[216:219], v[98:101]
	v_mfma_f32_16x16x32_bf16 v[86:89], v[146:149], v[224:227], v[86:89]
	v_mfma_f32_16x16x32_bf16 v[82:85], v[184:187], v[224:227], v[82:85]
	v_mfma_f32_16x16x32_bf16 v[134:137], v[150:153], v[204:207], v[134:137]
	v_mfma_f32_16x16x32_bf16 v[130:133], v[188:191], v[204:207], v[130:133]
	v_mfma_f32_16x16x32_bf16 v[118:121], v[150:153], v[212:215], v[118:121]
	v_mfma_f32_16x16x32_bf16 v[114:117], v[188:191], v[212:215], v[114:117]
	v_mfma_f32_16x16x32_bf16 v[102:105], v[150:153], v[220:223], v[102:105]
	v_mfma_f32_16x16x32_bf16 v[98:101], v[188:191], v[220:223], v[98:101]
	v_mfma_f32_16x16x32_bf16 v[86:89], v[150:153], v[228:231], v[86:89]
	v_mfma_f32_16x16x32_bf16 v[82:85], v[188:191], v[228:231], v[82:85]
	s_setprio 0
	s_barrier
	s_add_i32 s6, s12, s81
	v_lshl_add_u64 v[192:193], v[192:193], 0, s[44:45]
	s_mov_b32 m0, s6
	ds_read_b128 v[200:203], v198 offset:49152
	ds_read_b128 v[204:207], v198 offset:50176
	ds_read_b128 v[208:211], v198 offset:51200
	ds_read_b128 v[212:215], v198 offset:52224
	ds_read_b128 v[216:219], v198 offset:53248
	ds_read_b128 v[220:223], v198 offset:54272
	ds_read_b128 v[224:227], v198 offset:55296
	ds_read_b128 v[228:231], v198 offset:56320
	global_load_lds_dwordx4 v[192:193], off
	v_lshl_add_u64 v[192:193], v[232:233], 0, s[44:45]
	s_add_i32 m0, s6, 0x2000
	s_add_i32 s6, s13, s81
	global_load_lds_dwordx4 v[192:193], off
	v_lshl_add_u64 v[192:193], v[234:235], 0, s[44:45]
	s_mov_b32 m0, s6
	s_nop 0
	global_load_lds_dwordx4 v[192:193], off
	v_lshl_add_u64 v[192:193], v[236:237], 0, s[44:45]
	s_add_i32 m0, s6, 0x2000
	s_nop 0
	global_load_lds_dwordx4 v[192:193], off
	v_lshl_add_u64 v[192:193], v[238:239], 0, s[44:45]
	s_mov_b32 m0, s17
	s_nop 0
	global_load_lds_dwordx4 v[192:193], off
	v_lshl_add_u64 v[192:193], v[240:241], 0, s[44:45]
	s_mov_b32 m0, s94
	s_nop 0
	global_load_lds_dwordx4 v[192:193], off
	s_waitcnt vmcnt(8)
	s_waitcnt lgkmcnt(0)
	s_setprio 1
	s_waitcnt lgkmcnt(0)
	v_mfma_f32_16x16x32_bf16 v[78:81], v[50:53], v[200:203], v[78:81]
	v_mfma_f32_16x16x32_bf16 v[74:77], v[66:69], v[200:203], v[74:77]
	s_barrier
	v_mfma_f32_16x16x32_bf16 v[62:65], v[50:53], v[208:211], v[62:65]
	v_mfma_f32_16x16x32_bf16 v[58:61], v[66:69], v[208:211], v[58:61]
	v_mfma_f32_16x16x32_bf16 v[30:33], v[50:53], v[216:219], v[30:33]
	v_mfma_f32_16x16x32_bf16 v[26:29], v[66:69], v[216:219], v[26:29]
	v_mfma_f32_16x16x32_bf16 v[14:17], v[50:53], v[224:227], v[14:17]
	v_mfma_f32_16x16x32_bf16 v[10:13], v[66:69], v[224:227], v[10:13]
	v_mfma_f32_16x16x32_bf16 v[78:81], v[54:57], v[204:207], v[78:81]
	v_mfma_f32_16x16x32_bf16 v[74:77], v[70:73], v[204:207], v[74:77]
	v_mfma_f32_16x16x32_bf16 v[62:65], v[54:57], v[212:215], v[62:65]
	v_mfma_f32_16x16x32_bf16 v[58:61], v[70:73], v[212:215], v[58:61]
	v_mfma_f32_16x16x32_bf16 v[30:33], v[54:57], v[220:223], v[30:33]
	v_mfma_f32_16x16x32_bf16 v[26:29], v[70:73], v[220:223], v[26:29]
	v_mfma_f32_16x16x32_bf16 v[14:17], v[54:57], v[228:231], v[14:17]
	v_mfma_f32_16x16x32_bf16 v[10:13], v[70:73], v[228:231], v[10:13]
	s_setprio 0
	s_setprio 1
	v_mfma_f32_16x16x32_bf16 v[34:37], v[146:149], v[200:203], v[34:37]
	v_mfma_f32_16x16x32_bf16 v[70:73], v[150:153], v[204:207], v[34:37]
	v_mfma_f32_16x16x32_bf16 v[34:37], v[184:187], v[200:203], v[38:41]
	v_mfma_f32_16x16x32_bf16 v[66:69], v[188:191], v[204:207], v[34:37]
	v_mfma_f32_16x16x32_bf16 v[34:37], v[146:149], v[208:211], v[42:45]
	v_mfma_f32_16x16x32_bf16 v[54:57], v[150:153], v[212:215], v[34:37]
	v_mfma_f32_16x16x32_bf16 v[34:37], v[184:187], v[208:211], v[46:49]
	v_mfma_f32_16x16x32_bf16 v[22:25], v[146:149], v[216:219], v[22:25]
	v_mfma_f32_16x16x32_bf16 v[18:21], v[184:187], v[216:219], v[18:21]
	v_mfma_f32_16x16x32_bf16 v[6:9], v[146:149], v[224:227], v[6:9]
	v_mfma_f32_16x16x32_bf16 v[2:5], v[184:187], v[224:227], v[2:5]
	v_mfma_f32_16x16x32_bf16 v[50:53], v[188:191], v[212:215], v[34:37]
	v_mfma_f32_16x16x32_bf16 v[22:25], v[150:153], v[220:223], v[22:25]
	v_mfma_f32_16x16x32_bf16 v[18:21], v[188:191], v[220:223], v[18:21]
	v_mfma_f32_16x16x32_bf16 v[6:9], v[150:153], v[228:231], v[6:9]
	v_mfma_f32_16x16x32_bf16 v[2:5], v[188:191], v[228:231], v[2:5]
	s_setprio 0
	s_barrier
	s_add_u32 s4, s4, 0x100
	s_addc_u32 s5, s5, 0
	s_add_u32 s8, s8, 0x100
	s_addc_u32 s9, s9, 0
	s_cmp_ge_i32 s11, s26
	s_mov_b32 s6, s11
	s_cbranch_scc0 .LBB0_408

.LBB0_895:
	v_add_u32_e32 v158, s84, v227
	v_add_u32_e32 v174, s85, v227
	ds_read_b128 v[146:149], v158
	ds_read_b128 v[150:153], v158 offset:1024
	ds_read_b128 v[154:157], v158 offset:2048
	ds_read_b128 v[158:161], v158 offset:3072
	ds_read_b128 v[162:165], v174
	ds_read_b128 v[166:169], v174 offset:1024
	ds_read_b128 v[170:173], v174 offset:2048
	ds_read_b128 v[174:177], v174 offset:3072
	s_add_i32 s16, s50, 2
	s_add_u32 s17, s46, 0x80
	s_addc_u32 s51, s47, 0
	s_cmp_eq_u32 s81, s50
	s_cselect_b32 s50, s4, s17
	s_cselect_b32 s51, s5, s51
	s_cselect_b32 s55, s45, vcc_hi
	s_cselect_b32 s54, s44, vcc_lo
	v_lshl_add_u64 v[210:211], s[46:47], 0, v[138:139]
	s_add_i32 m0, s63, 0xc000
	ds_read_b128 v[178:181], v229
	ds_read_b128 v[182:185], v229 offset:1024
	ds_read_b128 v[186:189], v229 offset:2048
	ds_read_b128 v[190:193], v229 offset:3072
	ds_read_b128 v[194:197], v229 offset:4096
	ds_read_b128 v[198:201], v229 offset:5120
	ds_read_b128 v[202:205], v229 offset:6144
	ds_read_b128 v[206:209], v229 offset:7168
	global_load_lds_dwordx4 v[210:211], off
	v_lshl_add_u64 v[210:211], s[46:47], 0, v[140:141]
	s_add_i32 m0, s63, 0xe000
	s_nop 0
	global_load_lds_dwordx4 v[210:211], off
	s_waitcnt vmcnt(8)
	s_waitcnt lgkmcnt(0)
	s_setprio 1
	s_waitcnt lgkmcnt(0)
	v_mfma_i32_16x16x64_i8 v[126:129], v[146:149], v[178:181], v[126:129]
	v_mfma_i32_16x16x64_i8 v[122:125], v[154:157], v[178:181], v[122:125]
	s_barrier
	v_mfma_i32_16x16x64_i8 v[118:121], v[146:149], v[186:189], v[118:121]
	v_mfma_i32_16x16x64_i8 v[114:117], v[154:157], v[186:189], v[114:117]
	v_mfma_i32_16x16x64_i8 v[106:109], v[146:149], v[194:197], v[106:109]
	v_mfma_i32_16x16x64_i8 v[98:101], v[154:157], v[194:197], v[98:101]
	v_mfma_i32_16x16x64_i8 v[90:93], v[146:149], v[202:205], v[90:93]
	v_mfma_i32_16x16x64_i8 v[82:85], v[154:157], v[202:205], v[82:85]
	v_mfma_i32_16x16x64_i8 v[126:129], v[150:153], v[182:185], v[126:129]
	v_mfma_i32_16x16x64_i8 v[122:125], v[158:161], v[182:185], v[122:125]
	v_mfma_i32_16x16x64_i8 v[118:121], v[150:153], v[190:193], v[118:121]
	v_mfma_i32_16x16x64_i8 v[114:117], v[158:161], v[190:193], v[114:117]
	v_mfma_i32_16x16x64_i8 v[106:109], v[150:153], v[198:201], v[106:109]
	v_mfma_i32_16x16x64_i8 v[98:101], v[158:161], v[198:201], v[98:101]
	v_mfma_i32_16x16x64_i8 v[90:93], v[150:153], v[206:209], v[90:93]
	v_mfma_i32_16x16x64_i8 v[82:85], v[158:161], v[206:209], v[82:85]
	s_setprio 0
	s_setprio 1
	v_mfma_i32_16x16x64_i8 v[110:113], v[162:165], v[178:181], v[110:113]
	v_mfma_i32_16x16x64_i8 v[102:105], v[170:173], v[178:181], v[102:105]
	v_mfma_i32_16x16x64_i8 v[94:97], v[162:165], v[186:189], v[94:97]
	v_mfma_i32_16x16x64_i8 v[86:89], v[170:173], v[186:189], v[86:89]
	v_mfma_i32_16x16x64_i8 v[78:81], v[162:165], v[194:197], v[78:81]
	v_mfma_i32_16x16x64_i8 v[74:77], v[170:173], v[194:197], v[74:77]
	v_mfma_i32_16x16x64_i8 v[70:73], v[162:165], v[202:205], v[70:73]
	v_mfma_i32_16x16x64_i8 v[66:69], v[170:173], v[202:205], v[66:69]
	v_mfma_i32_16x16x64_i8 v[110:113], v[166:169], v[182:185], v[110:113]
	v_mfma_i32_16x16x64_i8 v[102:105], v[174:177], v[182:185], v[102:105]
	v_mfma_i32_16x16x64_i8 v[94:97], v[166:169], v[190:193], v[94:97]
	v_mfma_i32_16x16x64_i8 v[86:89], v[174:177], v[190:193], v[86:89]
	v_mfma_i32_16x16x64_i8 v[78:81], v[166:169], v[198:201], v[78:81]
	v_mfma_i32_16x16x64_i8 v[74:77], v[174:177], v[198:201], v[74:77]
	v_mfma_i32_16x16x64_i8 v[70:73], v[166:169], v[206:209], v[70:73]
	v_mfma_i32_16x16x64_i8 v[66:69], v[174:177], v[206:209], v[66:69]
	s_setprio 0
	s_barrier
	s_add_i32 s17, s84, s62
	v_lshl_add_u64 v[210:211], s[54:55], 0, v[132:133]
	s_mov_b32 m0, s17
	ds_read_b128 v[178:181], v229 offset:16384
	ds_read_b128 v[182:185], v229 offset:17408
	ds_read_b128 v[186:189], v229 offset:18432
	ds_read_b128 v[190:193], v229 offset:19456
	ds_read_b128 v[194:197], v229 offset:20480
	ds_read_b128 v[198:201], v229 offset:21504
	ds_read_b128 v[202:205], v229 offset:22528
	ds_read_b128 v[206:209], v229 offset:23552
	global_load_lds_dwordx4 v[210:211], off
	s_add_i32 m0, s17, 0x2000
	v_lshl_add_u64 v[212:213], s[54:55], 0, v[136:137]
	s_add_u32 s54, s54, s8
	s_addc_u32 s55, s55, s9
	s_add_i32 s17, s85, s62
	global_load_lds_dwordx4 v[212:213], off
	v_lshl_add_u64 v[214:215], s[54:55], 0, v[132:133]
	s_mov_b32 m0, s17
	v_lshl_add_u64 v[216:217], s[54:55], 0, v[136:137]
	global_load_lds_dwordx4 v[214:215], off
	s_add_i32 m0, s17, 0x2000
	v_lshl_add_u64 v[218:219], s[50:51], 0, v[130:131]
	global_load_lds_dwordx4 v[216:217], off
	s_mov_b32 m0, s63
	v_lshl_add_u64 v[220:221], s[50:51], 0, v[134:135]
	global_load_lds_dwordx4 v[218:219], off
	s_mov_b32 m0, s64
	s_nop 0
	global_load_lds_dwordx4 v[220:221], off
	s_waitcnt vmcnt(8)
	s_waitcnt lgkmcnt(0)
	s_setprio 1
	s_waitcnt lgkmcnt(0)
	v_mfma_i32_16x16x64_i8 v[62:65], v[146:149], v[178:181], v[62:65]
	v_mfma_i32_16x16x64_i8 v[58:61], v[154:157], v[178:181], v[58:61]
	s_barrier
	v_mfma_i32_16x16x64_i8 v[54:57], v[146:149], v[186:189], v[54:57]
	v_mfma_i32_16x16x64_i8 v[50:53], v[154:157], v[186:189], v[50:53]
	v_mfma_i32_16x16x64_i8 v[42:45], v[146:149], v[194:197], v[42:45]
	v_mfma_i32_16x16x64_i8 v[34:37], v[154:157], v[194:197], v[34:37]
	v_mfma_i32_16x16x64_i8 v[26:29], v[146:149], v[202:205], v[26:29]
	v_mfma_i32_16x16x64_i8 v[18:21], v[154:157], v[202:205], v[18:21]
	v_mfma_i32_16x16x64_i8 v[62:65], v[150:153], v[182:185], v[62:65]
	v_mfma_i32_16x16x64_i8 v[58:61], v[158:161], v[182:185], v[58:61]
	v_mfma_i32_16x16x64_i8 v[54:57], v[150:153], v[190:193], v[54:57]
	v_mfma_i32_16x16x64_i8 v[50:53], v[158:161], v[190:193], v[50:53]
	v_mfma_i32_16x16x64_i8 v[42:45], v[150:153], v[198:201], v[42:45]
	v_mfma_i32_16x16x64_i8 v[34:37], v[158:161], v[198:201], v[34:37]
	v_mfma_i32_16x16x64_i8 v[26:29], v[150:153], v[206:209], v[26:29]
	v_mfma_i32_16x16x64_i8 v[18:21], v[158:161], v[206:209], v[18:21]
	s_setprio 0
	s_setprio 1
	v_mfma_i32_16x16x64_i8 v[46:49], v[162:165], v[178:181], v[46:49]
	v_mfma_i32_16x16x64_i8 v[38:41], v[170:173], v[178:181], v[38:41]
	v_mfma_i32_16x16x64_i8 v[30:33], v[162:165], v[186:189], v[30:33]
	v_mfma_i32_16x16x64_i8 v[22:25], v[170:173], v[186:189], v[22:25]
	v_mfma_i32_16x16x64_i8 v[14:17], v[162:165], v[194:197], v[14:17]
	v_mfma_i32_16x16x64_i8 v[10:13], v[170:173], v[194:197], v[10:13]
	v_mfma_i32_16x16x64_i8 v[6:9], v[162:165], v[202:205], v[6:9]
	v_mfma_i32_16x16x64_i8 v[2:5], v[170:173], v[202:205], v[2:5]
	v_mfma_i32_16x16x64_i8 v[46:49], v[166:169], v[182:185], v[46:49]
	v_mfma_i32_16x16x64_i8 v[38:41], v[174:177], v[182:185], v[38:41]
	v_mfma_i32_16x16x64_i8 v[30:33], v[166:169], v[190:193], v[30:33]
	v_mfma_i32_16x16x64_i8 v[22:25], v[174:177], v[190:193], v[22:25]
	v_mfma_i32_16x16x64_i8 v[14:17], v[166:169], v[198:201], v[14:17]
	v_mfma_i32_16x16x64_i8 v[10:13], v[174:177], v[198:201], v[10:13]
	v_mfma_i32_16x16x64_i8 v[6:9], v[166:169], v[206:209], v[6:9]
	v_mfma_i32_16x16x64_i8 v[2:5], v[174:177], v[206:209], v[2:5]
	s_setprio 0
	s_barrier
	s_add_i32 s17, 0, 0x18000
	s_add_i32 s54, 0, 0x1c000
	v_add_u32_e32 v158, s17, v227
	v_add_u32_e32 v174, s54, v227
	ds_read_b128 v[146:149], v158
	ds_read_b128 v[150:153], v158 offset:1024
	ds_read_b128 v[154:157], v158 offset:2048
	ds_read_b128 v[158:161], v158 offset:3072
	ds_read_b128 v[162:165], v174
	ds_read_b128 v[166:169], v174 offset:1024
	ds_read_b128 v[170:173], v174 offset:2048
	ds_read_b128 v[174:177], v174 offset:3072
	s_add_u32 s50, s50, s8
	s_addc_u32 s51, s51, s9
	s_mov_b32 m0, s65
	v_lshl_add_u64 v[222:223], s[50:51], 0, v[130:131]
	ds_read_b128 v[178:181], v229 offset:32768
	ds_read_b128 v[182:185], v229 offset:33792
	ds_read_b128 v[186:189], v229 offset:34816
	ds_read_b128 v[190:193], v229 offset:35840
	ds_read_b128 v[194:197], v229 offset:36864
	ds_read_b128 v[198:201], v229 offset:37888
	ds_read_b128 v[202:205], v229 offset:38912
	ds_read_b128 v[206:209], v229 offset:39936
	global_load_lds_dwordx4 v[222:223], off
	v_lshl_add_u64 v[222:223], s[50:51], 0, v[134:135]
	s_mov_b32 m0, s86
	s_nop 0
	global_load_lds_dwordx4 v[222:223], off
	s_waitcnt vmcnt(8)
	s_waitcnt lgkmcnt(0)
	s_setprio 1
	s_waitcnt lgkmcnt(0)
	v_mfma_i32_16x16x64_i8 v[126:129], v[146:149], v[178:181], v[126:129]
	v_mfma_i32_16x16x64_i8 v[122:125], v[154:157], v[178:181], v[122:125]
	s_barrier
	v_mfma_i32_16x16x64_i8 v[118:121], v[146:149], v[186:189], v[118:121]
	v_mfma_i32_16x16x64_i8 v[114:117], v[154:157], v[186:189], v[114:117]
	v_mfma_i32_16x16x64_i8 v[106:109], v[146:149], v[194:197], v[106:109]
	v_mfma_i32_16x16x64_i8 v[98:101], v[154:157], v[194:197], v[98:101]
	v_mfma_i32_16x16x64_i8 v[90:93], v[146:149], v[202:205], v[90:93]
	v_mfma_i32_16x16x64_i8 v[82:85], v[154:157], v[202:205], v[82:85]
	v_mfma_i32_16x16x64_i8 v[126:129], v[150:153], v[182:185], v[126:129]
	v_mfma_i32_16x16x64_i8 v[122:125], v[158:161], v[182:185], v[122:125]
	v_mfma_i32_16x16x64_i8 v[118:121], v[150:153], v[190:193], v[118:121]
	v_mfma_i32_16x16x64_i8 v[114:117], v[158:161], v[190:193], v[114:117]
	v_mfma_i32_16x16x64_i8 v[106:109], v[150:153], v[198:201], v[106:109]
	v_mfma_i32_16x16x64_i8 v[98:101], v[158:161], v[198:201], v[98:101]
	v_mfma_i32_16x16x64_i8 v[90:93], v[150:153], v[206:209], v[90:93]
	v_mfma_i32_16x16x64_i8 v[82:85], v[158:161], v[206:209], v[82:85]
	s_setprio 0
	s_setprio 1
	v_mfma_i32_16x16x64_i8 v[110:113], v[162:165], v[178:181], v[110:113]
	v_mfma_i32_16x16x64_i8 v[102:105], v[170:173], v[178:181], v[102:105]
	v_mfma_i32_16x16x64_i8 v[94:97], v[162:165], v[186:189], v[94:97]
	v_mfma_i32_16x16x64_i8 v[86:89], v[170:173], v[186:189], v[86:89]
	v_mfma_i32_16x16x64_i8 v[78:81], v[162:165], v[194:197], v[78:81]
	v_mfma_i32_16x16x64_i8 v[74:77], v[170:173], v[194:197], v[74:77]
	v_mfma_i32_16x16x64_i8 v[70:73], v[162:165], v[202:205], v[70:73]
	v_mfma_i32_16x16x64_i8 v[66:69], v[170:173], v[202:205], v[66:69]
	v_mfma_i32_16x16x64_i8 v[110:113], v[166:169], v[182:185], v[110:113]
	v_mfma_i32_16x16x64_i8 v[102:105], v[174:177], v[182:185], v[102:105]
	v_mfma_i32_16x16x64_i8 v[94:97], v[166:169], v[190:193], v[94:97]
	v_mfma_i32_16x16x64_i8 v[86:89], v[174:177], v[190:193], v[86:89]
	v_mfma_i32_16x16x64_i8 v[78:81], v[166:169], v[198:201], v[78:81]
	v_mfma_i32_16x16x64_i8 v[74:77], v[174:177], v[198:201], v[74:77]
	v_mfma_i32_16x16x64_i8 v[70:73], v[166:169], v[206:209], v[70:73]
	v_mfma_i32_16x16x64_i8 v[66:69], v[174:177], v[206:209], v[66:69]
	s_setprio 0
	s_barrier
	s_add_i32 s17, s17, s62
	v_lshl_add_u64 v[210:211], v[210:211], 0, s[36:37]
	s_mov_b32 m0, s17
	ds_read_b128 v[178:181], v229 offset:49152
	ds_read_b128 v[182:185], v229 offset:50176
	ds_read_b128 v[186:189], v229 offset:51200
	ds_read_b128 v[190:193], v229 offset:52224
	ds_read_b128 v[194:197], v229 offset:53248
	ds_read_b128 v[198:201], v229 offset:54272
	ds_read_b128 v[202:205], v229 offset:55296
	ds_read_b128 v[206:209], v229 offset:56320
	global_load_lds_dwordx4 v[210:211], off
	v_lshl_add_u64 v[210:211], v[212:213], 0, s[36:37]
	s_add_i32 m0, s17, 0x2000
	s_add_i32 s17, s54, s62
	global_load_lds_dwordx4 v[210:211], off
	v_lshl_add_u64 v[210:211], v[214:215], 0, s[36:37]
	s_mov_b32 m0, s17
	s_nop 0
	global_load_lds_dwordx4 v[210:211], off
	v_lshl_add_u64 v[210:211], v[216:217], 0, s[36:37]
	s_add_i32 m0, s17, 0x2000
	s_nop 0
	global_load_lds_dwordx4 v[210:211], off
	v_lshl_add_u64 v[210:211], v[218:219], 0, s[36:37]
	s_mov_b32 m0, s95
	s_nop 0
	global_load_lds_dwordx4 v[210:211], off
	v_lshl_add_u64 v[210:211], v[220:221], 0, s[36:37]
	s_mov_b32 m0, s80
	s_nop 0
	global_load_lds_dwordx4 v[210:211], off
	s_waitcnt vmcnt(8)
	s_waitcnt lgkmcnt(0)
	s_setprio 1
	s_waitcnt lgkmcnt(0)
	v_mfma_i32_16x16x64_i8 v[62:65], v[146:149], v[178:181], v[62:65]
	v_mfma_i32_16x16x64_i8 v[58:61], v[154:157], v[178:181], v[58:61]
	s_barrier
	v_mfma_i32_16x16x64_i8 v[54:57], v[146:149], v[186:189], v[54:57]
	v_mfma_i32_16x16x64_i8 v[50:53], v[154:157], v[186:189], v[50:53]
	v_mfma_i32_16x16x64_i8 v[42:45], v[146:149], v[194:197], v[42:45]
	v_mfma_i32_16x16x64_i8 v[34:37], v[154:157], v[194:197], v[34:37]
	v_mfma_i32_16x16x64_i8 v[26:29], v[146:149], v[202:205], v[26:29]
	v_mfma_i32_16x16x64_i8 v[18:21], v[154:157], v[202:205], v[18:21]
	v_mfma_i32_16x16x64_i8 v[62:65], v[150:153], v[182:185], v[62:65]
	v_mfma_i32_16x16x64_i8 v[58:61], v[158:161], v[182:185], v[58:61]
	v_mfma_i32_16x16x64_i8 v[54:57], v[150:153], v[190:193], v[54:57]
	v_mfma_i32_16x16x64_i8 v[50:53], v[158:161], v[190:193], v[50:53]
	v_mfma_i32_16x16x64_i8 v[42:45], v[150:153], v[198:201], v[42:45]
	v_mfma_i32_16x16x64_i8 v[34:37], v[158:161], v[198:201], v[34:37]
	v_mfma_i32_16x16x64_i8 v[26:29], v[150:153], v[206:209], v[26:29]
	v_mfma_i32_16x16x64_i8 v[18:21], v[158:161], v[206:209], v[18:21]
	s_setprio 0
	s_setprio 1
	v_mfma_i32_16x16x64_i8 v[46:49], v[162:165], v[178:181], v[46:49]
	v_mfma_i32_16x16x64_i8 v[38:41], v[170:173], v[178:181], v[38:41]
	v_mfma_i32_16x16x64_i8 v[30:33], v[162:165], v[186:189], v[30:33]
	v_mfma_i32_16x16x64_i8 v[22:25], v[170:173], v[186:189], v[22:25]
	v_mfma_i32_16x16x64_i8 v[14:17], v[162:165], v[194:197], v[14:17]
	v_mfma_i32_16x16x64_i8 v[10:13], v[170:173], v[194:197], v[10:13]
	v_mfma_i32_16x16x64_i8 v[6:9], v[162:165], v[202:205], v[6:9]
	v_mfma_i32_16x16x64_i8 v[2:5], v[170:173], v[202:205], v[2:5]
	v_mfma_i32_16x16x64_i8 v[46:49], v[166:169], v[182:185], v[46:49]
	v_mfma_i32_16x16x64_i8 v[38:41], v[174:177], v[182:185], v[38:41]
	v_mfma_i32_16x16x64_i8 v[30:33], v[166:169], v[190:193], v[30:33]
	v_mfma_i32_16x16x64_i8 v[22:25], v[174:177], v[190:193], v[22:25]
	v_mfma_i32_16x16x64_i8 v[14:17], v[166:169], v[198:201], v[14:17]
	v_mfma_i32_16x16x64_i8 v[10:13], v[174:177], v[198:201], v[10:13]
	v_mfma_i32_16x16x64_i8 v[6:9], v[166:169], v[206:209], v[6:9]
	v_mfma_i32_16x16x64_i8 v[2:5], v[174:177], v[206:209], v[2:5]
	s_setprio 0
	s_barrier
	s_add_u32 s46, s46, 0x100
	s_addc_u32 s47, s47, 0
	s_add_u32 vcc_lo, vcc_lo, 0x100
	s_addc_u32 vcc_hi, vcc_hi, 0
	s_cmp_ge_i32 s16, s90
	s_mov_b32 s50, s16
	s_cbranch_scc0 .LBB0_895
	v_cvt_f32_i32_e32 v220, v126
	v_cvt_f32_i32_e32 v221, v127
	v_cvt_f32_i32_e32 v218, v128
	v_cvt_f32_i32_e32 v219, v129
	v_cvt_f32_i32_e32 v224, v122
	v_cvt_f32_i32_e32 v225, v123
	v_cvt_f32_i32_e32 v222, v124
	v_cvt_f32_i32_e32 v223, v125
	v_cvt_f32_i32_e32 v212, v110
	v_cvt_f32_i32_e32 v213, v111
	v_cvt_f32_i32_e32 v210, v112
	v_cvt_f32_i32_e32 v211, v113
	v_cvt_f32_i32_e32 v216, v102
	v_cvt_f32_i32_e32 v217, v103
	v_cvt_f32_i32_e32 v214, v104
	v_cvt_f32_i32_e32 v215, v105
	v_cvt_f32_i32_e32 v204, v118
	v_cvt_f32_i32_e32 v205, v119
	v_cvt_f32_i32_e32 v202, v120
	v_cvt_f32_i32_e32 v203, v121
	v_cvt_f32_i32_e32 v208, v114
	v_cvt_f32_i32_e32 v209, v115
	v_cvt_f32_i32_e32 v206, v116
	v_cvt_f32_i32_e32 v207, v117
	v_cvt_f32_i32_e32 v198, v94
	v_cvt_f32_i32_e32 v199, v95
	v_cvt_f32_i32_e32 v194, v96
	v_cvt_f32_i32_e32 v195, v97
	v_cvt_f32_i32_e32 v200, v86
	v_cvt_f32_i32_e32 v201, v87
	v_cvt_f32_i32_e32 v196, v88
	v_cvt_f32_i32_e32 v197, v89
	v_cvt_f32_i32_e32 v188, v106
	v_cvt_f32_i32_e32 v189, v107
	v_cvt_f32_i32_e32 v186, v108
	v_cvt_f32_i32_e32 v187, v109
	v_cvt_f32_i32_e32 v192, v98
	v_cvt_f32_i32_e32 v193, v99
	v_cvt_f32_i32_e32 v190, v100
	v_cvt_f32_i32_e32 v191, v101
	v_cvt_f32_i32_e32 v182, v78
	v_cvt_f32_i32_e32 v183, v79
	v_cvt_f32_i32_e32 v178, v80
	v_cvt_f32_i32_e32 v179, v81
	v_cvt_f32_i32_e32 v184, v74
	v_cvt_f32_i32_e32 v185, v75
	v_cvt_f32_i32_e32 v180, v76
	v_cvt_f32_i32_e32 v181, v77
	v_cvt_f32_i32_e32 v170, v90
	v_cvt_f32_i32_e32 v171, v91
	v_cvt_f32_i32_e32 v168, v92
	v_cvt_f32_i32_e32 v169, v93
	v_cvt_f32_i32_e32 v174, v82
	v_cvt_f32_i32_e32 v175, v83
	v_cvt_f32_i32_e32 v172, v84
	v_cvt_f32_i32_e32 v173, v85
	v_cvt_f32_i32_e32 v164, v70
	v_cvt_f32_i32_e32 v165, v71
	v_cvt_f32_i32_e32 v160, v72
	v_cvt_f32_i32_e32 v161, v73
	v_cvt_f32_i32_e32 v166, v66
	v_cvt_f32_i32_e32 v167, v67
	v_cvt_f32_i32_e32 v162, v68
	v_cvt_f32_i32_e32 v163, v69
	v_cvt_f32_i32_e32 v154, v62
	v_cvt_f32_i32_e32 v155, v63
	v_cvt_f32_i32_e32 v152, v64
	v_cvt_f32_i32_e32 v153, v65
	v_cvt_f32_i32_e32 v158, v58
	v_cvt_f32_i32_e32 v159, v59
	v_cvt_f32_i32_e32 v156, v60
	v_cvt_f32_i32_e32 v157, v61
	v_cvt_f32_i32_e32 v148, v46
	v_cvt_f32_i32_e32 v149, v47
	v_cvt_f32_i32_e32 v128, v48
	v_cvt_f32_i32_e32 v129, v49
	v_cvt_f32_i32_e32 v150, v38
	v_cvt_f32_i32_e32 v151, v39
	v_cvt_f32_i32_e32 v146, v40
	v_cvt_f32_i32_e32 v147, v41
	v_cvt_f32_i32_e32 v122, v54
	v_cvt_f32_i32_e32 v123, v55
	v_cvt_f32_i32_e32 v120, v56
	v_cvt_f32_i32_e32 v121, v57
	v_cvt_f32_i32_e32 v126, v50
	v_cvt_f32_i32_e32 v127, v51
	v_cvt_f32_i32_e32 v124, v52
	v_cvt_f32_i32_e32 v125, v53
	v_cvt_f32_i32_e32 v114, v30
	v_cvt_f32_i32_e32 v115, v31
	v_cvt_f32_i32_e32 v110, v32
	v_cvt_f32_i32_e32 v111, v33
	v_cvt_f32_i32_e32 v116, v22
	v_cvt_f32_i32_e32 v117, v23
	v_cvt_f32_i32_e32 v112, v24
	v_cvt_f32_i32_e32 v113, v25
	v_cvt_f32_i32_e32 v102, v42
	v_cvt_f32_i32_e32 v103, v43
	v_cvt_f32_i32_e32 v100, v44
	v_cvt_f32_i32_e32 v101, v45
	v_cvt_f32_i32_e32 v106, v34
	v_cvt_f32_i32_e32 v107, v35
	v_cvt_f32_i32_e32 v104, v36
	v_cvt_f32_i32_e32 v105, v37
	v_cvt_f32_i32_e32 v96, v14
	v_cvt_f32_i32_e32 v97, v15
	v_cvt_f32_i32_e32 v92, v16
	v_cvt_f32_i32_e32 v93, v17
	v_cvt_f32_i32_e32 v98, v10
	v_cvt_f32_i32_e32 v99, v11
	v_cvt_f32_i32_e32 v94, v12
	v_cvt_f32_i32_e32 v95, v13
	v_cvt_f32_i32_e32 v52, v26
	v_cvt_f32_i32_e32 v53, v27
	v_cvt_f32_i32_e32 v50, v28
	v_cvt_f32_i32_e32 v51, v29
	v_cvt_f32_i32_e32 v56, v18
	v_cvt_f32_i32_e32 v57, v19
	v_cvt_f32_i32_e32 v54, v20
	v_cvt_f32_i32_e32 v55, v21
	v_cvt_f32_i32_e32 v46, v6
	v_cvt_f32_i32_e32 v47, v7
	v_cvt_f32_i32_e32 v42, v8
	v_cvt_f32_i32_e32 v43, v9
	v_cvt_f32_i32_e32 v48, v2
	v_cvt_f32_i32_e32 v49, v3
	v_cvt_f32_i32_e32 v44, v4
	v_cvt_f32_i32_e32 v45, v5

.LBB0_1087:
	v_add_u32_e32 v138, s80, v188
	ds_read_b128 v[148:151], v138
	ds_read_b128 v[152:155], v138 offset:1024
	ds_read_b128 v[156:159], v138 offset:2048
	ds_read_b128 v[160:163], v138 offset:3072
	v_add_u32_e32 v138, s81, v188
	ds_read_b128 v[164:167], v138
	ds_read_b128 v[168:171], v138 offset:1024
	ds_read_b128 v[172:175], v138 offset:2048
	ds_read_b128 v[176:179], v138 offset:3072
	s_add_i32 s84, s34, 2
	s_add_u32 s85, s30, 0x80
	s_addc_u32 s35, s31, 0
	s_cmp_eq_u32 s64, s34
	s_cselect_b32 s34, s2, s85
	s_cselect_b32 s35, s3, s35
	s_cselect_b32 s87, s29, s39
	s_cselect_b32 s86, s28, s38
	v_lshl_add_u64 v[184:185], s[30:31], 0, v[140:141]
	s_add_i32 m0, s50, 0xc000
	ds_read_b128 v[180:183], v189
	ds_read_b128 v[190:193], v189 offset:1024
	ds_read_b128 v[194:197], v189 offset:2048
	ds_read_b128 v[198:201], v189 offset:3072
	ds_read_b128 v[202:205], v189 offset:4096
	ds_read_b128 v[206:209], v189 offset:5120
	ds_read_b128 v[210:213], v189 offset:6144
	ds_read_b128 v[214:217], v189 offset:7168
	global_load_lds_dwordx4 v[184:185], off
	v_lshl_add_u64 v[184:185], s[30:31], 0, v[142:143]
	s_add_i32 m0, s50, 0xe000
	s_nop 0
	global_load_lds_dwordx4 v[184:185], off
	s_waitcnt vmcnt(8)
	s_waitcnt lgkmcnt(0)
	s_setprio 1
	s_waitcnt lgkmcnt(0)
	v_mfma_i32_16x16x64_i8 v[126:129], v[148:151], v[180:183], v[126:129]
	v_mfma_i32_16x16x64_i8 v[122:125], v[156:159], v[180:183], v[122:125]
	s_barrier
	v_mfma_i32_16x16x64_i8 v[118:121], v[148:151], v[194:197], v[118:121]
	v_mfma_i32_16x16x64_i8 v[114:117], v[156:159], v[194:197], v[114:117]
	v_mfma_i32_16x16x64_i8 v[106:109], v[148:151], v[202:205], v[106:109]
	v_mfma_i32_16x16x64_i8 v[98:101], v[156:159], v[202:205], v[98:101]
	v_mfma_i32_16x16x64_i8 v[90:93], v[148:151], v[210:213], v[90:93]
	v_mfma_i32_16x16x64_i8 v[82:85], v[156:159], v[210:213], v[82:85]
	v_mfma_i32_16x16x64_i8 v[126:129], v[152:155], v[190:193], v[126:129]
	v_mfma_i32_16x16x64_i8 v[122:125], v[160:163], v[190:193], v[122:125]
	v_mfma_i32_16x16x64_i8 v[118:121], v[152:155], v[198:201], v[118:121]
	v_mfma_i32_16x16x64_i8 v[114:117], v[160:163], v[198:201], v[114:117]
	v_mfma_i32_16x16x64_i8 v[106:109], v[152:155], v[206:209], v[106:109]
	v_mfma_i32_16x16x64_i8 v[98:101], v[160:163], v[206:209], v[98:101]
	v_mfma_i32_16x16x64_i8 v[90:93], v[152:155], v[214:217], v[90:93]
	v_mfma_i32_16x16x64_i8 v[82:85], v[160:163], v[214:217], v[82:85]
	s_setprio 0
	s_setprio 1
	v_mfma_i32_16x16x64_i8 v[110:113], v[164:167], v[180:183], v[110:113]
	v_mfma_i32_16x16x64_i8 v[102:105], v[172:175], v[180:183], v[102:105]
	v_mfma_i32_16x16x64_i8 v[94:97], v[164:167], v[194:197], v[94:97]
	v_mfma_i32_16x16x64_i8 v[86:89], v[172:175], v[194:197], v[86:89]
	v_mfma_i32_16x16x64_i8 v[78:81], v[164:167], v[202:205], v[78:81]
	v_mfma_i32_16x16x64_i8 v[74:77], v[172:175], v[202:205], v[74:77]
	v_mfma_i32_16x16x64_i8 v[70:73], v[164:167], v[210:213], v[70:73]
	v_mfma_i32_16x16x64_i8 v[66:69], v[172:175], v[210:213], v[66:69]
	v_mfma_i32_16x16x64_i8 v[110:113], v[168:171], v[190:193], v[110:113]
	v_mfma_i32_16x16x64_i8 v[102:105], v[176:179], v[190:193], v[102:105]
	v_mfma_i32_16x16x64_i8 v[94:97], v[168:171], v[198:201], v[94:97]
	v_mfma_i32_16x16x64_i8 v[86:89], v[176:179], v[198:201], v[86:89]
	v_mfma_i32_16x16x64_i8 v[78:81], v[168:171], v[206:209], v[78:81]
	v_mfma_i32_16x16x64_i8 v[74:77], v[176:179], v[206:209], v[74:77]
	v_mfma_i32_16x16x64_i8 v[70:73], v[168:171], v[214:217], v[70:73]
	v_mfma_i32_16x16x64_i8 v[66:69], v[176:179], v[214:217], v[66:69]
	s_setprio 0
	s_barrier
	s_add_i32 s85, s80, s47
	v_lshl_add_u64 v[184:185], s[86:87], 0, v[132:133]
	s_mov_b32 m0, s85
	ds_read_b128 v[180:183], v189 offset:16384
	ds_read_b128 v[190:193], v189 offset:17408
	ds_read_b128 v[194:197], v189 offset:18432
	ds_read_b128 v[198:201], v189 offset:19456
	ds_read_b128 v[202:205], v189 offset:20480
	ds_read_b128 v[206:209], v189 offset:21504
	ds_read_b128 v[210:213], v189 offset:22528
	ds_read_b128 v[214:217], v189 offset:23552
	global_load_lds_dwordx4 v[184:185], off
	s_add_i32 m0, s85, 0x2000
	v_lshl_add_u64 v[218:219], s[86:87], 0, v[136:137]
	s_add_u32 s86, s86, s6
	s_addc_u32 s87, s87, s7
	s_add_i32 s85, s81, s47
	global_load_lds_dwordx4 v[218:219], off
	v_lshl_add_u64 v[220:221], s[86:87], 0, v[132:133]
	s_mov_b32 m0, s85
	v_lshl_add_u64 v[222:223], s[86:87], 0, v[136:137]
	global_load_lds_dwordx4 v[220:221], off
	s_add_i32 m0, s85, 0x2000
	v_lshl_add_u64 v[224:225], s[34:35], 0, v[130:131]
	global_load_lds_dwordx4 v[222:223], off
	s_mov_b32 m0, s50
	v_lshl_add_u64 v[226:227], s[34:35], 0, v[134:135]
	global_load_lds_dwordx4 v[224:225], off
	s_mov_b32 m0, s51
	s_nop 0
	global_load_lds_dwordx4 v[226:227], off
	s_waitcnt vmcnt(8)
	s_waitcnt lgkmcnt(0)
	s_setprio 1
	s_waitcnt lgkmcnt(0)
	v_mfma_i32_16x16x64_i8 v[62:65], v[148:151], v[180:183], v[62:65]
	v_mfma_i32_16x16x64_i8 v[58:61], v[156:159], v[180:183], v[58:61]
	s_barrier
	v_mfma_i32_16x16x64_i8 v[54:57], v[148:151], v[194:197], v[54:57]
	v_mfma_i32_16x16x64_i8 v[50:53], v[156:159], v[194:197], v[50:53]
	v_mfma_i32_16x16x64_i8 v[42:45], v[148:151], v[202:205], v[42:45]
	v_mfma_i32_16x16x64_i8 v[34:37], v[156:159], v[202:205], v[34:37]
	v_mfma_i32_16x16x64_i8 v[26:29], v[148:151], v[210:213], v[26:29]
	v_mfma_i32_16x16x64_i8 v[18:21], v[156:159], v[210:213], v[18:21]
	v_mfma_i32_16x16x64_i8 v[62:65], v[152:155], v[190:193], v[62:65]
	v_mfma_i32_16x16x64_i8 v[58:61], v[160:163], v[190:193], v[58:61]
	v_mfma_i32_16x16x64_i8 v[54:57], v[152:155], v[198:201], v[54:57]
	v_mfma_i32_16x16x64_i8 v[50:53], v[160:163], v[198:201], v[50:53]
	v_mfma_i32_16x16x64_i8 v[42:45], v[152:155], v[206:209], v[42:45]
	v_mfma_i32_16x16x64_i8 v[34:37], v[160:163], v[206:209], v[34:37]
	v_mfma_i32_16x16x64_i8 v[26:29], v[152:155], v[214:217], v[26:29]
	v_mfma_i32_16x16x64_i8 v[18:21], v[160:163], v[214:217], v[18:21]
	s_setprio 0
	s_setprio 1
	v_mfma_i32_16x16x64_i8 v[46:49], v[164:167], v[180:183], v[46:49]
	v_mfma_i32_16x16x64_i8 v[38:41], v[172:175], v[180:183], v[38:41]
	v_mfma_i32_16x16x64_i8 v[30:33], v[164:167], v[194:197], v[30:33]
	v_mfma_i32_16x16x64_i8 v[22:25], v[172:175], v[194:197], v[22:25]
	v_mfma_i32_16x16x64_i8 v[14:17], v[164:167], v[202:205], v[14:17]
	v_mfma_i32_16x16x64_i8 v[10:13], v[172:175], v[202:205], v[10:13]
	v_mfma_i32_16x16x64_i8 v[6:9], v[164:167], v[210:213], v[6:9]
	v_mfma_i32_16x16x64_i8 v[2:5], v[172:175], v[210:213], v[2:5]
	v_mfma_i32_16x16x64_i8 v[46:49], v[168:171], v[190:193], v[46:49]
	v_mfma_i32_16x16x64_i8 v[38:41], v[176:179], v[190:193], v[38:41]
	v_mfma_i32_16x16x64_i8 v[30:33], v[168:171], v[198:201], v[30:33]
	v_mfma_i32_16x16x64_i8 v[22:25], v[176:179], v[198:201], v[22:25]
	v_mfma_i32_16x16x64_i8 v[14:17], v[168:171], v[206:209], v[14:17]
	v_mfma_i32_16x16x64_i8 v[10:13], v[176:179], v[206:209], v[10:13]
	v_mfma_i32_16x16x64_i8 v[6:9], v[168:171], v[214:217], v[6:9]
	v_mfma_i32_16x16x64_i8 v[2:5], v[176:179], v[214:217], v[2:5]
	s_setprio 0
	s_barrier
	s_add_i32 s85, 0, 0x18000
	v_add_u32_e32 v138, s85, v188
	s_add_i32 s86, 0, 0x1c000
	ds_read_b128 v[148:151], v138
	ds_read_b128 v[152:155], v138 offset:1024
	ds_read_b128 v[156:159], v138 offset:2048
	ds_read_b128 v[160:163], v138 offset:3072
	v_add_u32_e32 v138, s86, v188
	ds_read_b128 v[164:167], v138
	ds_read_b128 v[168:171], v138 offset:1024
	ds_read_b128 v[172:175], v138 offset:2048
	ds_read_b128 v[176:179], v138 offset:3072
	s_add_u32 s34, s34, s6
	s_addc_u32 s35, s35, s7
	s_mov_b32 m0, s54
	v_lshl_add_u64 v[228:229], s[34:35], 0, v[130:131]
	ds_read_b128 v[180:183], v189 offset:32768
	ds_read_b128 v[190:193], v189 offset:33792
	ds_read_b128 v[194:197], v189 offset:34816
	ds_read_b128 v[198:201], v189 offset:35840
	ds_read_b128 v[202:205], v189 offset:36864
	ds_read_b128 v[206:209], v189 offset:37888
	ds_read_b128 v[210:213], v189 offset:38912
	ds_read_b128 v[214:217], v189 offset:39936
	global_load_lds_dwordx4 v[228:229], off
	v_lshl_add_u64 v[228:229], s[34:35], 0, v[134:135]
	s_mov_b32 m0, s55
	s_nop 0
	global_load_lds_dwordx4 v[228:229], off
	s_waitcnt vmcnt(8)
	s_waitcnt lgkmcnt(0)
	s_setprio 1
	s_waitcnt lgkmcnt(0)
	v_mfma_i32_16x16x64_i8 v[126:129], v[148:151], v[180:183], v[126:129]
	v_mfma_i32_16x16x64_i8 v[122:125], v[156:159], v[180:183], v[122:125]
	s_barrier
	v_mfma_i32_16x16x64_i8 v[118:121], v[148:151], v[194:197], v[118:121]
	v_mfma_i32_16x16x64_i8 v[114:117], v[156:159], v[194:197], v[114:117]
	v_mfma_i32_16x16x64_i8 v[106:109], v[148:151], v[202:205], v[106:109]
	v_mfma_i32_16x16x64_i8 v[98:101], v[156:159], v[202:205], v[98:101]
	v_mfma_i32_16x16x64_i8 v[90:93], v[148:151], v[210:213], v[90:93]
	v_mfma_i32_16x16x64_i8 v[82:85], v[156:159], v[210:213], v[82:85]
	v_mfma_i32_16x16x64_i8 v[126:129], v[152:155], v[190:193], v[126:129]
	v_mfma_i32_16x16x64_i8 v[122:125], v[160:163], v[190:193], v[122:125]
	v_mfma_i32_16x16x64_i8 v[118:121], v[152:155], v[198:201], v[118:121]
	v_mfma_i32_16x16x64_i8 v[114:117], v[160:163], v[198:201], v[114:117]
	v_mfma_i32_16x16x64_i8 v[106:109], v[152:155], v[206:209], v[106:109]
	v_mfma_i32_16x16x64_i8 v[98:101], v[160:163], v[206:209], v[98:101]
	v_mfma_i32_16x16x64_i8 v[90:93], v[152:155], v[214:217], v[90:93]
	v_mfma_i32_16x16x64_i8 v[82:85], v[160:163], v[214:217], v[82:85]
	s_setprio 0
	s_setprio 1
	v_mfma_i32_16x16x64_i8 v[110:113], v[164:167], v[180:183], v[110:113]
	v_mfma_i32_16x16x64_i8 v[102:105], v[172:175], v[180:183], v[102:105]
	v_mfma_i32_16x16x64_i8 v[94:97], v[164:167], v[194:197], v[94:97]
	v_mfma_i32_16x16x64_i8 v[86:89], v[172:175], v[194:197], v[86:89]
	v_mfma_i32_16x16x64_i8 v[78:81], v[164:167], v[202:205], v[78:81]
	v_mfma_i32_16x16x64_i8 v[74:77], v[172:175], v[202:205], v[74:77]
	v_mfma_i32_16x16x64_i8 v[70:73], v[164:167], v[210:213], v[70:73]
	v_mfma_i32_16x16x64_i8 v[66:69], v[172:175], v[210:213], v[66:69]
	v_mfma_i32_16x16x64_i8 v[110:113], v[168:171], v[190:193], v[110:113]
	v_mfma_i32_16x16x64_i8 v[102:105], v[176:179], v[190:193], v[102:105]
	v_mfma_i32_16x16x64_i8 v[94:97], v[168:171], v[198:201], v[94:97]
	v_mfma_i32_16x16x64_i8 v[86:89], v[176:179], v[198:201], v[86:89]
	v_mfma_i32_16x16x64_i8 v[78:81], v[168:171], v[206:209], v[78:81]
	v_mfma_i32_16x16x64_i8 v[74:77], v[176:179], v[206:209], v[74:77]
	v_mfma_i32_16x16x64_i8 v[70:73], v[168:171], v[214:217], v[70:73]
	v_mfma_i32_16x16x64_i8 v[66:69], v[176:179], v[214:217], v[66:69]
	s_setprio 0
	s_barrier
	s_add_i32 s34, s85, s47
	v_lshl_add_u64 v[184:185], v[184:185], 0, s[22:23]
	s_mov_b32 m0, s34
	ds_read_b128 v[180:183], v189 offset:49152
	ds_read_b128 v[190:193], v189 offset:50176
	ds_read_b128 v[194:197], v189 offset:51200
	ds_read_b128 v[198:201], v189 offset:52224
	ds_read_b128 v[202:205], v189 offset:53248
	ds_read_b128 v[206:209], v189 offset:54272
	ds_read_b128 v[210:213], v189 offset:55296
	ds_read_b128 v[214:217], v189 offset:56320
	global_load_lds_dwordx4 v[184:185], off
	v_lshl_add_u64 v[184:185], v[218:219], 0, s[22:23]
	s_add_i32 m0, s34, 0x2000
	s_add_i32 s34, s86, s47
	global_load_lds_dwordx4 v[184:185], off
	v_lshl_add_u64 v[184:185], v[220:221], 0, s[22:23]
	s_mov_b32 m0, s34
	s_nop 0
	global_load_lds_dwordx4 v[184:185], off
	v_lshl_add_u64 v[184:185], v[222:223], 0, s[22:23]
	s_add_i32 m0, s34, 0x2000
	s_nop 0
	global_load_lds_dwordx4 v[184:185], off
	v_lshl_add_u64 v[184:185], v[224:225], 0, s[22:23]
	s_mov_b32 m0, s59
	s_nop 0
	global_load_lds_dwordx4 v[184:185], off
	v_lshl_add_u64 v[184:185], v[226:227], 0, s[22:23]
	s_mov_b32 m0, s60
	s_nop 0
	global_load_lds_dwordx4 v[184:185], off
	s_waitcnt vmcnt(8)
	s_waitcnt lgkmcnt(0)
	s_setprio 1
	s_waitcnt lgkmcnt(0)
	v_mfma_i32_16x16x64_i8 v[62:65], v[148:151], v[180:183], v[62:65]
	v_mfma_i32_16x16x64_i8 v[58:61], v[156:159], v[180:183], v[58:61]
	s_barrier
	v_mfma_i32_16x16x64_i8 v[54:57], v[148:151], v[194:197], v[54:57]
	v_mfma_i32_16x16x64_i8 v[50:53], v[156:159], v[194:197], v[50:53]
	v_mfma_i32_16x16x64_i8 v[42:45], v[148:151], v[202:205], v[42:45]
	v_mfma_i32_16x16x64_i8 v[34:37], v[156:159], v[202:205], v[34:37]
	v_mfma_i32_16x16x64_i8 v[26:29], v[148:151], v[210:213], v[26:29]
	v_mfma_i32_16x16x64_i8 v[18:21], v[156:159], v[210:213], v[18:21]
	v_mfma_i32_16x16x64_i8 v[62:65], v[152:155], v[190:193], v[62:65]
	v_mfma_i32_16x16x64_i8 v[58:61], v[160:163], v[190:193], v[58:61]
	v_mfma_i32_16x16x64_i8 v[54:57], v[152:155], v[198:201], v[54:57]
	v_mfma_i32_16x16x64_i8 v[50:53], v[160:163], v[198:201], v[50:53]
	v_mfma_i32_16x16x64_i8 v[42:45], v[152:155], v[206:209], v[42:45]
	v_mfma_i32_16x16x64_i8 v[34:37], v[160:163], v[206:209], v[34:37]
	v_mfma_i32_16x16x64_i8 v[26:29], v[152:155], v[214:217], v[26:29]
	v_mfma_i32_16x16x64_i8 v[18:21], v[160:163], v[214:217], v[18:21]
	s_setprio 0
	s_setprio 1
	v_mfma_i32_16x16x64_i8 v[46:49], v[164:167], v[180:183], v[46:49]
	v_mfma_i32_16x16x64_i8 v[38:41], v[172:175], v[180:183], v[38:41]
	v_mfma_i32_16x16x64_i8 v[30:33], v[164:167], v[194:197], v[30:33]
	v_mfma_i32_16x16x64_i8 v[22:25], v[172:175], v[194:197], v[22:25]
	v_mfma_i32_16x16x64_i8 v[14:17], v[164:167], v[202:205], v[14:17]
	v_mfma_i32_16x16x64_i8 v[10:13], v[172:175], v[202:205], v[10:13]
	v_mfma_i32_16x16x64_i8 v[6:9], v[164:167], v[210:213], v[6:9]
	v_mfma_i32_16x16x64_i8 v[2:5], v[172:175], v[210:213], v[2:5]
	v_mfma_i32_16x16x64_i8 v[46:49], v[168:171], v[190:193], v[46:49]
	v_mfma_i32_16x16x64_i8 v[38:41], v[176:179], v[190:193], v[38:41]
	v_mfma_i32_16x16x64_i8 v[30:33], v[168:171], v[198:201], v[30:33]
	v_mfma_i32_16x16x64_i8 v[22:25], v[176:179], v[198:201], v[22:25]
	v_mfma_i32_16x16x64_i8 v[14:17], v[168:171], v[206:209], v[14:17]
	v_mfma_i32_16x16x64_i8 v[10:13], v[176:179], v[206:209], v[10:13]
	v_mfma_i32_16x16x64_i8 v[6:9], v[168:171], v[214:217], v[6:9]
	v_mfma_i32_16x16x64_i8 v[2:5], v[176:179], v[214:217], v[2:5]
	s_setprio 0
	s_barrier
	s_add_u32 s30, s30, 0x100
	s_addc_u32 s31, s31, 0
	s_add_u32 s38, s38, 0x100
	s_addc_u32 s39, s39, 0
	s_cmp_ge_i32 s84, s61
	s_mov_b32 s34, s84
	s_cbranch_scc0 .LBB0_1087
	v_cvt_f32_i32_e32 v172, v126
	v_cvt_f32_i32_e32 v173, v127
	v_cvt_f32_i32_e32 v170, v128
	v_cvt_f32_i32_e32 v171, v129
	v_cvt_f32_i32_e32 v174, v122
	v_cvt_f32_i32_e32 v175, v123
	v_cvt_f32_i32_e32 v176, v124
	v_cvt_f32_i32_e32 v177, v125
	v_cvt_f32_i32_e32 v180, v110
	v_cvt_f32_i32_e32 v181, v111
	v_cvt_f32_i32_e32 v182, v112
	v_cvt_f32_i32_e32 v183, v113
	v_cvt_f32_i32_e32 v178, v102
	v_cvt_f32_i32_e32 v179, v103
	v_cvt_f32_i32_e32 v184, v104
	v_cvt_f32_i32_e32 v185, v105
	v_cvt_f32_i32_e32 v152, v118
	v_cvt_f32_i32_e32 v153, v119
	v_cvt_f32_i32_e32 v154, v120
	v_cvt_f32_i32_e32 v155, v121
	v_cvt_f32_i32_e32 v156, v114
	v_cvt_f32_i32_e32 v157, v115
	v_cvt_f32_i32_e32 v158, v116
	v_cvt_f32_i32_e32 v159, v117
	v_cvt_f32_i32_e32 v160, v94
	v_cvt_f32_i32_e32 v161, v95
	v_cvt_f32_i32_e32 v162, v96
	v_cvt_f32_i32_e32 v163, v97
	v_cvt_f32_i32_e32 v164, v86
	v_cvt_f32_i32_e32 v165, v87
	v_cvt_f32_i32_e32 v166, v88
	v_cvt_f32_i32_e32 v167, v89
	v_cvt_f32_i32_e32 v118, v106
	v_cvt_f32_i32_e32 v119, v107
	v_cvt_f32_i32_e32 v120, v108
	v_cvt_f32_i32_e32 v121, v109
	v_cvt_f32_i32_e32 v122, v98
	v_cvt_f32_i32_e32 v123, v99
	v_cvt_f32_i32_e32 v124, v100
	v_cvt_f32_i32_e32 v125, v101
	v_cvt_f32_i32_e32 v126, v78
	v_cvt_f32_i32_e32 v127, v79
	v_cvt_f32_i32_e32 v128, v80
	v_cvt_f32_i32_e32 v129, v81
	v_cvt_f32_i32_e32 v148, v74
	v_cvt_f32_i32_e32 v149, v75
	v_cvt_f32_i32_e32 v150, v76
	v_cvt_f32_i32_e32 v151, v77
	v_cvt_f32_i32_e32 v102, v90
	v_cvt_f32_i32_e32 v103, v91
	v_cvt_f32_i32_e32 v104, v92
	v_cvt_f32_i32_e32 v105, v93
	v_cvt_f32_i32_e32 v106, v82
	v_cvt_f32_i32_e32 v107, v83
	v_cvt_f32_i32_e32 v108, v84
	v_cvt_f32_i32_e32 v109, v85
	v_cvt_f32_i32_e32 v110, v70
	v_cvt_f32_i32_e32 v111, v71
	v_cvt_f32_i32_e32 v112, v72
	v_cvt_f32_i32_e32 v113, v73
	v_cvt_f32_i32_e32 v114, v66
	v_cvt_f32_i32_e32 v115, v67
	v_cvt_f32_i32_e32 v116, v68
	v_cvt_f32_i32_e32 v117, v69
	v_cvt_f32_i32_e32 v82, v62
	v_cvt_f32_i32_e32 v83, v63
	v_cvt_f32_i32_e32 v84, v64
	v_cvt_f32_i32_e32 v85, v65
	v_cvt_f32_i32_e32 v86, v58
	v_cvt_f32_i32_e32 v87, v59
	v_cvt_f32_i32_e32 v88, v60
	v_cvt_f32_i32_e32 v89, v61
	v_cvt_f32_i32_e32 v92, v46
	v_cvt_f32_i32_e32 v93, v47
	v_cvt_f32_i32_e32 v94, v48
	v_cvt_f32_i32_e32 v95, v49
	v_cvt_f32_i32_e32 v96, v38
	v_cvt_f32_i32_e32 v97, v39
	v_cvt_f32_i32_e32 v98, v40
	v_cvt_f32_i32_e32 v99, v41
	v_cvt_f32_i32_e32 v66, v54
	v_cvt_f32_i32_e32 v67, v55
	v_cvt_f32_i32_e32 v68, v56
	v_cvt_f32_i32_e32 v69, v57
	v_cvt_f32_i32_e32 v70, v50
	v_cvt_f32_i32_e32 v71, v51
	v_cvt_f32_i32_e32 v72, v52
	v_cvt_f32_i32_e32 v73, v53
	v_cvt_f32_i32_e32 v74, v30
	v_cvt_f32_i32_e32 v75, v31
	v_cvt_f32_i32_e32 v76, v32
	v_cvt_f32_i32_e32 v77, v33
	v_cvt_f32_i32_e32 v78, v22
	v_cvt_f32_i32_e32 v79, v23
	v_cvt_f32_i32_e32 v80, v24
	v_cvt_f32_i32_e32 v81, v25
	v_cvt_f32_i32_e32 v50, v42
	v_cvt_f32_i32_e32 v51, v43
	v_cvt_f32_i32_e32 v52, v44
	v_cvt_f32_i32_e32 v53, v45
	v_cvt_f32_i32_e32 v54, v34
	v_cvt_f32_i32_e32 v55, v35
	v_cvt_f32_i32_e32 v56, v36
	v_cvt_f32_i32_e32 v57, v37
	v_cvt_f32_i32_e32 v58, v14
	v_cvt_f32_i32_e32 v59, v15
	v_cvt_f32_i32_e32 v60, v16
	v_cvt_f32_i32_e32 v61, v17
	v_cvt_f32_i32_e32 v62, v10
	v_cvt_f32_i32_e32 v63, v11
	v_cvt_f32_i32_e32 v64, v12
	v_cvt_f32_i32_e32 v65, v13
	v_cvt_f32_i32_e32 v34, v26
	v_cvt_f32_i32_e32 v35, v27
	v_cvt_f32_i32_e32 v36, v28
	v_cvt_f32_i32_e32 v37, v29
	v_cvt_f32_i32_e32 v38, v18
	v_cvt_f32_i32_e32 v39, v19
	v_cvt_f32_i32_e32 v40, v20
	v_cvt_f32_i32_e32 v41, v21
	v_cvt_f32_i32_e32 v42, v6
	v_cvt_f32_i32_e32 v43, v7
	v_cvt_f32_i32_e32 v44, v8
	v_cvt_f32_i32_e32 v45, v9
	v_cvt_f32_i32_e32 v46, v2
	v_cvt_f32_i32_e32 v47, v3
	v_cvt_f32_i32_e32 v48, v4
	v_cvt_f32_i32_e32 v49, v5

.LBB0_1170:
	s_waitcnt lgkmcnt(0)
	ds_read_b128 v[114:117], v209
	ds_read_b128 v[118:121], v209 offset:1024
	ds_read_b128 v[122:125], v209 offset:2048
	ds_read_b128 v[126:129], v209 offset:3072
	ds_read_b128 v[146:149], v210
	ds_read_b128 v[150:153], v210 offset:1024
	ds_read_b128 v[154:157], v210 offset:2048
	ds_read_b128 v[158:161], v210 offset:3072
	s_add_i32 s92, s42, 2
	s_add_u32 s43, s38, 0x4000
	s_addc_u32 s44, s39, 0
	s_cmp_eq_u32 s81, s42
	s_cselect_b32 s45, s5, s44
	s_cselect_b32 s44, s4, s43
	s_cselect_b32 s94, s36, s90
	s_cselect_b32 s95, s37, s91
	s_add_u32 s42, s44, 0x8000
	s_addc_u32 s43, s45, 0
	v_lshl_add_u64 v[218:219], s[38:39], 0, v[170:171]
	s_add_i32 m0, s55, 0xc000
	ds_read_b128 v[178:181], v211
	ds_read_b128 v[182:185], v211 offset:1024
	ds_read_b128 v[186:189], v211 offset:2048
	ds_read_b128 v[190:193], v211 offset:3072
	ds_read_b128 v[194:197], v211 offset:4096
	ds_read_b128 v[198:201], v211 offset:5120
	ds_read_b128 v[202:205], v211 offset:6144
	ds_read_b128 v[214:217], v211 offset:7168
	global_load_lds_dwordx4 v[218:219], off
	v_lshl_add_u64 v[218:219], s[38:39], 0, v[172:173]
	s_add_i32 m0, s55, 0xe000
	s_nop 0
	global_load_lds_dwordx4 v[218:219], off
	s_waitcnt vmcnt(8)
	s_waitcnt lgkmcnt(0)
	s_setprio 1
	s_waitcnt lgkmcnt(0)
	v_mfma_f32_16x16x32_bf16 v[142:145], v[114:117], v[178:181], v[142:145]
	v_mfma_f32_16x16x32_bf16 v[138:141], v[122:125], v[178:181], v[138:141]
	s_barrier
	v_mfma_f32_16x16x32_bf16 v[110:113], v[114:117], v[186:189], v[110:113]
	v_mfma_f32_16x16x32_bf16 v[106:109], v[122:125], v[186:189], v[106:109]
	v_mfma_f32_16x16x32_bf16 v[94:97], v[114:117], v[194:197], v[94:97]
	v_mfma_f32_16x16x32_bf16 v[90:93], v[122:125], v[194:197], v[90:93]
	v_mfma_f32_16x16x32_bf16 v[78:81], v[114:117], v[202:205], v[78:81]
	v_mfma_f32_16x16x32_bf16 v[74:77], v[122:125], v[202:205], v[74:77]
	v_mfma_f32_16x16x32_bf16 v[142:145], v[118:121], v[182:185], v[142:145]
	v_mfma_f32_16x16x32_bf16 v[138:141], v[126:129], v[182:185], v[138:141]
	v_mfma_f32_16x16x32_bf16 v[110:113], v[118:121], v[190:193], v[110:113]
	v_mfma_f32_16x16x32_bf16 v[106:109], v[126:129], v[190:193], v[106:109]
	v_mfma_f32_16x16x32_bf16 v[94:97], v[118:121], v[198:201], v[94:97]
	v_mfma_f32_16x16x32_bf16 v[90:93], v[126:129], v[198:201], v[90:93]
	v_mfma_f32_16x16x32_bf16 v[78:81], v[118:121], v[214:217], v[78:81]
	v_mfma_f32_16x16x32_bf16 v[74:77], v[126:129], v[214:217], v[74:77]
	s_setprio 0
	s_setprio 1
	v_mfma_f32_16x16x32_bf16 v[134:137], v[146:149], v[178:181], v[134:137]
	v_mfma_f32_16x16x32_bf16 v[130:133], v[154:157], v[178:181], v[130:133]
	v_mfma_f32_16x16x32_bf16 v[102:105], v[146:149], v[186:189], v[102:105]
	v_mfma_f32_16x16x32_bf16 v[98:101], v[154:157], v[186:189], v[98:101]
	v_mfma_f32_16x16x32_bf16 v[86:89], v[146:149], v[194:197], v[86:89]
	v_mfma_f32_16x16x32_bf16 v[82:85], v[154:157], v[194:197], v[82:85]
	v_mfma_f32_16x16x32_bf16 v[70:73], v[146:149], v[202:205], v[70:73]
	v_mfma_f32_16x16x32_bf16 v[66:69], v[154:157], v[202:205], v[66:69]
	v_mfma_f32_16x16x32_bf16 v[134:137], v[150:153], v[182:185], v[134:137]
	v_mfma_f32_16x16x32_bf16 v[130:133], v[158:161], v[182:185], v[130:133]
	v_mfma_f32_16x16x32_bf16 v[102:105], v[150:153], v[190:193], v[102:105]
	v_mfma_f32_16x16x32_bf16 v[98:101], v[158:161], v[190:193], v[98:101]
	v_mfma_f32_16x16x32_bf16 v[86:89], v[150:153], v[198:201], v[86:89]
	v_mfma_f32_16x16x32_bf16 v[82:85], v[158:161], v[198:201], v[82:85]
	v_mfma_f32_16x16x32_bf16 v[70:73], v[150:153], v[214:217], v[70:73]
	v_mfma_f32_16x16x32_bf16 v[66:69], v[158:161], v[214:217], v[66:69]
	s_setprio 0
	s_barrier
	s_add_i32 s93, s84, s54
	v_lshl_add_u64 v[218:219], s[94:95], 0, v[164:165]
	s_mov_b32 m0, s93
	ds_read_b128 v[178:181], v211 offset:16384
	ds_read_b128 v[182:185], v211 offset:17408
	ds_read_b128 v[186:189], v211 offset:18432
	ds_read_b128 v[190:193], v211 offset:19456
	ds_read_b128 v[194:197], v211 offset:20480
	ds_read_b128 v[198:201], v211 offset:21504
	ds_read_b128 v[202:205], v211 offset:22528
	ds_read_b128 v[214:217], v211 offset:23552
	global_load_lds_dwordx4 v[218:219], off
	s_add_i32 m0, s93, 0x2000
	v_lshl_add_u64 v[220:221], s[94:95], 0, v[168:169]
	s_add_u32 s94, s94, s8
	s_addc_u32 s95, s95, s9
	s_add_i32 s93, s85, s54
	global_load_lds_dwordx4 v[220:221], off
	v_lshl_add_u64 v[222:223], s[94:95], 0, v[164:165]
	s_mov_b32 m0, s93
	v_lshl_add_u64 v[224:225], s[94:95], 0, v[168:169]
	global_load_lds_dwordx4 v[222:223], off
	s_add_i32 m0, s93, 0x2000
	v_lshl_add_u64 v[226:227], s[44:45], 0, v[162:163]
	global_load_lds_dwordx4 v[224:225], off
	s_mov_b32 m0, s55
	s_nop 0
	global_load_lds_dwordx4 v[226:227], off
	v_lshl_add_u64 v[226:227], s[44:45], 0, v[166:167]
	s_mov_b32 m0, s56
	s_nop 0
	global_load_lds_dwordx4 v[226:227], off
	s_waitcnt vmcnt(8)
	s_waitcnt lgkmcnt(0)
	s_setprio 1
	s_waitcnt lgkmcnt(0)
	v_mfma_f32_16x16x32_bf16 v[62:65], v[114:117], v[178:181], v[62:65]
	v_mfma_f32_16x16x32_bf16 v[58:61], v[122:125], v[178:181], v[58:61]
	s_barrier
	v_mfma_f32_16x16x32_bf16 v[46:49], v[114:117], v[186:189], v[46:49]
	v_mfma_f32_16x16x32_bf16 v[42:45], v[122:125], v[186:189], v[42:45]
	v_mfma_f32_16x16x32_bf16 v[30:33], v[114:117], v[194:197], v[30:33]
	v_mfma_f32_16x16x32_bf16 v[26:29], v[122:125], v[194:197], v[26:29]
	v_mfma_f32_16x16x32_bf16 v[14:17], v[114:117], v[202:205], v[14:17]
	v_mfma_f32_16x16x32_bf16 v[10:13], v[122:125], v[202:205], v[10:13]
	v_mfma_f32_16x16x32_bf16 v[62:65], v[118:121], v[182:185], v[62:65]
	v_mfma_f32_16x16x32_bf16 v[58:61], v[126:129], v[182:185], v[58:61]
	v_mfma_f32_16x16x32_bf16 v[46:49], v[118:121], v[190:193], v[46:49]
	v_mfma_f32_16x16x32_bf16 v[42:45], v[126:129], v[190:193], v[42:45]
	v_mfma_f32_16x16x32_bf16 v[30:33], v[118:121], v[198:201], v[30:33]
	v_mfma_f32_16x16x32_bf16 v[26:29], v[126:129], v[198:201], v[26:29]
	v_mfma_f32_16x16x32_bf16 v[14:17], v[118:121], v[214:217], v[14:17]
	v_mfma_f32_16x16x32_bf16 v[10:13], v[126:129], v[214:217], v[10:13]
	s_setprio 0
	s_setprio 1
	v_mfma_f32_16x16x32_bf16 v[54:57], v[146:149], v[178:181], v[54:57]
	v_mfma_f32_16x16x32_bf16 v[50:53], v[154:157], v[178:181], v[50:53]
	v_mfma_f32_16x16x32_bf16 v[38:41], v[146:149], v[186:189], v[38:41]
	v_mfma_f32_16x16x32_bf16 v[34:37], v[154:157], v[186:189], v[34:37]
	v_mfma_f32_16x16x32_bf16 v[22:25], v[146:149], v[194:197], v[22:25]
	v_mfma_f32_16x16x32_bf16 v[18:21], v[154:157], v[194:197], v[18:21]
	v_mfma_f32_16x16x32_bf16 v[6:9], v[146:149], v[202:205], v[6:9]
	v_mfma_f32_16x16x32_bf16 v[2:5], v[154:157], v[202:205], v[2:5]
	v_mfma_f32_16x16x32_bf16 v[54:57], v[150:153], v[182:185], v[54:57]
	v_mfma_f32_16x16x32_bf16 v[50:53], v[158:161], v[182:185], v[50:53]
	v_mfma_f32_16x16x32_bf16 v[38:41], v[150:153], v[190:193], v[38:41]
	v_mfma_f32_16x16x32_bf16 v[34:37], v[158:161], v[190:193], v[34:37]
	v_mfma_f32_16x16x32_bf16 v[22:25], v[150:153], v[198:201], v[22:25]
	v_mfma_f32_16x16x32_bf16 v[18:21], v[158:161], v[198:201], v[18:21]
	v_mfma_f32_16x16x32_bf16 v[6:9], v[150:153], v[214:217], v[6:9]
	v_mfma_f32_16x16x32_bf16 v[2:5], v[158:161], v[214:217], v[2:5]
	s_setprio 0
	s_barrier
	s_add_i32 s93, 0, 0x18000
	s_add_i32 s94, 0, 0x1c000
	v_add_u32_e32 v126, s93, v207
	v_add_u32_e32 v158, s94, v207
	ds_read_b128 v[114:117], v126
	ds_read_b128 v[118:121], v126 offset:1024
	ds_read_b128 v[122:125], v126 offset:2048
	ds_read_b128 v[126:129], v126 offset:3072
	ds_read_b128 v[146:149], v158
	ds_read_b128 v[150:153], v158 offset:1024
	ds_read_b128 v[154:157], v158 offset:2048
	ds_read_b128 v[158:161], v158 offset:3072
	s_add_u32 s44, s44, 0x4000
	s_addc_u32 s45, s45, 0
	s_mov_b32 m0, s57
	v_lshl_add_u64 v[226:227], s[44:45], 0, v[162:163]
	ds_read_b128 v[178:181], v211 offset:32768
	ds_read_b128 v[182:185], v211 offset:33792
	ds_read_b128 v[186:189], v211 offset:34816
	ds_read_b128 v[190:193], v211 offset:35840
	ds_read_b128 v[194:197], v211 offset:36864
	ds_read_b128 v[198:201], v211 offset:37888
	ds_read_b128 v[202:205], v211 offset:38912
	ds_read_b128 v[214:217], v211 offset:39936
	global_load_lds_dwordx4 v[226:227], off
	v_lshl_add_u64 v[226:227], s[44:45], 0, v[166:167]
	s_mov_b32 m0, s58
	s_nop 0
	global_load_lds_dwordx4 v[226:227], off
	s_waitcnt vmcnt(8)
	s_waitcnt lgkmcnt(0)
	s_setprio 1
	s_waitcnt lgkmcnt(0)
	v_mfma_f32_16x16x32_bf16 v[142:145], v[114:117], v[178:181], v[142:145]
	v_mfma_f32_16x16x32_bf16 v[138:141], v[122:125], v[178:181], v[138:141]
	s_barrier
	v_mfma_f32_16x16x32_bf16 v[110:113], v[114:117], v[186:189], v[110:113]
	v_mfma_f32_16x16x32_bf16 v[106:109], v[122:125], v[186:189], v[106:109]
	v_mfma_f32_16x16x32_bf16 v[94:97], v[114:117], v[194:197], v[94:97]
	v_mfma_f32_16x16x32_bf16 v[90:93], v[122:125], v[194:197], v[90:93]
	v_mfma_f32_16x16x32_bf16 v[78:81], v[114:117], v[202:205], v[78:81]
	v_mfma_f32_16x16x32_bf16 v[74:77], v[122:125], v[202:205], v[74:77]
	v_mfma_f32_16x16x32_bf16 v[142:145], v[118:121], v[182:185], v[142:145]
	v_mfma_f32_16x16x32_bf16 v[138:141], v[126:129], v[182:185], v[138:141]
	v_mfma_f32_16x16x32_bf16 v[110:113], v[118:121], v[190:193], v[110:113]
	v_mfma_f32_16x16x32_bf16 v[106:109], v[126:129], v[190:193], v[106:109]
	v_mfma_f32_16x16x32_bf16 v[94:97], v[118:121], v[198:201], v[94:97]
	v_mfma_f32_16x16x32_bf16 v[90:93], v[126:129], v[198:201], v[90:93]
	v_mfma_f32_16x16x32_bf16 v[78:81], v[118:121], v[214:217], v[78:81]
	v_mfma_f32_16x16x32_bf16 v[74:77], v[126:129], v[214:217], v[74:77]
	s_setprio 0
	s_setprio 1
	v_mfma_f32_16x16x32_bf16 v[134:137], v[146:149], v[178:181], v[134:137]
	v_mfma_f32_16x16x32_bf16 v[130:133], v[154:157], v[178:181], v[130:133]
	v_mfma_f32_16x16x32_bf16 v[102:105], v[146:149], v[186:189], v[102:105]
	v_mfma_f32_16x16x32_bf16 v[98:101], v[154:157], v[186:189], v[98:101]
	v_mfma_f32_16x16x32_bf16 v[86:89], v[146:149], v[194:197], v[86:89]
	v_mfma_f32_16x16x32_bf16 v[82:85], v[154:157], v[194:197], v[82:85]
	v_mfma_f32_16x16x32_bf16 v[70:73], v[146:149], v[202:205], v[70:73]
	v_mfma_f32_16x16x32_bf16 v[66:69], v[154:157], v[202:205], v[66:69]
	v_mfma_f32_16x16x32_bf16 v[134:137], v[150:153], v[182:185], v[134:137]
	v_mfma_f32_16x16x32_bf16 v[130:133], v[158:161], v[182:185], v[130:133]
	v_mfma_f32_16x16x32_bf16 v[102:105], v[150:153], v[190:193], v[102:105]
	v_mfma_f32_16x16x32_bf16 v[98:101], v[158:161], v[190:193], v[98:101]
	v_mfma_f32_16x16x32_bf16 v[86:89], v[150:153], v[198:201], v[86:89]
	v_mfma_f32_16x16x32_bf16 v[82:85], v[158:161], v[198:201], v[82:85]
	v_mfma_f32_16x16x32_bf16 v[70:73], v[150:153], v[214:217], v[70:73]
	v_mfma_f32_16x16x32_bf16 v[66:69], v[158:161], v[214:217], v[66:69]
	s_setprio 0
	s_barrier
	s_add_i32 s44, s93, s54
	v_lshl_add_u64 v[218:219], v[218:219], 0, s[28:29]
	s_mov_b32 m0, s44
	ds_read_b128 v[178:181], v211 offset:49152
	ds_read_b128 v[182:185], v211 offset:50176
	ds_read_b128 v[186:189], v211 offset:51200
	ds_read_b128 v[190:193], v211 offset:52224
	ds_read_b128 v[194:197], v211 offset:53248
	ds_read_b128 v[198:201], v211 offset:54272
	ds_read_b128 v[202:205], v211 offset:55296
	ds_read_b128 v[214:217], v211 offset:56320
	global_load_lds_dwordx4 v[218:219], off
	v_lshl_add_u64 v[218:219], v[220:221], 0, s[28:29]
	s_add_i32 m0, s44, 0x2000
	s_add_i32 s44, s94, s54
	global_load_lds_dwordx4 v[218:219], off
	v_lshl_add_u64 v[218:219], v[222:223], 0, s[28:29]
	s_mov_b32 m0, s44
	s_nop 0
	global_load_lds_dwordx4 v[218:219], off
	v_lshl_add_u64 v[218:219], v[224:225], 0, s[28:29]
	s_add_i32 m0, s44, 0x2000
	s_nop 0
	global_load_lds_dwordx4 v[218:219], off
	v_lshl_add_u64 v[218:219], s[42:43], 0, v[162:163]
	s_mov_b32 m0, s65
	s_nop 0
	global_load_lds_dwordx4 v[218:219], off
	v_lshl_add_u64 v[218:219], s[42:43], 0, v[166:167]
	s_mov_b32 m0, s80
	s_nop 0
	global_load_lds_dwordx4 v[218:219], off
	s_waitcnt vmcnt(8)
	s_waitcnt lgkmcnt(0)
	s_setprio 1
	s_waitcnt lgkmcnt(0)
	v_mfma_f32_16x16x32_bf16 v[62:65], v[114:117], v[178:181], v[62:65]
	v_mfma_f32_16x16x32_bf16 v[58:61], v[122:125], v[178:181], v[58:61]
	s_barrier
	v_mfma_f32_16x16x32_bf16 v[46:49], v[114:117], v[186:189], v[46:49]
	v_mfma_f32_16x16x32_bf16 v[42:45], v[122:125], v[186:189], v[42:45]
	v_mfma_f32_16x16x32_bf16 v[30:33], v[114:117], v[194:197], v[30:33]
	v_mfma_f32_16x16x32_bf16 v[26:29], v[122:125], v[194:197], v[26:29]
	v_mfma_f32_16x16x32_bf16 v[14:17], v[114:117], v[202:205], v[14:17]
	v_mfma_f32_16x16x32_bf16 v[10:13], v[122:125], v[202:205], v[10:13]
	v_mfma_f32_16x16x32_bf16 v[62:65], v[118:121], v[182:185], v[62:65]
	v_mfma_f32_16x16x32_bf16 v[58:61], v[126:129], v[182:185], v[58:61]
	v_mfma_f32_16x16x32_bf16 v[46:49], v[118:121], v[190:193], v[46:49]
	v_mfma_f32_16x16x32_bf16 v[42:45], v[126:129], v[190:193], v[42:45]
	v_mfma_f32_16x16x32_bf16 v[30:33], v[118:121], v[198:201], v[30:33]
	v_mfma_f32_16x16x32_bf16 v[26:29], v[126:129], v[198:201], v[26:29]
	v_mfma_f32_16x16x32_bf16 v[14:17], v[118:121], v[214:217], v[14:17]
	v_mfma_f32_16x16x32_bf16 v[10:13], v[126:129], v[214:217], v[10:13]
	s_setprio 0
	s_setprio 1
	v_mfma_f32_16x16x32_bf16 v[54:57], v[146:149], v[178:181], v[54:57]
	v_mfma_f32_16x16x32_bf16 v[50:53], v[154:157], v[178:181], v[50:53]
	v_mfma_f32_16x16x32_bf16 v[38:41], v[146:149], v[186:189], v[38:41]
	v_mfma_f32_16x16x32_bf16 v[34:37], v[154:157], v[186:189], v[34:37]
	v_mfma_f32_16x16x32_bf16 v[22:25], v[146:149], v[194:197], v[22:25]
	v_mfma_f32_16x16x32_bf16 v[18:21], v[154:157], v[194:197], v[18:21]
	v_mfma_f32_16x16x32_bf16 v[6:9], v[146:149], v[202:205], v[6:9]
	v_mfma_f32_16x16x32_bf16 v[2:5], v[154:157], v[202:205], v[2:5]
	v_mfma_f32_16x16x32_bf16 v[54:57], v[150:153], v[182:185], v[54:57]
	v_mfma_f32_16x16x32_bf16 v[50:53], v[158:161], v[182:185], v[50:53]
	v_mfma_f32_16x16x32_bf16 v[38:41], v[150:153], v[190:193], v[38:41]
	v_mfma_f32_16x16x32_bf16 v[34:37], v[158:161], v[190:193], v[34:37]
	v_mfma_f32_16x16x32_bf16 v[22:25], v[150:153], v[198:201], v[22:25]
	v_mfma_f32_16x16x32_bf16 v[18:21], v[158:161], v[198:201], v[18:21]
	v_mfma_f32_16x16x32_bf16 v[6:9], v[150:153], v[214:217], v[6:9]
	v_mfma_f32_16x16x32_bf16 v[2:5], v[158:161], v[214:217], v[2:5]
	s_setprio 0
	s_barrier
	s_add_u32 s90, s90, 0x100
	s_addc_u32 s91, s91, 0
	s_add_u32 s38, s38, 0x10000
	s_addc_u32 s39, s39, 0
	s_cmp_ge_i32 s92, s64
	s_mov_b32 s42, s92
	s_cbranch_scc0 .LBB0_1170

.LBB0_1276:
	ds_read_b128 v[114:117], v171
	ds_read_b128 v[118:121], v171 offset:1024
	ds_read_b128 v[122:125], v171 offset:2048
	ds_read_b128 v[130:133], v171 offset:3072
	ds_read_b128 v[162:165], v172
	ds_read_b128 v[176:179], v172 offset:1024
	ds_read_b128 v[180:183], v172 offset:2048
	ds_read_b128 v[184:187], v172 offset:3072
	s_add_i32 s82, s30, 2
	s_add_u32 s83, s2, 0x80
	s_addc_u32 s31, s3, 0
	s_cmp_eq_u32 s58, s30
	s_cselect_b32 s30, s26, s83
	s_cselect_b32 s31, s27, s31
	s_cselect_b32 s85, s29, s35
	s_cselect_b32 s84, s28, s34
	v_lshl_add_u64 v[220:221], s[2:3], 0, v[154:155]
	s_add_i32 m0, s44, 0xc000
	ds_read_b128 v[188:191], v173
	ds_read_b128 v[192:195], v173 offset:1024
	ds_read_b128 v[196:199], v173 offset:2048
	ds_read_b128 v[200:203], v173 offset:3072
	ds_read_b128 v[204:207], v173 offset:4096
	ds_read_b128 v[208:211], v173 offset:5120
	ds_read_b128 v[212:215], v173 offset:6144
	ds_read_b128 v[216:219], v173 offset:7168
	global_load_lds_dwordx4 v[220:221], off
	v_lshl_add_u64 v[220:221], s[2:3], 0, v[156:157]
	s_add_i32 m0, s44, 0xe000
	s_nop 0
	global_load_lds_dwordx4 v[220:221], off
	s_waitcnt vmcnt(8)
	s_waitcnt lgkmcnt(0)
	s_setprio 1
	s_waitcnt lgkmcnt(0)
	v_mfma_f32_16x16x32_bf16 v[142:145], v[114:117], v[188:191], v[142:145]
	v_mfma_f32_16x16x32_bf16 v[138:141], v[122:125], v[188:191], v[138:141]
	s_barrier
	v_mfma_f32_16x16x32_bf16 v[110:113], v[114:117], v[196:199], v[110:113]
	v_mfma_f32_16x16x32_bf16 v[106:109], v[122:125], v[196:199], v[106:109]
	v_mfma_f32_16x16x32_bf16 v[94:97], v[114:117], v[204:207], v[94:97]
	v_mfma_f32_16x16x32_bf16 v[90:93], v[122:125], v[204:207], v[90:93]
	v_mfma_f32_16x16x32_bf16 v[78:81], v[114:117], v[212:215], v[78:81]
	v_mfma_f32_16x16x32_bf16 v[74:77], v[122:125], v[212:215], v[74:77]
	v_mfma_f32_16x16x32_bf16 v[142:145], v[118:121], v[192:195], v[142:145]
	v_mfma_f32_16x16x32_bf16 v[138:141], v[130:133], v[192:195], v[138:141]
	v_mfma_f32_16x16x32_bf16 v[110:113], v[118:121], v[200:203], v[110:113]
	v_mfma_f32_16x16x32_bf16 v[106:109], v[130:133], v[200:203], v[106:109]
	v_mfma_f32_16x16x32_bf16 v[94:97], v[118:121], v[208:211], v[94:97]
	v_mfma_f32_16x16x32_bf16 v[90:93], v[130:133], v[208:211], v[90:93]
	v_mfma_f32_16x16x32_bf16 v[78:81], v[118:121], v[216:219], v[78:81]
	v_mfma_f32_16x16x32_bf16 v[74:77], v[130:133], v[216:219], v[74:77]
	s_setprio 0
	s_setprio 1
	v_mfma_f32_16x16x32_bf16 v[134:137], v[162:165], v[188:191], v[134:137]
	v_mfma_f32_16x16x32_bf16 v[126:129], v[180:183], v[188:191], v[126:129]
	v_mfma_f32_16x16x32_bf16 v[102:105], v[162:165], v[196:199], v[102:105]
	v_mfma_f32_16x16x32_bf16 v[98:101], v[180:183], v[196:199], v[98:101]
	v_mfma_f32_16x16x32_bf16 v[86:89], v[162:165], v[204:207], v[86:89]
	v_mfma_f32_16x16x32_bf16 v[82:85], v[180:183], v[204:207], v[82:85]
	v_mfma_f32_16x16x32_bf16 v[70:73], v[162:165], v[212:215], v[70:73]
	v_mfma_f32_16x16x32_bf16 v[66:69], v[180:183], v[212:215], v[66:69]
	v_mfma_f32_16x16x32_bf16 v[134:137], v[176:179], v[192:195], v[134:137]
	v_mfma_f32_16x16x32_bf16 v[126:129], v[184:187], v[192:195], v[126:129]
	v_mfma_f32_16x16x32_bf16 v[102:105], v[176:179], v[200:203], v[102:105]
	v_mfma_f32_16x16x32_bf16 v[98:101], v[184:187], v[200:203], v[98:101]
	v_mfma_f32_16x16x32_bf16 v[86:89], v[176:179], v[208:211], v[86:89]
	v_mfma_f32_16x16x32_bf16 v[82:85], v[184:187], v[208:211], v[82:85]
	v_mfma_f32_16x16x32_bf16 v[70:73], v[176:179], v[216:219], v[70:73]
	v_mfma_f32_16x16x32_bf16 v[66:69], v[184:187], v[216:219], v[66:69]
	s_setprio 0
	s_barrier
	s_add_i32 s83, s61, s37
	v_lshl_add_u64 v[220:221], s[84:85], 0, v[148:149]
	s_mov_b32 m0, s83
	ds_read_b128 v[188:191], v173 offset:16384
	ds_read_b128 v[192:195], v173 offset:17408
	ds_read_b128 v[196:199], v173 offset:18432
	ds_read_b128 v[200:203], v173 offset:19456
	ds_read_b128 v[204:207], v173 offset:20480
	ds_read_b128 v[208:211], v173 offset:21504
	ds_read_b128 v[212:215], v173 offset:22528
	ds_read_b128 v[216:219], v173 offset:23552
	global_load_lds_dwordx4 v[220:221], off
	s_add_i32 m0, s83, 0x2000
	v_lshl_add_u64 v[222:223], s[84:85], 0, v[152:153]
	s_add_u32 s84, s84, s6
	s_addc_u32 s85, s85, s7
	s_add_i32 s83, s62, s37
	global_load_lds_dwordx4 v[222:223], off
	v_lshl_add_u64 v[224:225], s[84:85], 0, v[148:149]
	s_mov_b32 m0, s83
	v_lshl_add_u64 v[226:227], s[84:85], 0, v[152:153]
	global_load_lds_dwordx4 v[224:225], off
	s_add_i32 m0, s83, 0x2000
	v_lshl_add_u64 v[228:229], s[30:31], 0, v[146:147]
	global_load_lds_dwordx4 v[226:227], off
	s_mov_b32 m0, s44
	v_lshl_add_u64 v[230:231], s[30:31], 0, v[150:151]
	global_load_lds_dwordx4 v[228:229], off
	s_mov_b32 m0, s45
	s_nop 0
	global_load_lds_dwordx4 v[230:231], off
	s_waitcnt vmcnt(8)
	s_waitcnt lgkmcnt(0)
	s_setprio 1
	s_waitcnt lgkmcnt(0)
	v_mfma_f32_16x16x32_bf16 v[62:65], v[114:117], v[188:191], v[62:65]
	v_mfma_f32_16x16x32_bf16 v[58:61], v[122:125], v[188:191], v[58:61]
	s_barrier
	v_mfma_f32_16x16x32_bf16 v[46:49], v[114:117], v[196:199], v[46:49]
	v_mfma_f32_16x16x32_bf16 v[42:45], v[122:125], v[196:199], v[42:45]
	v_mfma_f32_16x16x32_bf16 v[30:33], v[114:117], v[204:207], v[30:33]
	v_mfma_f32_16x16x32_bf16 v[26:29], v[122:125], v[204:207], v[26:29]
	v_mfma_f32_16x16x32_bf16 v[14:17], v[114:117], v[212:215], v[14:17]
	v_mfma_f32_16x16x32_bf16 v[10:13], v[122:125], v[212:215], v[10:13]
	v_mfma_f32_16x16x32_bf16 v[62:65], v[118:121], v[192:195], v[62:65]
	v_mfma_f32_16x16x32_bf16 v[58:61], v[130:133], v[192:195], v[58:61]
	v_mfma_f32_16x16x32_bf16 v[46:49], v[118:121], v[200:203], v[46:49]
	v_mfma_f32_16x16x32_bf16 v[42:45], v[130:133], v[200:203], v[42:45]
	v_mfma_f32_16x16x32_bf16 v[30:33], v[118:121], v[208:211], v[30:33]
	v_mfma_f32_16x16x32_bf16 v[26:29], v[130:133], v[208:211], v[26:29]
	v_mfma_f32_16x16x32_bf16 v[14:17], v[118:121], v[216:219], v[14:17]
	v_mfma_f32_16x16x32_bf16 v[10:13], v[130:133], v[216:219], v[10:13]
	s_setprio 0
	s_setprio 1
	v_mfma_f32_16x16x32_bf16 v[54:57], v[162:165], v[188:191], v[54:57]
	v_mfma_f32_16x16x32_bf16 v[50:53], v[180:183], v[188:191], v[50:53]
	v_mfma_f32_16x16x32_bf16 v[38:41], v[162:165], v[196:199], v[38:41]
	v_mfma_f32_16x16x32_bf16 v[34:37], v[180:183], v[196:199], v[34:37]
	v_mfma_f32_16x16x32_bf16 v[22:25], v[162:165], v[204:207], v[22:25]
	v_mfma_f32_16x16x32_bf16 v[18:21], v[180:183], v[204:207], v[18:21]
	v_mfma_f32_16x16x32_bf16 v[6:9], v[162:165], v[212:215], v[6:9]
	v_mfma_f32_16x16x32_bf16 v[2:5], v[180:183], v[212:215], v[2:5]
	v_mfma_f32_16x16x32_bf16 v[54:57], v[176:179], v[192:195], v[54:57]
	v_mfma_f32_16x16x32_bf16 v[50:53], v[184:187], v[192:195], v[50:53]
	v_mfma_f32_16x16x32_bf16 v[38:41], v[176:179], v[200:203], v[38:41]
	v_mfma_f32_16x16x32_bf16 v[34:37], v[184:187], v[200:203], v[34:37]
	v_mfma_f32_16x16x32_bf16 v[22:25], v[176:179], v[208:211], v[22:25]
	v_mfma_f32_16x16x32_bf16 v[18:21], v[184:187], v[208:211], v[18:21]
	v_mfma_f32_16x16x32_bf16 v[6:9], v[176:179], v[216:219], v[6:9]
	v_mfma_f32_16x16x32_bf16 v[2:5], v[184:187], v[216:219], v[2:5]
	s_setprio 0
	s_barrier
	s_add_i32 s83, 0, 0x18000
	s_add_i32 s84, 0, 0x1c000
	v_add_u32_e32 v130, s83, v168
	v_add_u32_e32 v166, s84, v168
	ds_read_b128 v[114:117], v130
	ds_read_b128 v[118:121], v130 offset:1024
	ds_read_b128 v[122:125], v130 offset:2048
	ds_read_b128 v[130:133], v130 offset:3072
	ds_read_b128 v[162:165], v166
	ds_read_b128 v[176:179], v166 offset:1024
	ds_read_b128 v[180:183], v166 offset:2048
	ds_read_b128 v[184:187], v166 offset:3072
	s_add_u32 s30, s30, s6
	s_addc_u32 s31, s31, s7
	s_mov_b32 m0, s46
	v_lshl_add_u64 v[232:233], s[30:31], 0, v[146:147]
	ds_read_b128 v[188:191], v173 offset:32768
	ds_read_b128 v[192:195], v173 offset:33792
	ds_read_b128 v[196:199], v173 offset:34816
	ds_read_b128 v[200:203], v173 offset:35840
	ds_read_b128 v[204:207], v173 offset:36864
	ds_read_b128 v[208:211], v173 offset:37888
	ds_read_b128 v[212:215], v173 offset:38912
	ds_read_b128 v[216:219], v173 offset:39936
	global_load_lds_dwordx4 v[232:233], off
	v_lshl_add_u64 v[232:233], s[30:31], 0, v[150:151]
	s_mov_b32 m0, s47
	s_nop 0
	global_load_lds_dwordx4 v[232:233], off
	s_waitcnt vmcnt(8)
	s_waitcnt lgkmcnt(0)
	s_setprio 1
	s_waitcnt lgkmcnt(0)
	v_mfma_f32_16x16x32_bf16 v[142:145], v[114:117], v[188:191], v[142:145]
	v_mfma_f32_16x16x32_bf16 v[138:141], v[122:125], v[188:191], v[138:141]
	s_barrier
	v_mfma_f32_16x16x32_bf16 v[110:113], v[114:117], v[196:199], v[110:113]
	v_mfma_f32_16x16x32_bf16 v[106:109], v[122:125], v[196:199], v[106:109]
	v_mfma_f32_16x16x32_bf16 v[94:97], v[114:117], v[204:207], v[94:97]
	v_mfma_f32_16x16x32_bf16 v[90:93], v[122:125], v[204:207], v[90:93]
	v_mfma_f32_16x16x32_bf16 v[78:81], v[114:117], v[212:215], v[78:81]
	v_mfma_f32_16x16x32_bf16 v[74:77], v[122:125], v[212:215], v[74:77]
	v_mfma_f32_16x16x32_bf16 v[142:145], v[118:121], v[192:195], v[142:145]
	v_mfma_f32_16x16x32_bf16 v[138:141], v[130:133], v[192:195], v[138:141]
	v_mfma_f32_16x16x32_bf16 v[110:113], v[118:121], v[200:203], v[110:113]
	v_mfma_f32_16x16x32_bf16 v[106:109], v[130:133], v[200:203], v[106:109]
	v_mfma_f32_16x16x32_bf16 v[94:97], v[118:121], v[208:211], v[94:97]
	v_mfma_f32_16x16x32_bf16 v[90:93], v[130:133], v[208:211], v[90:93]
	v_mfma_f32_16x16x32_bf16 v[78:81], v[118:121], v[216:219], v[78:81]
	v_mfma_f32_16x16x32_bf16 v[74:77], v[130:133], v[216:219], v[74:77]
	s_setprio 0
	s_setprio 1
	v_mfma_f32_16x16x32_bf16 v[134:137], v[162:165], v[188:191], v[134:137]
	v_mfma_f32_16x16x32_bf16 v[126:129], v[180:183], v[188:191], v[126:129]
	v_mfma_f32_16x16x32_bf16 v[102:105], v[162:165], v[196:199], v[102:105]
	v_mfma_f32_16x16x32_bf16 v[98:101], v[180:183], v[196:199], v[98:101]
	v_mfma_f32_16x16x32_bf16 v[86:89], v[162:165], v[204:207], v[86:89]
	v_mfma_f32_16x16x32_bf16 v[82:85], v[180:183], v[204:207], v[82:85]
	v_mfma_f32_16x16x32_bf16 v[70:73], v[162:165], v[212:215], v[70:73]
	v_mfma_f32_16x16x32_bf16 v[66:69], v[180:183], v[212:215], v[66:69]
	v_mfma_f32_16x16x32_bf16 v[134:137], v[176:179], v[192:195], v[134:137]
	v_mfma_f32_16x16x32_bf16 v[126:129], v[184:187], v[192:195], v[126:129]
	v_mfma_f32_16x16x32_bf16 v[102:105], v[176:179], v[200:203], v[102:105]
	v_mfma_f32_16x16x32_bf16 v[98:101], v[184:187], v[200:203], v[98:101]
	v_mfma_f32_16x16x32_bf16 v[86:89], v[176:179], v[208:211], v[86:89]
	v_mfma_f32_16x16x32_bf16 v[82:85], v[184:187], v[208:211], v[82:85]
	v_mfma_f32_16x16x32_bf16 v[70:73], v[176:179], v[216:219], v[70:73]
	v_mfma_f32_16x16x32_bf16 v[66:69], v[184:187], v[216:219], v[66:69]
	s_setprio 0
	s_barrier
	s_add_i32 s30, s83, s37
	v_lshl_add_u64 v[220:221], v[220:221], 0, s[20:21]
	s_mov_b32 m0, s30
	ds_read_b128 v[188:191], v173 offset:49152
	ds_read_b128 v[192:195], v173 offset:50176
	ds_read_b128 v[196:199], v173 offset:51200
	ds_read_b128 v[200:203], v173 offset:52224
	ds_read_b128 v[204:207], v173 offset:53248
	ds_read_b128 v[208:211], v173 offset:54272
	ds_read_b128 v[212:215], v173 offset:55296
	ds_read_b128 v[216:219], v173 offset:56320
	global_load_lds_dwordx4 v[220:221], off
	v_lshl_add_u64 v[220:221], v[222:223], 0, s[20:21]
	s_add_i32 m0, s30, 0x2000
	s_add_i32 s30, s84, s37
	global_load_lds_dwordx4 v[220:221], off
	v_lshl_add_u64 v[220:221], v[224:225], 0, s[20:21]
	s_mov_b32 m0, s30
	s_nop 0
	global_load_lds_dwordx4 v[220:221], off
	v_lshl_add_u64 v[220:221], v[226:227], 0, s[20:21]
	s_add_i32 m0, s30, 0x2000
	s_nop 0
	global_load_lds_dwordx4 v[220:221], off
	v_lshl_add_u64 v[220:221], v[228:229], 0, s[20:21]
	s_mov_b32 m0, s55
	s_nop 0
	global_load_lds_dwordx4 v[220:221], off
	v_lshl_add_u64 v[220:221], v[230:231], 0, s[20:21]
	s_mov_b32 m0, s56
	s_nop 0
	global_load_lds_dwordx4 v[220:221], off
	s_waitcnt vmcnt(8)
	s_waitcnt lgkmcnt(0)
	s_setprio 1
	s_waitcnt lgkmcnt(0)
	v_mfma_f32_16x16x32_bf16 v[62:65], v[114:117], v[188:191], v[62:65]
	v_mfma_f32_16x16x32_bf16 v[58:61], v[122:125], v[188:191], v[58:61]
	s_barrier
	v_mfma_f32_16x16x32_bf16 v[46:49], v[114:117], v[196:199], v[46:49]
	v_mfma_f32_16x16x32_bf16 v[42:45], v[122:125], v[196:199], v[42:45]
	v_mfma_f32_16x16x32_bf16 v[30:33], v[114:117], v[204:207], v[30:33]
	v_mfma_f32_16x16x32_bf16 v[26:29], v[122:125], v[204:207], v[26:29]
	v_mfma_f32_16x16x32_bf16 v[14:17], v[114:117], v[212:215], v[14:17]
	v_mfma_f32_16x16x32_bf16 v[10:13], v[122:125], v[212:215], v[10:13]
	v_mfma_f32_16x16x32_bf16 v[62:65], v[118:121], v[192:195], v[62:65]
	v_mfma_f32_16x16x32_bf16 v[58:61], v[130:133], v[192:195], v[58:61]
	v_mfma_f32_16x16x32_bf16 v[46:49], v[118:121], v[200:203], v[46:49]
	v_mfma_f32_16x16x32_bf16 v[42:45], v[130:133], v[200:203], v[42:45]
	v_mfma_f32_16x16x32_bf16 v[30:33], v[118:121], v[208:211], v[30:33]
	v_mfma_f32_16x16x32_bf16 v[26:29], v[130:133], v[208:211], v[26:29]
	v_mfma_f32_16x16x32_bf16 v[14:17], v[118:121], v[216:219], v[14:17]
	v_mfma_f32_16x16x32_bf16 v[10:13], v[130:133], v[216:219], v[10:13]
	s_setprio 0
	s_setprio 1
	v_mfma_f32_16x16x32_bf16 v[54:57], v[162:165], v[188:191], v[54:57]
	v_mfma_f32_16x16x32_bf16 v[50:53], v[180:183], v[188:191], v[50:53]
	v_mfma_f32_16x16x32_bf16 v[38:41], v[162:165], v[196:199], v[38:41]
	v_mfma_f32_16x16x32_bf16 v[34:37], v[180:183], v[196:199], v[34:37]
	v_mfma_f32_16x16x32_bf16 v[22:25], v[162:165], v[204:207], v[22:25]
	v_mfma_f32_16x16x32_bf16 v[18:21], v[180:183], v[204:207], v[18:21]
	v_mfma_f32_16x16x32_bf16 v[6:9], v[162:165], v[212:215], v[6:9]
	v_mfma_f32_16x16x32_bf16 v[2:5], v[180:183], v[212:215], v[2:5]
	v_mfma_f32_16x16x32_bf16 v[54:57], v[176:179], v[192:195], v[54:57]
	v_mfma_f32_16x16x32_bf16 v[50:53], v[184:187], v[192:195], v[50:53]
	v_mfma_f32_16x16x32_bf16 v[38:41], v[176:179], v[200:203], v[38:41]
	v_mfma_f32_16x16x32_bf16 v[34:37], v[184:187], v[200:203], v[34:37]
	v_mfma_f32_16x16x32_bf16 v[22:25], v[176:179], v[208:211], v[22:25]
	v_mfma_f32_16x16x32_bf16 v[18:21], v[184:187], v[208:211], v[18:21]
	v_mfma_f32_16x16x32_bf16 v[6:9], v[176:179], v[216:219], v[6:9]
	v_mfma_f32_16x16x32_bf16 v[2:5], v[184:187], v[216:219], v[2:5]
	s_setprio 0
	s_barrier
	s_add_u32 s2, s2, 0x100
	s_addc_u32 s3, s3, 0
	s_add_u32 s34, s34, 0x100
	s_addc_u32 s35, s35, 0
	s_cmp_ge_i32 s82, s57
	s_mov_b32 s30, s82
	s_cbranch_scc0 .LBB0_1276

.LBB0_1461:
	ds_read_b128 v[148:151], v168
	ds_read_b128 v[172:175], v168 offset:1024
	ds_read_b128 v[176:179], v168 offset:2048
	ds_read_b128 v[180:183], v168 offset:3072
	ds_read_b128 v[184:187], v169
	ds_read_b128 v[188:191], v169 offset:1024
	ds_read_b128 v[192:195], v169 offset:2048
	ds_read_b128 v[196:199], v169 offset:3072
	s_add_i32 s67, s26, 2
	s_add_u32 s68, s24, 0x80
	s_addc_u32 s27, s25, 0
	s_cmp_eq_u32 s50, s26
	s_cselect_b32 s26, s2, s68
	s_cselect_b32 s27, s3, s27
	s_cselect_b32 s69, s23, s66
	s_cselect_b32 s68, s22, s65
	v_lshl_add_u64 v[232:233], s[24:25], 0, v[140:141]
	s_add_i32 m0, s37, 0xc000
	ds_read_b128 v[200:203], v170
	ds_read_b128 v[204:207], v170 offset:1024
	ds_read_b128 v[208:211], v170 offset:2048
	ds_read_b128 v[212:215], v170 offset:3072
	ds_read_b128 v[216:219], v170 offset:4096
	ds_read_b128 v[220:223], v170 offset:5120
	ds_read_b128 v[224:227], v170 offset:6144
	ds_read_b128 v[228:231], v170 offset:7168
	global_load_lds_dwordx4 v[232:233], off
	v_lshl_add_u64 v[232:233], s[24:25], 0, v[142:143]
	s_add_i32 m0, s37, 0xe000
	s_nop 0
	global_load_lds_dwordx4 v[232:233], off
	s_waitcnt vmcnt(8)
	s_waitcnt lgkmcnt(0)
	s_setprio 1
	s_waitcnt lgkmcnt(0)
	v_mfma_f32_16x16x32_bf16 v[128:131], v[148:151], v[200:203], v[128:131]
	v_mfma_f32_16x16x32_bf16 v[124:127], v[176:179], v[200:203], v[124:127]
	s_barrier
	v_mfma_f32_16x16x32_bf16 v[120:123], v[148:151], v[208:211], v[120:123]
	v_mfma_f32_16x16x32_bf16 v[116:119], v[176:179], v[208:211], v[116:119]
	v_mfma_f32_16x16x32_bf16 v[112:115], v[148:151], v[216:219], v[112:115]
	v_mfma_f32_16x16x32_bf16 v[108:111], v[176:179], v[216:219], v[108:111]
	v_mfma_f32_16x16x32_bf16 v[104:107], v[148:151], v[224:227], v[104:107]
	v_mfma_f32_16x16x32_bf16 v[100:103], v[176:179], v[224:227], v[100:103]
	v_mfma_f32_16x16x32_bf16 v[128:131], v[172:175], v[204:207], v[128:131]
	v_mfma_f32_16x16x32_bf16 v[124:127], v[180:183], v[204:207], v[124:127]
	v_mfma_f32_16x16x32_bf16 v[120:123], v[172:175], v[212:215], v[120:123]
	v_mfma_f32_16x16x32_bf16 v[116:119], v[180:183], v[212:215], v[116:119]
	v_mfma_f32_16x16x32_bf16 v[112:115], v[172:175], v[220:223], v[112:115]
	v_mfma_f32_16x16x32_bf16 v[108:111], v[180:183], v[220:223], v[108:111]
	v_mfma_f32_16x16x32_bf16 v[104:107], v[172:175], v[228:231], v[104:107]
	v_mfma_f32_16x16x32_bf16 v[100:103], v[180:183], v[228:231], v[100:103]
	s_setprio 0
	s_setprio 1
	v_mfma_f32_16x16x32_bf16 v[64:67], v[184:187], v[200:203], v[64:67]
	v_mfma_f32_16x16x32_bf16 v[60:63], v[192:195], v[200:203], v[60:63]
	v_mfma_f32_16x16x32_bf16 v[56:59], v[184:187], v[208:211], v[56:59]
	v_mfma_f32_16x16x32_bf16 v[52:55], v[192:195], v[208:211], v[52:55]
	v_mfma_f32_16x16x32_bf16 v[48:51], v[184:187], v[216:219], v[48:51]
	v_mfma_f32_16x16x32_bf16 v[44:47], v[192:195], v[216:219], v[44:47]
	v_mfma_f32_16x16x32_bf16 v[40:43], v[184:187], v[224:227], v[40:43]
	v_mfma_f32_16x16x32_bf16 v[36:39], v[192:195], v[224:227], v[36:39]
	v_mfma_f32_16x16x32_bf16 v[64:67], v[188:191], v[204:207], v[64:67]
	v_mfma_f32_16x16x32_bf16 v[60:63], v[196:199], v[204:207], v[60:63]
	v_mfma_f32_16x16x32_bf16 v[56:59], v[188:191], v[212:215], v[56:59]
	v_mfma_f32_16x16x32_bf16 v[52:55], v[196:199], v[212:215], v[52:55]
	v_mfma_f32_16x16x32_bf16 v[48:51], v[188:191], v[220:223], v[48:51]
	v_mfma_f32_16x16x32_bf16 v[44:47], v[196:199], v[220:223], v[44:47]
	v_mfma_f32_16x16x32_bf16 v[40:43], v[188:191], v[228:231], v[40:43]
	v_mfma_f32_16x16x32_bf16 v[36:39], v[196:199], v[228:231], v[36:39]
	s_setprio 0
	s_barrier
	s_add_i32 s80, s57, s36
	v_lshl_add_u64 v[232:233], s[68:69], 0, v[134:135]
	s_mov_b32 m0, s80
	ds_read_b128 v[200:203], v170 offset:16384
	ds_read_b128 v[204:207], v170 offset:17408
	ds_read_b128 v[208:211], v170 offset:18432
	ds_read_b128 v[212:215], v170 offset:19456
	ds_read_b128 v[216:219], v170 offset:20480
	ds_read_b128 v[220:223], v170 offset:21504
	ds_read_b128 v[224:227], v170 offset:22528
	ds_read_b128 v[228:231], v170 offset:23552
	global_load_lds_dwordx4 v[232:233], off
	s_add_i32 m0, s80, 0x2000
	v_lshl_add_u64 v[234:235], s[68:69], 0, v[138:139]
	s_add_u32 s68, s68, s6
	s_addc_u32 s69, s69, s7
	s_add_i32 s80, s58, s36
	global_load_lds_dwordx4 v[234:235], off
	v_lshl_add_u64 v[236:237], s[68:69], 0, v[134:135]
	s_mov_b32 m0, s80
	v_lshl_add_u64 v[238:239], s[68:69], 0, v[138:139]
	global_load_lds_dwordx4 v[236:237], off
	s_add_i32 m0, s80, 0x2000
	v_lshl_add_u64 v[240:241], s[26:27], 0, v[132:133]
	global_load_lds_dwordx4 v[238:239], off
	s_mov_b32 m0, s37
	v_lshl_add_u64 v[242:243], s[26:27], 0, v[136:137]
	global_load_lds_dwordx4 v[240:241], off
	s_mov_b32 m0, s38
	s_nop 0
	global_load_lds_dwordx4 v[242:243], off
	s_waitcnt vmcnt(8)
	s_waitcnt lgkmcnt(0)
	s_setprio 1
	s_waitcnt lgkmcnt(0)
	v_mfma_f32_16x16x32_bf16 v[96:99], v[148:151], v[200:203], v[96:99]
	v_mfma_f32_16x16x32_bf16 v[92:95], v[176:179], v[200:203], v[92:95]
	s_barrier
	v_mfma_f32_16x16x32_bf16 v[88:91], v[148:151], v[208:211], v[88:91]
	v_mfma_f32_16x16x32_bf16 v[84:87], v[176:179], v[208:211], v[84:87]
	v_mfma_f32_16x16x32_bf16 v[80:83], v[148:151], v[216:219], v[80:83]
	v_mfma_f32_16x16x32_bf16 v[76:79], v[176:179], v[216:219], v[76:79]
	v_mfma_f32_16x16x32_bf16 v[72:75], v[148:151], v[224:227], v[72:75]
	v_mfma_f32_16x16x32_bf16 v[68:71], v[176:179], v[224:227], v[68:71]
	v_mfma_f32_16x16x32_bf16 v[96:99], v[172:175], v[204:207], v[96:99]
	v_mfma_f32_16x16x32_bf16 v[92:95], v[180:183], v[204:207], v[92:95]
	v_mfma_f32_16x16x32_bf16 v[88:91], v[172:175], v[212:215], v[88:91]
	v_mfma_f32_16x16x32_bf16 v[84:87], v[180:183], v[212:215], v[84:87]
	v_mfma_f32_16x16x32_bf16 v[80:83], v[172:175], v[220:223], v[80:83]
	v_mfma_f32_16x16x32_bf16 v[76:79], v[180:183], v[220:223], v[76:79]
	v_mfma_f32_16x16x32_bf16 v[72:75], v[172:175], v[228:231], v[72:75]
	v_mfma_f32_16x16x32_bf16 v[68:71], v[180:183], v[228:231], v[68:71]
	s_setprio 0
	s_setprio 1
	v_mfma_f32_16x16x32_bf16 v[32:35], v[184:187], v[200:203], v[32:35]
	v_mfma_f32_16x16x32_bf16 v[28:31], v[192:195], v[200:203], v[28:31]
	v_mfma_f32_16x16x32_bf16 v[24:27], v[184:187], v[208:211], v[24:27]
	v_mfma_f32_16x16x32_bf16 v[20:23], v[192:195], v[208:211], v[20:23]
	v_mfma_f32_16x16x32_bf16 v[16:19], v[184:187], v[216:219], v[16:19]
	v_mfma_f32_16x16x32_bf16 v[12:15], v[192:195], v[216:219], v[12:15]
	v_mfma_f32_16x16x32_bf16 v[8:11], v[184:187], v[224:227], v[8:11]
	v_mfma_f32_16x16x32_bf16 v[4:7], v[192:195], v[224:227], v[4:7]
	v_mfma_f32_16x16x32_bf16 v[32:35], v[188:191], v[204:207], v[32:35]
	v_mfma_f32_16x16x32_bf16 v[28:31], v[196:199], v[204:207], v[28:31]
	v_mfma_f32_16x16x32_bf16 v[24:27], v[188:191], v[212:215], v[24:27]
	v_mfma_f32_16x16x32_bf16 v[20:23], v[196:199], v[212:215], v[20:23]
	v_mfma_f32_16x16x32_bf16 v[16:19], v[188:191], v[220:223], v[16:19]
	v_mfma_f32_16x16x32_bf16 v[12:15], v[196:199], v[220:223], v[12:15]
	v_mfma_f32_16x16x32_bf16 v[8:11], v[188:191], v[228:231], v[8:11]
	v_mfma_f32_16x16x32_bf16 v[4:7], v[196:199], v[228:231], v[4:7]
	s_setprio 0
	s_barrier
	s_add_i32 s68, 0, 0x18000
	v_add_u32_e32 v3, s68, v166
	s_add_i32 s69, 0, 0x1c000
	ds_read_b128 v[148:151], v3
	ds_read_b128 v[172:175], v3 offset:1024
	ds_read_b128 v[176:179], v3 offset:2048
	ds_read_b128 v[180:183], v3 offset:3072
	v_add_u32_e32 v3, s69, v166
	ds_read_b128 v[184:187], v3
	ds_read_b128 v[188:191], v3 offset:1024
	ds_read_b128 v[192:195], v3 offset:2048
	ds_read_b128 v[196:199], v3 offset:3072
	s_add_u32 s26, s26, s6
	s_addc_u32 s27, s27, s7
	s_mov_b32 m0, s39
	v_lshl_add_u64 v[244:245], s[26:27], 0, v[132:133]
	ds_read_b128 v[200:203], v170 offset:32768
	ds_read_b128 v[204:207], v170 offset:33792
	ds_read_b128 v[208:211], v170 offset:34816
	ds_read_b128 v[212:215], v170 offset:35840
	ds_read_b128 v[216:219], v170 offset:36864
	ds_read_b128 v[220:223], v170 offset:37888
	ds_read_b128 v[224:227], v170 offset:38912
	ds_read_b128 v[228:231], v170 offset:39936
	global_load_lds_dwordx4 v[244:245], off
	v_lshl_add_u64 v[244:245], s[26:27], 0, v[136:137]
	s_mov_b32 m0, s42
	s_nop 0
	global_load_lds_dwordx4 v[244:245], off
	s_waitcnt vmcnt(8)
	s_waitcnt lgkmcnt(0)
	s_setprio 1
	s_waitcnt lgkmcnt(0)
	v_mfma_f32_16x16x32_bf16 v[128:131], v[148:151], v[200:203], v[128:131]
	v_mfma_f32_16x16x32_bf16 v[124:127], v[176:179], v[200:203], v[124:127]
	s_barrier
	v_mfma_f32_16x16x32_bf16 v[120:123], v[148:151], v[208:211], v[120:123]
	v_mfma_f32_16x16x32_bf16 v[116:119], v[176:179], v[208:211], v[116:119]
	v_mfma_f32_16x16x32_bf16 v[112:115], v[148:151], v[216:219], v[112:115]
	v_mfma_f32_16x16x32_bf16 v[108:111], v[176:179], v[216:219], v[108:111]
	v_mfma_f32_16x16x32_bf16 v[104:107], v[148:151], v[224:227], v[104:107]
	v_mfma_f32_16x16x32_bf16 v[100:103], v[176:179], v[224:227], v[100:103]
	v_mfma_f32_16x16x32_bf16 v[128:131], v[172:175], v[204:207], v[128:131]
	v_mfma_f32_16x16x32_bf16 v[124:127], v[180:183], v[204:207], v[124:127]
	v_mfma_f32_16x16x32_bf16 v[120:123], v[172:175], v[212:215], v[120:123]
	v_mfma_f32_16x16x32_bf16 v[116:119], v[180:183], v[212:215], v[116:119]
	v_mfma_f32_16x16x32_bf16 v[112:115], v[172:175], v[220:223], v[112:115]
	v_mfma_f32_16x16x32_bf16 v[108:111], v[180:183], v[220:223], v[108:111]
	v_mfma_f32_16x16x32_bf16 v[104:107], v[172:175], v[228:231], v[104:107]
	v_mfma_f32_16x16x32_bf16 v[100:103], v[180:183], v[228:231], v[100:103]
	s_setprio 0
	s_setprio 1
	v_mfma_f32_16x16x32_bf16 v[64:67], v[184:187], v[200:203], v[64:67]
	v_mfma_f32_16x16x32_bf16 v[60:63], v[192:195], v[200:203], v[60:63]
	v_mfma_f32_16x16x32_bf16 v[56:59], v[184:187], v[208:211], v[56:59]
	v_mfma_f32_16x16x32_bf16 v[52:55], v[192:195], v[208:211], v[52:55]
	v_mfma_f32_16x16x32_bf16 v[48:51], v[184:187], v[216:219], v[48:51]
	v_mfma_f32_16x16x32_bf16 v[44:47], v[192:195], v[216:219], v[44:47]
	v_mfma_f32_16x16x32_bf16 v[40:43], v[184:187], v[224:227], v[40:43]
	v_mfma_f32_16x16x32_bf16 v[36:39], v[192:195], v[224:227], v[36:39]
	v_mfma_f32_16x16x32_bf16 v[64:67], v[188:191], v[204:207], v[64:67]
	v_mfma_f32_16x16x32_bf16 v[60:63], v[196:199], v[204:207], v[60:63]
	v_mfma_f32_16x16x32_bf16 v[56:59], v[188:191], v[212:215], v[56:59]
	v_mfma_f32_16x16x32_bf16 v[52:55], v[196:199], v[212:215], v[52:55]
	v_mfma_f32_16x16x32_bf16 v[48:51], v[188:191], v[220:223], v[48:51]
	v_mfma_f32_16x16x32_bf16 v[44:47], v[196:199], v[220:223], v[44:47]
	v_mfma_f32_16x16x32_bf16 v[40:43], v[188:191], v[228:231], v[40:43]
	v_mfma_f32_16x16x32_bf16 v[36:39], v[196:199], v[228:231], v[36:39]
	s_setprio 0
	s_barrier
	s_add_i32 s26, s68, s36
	v_lshl_add_u64 v[232:233], v[232:233], 0, s[16:17]
	s_mov_b32 m0, s26
	ds_read_b128 v[200:203], v170 offset:49152
	ds_read_b128 v[204:207], v170 offset:50176
	ds_read_b128 v[208:211], v170 offset:51200
	ds_read_b128 v[212:215], v170 offset:52224
	ds_read_b128 v[216:219], v170 offset:53248
	ds_read_b128 v[220:223], v170 offset:54272
	ds_read_b128 v[224:227], v170 offset:55296
	ds_read_b128 v[228:231], v170 offset:56320
	global_load_lds_dwordx4 v[232:233], off
	v_lshl_add_u64 v[232:233], v[234:235], 0, s[16:17]
	s_add_i32 m0, s26, 0x2000
	s_add_i32 s26, s69, s36
	global_load_lds_dwordx4 v[232:233], off
	v_lshl_add_u64 v[232:233], v[236:237], 0, s[16:17]
	s_mov_b32 m0, s26
	s_nop 0
	global_load_lds_dwordx4 v[232:233], off
	v_lshl_add_u64 v[232:233], v[238:239], 0, s[16:17]
	s_add_i32 m0, s26, 0x2000
	s_nop 0
	global_load_lds_dwordx4 v[232:233], off
	v_lshl_add_u64 v[232:233], v[240:241], 0, s[16:17]
	s_mov_b32 m0, s44
	s_nop 0
	global_load_lds_dwordx4 v[232:233], off
	v_lshl_add_u64 v[232:233], v[242:243], 0, s[16:17]
	s_mov_b32 m0, s45
	s_nop 0
	global_load_lds_dwordx4 v[232:233], off
	s_waitcnt vmcnt(8)
	s_waitcnt lgkmcnt(0)
	s_setprio 1
	s_waitcnt lgkmcnt(0)
	v_mfma_f32_16x16x32_bf16 v[96:99], v[148:151], v[200:203], v[96:99]
	v_mfma_f32_16x16x32_bf16 v[92:95], v[176:179], v[200:203], v[92:95]
	s_barrier
	v_mfma_f32_16x16x32_bf16 v[88:91], v[148:151], v[208:211], v[88:91]
	v_mfma_f32_16x16x32_bf16 v[84:87], v[176:179], v[208:211], v[84:87]
	v_mfma_f32_16x16x32_bf16 v[80:83], v[148:151], v[216:219], v[80:83]
	v_mfma_f32_16x16x32_bf16 v[76:79], v[176:179], v[216:219], v[76:79]
	v_mfma_f32_16x16x32_bf16 v[72:75], v[148:151], v[224:227], v[72:75]
	v_mfma_f32_16x16x32_bf16 v[68:71], v[176:179], v[224:227], v[68:71]
	v_mfma_f32_16x16x32_bf16 v[96:99], v[172:175], v[204:207], v[96:99]
	v_mfma_f32_16x16x32_bf16 v[92:95], v[180:183], v[204:207], v[92:95]
	v_mfma_f32_16x16x32_bf16 v[88:91], v[172:175], v[212:215], v[88:91]
	v_mfma_f32_16x16x32_bf16 v[84:87], v[180:183], v[212:215], v[84:87]
	v_mfma_f32_16x16x32_bf16 v[80:83], v[172:175], v[220:223], v[80:83]
	v_mfma_f32_16x16x32_bf16 v[76:79], v[180:183], v[220:223], v[76:79]
	v_mfma_f32_16x16x32_bf16 v[72:75], v[172:175], v[228:231], v[72:75]
	v_mfma_f32_16x16x32_bf16 v[68:71], v[180:183], v[228:231], v[68:71]
	s_setprio 0
	s_setprio 1
	v_mfma_f32_16x16x32_bf16 v[32:35], v[184:187], v[200:203], v[32:35]
	v_mfma_f32_16x16x32_bf16 v[28:31], v[192:195], v[200:203], v[28:31]
	v_mfma_f32_16x16x32_bf16 v[24:27], v[184:187], v[208:211], v[24:27]
	v_mfma_f32_16x16x32_bf16 v[20:23], v[192:195], v[208:211], v[20:23]
	v_mfma_f32_16x16x32_bf16 v[16:19], v[184:187], v[216:219], v[16:19]
	v_mfma_f32_16x16x32_bf16 v[12:15], v[192:195], v[216:219], v[12:15]
	v_mfma_f32_16x16x32_bf16 v[8:11], v[184:187], v[224:227], v[8:11]
	v_mfma_f32_16x16x32_bf16 v[4:7], v[192:195], v[224:227], v[4:7]
	v_mfma_f32_16x16x32_bf16 v[32:35], v[188:191], v[204:207], v[32:35]
	v_mfma_f32_16x16x32_bf16 v[28:31], v[196:199], v[204:207], v[28:31]
	v_mfma_f32_16x16x32_bf16 v[24:27], v[188:191], v[212:215], v[24:27]
	v_mfma_f32_16x16x32_bf16 v[20:23], v[196:199], v[212:215], v[20:23]
	v_mfma_f32_16x16x32_bf16 v[16:19], v[188:191], v[220:223], v[16:19]
	v_mfma_f32_16x16x32_bf16 v[12:15], v[196:199], v[220:223], v[12:15]
	v_mfma_f32_16x16x32_bf16 v[8:11], v[188:191], v[228:231], v[8:11]
	v_mfma_f32_16x16x32_bf16 v[4:7], v[196:199], v[228:231], v[4:7]
	s_setprio 0
	s_barrier
	s_add_u32 s24, s24, 0x100
	s_addc_u32 s25, s25, 0
	s_add_u32 s65, s65, 0x100
	s_addc_u32 s66, s66, 0
	s_cmp_ge_i32 s67, s46
	s_mov_b32 s26, s67
	s_cbranch_scc0 .LBB0_1461

.LBB0_1514:
	ds_read_b128 v[152:155], v149
	ds_read_b128 v[156:159], v149 offset:1024
	ds_read_b128 v[160:163], v149 offset:2048
	ds_read_b128 v[164:167], v149 offset:3072
	ds_read_b128 v[168:171], v150
	ds_read_b128 v[172:175], v150 offset:1024
	ds_read_b128 v[176:179], v150 offset:2048
	ds_read_b128 v[180:183], v150 offset:3072
	s_add_i32 s69, s36, 2
	s_add_u32 s80, s34, 0x80
	s_addc_u32 s37, s35, 0
	s_cmp_eq_u32 s59, s36
	s_cselect_b32 s36, s2, s80
	s_cselect_b32 s37, s3, s37
	s_cselect_b32 s81, s31, s68
	s_cselect_b32 s80, s30, s67
	v_lshl_add_u64 v[216:217], s[34:35], 0, v[138:139]
	s_add_i32 m0, s47, 0xc000
	ds_read_b128 v[184:187], v151
	ds_read_b128 v[188:191], v151 offset:1024
	ds_read_b128 v[192:195], v151 offset:2048
	ds_read_b128 v[196:199], v151 offset:3072
	ds_read_b128 v[200:203], v151 offset:4096
	ds_read_b128 v[204:207], v151 offset:5120
	ds_read_b128 v[208:211], v151 offset:6144
	ds_read_b128 v[212:215], v151 offset:7168
	global_load_lds_dwordx4 v[216:217], off
	v_lshl_add_u64 v[216:217], s[34:35], 0, v[140:141]
	s_add_i32 m0, s47, 0xe000
	s_nop 0
	global_load_lds_dwordx4 v[216:217], off
	s_waitcnt vmcnt(8)
	s_waitcnt lgkmcnt(0)
	s_setprio 1
	s_waitcnt lgkmcnt(0)
	v_mfma_f32_16x16x32_bf16 v[122:125], v[152:155], v[184:187], v[122:125]
	v_mfma_f32_16x16x32_bf16 v[126:129], v[160:163], v[184:187], v[126:129]
	s_barrier
	v_mfma_f32_16x16x32_bf16 v[110:113], v[152:155], v[192:195], v[110:113]
	v_mfma_f32_16x16x32_bf16 v[106:109], v[160:163], v[192:195], v[106:109]
	v_mfma_f32_16x16x32_bf16 v[94:97], v[152:155], v[200:203], v[94:97]
	v_mfma_f32_16x16x32_bf16 v[90:93], v[160:163], v[200:203], v[90:93]
	v_mfma_f32_16x16x32_bf16 v[78:81], v[152:155], v[208:211], v[78:81]
	v_mfma_f32_16x16x32_bf16 v[74:77], v[160:163], v[208:211], v[74:77]
	v_mfma_f32_16x16x32_bf16 v[122:125], v[156:159], v[188:191], v[122:125]
	v_mfma_f32_16x16x32_bf16 v[126:129], v[164:167], v[188:191], v[126:129]
	v_mfma_f32_16x16x32_bf16 v[110:113], v[156:159], v[196:199], v[110:113]
	v_mfma_f32_16x16x32_bf16 v[106:109], v[164:167], v[196:199], v[106:109]
	v_mfma_f32_16x16x32_bf16 v[94:97], v[156:159], v[204:207], v[94:97]
	v_mfma_f32_16x16x32_bf16 v[90:93], v[164:167], v[204:207], v[90:93]
	v_mfma_f32_16x16x32_bf16 v[78:81], v[156:159], v[212:215], v[78:81]
	v_mfma_f32_16x16x32_bf16 v[74:77], v[164:167], v[212:215], v[74:77]
	s_setprio 0
	s_setprio 1
	v_mfma_f32_16x16x32_bf16 v[118:121], v[168:171], v[184:187], v[118:121]
	v_mfma_f32_16x16x32_bf16 v[114:117], v[176:179], v[184:187], v[114:117]
	v_mfma_f32_16x16x32_bf16 v[102:105], v[168:171], v[192:195], v[102:105]
	v_mfma_f32_16x16x32_bf16 v[98:101], v[176:179], v[192:195], v[98:101]
	v_mfma_f32_16x16x32_bf16 v[86:89], v[168:171], v[200:203], v[86:89]
	v_mfma_f32_16x16x32_bf16 v[82:85], v[176:179], v[200:203], v[82:85]
	v_mfma_f32_16x16x32_bf16 v[70:73], v[168:171], v[208:211], v[70:73]
	v_mfma_f32_16x16x32_bf16 v[66:69], v[176:179], v[208:211], v[66:69]
	v_mfma_f32_16x16x32_bf16 v[118:121], v[172:175], v[188:191], v[118:121]
	v_mfma_f32_16x16x32_bf16 v[114:117], v[180:183], v[188:191], v[114:117]
	v_mfma_f32_16x16x32_bf16 v[102:105], v[172:175], v[196:199], v[102:105]
	v_mfma_f32_16x16x32_bf16 v[98:101], v[180:183], v[196:199], v[98:101]
	v_mfma_f32_16x16x32_bf16 v[86:89], v[172:175], v[204:207], v[86:89]
	v_mfma_f32_16x16x32_bf16 v[82:85], v[180:183], v[204:207], v[82:85]
	v_mfma_f32_16x16x32_bf16 v[70:73], v[172:175], v[212:215], v[70:73]
	v_mfma_f32_16x16x32_bf16 v[66:69], v[180:183], v[212:215], v[66:69]
	s_setprio 0
	s_barrier
	s_add_i32 s82, s61, s44
	v_lshl_add_u64 v[216:217], s[80:81], 0, v[134:135]
	s_mov_b32 m0, s82
	ds_read_b128 v[184:187], v151 offset:16384
	ds_read_b128 v[188:191], v151 offset:17408
	ds_read_b128 v[192:195], v151 offset:18432
	ds_read_b128 v[196:199], v151 offset:19456
	ds_read_b128 v[200:203], v151 offset:20480
	ds_read_b128 v[204:207], v151 offset:21504
	ds_read_b128 v[208:211], v151 offset:22528
	ds_read_b128 v[212:215], v151 offset:23552
	global_load_lds_dwordx4 v[216:217], off
	s_add_i32 m0, s82, 0x2000
	v_lshl_add_u64 v[218:219], s[80:81], 0, v[130:131]
	s_add_u32 s80, s80, s6
	s_addc_u32 s81, s81, s7
	s_add_i32 s82, s62, s44
	global_load_lds_dwordx4 v[218:219], off
	v_lshl_add_u64 v[220:221], s[80:81], 0, v[134:135]
	s_mov_b32 m0, s82
	v_lshl_add_u64 v[222:223], s[80:81], 0, v[130:131]
	global_load_lds_dwordx4 v[220:221], off
	s_add_i32 m0, s82, 0x2000
	v_lshl_add_u64 v[224:225], s[36:37], 0, v[136:137]
	global_load_lds_dwordx4 v[222:223], off
	s_mov_b32 m0, s47
	v_lshl_add_u64 v[226:227], s[36:37], 0, v[132:133]
	global_load_lds_dwordx4 v[224:225], off
	s_mov_b32 m0, s50
	s_nop 0
	global_load_lds_dwordx4 v[226:227], off
	s_waitcnt vmcnt(8)
	s_waitcnt lgkmcnt(0)
	s_setprio 1
	s_waitcnt lgkmcnt(0)
	v_mfma_f32_16x16x32_bf16 v[62:65], v[152:155], v[184:187], v[62:65]
	v_mfma_f32_16x16x32_bf16 v[58:61], v[160:163], v[184:187], v[58:61]
	s_barrier
	v_mfma_f32_16x16x32_bf16 v[46:49], v[152:155], v[192:195], v[46:49]
	v_mfma_f32_16x16x32_bf16 v[42:45], v[160:163], v[192:195], v[42:45]
	v_mfma_f32_16x16x32_bf16 v[30:33], v[152:155], v[200:203], v[30:33]
	v_mfma_f32_16x16x32_bf16 v[26:29], v[160:163], v[200:203], v[26:29]
	v_mfma_f32_16x16x32_bf16 v[14:17], v[152:155], v[208:211], v[14:17]
	v_mfma_f32_16x16x32_bf16 v[10:13], v[160:163], v[208:211], v[10:13]
	v_mfma_f32_16x16x32_bf16 v[62:65], v[156:159], v[188:191], v[62:65]
	v_mfma_f32_16x16x32_bf16 v[58:61], v[164:167], v[188:191], v[58:61]
	v_mfma_f32_16x16x32_bf16 v[46:49], v[156:159], v[196:199], v[46:49]
	v_mfma_f32_16x16x32_bf16 v[42:45], v[164:167], v[196:199], v[42:45]
	v_mfma_f32_16x16x32_bf16 v[30:33], v[156:159], v[204:207], v[30:33]
	v_mfma_f32_16x16x32_bf16 v[26:29], v[164:167], v[204:207], v[26:29]
	v_mfma_f32_16x16x32_bf16 v[14:17], v[156:159], v[212:215], v[14:17]
	v_mfma_f32_16x16x32_bf16 v[10:13], v[164:167], v[212:215], v[10:13]
	s_setprio 0
	s_setprio 1
	v_mfma_f32_16x16x32_bf16 v[54:57], v[168:171], v[184:187], v[54:57]
	v_mfma_f32_16x16x32_bf16 v[50:53], v[176:179], v[184:187], v[50:53]
	v_mfma_f32_16x16x32_bf16 v[38:41], v[168:171], v[192:195], v[38:41]
	v_mfma_f32_16x16x32_bf16 v[34:37], v[176:179], v[192:195], v[34:37]
	v_mfma_f32_16x16x32_bf16 v[22:25], v[168:171], v[200:203], v[22:25]
	v_mfma_f32_16x16x32_bf16 v[18:21], v[176:179], v[200:203], v[18:21]
	v_mfma_f32_16x16x32_bf16 v[6:9], v[168:171], v[208:211], v[6:9]
	v_mfma_f32_16x16x32_bf16 v[2:5], v[176:179], v[208:211], v[2:5]
	v_mfma_f32_16x16x32_bf16 v[54:57], v[172:175], v[188:191], v[54:57]
	v_mfma_f32_16x16x32_bf16 v[50:53], v[180:183], v[188:191], v[50:53]
	v_mfma_f32_16x16x32_bf16 v[38:41], v[172:175], v[196:199], v[38:41]
	v_mfma_f32_16x16x32_bf16 v[34:37], v[180:183], v[196:199], v[34:37]
	v_mfma_f32_16x16x32_bf16 v[22:25], v[172:175], v[204:207], v[22:25]
	v_mfma_f32_16x16x32_bf16 v[18:21], v[180:183], v[204:207], v[18:21]
	v_mfma_f32_16x16x32_bf16 v[6:9], v[172:175], v[212:215], v[6:9]
	v_mfma_f32_16x16x32_bf16 v[2:5], v[180:183], v[212:215], v[2:5]
	s_setprio 0
	s_barrier
	s_add_i32 s80, 0, 0x18000
	s_add_i32 s81, 0, 0x1c000
	v_add_u32_e32 v164, s80, v147
	v_add_u32_e32 v180, s81, v147
	ds_read_b128 v[152:155], v164
	ds_read_b128 v[156:159], v164 offset:1024
	ds_read_b128 v[160:163], v164 offset:2048
	ds_read_b128 v[164:167], v164 offset:3072
	ds_read_b128 v[168:171], v180
	ds_read_b128 v[172:175], v180 offset:1024
	ds_read_b128 v[176:179], v180 offset:2048
	ds_read_b128 v[180:183], v180 offset:3072
	s_add_u32 s36, s36, s6
	s_addc_u32 s37, s37, s7
	s_mov_b32 m0, s51
	v_lshl_add_u64 v[228:229], s[36:37], 0, v[136:137]
	ds_read_b128 v[184:187], v151 offset:32768
	ds_read_b128 v[188:191], v151 offset:33792
	ds_read_b128 v[192:195], v151 offset:34816
	ds_read_b128 v[196:199], v151 offset:35840
	ds_read_b128 v[200:203], v151 offset:36864
	ds_read_b128 v[204:207], v151 offset:37888
	ds_read_b128 v[208:211], v151 offset:38912
	ds_read_b128 v[212:215], v151 offset:39936
	global_load_lds_dwordx4 v[228:229], off
	v_lshl_add_u64 v[228:229], s[36:37], 0, v[132:133]
	s_mov_b32 m0, s54
	s_nop 0
	global_load_lds_dwordx4 v[228:229], off
	s_waitcnt vmcnt(8)
	s_waitcnt lgkmcnt(0)
	s_setprio 1
	s_waitcnt lgkmcnt(0)
	v_mfma_f32_16x16x32_bf16 v[122:125], v[152:155], v[184:187], v[122:125]
	v_mfma_f32_16x16x32_bf16 v[126:129], v[160:163], v[184:187], v[126:129]
	s_barrier
	v_mfma_f32_16x16x32_bf16 v[110:113], v[152:155], v[192:195], v[110:113]
	v_mfma_f32_16x16x32_bf16 v[106:109], v[160:163], v[192:195], v[106:109]
	v_mfma_f32_16x16x32_bf16 v[94:97], v[152:155], v[200:203], v[94:97]
	v_mfma_f32_16x16x32_bf16 v[90:93], v[160:163], v[200:203], v[90:93]
	v_mfma_f32_16x16x32_bf16 v[78:81], v[152:155], v[208:211], v[78:81]
	v_mfma_f32_16x16x32_bf16 v[74:77], v[160:163], v[208:211], v[74:77]
	v_mfma_f32_16x16x32_bf16 v[122:125], v[156:159], v[188:191], v[122:125]
	v_mfma_f32_16x16x32_bf16 v[126:129], v[164:167], v[188:191], v[126:129]
	v_mfma_f32_16x16x32_bf16 v[110:113], v[156:159], v[196:199], v[110:113]
	v_mfma_f32_16x16x32_bf16 v[106:109], v[164:167], v[196:199], v[106:109]
	v_mfma_f32_16x16x32_bf16 v[94:97], v[156:159], v[204:207], v[94:97]
	v_mfma_f32_16x16x32_bf16 v[90:93], v[164:167], v[204:207], v[90:93]
	v_mfma_f32_16x16x32_bf16 v[78:81], v[156:159], v[212:215], v[78:81]
	v_mfma_f32_16x16x32_bf16 v[74:77], v[164:167], v[212:215], v[74:77]
	s_setprio 0
	s_setprio 1
	v_mfma_f32_16x16x32_bf16 v[118:121], v[168:171], v[184:187], v[118:121]
	v_mfma_f32_16x16x32_bf16 v[114:117], v[176:179], v[184:187], v[114:117]
	v_mfma_f32_16x16x32_bf16 v[102:105], v[168:171], v[192:195], v[102:105]
	v_mfma_f32_16x16x32_bf16 v[98:101], v[176:179], v[192:195], v[98:101]
	v_mfma_f32_16x16x32_bf16 v[86:89], v[168:171], v[200:203], v[86:89]
	v_mfma_f32_16x16x32_bf16 v[82:85], v[176:179], v[200:203], v[82:85]
	v_mfma_f32_16x16x32_bf16 v[70:73], v[168:171], v[208:211], v[70:73]
	v_mfma_f32_16x16x32_bf16 v[66:69], v[176:179], v[208:211], v[66:69]
	v_mfma_f32_16x16x32_bf16 v[118:121], v[172:175], v[188:191], v[118:121]
	v_mfma_f32_16x16x32_bf16 v[114:117], v[180:183], v[188:191], v[114:117]
	v_mfma_f32_16x16x32_bf16 v[102:105], v[172:175], v[196:199], v[102:105]
	v_mfma_f32_16x16x32_bf16 v[98:101], v[180:183], v[196:199], v[98:101]
	v_mfma_f32_16x16x32_bf16 v[86:89], v[172:175], v[204:207], v[86:89]
	v_mfma_f32_16x16x32_bf16 v[82:85], v[180:183], v[204:207], v[82:85]
	v_mfma_f32_16x16x32_bf16 v[70:73], v[172:175], v[212:215], v[70:73]
	v_mfma_f32_16x16x32_bf16 v[66:69], v[180:183], v[212:215], v[66:69]
	s_setprio 0
	s_barrier
	s_add_i32 s36, s80, s44
	v_lshl_add_u64 v[216:217], v[216:217], 0, s[16:17]
	s_mov_b32 m0, s36
	ds_read_b128 v[184:187], v151 offset:49152
	ds_read_b128 v[188:191], v151 offset:50176
	ds_read_b128 v[192:195], v151 offset:51200
	ds_read_b128 v[196:199], v151 offset:52224
	ds_read_b128 v[200:203], v151 offset:53248
	ds_read_b128 v[204:207], v151 offset:54272
	ds_read_b128 v[208:211], v151 offset:55296
	ds_read_b128 v[212:215], v151 offset:56320
	global_load_lds_dwordx4 v[216:217], off
	v_lshl_add_u64 v[216:217], v[218:219], 0, s[16:17]
	s_add_i32 m0, s36, 0x2000
	s_add_i32 s36, s81, s44
	global_load_lds_dwordx4 v[216:217], off
	v_lshl_add_u64 v[216:217], v[220:221], 0, s[16:17]
	s_mov_b32 m0, s36
	s_nop 0
	global_load_lds_dwordx4 v[216:217], off
	v_lshl_add_u64 v[216:217], v[222:223], 0, s[16:17]
	s_add_i32 m0, s36, 0x2000
	s_nop 0
	global_load_lds_dwordx4 v[216:217], off
	v_lshl_add_u64 v[216:217], v[224:225], 0, s[16:17]
	s_mov_b32 m0, s56
	s_nop 0
	global_load_lds_dwordx4 v[216:217], off
	v_lshl_add_u64 v[216:217], v[226:227], 0, s[16:17]
	s_mov_b32 m0, s57
	s_nop 0
	global_load_lds_dwordx4 v[216:217], off
	s_waitcnt vmcnt(8)
	s_waitcnt lgkmcnt(0)
	s_setprio 1
	s_waitcnt lgkmcnt(0)
	v_mfma_f32_16x16x32_bf16 v[62:65], v[152:155], v[184:187], v[62:65]
	v_mfma_f32_16x16x32_bf16 v[58:61], v[160:163], v[184:187], v[58:61]
	s_barrier
	v_mfma_f32_16x16x32_bf16 v[46:49], v[152:155], v[192:195], v[46:49]
	v_mfma_f32_16x16x32_bf16 v[42:45], v[160:163], v[192:195], v[42:45]
	v_mfma_f32_16x16x32_bf16 v[30:33], v[152:155], v[200:203], v[30:33]
	v_mfma_f32_16x16x32_bf16 v[26:29], v[160:163], v[200:203], v[26:29]
	v_mfma_f32_16x16x32_bf16 v[14:17], v[152:155], v[208:211], v[14:17]
	v_mfma_f32_16x16x32_bf16 v[10:13], v[160:163], v[208:211], v[10:13]
	v_mfma_f32_16x16x32_bf16 v[62:65], v[156:159], v[188:191], v[62:65]
	v_mfma_f32_16x16x32_bf16 v[58:61], v[164:167], v[188:191], v[58:61]
	v_mfma_f32_16x16x32_bf16 v[46:49], v[156:159], v[196:199], v[46:49]
	v_mfma_f32_16x16x32_bf16 v[42:45], v[164:167], v[196:199], v[42:45]
	v_mfma_f32_16x16x32_bf16 v[30:33], v[156:159], v[204:207], v[30:33]
	v_mfma_f32_16x16x32_bf16 v[26:29], v[164:167], v[204:207], v[26:29]
	v_mfma_f32_16x16x32_bf16 v[14:17], v[156:159], v[212:215], v[14:17]
	v_mfma_f32_16x16x32_bf16 v[10:13], v[164:167], v[212:215], v[10:13]
	s_setprio 0
	s_setprio 1
	v_mfma_f32_16x16x32_bf16 v[54:57], v[168:171], v[184:187], v[54:57]
	v_mfma_f32_16x16x32_bf16 v[50:53], v[176:179], v[184:187], v[50:53]
	v_mfma_f32_16x16x32_bf16 v[38:41], v[168:171], v[192:195], v[38:41]
	v_mfma_f32_16x16x32_bf16 v[34:37], v[176:179], v[192:195], v[34:37]
	v_mfma_f32_16x16x32_bf16 v[22:25], v[168:171], v[200:203], v[22:25]
	v_mfma_f32_16x16x32_bf16 v[18:21], v[176:179], v[200:203], v[18:21]
	v_mfma_f32_16x16x32_bf16 v[6:9], v[168:171], v[208:211], v[6:9]
	v_mfma_f32_16x16x32_bf16 v[2:5], v[176:179], v[208:211], v[2:5]
	v_mfma_f32_16x16x32_bf16 v[54:57], v[172:175], v[188:191], v[54:57]
	v_mfma_f32_16x16x32_bf16 v[50:53], v[180:183], v[188:191], v[50:53]
	v_mfma_f32_16x16x32_bf16 v[38:41], v[172:175], v[196:199], v[38:41]
	v_mfma_f32_16x16x32_bf16 v[34:37], v[180:183], v[196:199], v[34:37]
	v_mfma_f32_16x16x32_bf16 v[22:25], v[172:175], v[204:207], v[22:25]
	v_mfma_f32_16x16x32_bf16 v[18:21], v[180:183], v[204:207], v[18:21]
	v_mfma_f32_16x16x32_bf16 v[6:9], v[172:175], v[212:215], v[6:9]
	v_mfma_f32_16x16x32_bf16 v[2:5], v[180:183], v[212:215], v[2:5]
	s_setprio 0
	s_barrier
	s_add_u32 s34, s34, 0x100
	s_addc_u32 s35, s35, 0
	s_add_u32 s67, s67, 0x100
	s_addc_u32 s68, s68, 0
	s_cmp_ge_i32 s69, s58
	s_mov_b32 s36, s69
	s_cbranch_scc0 .LBB0_1514

.LBB0_1754:
	v_add_u32_e32 v158, s80, v229
	v_add_u32_e32 v174, s81, v229
	ds_read_b128 v[146:149], v158
	ds_read_b128 v[150:153], v158 offset:1024
	ds_read_b128 v[154:157], v158 offset:2048
	ds_read_b128 v[158:161], v158 offset:3072
	ds_read_b128 v[162:165], v174
	ds_read_b128 v[166:169], v174 offset:1024
	ds_read_b128 v[170:173], v174 offset:2048
	ds_read_b128 v[174:177], v174 offset:3072
	s_add_i32 s88, s44, 2
	s_add_u32 s89, s42, 0x80
	s_addc_u32 s45, s43, 0
	s_cmp_eq_u32 s67, s44
	s_cselect_b32 s44, s4, s89
	s_cselect_b32 s45, s5, s45
	s_cselect_b32 s91, s39, s87
	s_cselect_b32 s90, s38, s86
	v_lshl_add_u64 v[210:211], s[42:43], 0, v[138:139]
	s_add_i32 m0, s55, 0xc000
	ds_read_b128 v[178:181], v231
	ds_read_b128 v[182:185], v231 offset:1024
	ds_read_b128 v[186:189], v231 offset:2048
	ds_read_b128 v[190:193], v231 offset:3072
	ds_read_b128 v[194:197], v231 offset:4096
	ds_read_b128 v[198:201], v231 offset:5120
	ds_read_b128 v[202:205], v231 offset:6144
	ds_read_b128 v[206:209], v231 offset:7168
	global_load_lds_dwordx4 v[210:211], off
	v_lshl_add_u64 v[210:211], s[42:43], 0, v[140:141]
	s_add_i32 m0, s55, 0xe000
	s_nop 0
	global_load_lds_dwordx4 v[210:211], off
	s_waitcnt vmcnt(8)
	s_waitcnt lgkmcnt(0)
	s_setprio 1
	s_waitcnt lgkmcnt(0)
	v_mfma_i32_16x16x64_i8 v[126:129], v[146:149], v[178:181], v[126:129]
	v_mfma_i32_16x16x64_i8 v[122:125], v[154:157], v[178:181], v[122:125]
	s_barrier
	v_mfma_i32_16x16x64_i8 v[118:121], v[146:149], v[186:189], v[118:121]
	v_mfma_i32_16x16x64_i8 v[114:117], v[154:157], v[186:189], v[114:117]
	v_mfma_i32_16x16x64_i8 v[106:109], v[146:149], v[194:197], v[106:109]
	v_mfma_i32_16x16x64_i8 v[98:101], v[154:157], v[194:197], v[98:101]
	v_mfma_i32_16x16x64_i8 v[90:93], v[146:149], v[202:205], v[90:93]
	v_mfma_i32_16x16x64_i8 v[82:85], v[154:157], v[202:205], v[82:85]
	v_mfma_i32_16x16x64_i8 v[126:129], v[150:153], v[182:185], v[126:129]
	v_mfma_i32_16x16x64_i8 v[122:125], v[158:161], v[182:185], v[122:125]
	v_mfma_i32_16x16x64_i8 v[118:121], v[150:153], v[190:193], v[118:121]
	v_mfma_i32_16x16x64_i8 v[114:117], v[158:161], v[190:193], v[114:117]
	v_mfma_i32_16x16x64_i8 v[106:109], v[150:153], v[198:201], v[106:109]
	v_mfma_i32_16x16x64_i8 v[98:101], v[158:161], v[198:201], v[98:101]
	v_mfma_i32_16x16x64_i8 v[90:93], v[150:153], v[206:209], v[90:93]
	v_mfma_i32_16x16x64_i8 v[82:85], v[158:161], v[206:209], v[82:85]
	s_setprio 0
	s_setprio 1
	v_mfma_i32_16x16x64_i8 v[110:113], v[162:165], v[178:181], v[110:113]
	v_mfma_i32_16x16x64_i8 v[102:105], v[170:173], v[178:181], v[102:105]
	v_mfma_i32_16x16x64_i8 v[94:97], v[162:165], v[186:189], v[94:97]
	v_mfma_i32_16x16x64_i8 v[86:89], v[170:173], v[186:189], v[86:89]
	v_mfma_i32_16x16x64_i8 v[78:81], v[162:165], v[194:197], v[78:81]
	v_mfma_i32_16x16x64_i8 v[74:77], v[170:173], v[194:197], v[74:77]
	v_mfma_i32_16x16x64_i8 v[70:73], v[162:165], v[202:205], v[70:73]
	v_mfma_i32_16x16x64_i8 v[66:69], v[170:173], v[202:205], v[66:69]
	v_mfma_i32_16x16x64_i8 v[110:113], v[166:169], v[182:185], v[110:113]
	v_mfma_i32_16x16x64_i8 v[102:105], v[174:177], v[182:185], v[102:105]
	v_mfma_i32_16x16x64_i8 v[94:97], v[166:169], v[190:193], v[94:97]
	v_mfma_i32_16x16x64_i8 v[86:89], v[174:177], v[190:193], v[86:89]
	v_mfma_i32_16x16x64_i8 v[78:81], v[166:169], v[198:201], v[78:81]
	v_mfma_i32_16x16x64_i8 v[74:77], v[174:177], v[198:201], v[74:77]
	v_mfma_i32_16x16x64_i8 v[70:73], v[166:169], v[206:209], v[70:73]
	v_mfma_i32_16x16x64_i8 v[66:69], v[174:177], v[206:209], v[66:69]
	s_setprio 0
	s_barrier
	s_add_i32 s89, s80, s54
	v_lshl_add_u64 v[210:211], s[90:91], 0, v[132:133]
	s_mov_b32 m0, s89
	ds_read_b128 v[178:181], v231 offset:16384
	ds_read_b128 v[182:185], v231 offset:17408
	ds_read_b128 v[186:189], v231 offset:18432
	ds_read_b128 v[190:193], v231 offset:19456
	ds_read_b128 v[194:197], v231 offset:20480
	ds_read_b128 v[198:201], v231 offset:21504
	ds_read_b128 v[202:205], v231 offset:22528
	ds_read_b128 v[206:209], v231 offset:23552
	global_load_lds_dwordx4 v[210:211], off
	s_add_i32 m0, s89, 0x2000
	v_lshl_add_u64 v[212:213], s[90:91], 0, v[136:137]
	s_add_u32 s90, s90, s8
	s_addc_u32 s91, s91, s9
	s_add_i32 s89, s81, s54
	global_load_lds_dwordx4 v[212:213], off
	v_lshl_add_u64 v[214:215], s[90:91], 0, v[132:133]
	s_mov_b32 m0, s89
	v_lshl_add_u64 v[216:217], s[90:91], 0, v[136:137]
	global_load_lds_dwordx4 v[214:215], off
	s_add_i32 m0, s89, 0x2000
	v_lshl_add_u64 v[218:219], s[44:45], 0, v[130:131]
	global_load_lds_dwordx4 v[216:217], off
	s_mov_b32 m0, s55
	v_lshl_add_u64 v[220:221], s[44:45], 0, v[134:135]
	global_load_lds_dwordx4 v[218:219], off
	s_mov_b32 m0, s56
	s_nop 0
	global_load_lds_dwordx4 v[220:221], off
	s_waitcnt vmcnt(8)
	s_waitcnt lgkmcnt(0)
	s_setprio 1
	s_waitcnt lgkmcnt(0)
	v_mfma_i32_16x16x64_i8 v[62:65], v[146:149], v[178:181], v[62:65]
	v_mfma_i32_16x16x64_i8 v[58:61], v[154:157], v[178:181], v[58:61]
	s_barrier
	v_mfma_i32_16x16x64_i8 v[54:57], v[146:149], v[186:189], v[54:57]
	v_mfma_i32_16x16x64_i8 v[50:53], v[154:157], v[186:189], v[50:53]
	v_mfma_i32_16x16x64_i8 v[42:45], v[146:149], v[194:197], v[42:45]
	v_mfma_i32_16x16x64_i8 v[34:37], v[154:157], v[194:197], v[34:37]
	v_mfma_i32_16x16x64_i8 v[26:29], v[146:149], v[202:205], v[26:29]
	v_mfma_i32_16x16x64_i8 v[18:21], v[154:157], v[202:205], v[18:21]
	v_mfma_i32_16x16x64_i8 v[62:65], v[150:153], v[182:185], v[62:65]
	v_mfma_i32_16x16x64_i8 v[58:61], v[158:161], v[182:185], v[58:61]
	v_mfma_i32_16x16x64_i8 v[54:57], v[150:153], v[190:193], v[54:57]
	v_mfma_i32_16x16x64_i8 v[50:53], v[158:161], v[190:193], v[50:53]
	v_mfma_i32_16x16x64_i8 v[42:45], v[150:153], v[198:201], v[42:45]
	v_mfma_i32_16x16x64_i8 v[34:37], v[158:161], v[198:201], v[34:37]
	v_mfma_i32_16x16x64_i8 v[26:29], v[150:153], v[206:209], v[26:29]
	v_mfma_i32_16x16x64_i8 v[18:21], v[158:161], v[206:209], v[18:21]
	s_setprio 0
	s_setprio 1
	v_mfma_i32_16x16x64_i8 v[46:49], v[162:165], v[178:181], v[46:49]
	v_mfma_i32_16x16x64_i8 v[38:41], v[170:173], v[178:181], v[38:41]
	v_mfma_i32_16x16x64_i8 v[30:33], v[162:165], v[186:189], v[30:33]
	v_mfma_i32_16x16x64_i8 v[22:25], v[170:173], v[186:189], v[22:25]
	v_mfma_i32_16x16x64_i8 v[14:17], v[162:165], v[194:197], v[14:17]
	v_mfma_i32_16x16x64_i8 v[10:13], v[170:173], v[194:197], v[10:13]
	v_mfma_i32_16x16x64_i8 v[6:9], v[162:165], v[202:205], v[6:9]
	v_mfma_i32_16x16x64_i8 v[2:5], v[170:173], v[202:205], v[2:5]
	v_mfma_i32_16x16x64_i8 v[46:49], v[166:169], v[182:185], v[46:49]
	v_mfma_i32_16x16x64_i8 v[38:41], v[174:177], v[182:185], v[38:41]
	v_mfma_i32_16x16x64_i8 v[30:33], v[166:169], v[190:193], v[30:33]
	v_mfma_i32_16x16x64_i8 v[22:25], v[174:177], v[190:193], v[22:25]
	v_mfma_i32_16x16x64_i8 v[14:17], v[166:169], v[198:201], v[14:17]
	v_mfma_i32_16x16x64_i8 v[10:13], v[174:177], v[198:201], v[10:13]
	v_mfma_i32_16x16x64_i8 v[6:9], v[166:169], v[206:209], v[6:9]
	v_mfma_i32_16x16x64_i8 v[2:5], v[174:177], v[206:209], v[2:5]
	s_setprio 0
	s_barrier
	s_add_i32 s89, 0, 0x18000
	s_add_i32 s90, 0, 0x1c000
	v_add_u32_e32 v158, s89, v229
	v_add_u32_e32 v174, s90, v229
	ds_read_b128 v[146:149], v158
	ds_read_b128 v[150:153], v158 offset:1024
	ds_read_b128 v[154:157], v158 offset:2048
	ds_read_b128 v[158:161], v158 offset:3072
	ds_read_b128 v[162:165], v174
	ds_read_b128 v[166:169], v174 offset:1024
	ds_read_b128 v[170:173], v174 offset:2048
	ds_read_b128 v[174:177], v174 offset:3072
	s_add_u32 s44, s44, s8
	s_addc_u32 s45, s45, s9
	s_mov_b32 m0, s57
	v_lshl_add_u64 v[222:223], s[44:45], 0, v[130:131]
	ds_read_b128 v[178:181], v231 offset:32768
	ds_read_b128 v[182:185], v231 offset:33792
	ds_read_b128 v[186:189], v231 offset:34816
	ds_read_b128 v[190:193], v231 offset:35840
	ds_read_b128 v[194:197], v231 offset:36864
	ds_read_b128 v[198:201], v231 offset:37888
	ds_read_b128 v[202:205], v231 offset:38912
	ds_read_b128 v[206:209], v231 offset:39936
	global_load_lds_dwordx4 v[222:223], off
	v_lshl_add_u64 v[222:223], s[44:45], 0, v[134:135]
	s_mov_b32 m0, s58
	s_nop 0
	global_load_lds_dwordx4 v[222:223], off
	s_waitcnt vmcnt(8)
	s_waitcnt lgkmcnt(0)
	s_setprio 1
	s_waitcnt lgkmcnt(0)
	v_mfma_i32_16x16x64_i8 v[126:129], v[146:149], v[178:181], v[126:129]
	v_mfma_i32_16x16x64_i8 v[122:125], v[154:157], v[178:181], v[122:125]
	s_barrier
	v_mfma_i32_16x16x64_i8 v[118:121], v[146:149], v[186:189], v[118:121]
	v_mfma_i32_16x16x64_i8 v[114:117], v[154:157], v[186:189], v[114:117]
	v_mfma_i32_16x16x64_i8 v[106:109], v[146:149], v[194:197], v[106:109]
	v_mfma_i32_16x16x64_i8 v[98:101], v[154:157], v[194:197], v[98:101]
	v_mfma_i32_16x16x64_i8 v[90:93], v[146:149], v[202:205], v[90:93]
	v_mfma_i32_16x16x64_i8 v[82:85], v[154:157], v[202:205], v[82:85]
	v_mfma_i32_16x16x64_i8 v[126:129], v[150:153], v[182:185], v[126:129]
	v_mfma_i32_16x16x64_i8 v[122:125], v[158:161], v[182:185], v[122:125]
	v_mfma_i32_16x16x64_i8 v[118:121], v[150:153], v[190:193], v[118:121]
	v_mfma_i32_16x16x64_i8 v[114:117], v[158:161], v[190:193], v[114:117]
	v_mfma_i32_16x16x64_i8 v[106:109], v[150:153], v[198:201], v[106:109]
	v_mfma_i32_16x16x64_i8 v[98:101], v[158:161], v[198:201], v[98:101]
	v_mfma_i32_16x16x64_i8 v[90:93], v[150:153], v[206:209], v[90:93]
	v_mfma_i32_16x16x64_i8 v[82:85], v[158:161], v[206:209], v[82:85]
	s_setprio 0
	s_setprio 1
	v_mfma_i32_16x16x64_i8 v[110:113], v[162:165], v[178:181], v[110:113]
	v_mfma_i32_16x16x64_i8 v[102:105], v[170:173], v[178:181], v[102:105]
	v_mfma_i32_16x16x64_i8 v[94:97], v[162:165], v[186:189], v[94:97]
	v_mfma_i32_16x16x64_i8 v[86:89], v[170:173], v[186:189], v[86:89]
	v_mfma_i32_16x16x64_i8 v[78:81], v[162:165], v[194:197], v[78:81]
	v_mfma_i32_16x16x64_i8 v[74:77], v[170:173], v[194:197], v[74:77]
	v_mfma_i32_16x16x64_i8 v[70:73], v[162:165], v[202:205], v[70:73]
	v_mfma_i32_16x16x64_i8 v[66:69], v[170:173], v[202:205], v[66:69]
	v_mfma_i32_16x16x64_i8 v[110:113], v[166:169], v[182:185], v[110:113]
	v_mfma_i32_16x16x64_i8 v[102:105], v[174:177], v[182:185], v[102:105]
	v_mfma_i32_16x16x64_i8 v[94:97], v[166:169], v[190:193], v[94:97]
	v_mfma_i32_16x16x64_i8 v[86:89], v[174:177], v[190:193], v[86:89]
	v_mfma_i32_16x16x64_i8 v[78:81], v[166:169], v[198:201], v[78:81]
	v_mfma_i32_16x16x64_i8 v[74:77], v[174:177], v[198:201], v[74:77]
	v_mfma_i32_16x16x64_i8 v[70:73], v[166:169], v[206:209], v[70:73]
	v_mfma_i32_16x16x64_i8 v[66:69], v[174:177], v[206:209], v[66:69]
	s_setprio 0
	s_barrier
	s_add_i32 s44, s89, s54
	v_lshl_add_u64 v[210:211], v[210:211], 0, s[30:31]
	s_mov_b32 m0, s44
	ds_read_b128 v[178:181], v231 offset:49152
	ds_read_b128 v[182:185], v231 offset:50176
	ds_read_b128 v[186:189], v231 offset:51200
	ds_read_b128 v[190:193], v231 offset:52224
	ds_read_b128 v[194:197], v231 offset:53248
	ds_read_b128 v[198:201], v231 offset:54272
	ds_read_b128 v[202:205], v231 offset:55296
	ds_read_b128 v[206:209], v231 offset:56320
	global_load_lds_dwordx4 v[210:211], off
	v_lshl_add_u64 v[210:211], v[212:213], 0, s[30:31]
	s_add_i32 m0, s44, 0x2000
	s_add_i32 s44, s90, s54
	global_load_lds_dwordx4 v[210:211], off
	v_lshl_add_u64 v[210:211], v[214:215], 0, s[30:31]
	s_mov_b32 m0, s44
	s_nop 0
	global_load_lds_dwordx4 v[210:211], off
	v_lshl_add_u64 v[210:211], v[216:217], 0, s[30:31]
	s_add_i32 m0, s44, 0x2000
	s_nop 0
	global_load_lds_dwordx4 v[210:211], off
	v_lshl_add_u64 v[210:211], v[218:219], 0, s[30:31]
	s_mov_b32 m0, s63
	s_nop 0
	global_load_lds_dwordx4 v[210:211], off
	v_lshl_add_u64 v[210:211], v[220:221], 0, s[30:31]
	s_mov_b32 m0, s64
	s_nop 0
	global_load_lds_dwordx4 v[210:211], off
	s_waitcnt vmcnt(8)
	s_waitcnt lgkmcnt(0)
	s_setprio 1
	s_waitcnt lgkmcnt(0)
	v_mfma_i32_16x16x64_i8 v[62:65], v[146:149], v[178:181], v[62:65]
	v_mfma_i32_16x16x64_i8 v[58:61], v[154:157], v[178:181], v[58:61]
	s_barrier
	v_mfma_i32_16x16x64_i8 v[54:57], v[146:149], v[186:189], v[54:57]
	v_mfma_i32_16x16x64_i8 v[50:53], v[154:157], v[186:189], v[50:53]
	v_mfma_i32_16x16x64_i8 v[42:45], v[146:149], v[194:197], v[42:45]
	v_mfma_i32_16x16x64_i8 v[34:37], v[154:157], v[194:197], v[34:37]
	v_mfma_i32_16x16x64_i8 v[26:29], v[146:149], v[202:205], v[26:29]
	v_mfma_i32_16x16x64_i8 v[18:21], v[154:157], v[202:205], v[18:21]
	v_mfma_i32_16x16x64_i8 v[62:65], v[150:153], v[182:185], v[62:65]
	v_mfma_i32_16x16x64_i8 v[58:61], v[158:161], v[182:185], v[58:61]
	v_mfma_i32_16x16x64_i8 v[54:57], v[150:153], v[190:193], v[54:57]
	v_mfma_i32_16x16x64_i8 v[50:53], v[158:161], v[190:193], v[50:53]
	v_mfma_i32_16x16x64_i8 v[42:45], v[150:153], v[198:201], v[42:45]
	v_mfma_i32_16x16x64_i8 v[34:37], v[158:161], v[198:201], v[34:37]
	v_mfma_i32_16x16x64_i8 v[26:29], v[150:153], v[206:209], v[26:29]
	v_mfma_i32_16x16x64_i8 v[18:21], v[158:161], v[206:209], v[18:21]
	s_setprio 0
	s_setprio 1
	v_mfma_i32_16x16x64_i8 v[46:49], v[162:165], v[178:181], v[46:49]
	v_mfma_i32_16x16x64_i8 v[38:41], v[170:173], v[178:181], v[38:41]
	v_mfma_i32_16x16x64_i8 v[30:33], v[162:165], v[186:189], v[30:33]
	v_mfma_i32_16x16x64_i8 v[22:25], v[170:173], v[186:189], v[22:25]
	v_mfma_i32_16x16x64_i8 v[14:17], v[162:165], v[194:197], v[14:17]
	v_mfma_i32_16x16x64_i8 v[10:13], v[170:173], v[194:197], v[10:13]
	v_mfma_i32_16x16x64_i8 v[6:9], v[162:165], v[202:205], v[6:9]
	v_mfma_i32_16x16x64_i8 v[2:5], v[170:173], v[202:205], v[2:5]
	v_mfma_i32_16x16x64_i8 v[46:49], v[166:169], v[182:185], v[46:49]
	v_mfma_i32_16x16x64_i8 v[38:41], v[174:177], v[182:185], v[38:41]
	v_mfma_i32_16x16x64_i8 v[30:33], v[166:169], v[190:193], v[30:33]
	v_mfma_i32_16x16x64_i8 v[22:25], v[174:177], v[190:193], v[22:25]
	v_mfma_i32_16x16x64_i8 v[14:17], v[166:169], v[198:201], v[14:17]
	v_mfma_i32_16x16x64_i8 v[10:13], v[174:177], v[198:201], v[10:13]
	v_mfma_i32_16x16x64_i8 v[6:9], v[166:169], v[206:209], v[6:9]
	v_mfma_i32_16x16x64_i8 v[2:5], v[174:177], v[206:209], v[2:5]
	s_setprio 0
	s_barrier
	s_add_u32 s42, s42, 0x100
	s_addc_u32 s43, s43, 0
	s_add_u32 s86, s86, 0x100
	s_addc_u32 s87, s87, 0
	s_cmp_ge_i32 s88, s66
	s_mov_b32 s44, s88
	s_cbranch_scc0 .LBB0_1754
	v_cvt_f32_i32_e32 v214, v126
	v_cvt_f32_i32_e32 v215, v127
	v_cvt_f32_i32_e32 v212, v128
	v_cvt_f32_i32_e32 v213, v129
	v_cvt_f32_i32_e32 v218, v122
	v_cvt_f32_i32_e32 v219, v123
	v_cvt_f32_i32_e32 v216, v124
	v_cvt_f32_i32_e32 v217, v125
	v_cvt_f32_i32_e32 v222, v110
	v_cvt_f32_i32_e32 v223, v111
	v_cvt_f32_i32_e32 v220, v112
	v_cvt_f32_i32_e32 v221, v113
	v_cvt_f32_i32_e32 v226, v102
	v_cvt_f32_i32_e32 v227, v103
	v_cvt_f32_i32_e32 v224, v104
	v_cvt_f32_i32_e32 v225, v105
	v_cvt_f32_i32_e32 v194, v118
	v_cvt_f32_i32_e32 v195, v119
	v_cvt_f32_i32_e32 v192, v120
	v_cvt_f32_i32_e32 v193, v121
	v_cvt_f32_i32_e32 v200, v114
	v_cvt_f32_i32_e32 v201, v115
	v_cvt_f32_i32_e32 v198, v116
	v_cvt_f32_i32_e32 v199, v117
	v_cvt_f32_i32_e32 v206, v94
	v_cvt_f32_i32_e32 v207, v95
	v_cvt_f32_i32_e32 v202, v96
	v_cvt_f32_i32_e32 v203, v97
	v_cvt_f32_i32_e32 v208, v86
	v_cvt_f32_i32_e32 v209, v87
	v_cvt_f32_i32_e32 v204, v88
	v_cvt_f32_i32_e32 v205, v89
	v_cvt_f32_i32_e32 v178, v106
	v_cvt_f32_i32_e32 v179, v107
	v_cvt_f32_i32_e32 v176, v108
	v_cvt_f32_i32_e32 v177, v109
	v_cvt_f32_i32_e32 v182, v98
	v_cvt_f32_i32_e32 v183, v99
	v_cvt_f32_i32_e32 v180, v100
	v_cvt_f32_i32_e32 v181, v101
	v_cvt_f32_i32_e32 v188, v78
	v_cvt_f32_i32_e32 v189, v79
	v_cvt_f32_i32_e32 v184, v80
	v_cvt_f32_i32_e32 v185, v81
	v_cvt_f32_i32_e32 v190, v74
	v_cvt_f32_i32_e32 v191, v75
	v_cvt_f32_i32_e32 v186, v76
	v_cvt_f32_i32_e32 v187, v77
	v_cvt_f32_i32_e32 v162, v90
	v_cvt_f32_i32_e32 v163, v91
	v_cvt_f32_i32_e32 v160, v92
	v_cvt_f32_i32_e32 v161, v93
	v_cvt_f32_i32_e32 v166, v82
	v_cvt_f32_i32_e32 v167, v83
	v_cvt_f32_i32_e32 v164, v84
	v_cvt_f32_i32_e32 v165, v85
	v_cvt_f32_i32_e32 v172, v70
	v_cvt_f32_i32_e32 v173, v71
	v_cvt_f32_i32_e32 v168, v72
	v_cvt_f32_i32_e32 v169, v73
	v_cvt_f32_i32_e32 v174, v66
	v_cvt_f32_i32_e32 v175, v67
	v_cvt_f32_i32_e32 v170, v68
	v_cvt_f32_i32_e32 v171, v69
	v_cvt_f32_i32_e32 v146, v62
	v_cvt_f32_i32_e32 v147, v63
	v_cvt_f32_i32_e32 v128, v64
	v_cvt_f32_i32_e32 v129, v65
	v_cvt_f32_i32_e32 v150, v58
	v_cvt_f32_i32_e32 v151, v59
	v_cvt_f32_i32_e32 v148, v60
	v_cvt_f32_i32_e32 v149, v61
	v_cvt_f32_i32_e32 v156, v46
	v_cvt_f32_i32_e32 v157, v47
	v_cvt_f32_i32_e32 v152, v48
	v_cvt_f32_i32_e32 v153, v49
	v_cvt_f32_i32_e32 v158, v38
	v_cvt_f32_i32_e32 v159, v39
	v_cvt_f32_i32_e32 v154, v40
	v_cvt_f32_i32_e32 v155, v41
	v_cvt_f32_i32_e32 v114, v54
	v_cvt_f32_i32_e32 v115, v55
	v_cvt_f32_i32_e32 v112, v56
	v_cvt_f32_i32_e32 v113, v57
	v_cvt_f32_i32_e32 v118, v50
	v_cvt_f32_i32_e32 v119, v51
	v_cvt_f32_i32_e32 v116, v52
	v_cvt_f32_i32_e32 v117, v53
	v_cvt_f32_i32_e32 v124, v30
	v_cvt_f32_i32_e32 v125, v31
	v_cvt_f32_i32_e32 v120, v32
	v_cvt_f32_i32_e32 v121, v33
	v_cvt_f32_i32_e32 v126, v22
	v_cvt_f32_i32_e32 v127, v23
	v_cvt_f32_i32_e32 v122, v24
	v_cvt_f32_i32_e32 v123, v25
	v_cvt_f32_i32_e32 v64, v42
	v_cvt_f32_i32_e32 v65, v43
	v_cvt_f32_i32_e32 v62, v44
	v_cvt_f32_i32_e32 v63, v45
	v_cvt_f32_i32_e32 v68, v34
	v_cvt_f32_i32_e32 v69, v35
	v_cvt_f32_i32_e32 v66, v36
	v_cvt_f32_i32_e32 v67, v37
	v_cvt_f32_i32_e32 v74, v14
	v_cvt_f32_i32_e32 v75, v15
	v_cvt_f32_i32_e32 v70, v16
	v_cvt_f32_i32_e32 v71, v17
	v_cvt_f32_i32_e32 v76, v10
	v_cvt_f32_i32_e32 v77, v11
	v_cvt_f32_i32_e32 v72, v12
	v_cvt_f32_i32_e32 v73, v13
	v_cvt_f32_i32_e32 v48, v26
	v_cvt_f32_i32_e32 v49, v27
	v_cvt_f32_i32_e32 v46, v28
	v_cvt_f32_i32_e32 v47, v29
	v_cvt_f32_i32_e32 v52, v18
	v_cvt_f32_i32_e32 v53, v19
	v_cvt_f32_i32_e32 v50, v20
	v_cvt_f32_i32_e32 v51, v21
	v_cvt_f32_i32_e32 v58, v6
	v_cvt_f32_i32_e32 v59, v7
	v_cvt_f32_i32_e32 v54, v8
	v_cvt_f32_i32_e32 v55, v9
	v_cvt_f32_i32_e32 v60, v2
	v_cvt_f32_i32_e32 v61, v3
	v_cvt_f32_i32_e32 v56, v4
	v_cvt_f32_i32_e32 v57, v5

.LBB0_1939:
	v_add_u32_e32 v138, s62, v188
	ds_read_b128 v[148:151], v138
	ds_read_b128 v[152:155], v138 offset:1024
	ds_read_b128 v[156:159], v138 offset:2048
	ds_read_b128 v[160:163], v138 offset:3072
	v_add_u32_e32 v138, s63, v188
	ds_read_b128 v[164:167], v138
	ds_read_b128 v[168:171], v138 offset:1024
	ds_read_b128 v[172:175], v138 offset:2048
	ds_read_b128 v[176:179], v138 offset:3072
	s_add_i32 s66, s28, 2
	s_add_u32 s67, s26, 0x80
	s_addc_u32 s29, s27, 0
	s_cmp_eq_u32 s60, s28
	s_cselect_b32 s28, s2, s67
	s_cselect_b32 s29, s3, s29
	s_cselect_b32 s69, s25, s35
	s_cselect_b32 s68, s24, s34
	v_lshl_add_u64 v[184:185], s[26:27], 0, v[140:141]
	s_add_i32 m0, s44, 0xc000
	ds_read_b128 v[180:183], v189
	ds_read_b128 v[190:193], v189 offset:1024
	ds_read_b128 v[194:197], v189 offset:2048
	ds_read_b128 v[198:201], v189 offset:3072
	ds_read_b128 v[202:205], v189 offset:4096
	ds_read_b128 v[206:209], v189 offset:5120
	ds_read_b128 v[210:213], v189 offset:6144
	ds_read_b128 v[214:217], v189 offset:7168
	global_load_lds_dwordx4 v[184:185], off
	v_lshl_add_u64 v[184:185], s[26:27], 0, v[142:143]
	s_add_i32 m0, s44, 0xe000
	s_nop 0
	global_load_lds_dwordx4 v[184:185], off
	s_waitcnt vmcnt(8)
	s_waitcnt lgkmcnt(0)
	s_setprio 1
	s_waitcnt lgkmcnt(0)
	v_mfma_i32_16x16x64_i8 v[126:129], v[148:151], v[180:183], v[126:129]
	v_mfma_i32_16x16x64_i8 v[122:125], v[156:159], v[180:183], v[122:125]
	s_barrier
	v_mfma_i32_16x16x64_i8 v[118:121], v[148:151], v[194:197], v[118:121]
	v_mfma_i32_16x16x64_i8 v[114:117], v[156:159], v[194:197], v[114:117]
	v_mfma_i32_16x16x64_i8 v[106:109], v[148:151], v[202:205], v[106:109]
	v_mfma_i32_16x16x64_i8 v[98:101], v[156:159], v[202:205], v[98:101]
	v_mfma_i32_16x16x64_i8 v[90:93], v[148:151], v[210:213], v[90:93]
	v_mfma_i32_16x16x64_i8 v[82:85], v[156:159], v[210:213], v[82:85]
	v_mfma_i32_16x16x64_i8 v[126:129], v[152:155], v[190:193], v[126:129]
	v_mfma_i32_16x16x64_i8 v[122:125], v[160:163], v[190:193], v[122:125]
	v_mfma_i32_16x16x64_i8 v[118:121], v[152:155], v[198:201], v[118:121]
	v_mfma_i32_16x16x64_i8 v[114:117], v[160:163], v[198:201], v[114:117]
	v_mfma_i32_16x16x64_i8 v[106:109], v[152:155], v[206:209], v[106:109]
	v_mfma_i32_16x16x64_i8 v[98:101], v[160:163], v[206:209], v[98:101]
	v_mfma_i32_16x16x64_i8 v[90:93], v[152:155], v[214:217], v[90:93]
	v_mfma_i32_16x16x64_i8 v[82:85], v[160:163], v[214:217], v[82:85]
	s_setprio 0
	s_setprio 1
	v_mfma_i32_16x16x64_i8 v[110:113], v[164:167], v[180:183], v[110:113]
	v_mfma_i32_16x16x64_i8 v[102:105], v[172:175], v[180:183], v[102:105]
	v_mfma_i32_16x16x64_i8 v[94:97], v[164:167], v[194:197], v[94:97]
	v_mfma_i32_16x16x64_i8 v[86:89], v[172:175], v[194:197], v[86:89]
	v_mfma_i32_16x16x64_i8 v[78:81], v[164:167], v[202:205], v[78:81]
	v_mfma_i32_16x16x64_i8 v[74:77], v[172:175], v[202:205], v[74:77]
	v_mfma_i32_16x16x64_i8 v[70:73], v[164:167], v[210:213], v[70:73]
	v_mfma_i32_16x16x64_i8 v[66:69], v[172:175], v[210:213], v[66:69]
	v_mfma_i32_16x16x64_i8 v[110:113], v[168:171], v[190:193], v[110:113]
	v_mfma_i32_16x16x64_i8 v[102:105], v[176:179], v[190:193], v[102:105]
	v_mfma_i32_16x16x64_i8 v[94:97], v[168:171], v[198:201], v[94:97]
	v_mfma_i32_16x16x64_i8 v[86:89], v[176:179], v[198:201], v[86:89]
	v_mfma_i32_16x16x64_i8 v[78:81], v[168:171], v[206:209], v[78:81]
	v_mfma_i32_16x16x64_i8 v[74:77], v[176:179], v[206:209], v[74:77]
	v_mfma_i32_16x16x64_i8 v[70:73], v[168:171], v[214:217], v[70:73]
	v_mfma_i32_16x16x64_i8 v[66:69], v[176:179], v[214:217], v[66:69]
	s_setprio 0
	s_barrier
	s_add_i32 s67, s62, s43
	v_lshl_add_u64 v[184:185], s[68:69], 0, v[132:133]
	s_mov_b32 m0, s67
	ds_read_b128 v[180:183], v189 offset:16384
	ds_read_b128 v[190:193], v189 offset:17408
	ds_read_b128 v[194:197], v189 offset:18432
	ds_read_b128 v[198:201], v189 offset:19456
	ds_read_b128 v[202:205], v189 offset:20480
	ds_read_b128 v[206:209], v189 offset:21504
	ds_read_b128 v[210:213], v189 offset:22528
	ds_read_b128 v[214:217], v189 offset:23552
	global_load_lds_dwordx4 v[184:185], off
	s_add_i32 m0, s67, 0x2000
	v_lshl_add_u64 v[218:219], s[68:69], 0, v[136:137]
	s_add_u32 s68, s68, s6
	s_addc_u32 s69, s69, s7
	s_add_i32 s67, s63, s43
	global_load_lds_dwordx4 v[218:219], off
	v_lshl_add_u64 v[220:221], s[68:69], 0, v[132:133]
	s_mov_b32 m0, s67
	v_lshl_add_u64 v[222:223], s[68:69], 0, v[136:137]
	global_load_lds_dwordx4 v[220:221], off
	s_add_i32 m0, s67, 0x2000
	v_lshl_add_u64 v[224:225], s[28:29], 0, v[130:131]
	global_load_lds_dwordx4 v[222:223], off
	s_mov_b32 m0, s44
	v_lshl_add_u64 v[226:227], s[28:29], 0, v[134:135]
	global_load_lds_dwordx4 v[224:225], off
	s_mov_b32 m0, s45
	s_nop 0
	global_load_lds_dwordx4 v[226:227], off
	s_waitcnt vmcnt(8)
	s_waitcnt lgkmcnt(0)
	s_setprio 1
	s_waitcnt lgkmcnt(0)
	v_mfma_i32_16x16x64_i8 v[62:65], v[148:151], v[180:183], v[62:65]
	v_mfma_i32_16x16x64_i8 v[58:61], v[156:159], v[180:183], v[58:61]
	s_barrier
	v_mfma_i32_16x16x64_i8 v[54:57], v[148:151], v[194:197], v[54:57]
	v_mfma_i32_16x16x64_i8 v[50:53], v[156:159], v[194:197], v[50:53]
	v_mfma_i32_16x16x64_i8 v[42:45], v[148:151], v[202:205], v[42:45]
	v_mfma_i32_16x16x64_i8 v[34:37], v[156:159], v[202:205], v[34:37]
	v_mfma_i32_16x16x64_i8 v[26:29], v[148:151], v[210:213], v[26:29]
	v_mfma_i32_16x16x64_i8 v[18:21], v[156:159], v[210:213], v[18:21]
	v_mfma_i32_16x16x64_i8 v[62:65], v[152:155], v[190:193], v[62:65]
	v_mfma_i32_16x16x64_i8 v[58:61], v[160:163], v[190:193], v[58:61]
	v_mfma_i32_16x16x64_i8 v[54:57], v[152:155], v[198:201], v[54:57]
	v_mfma_i32_16x16x64_i8 v[50:53], v[160:163], v[198:201], v[50:53]
	v_mfma_i32_16x16x64_i8 v[42:45], v[152:155], v[206:209], v[42:45]
	v_mfma_i32_16x16x64_i8 v[34:37], v[160:163], v[206:209], v[34:37]
	v_mfma_i32_16x16x64_i8 v[26:29], v[152:155], v[214:217], v[26:29]
	v_mfma_i32_16x16x64_i8 v[18:21], v[160:163], v[214:217], v[18:21]
	s_setprio 0
	s_setprio 1
	v_mfma_i32_16x16x64_i8 v[46:49], v[164:167], v[180:183], v[46:49]
	v_mfma_i32_16x16x64_i8 v[38:41], v[172:175], v[180:183], v[38:41]
	v_mfma_i32_16x16x64_i8 v[30:33], v[164:167], v[194:197], v[30:33]
	v_mfma_i32_16x16x64_i8 v[22:25], v[172:175], v[194:197], v[22:25]
	v_mfma_i32_16x16x64_i8 v[14:17], v[164:167], v[202:205], v[14:17]
	v_mfma_i32_16x16x64_i8 v[10:13], v[172:175], v[202:205], v[10:13]
	v_mfma_i32_16x16x64_i8 v[6:9], v[164:167], v[210:213], v[6:9]
	v_mfma_i32_16x16x64_i8 v[2:5], v[172:175], v[210:213], v[2:5]
	v_mfma_i32_16x16x64_i8 v[46:49], v[168:171], v[190:193], v[46:49]
	v_mfma_i32_16x16x64_i8 v[38:41], v[176:179], v[190:193], v[38:41]
	v_mfma_i32_16x16x64_i8 v[30:33], v[168:171], v[198:201], v[30:33]
	v_mfma_i32_16x16x64_i8 v[22:25], v[176:179], v[198:201], v[22:25]
	v_mfma_i32_16x16x64_i8 v[14:17], v[168:171], v[206:209], v[14:17]
	v_mfma_i32_16x16x64_i8 v[10:13], v[176:179], v[206:209], v[10:13]
	v_mfma_i32_16x16x64_i8 v[6:9], v[168:171], v[214:217], v[6:9]
	v_mfma_i32_16x16x64_i8 v[2:5], v[176:179], v[214:217], v[2:5]
	s_setprio 0
	s_barrier
	s_add_i32 s67, 0, 0x18000
	v_add_u32_e32 v138, s67, v188
	s_add_i32 s68, 0, 0x1c000
	ds_read_b128 v[148:151], v138
	ds_read_b128 v[152:155], v138 offset:1024
	ds_read_b128 v[156:159], v138 offset:2048
	ds_read_b128 v[160:163], v138 offset:3072
	v_add_u32_e32 v138, s68, v188
	ds_read_b128 v[164:167], v138
	ds_read_b128 v[168:171], v138 offset:1024
	ds_read_b128 v[172:175], v138 offset:2048
	ds_read_b128 v[176:179], v138 offset:3072
	s_add_u32 s28, s28, s6
	s_addc_u32 s29, s29, s7
	s_mov_b32 m0, s46
	v_lshl_add_u64 v[228:229], s[28:29], 0, v[130:131]
	ds_read_b128 v[180:183], v189 offset:32768
	ds_read_b128 v[190:193], v189 offset:33792
	ds_read_b128 v[194:197], v189 offset:34816
	ds_read_b128 v[198:201], v189 offset:35840
	ds_read_b128 v[202:205], v189 offset:36864
	ds_read_b128 v[206:209], v189 offset:37888
	ds_read_b128 v[210:213], v189 offset:38912
	ds_read_b128 v[214:217], v189 offset:39936
	global_load_lds_dwordx4 v[228:229], off
	v_lshl_add_u64 v[228:229], s[28:29], 0, v[134:135]
	s_mov_b32 m0, s47
	s_nop 0
	global_load_lds_dwordx4 v[228:229], off
	s_waitcnt vmcnt(8)
	s_waitcnt lgkmcnt(0)
	s_setprio 1
	s_waitcnt lgkmcnt(0)
	v_mfma_i32_16x16x64_i8 v[126:129], v[148:151], v[180:183], v[126:129]
	v_mfma_i32_16x16x64_i8 v[122:125], v[156:159], v[180:183], v[122:125]
	s_barrier
	v_mfma_i32_16x16x64_i8 v[118:121], v[148:151], v[194:197], v[118:121]
	v_mfma_i32_16x16x64_i8 v[114:117], v[156:159], v[194:197], v[114:117]
	v_mfma_i32_16x16x64_i8 v[106:109], v[148:151], v[202:205], v[106:109]
	v_mfma_i32_16x16x64_i8 v[98:101], v[156:159], v[202:205], v[98:101]
	v_mfma_i32_16x16x64_i8 v[90:93], v[148:151], v[210:213], v[90:93]
	v_mfma_i32_16x16x64_i8 v[82:85], v[156:159], v[210:213], v[82:85]
	v_mfma_i32_16x16x64_i8 v[126:129], v[152:155], v[190:193], v[126:129]
	v_mfma_i32_16x16x64_i8 v[122:125], v[160:163], v[190:193], v[122:125]
	v_mfma_i32_16x16x64_i8 v[118:121], v[152:155], v[198:201], v[118:121]
	v_mfma_i32_16x16x64_i8 v[114:117], v[160:163], v[198:201], v[114:117]
	v_mfma_i32_16x16x64_i8 v[106:109], v[152:155], v[206:209], v[106:109]
	v_mfma_i32_16x16x64_i8 v[98:101], v[160:163], v[206:209], v[98:101]
	v_mfma_i32_16x16x64_i8 v[90:93], v[152:155], v[214:217], v[90:93]
	v_mfma_i32_16x16x64_i8 v[82:85], v[160:163], v[214:217], v[82:85]
	s_setprio 0
	s_setprio 1
	v_mfma_i32_16x16x64_i8 v[110:113], v[164:167], v[180:183], v[110:113]
	v_mfma_i32_16x16x64_i8 v[102:105], v[172:175], v[180:183], v[102:105]
	v_mfma_i32_16x16x64_i8 v[94:97], v[164:167], v[194:197], v[94:97]
	v_mfma_i32_16x16x64_i8 v[86:89], v[172:175], v[194:197], v[86:89]
	v_mfma_i32_16x16x64_i8 v[78:81], v[164:167], v[202:205], v[78:81]
	v_mfma_i32_16x16x64_i8 v[74:77], v[172:175], v[202:205], v[74:77]
	v_mfma_i32_16x16x64_i8 v[70:73], v[164:167], v[210:213], v[70:73]
	v_mfma_i32_16x16x64_i8 v[66:69], v[172:175], v[210:213], v[66:69]
	v_mfma_i32_16x16x64_i8 v[110:113], v[168:171], v[190:193], v[110:113]
	v_mfma_i32_16x16x64_i8 v[102:105], v[176:179], v[190:193], v[102:105]
	v_mfma_i32_16x16x64_i8 v[94:97], v[168:171], v[198:201], v[94:97]
	v_mfma_i32_16x16x64_i8 v[86:89], v[176:179], v[198:201], v[86:89]
	v_mfma_i32_16x16x64_i8 v[78:81], v[168:171], v[206:209], v[78:81]
	v_mfma_i32_16x16x64_i8 v[74:77], v[176:179], v[206:209], v[74:77]
	v_mfma_i32_16x16x64_i8 v[70:73], v[168:171], v[214:217], v[70:73]
	v_mfma_i32_16x16x64_i8 v[66:69], v[176:179], v[214:217], v[66:69]
	s_setprio 0
	s_barrier
	s_add_i32 s28, s67, s43
	v_lshl_add_u64 v[184:185], v[184:185], 0, s[18:19]
	s_mov_b32 m0, s28
	ds_read_b128 v[180:183], v189 offset:49152
	ds_read_b128 v[190:193], v189 offset:50176
	ds_read_b128 v[194:197], v189 offset:51200
	ds_read_b128 v[198:201], v189 offset:52224
	ds_read_b128 v[202:205], v189 offset:53248
	ds_read_b128 v[206:209], v189 offset:54272
	ds_read_b128 v[210:213], v189 offset:55296
	ds_read_b128 v[214:217], v189 offset:56320
	global_load_lds_dwordx4 v[184:185], off
	v_lshl_add_u64 v[184:185], v[218:219], 0, s[18:19]
	s_add_i32 m0, s28, 0x2000
	s_add_i32 s28, s68, s43
	global_load_lds_dwordx4 v[184:185], off
	v_lshl_add_u64 v[184:185], v[220:221], 0, s[18:19]
	s_mov_b32 m0, s28
	s_nop 0
	global_load_lds_dwordx4 v[184:185], off
	v_lshl_add_u64 v[184:185], v[222:223], 0, s[18:19]
	s_add_i32 m0, s28, 0x2000
	s_nop 0
	global_load_lds_dwordx4 v[184:185], off
	v_lshl_add_u64 v[184:185], v[224:225], 0, s[18:19]
	s_mov_b32 m0, s55
	s_nop 0
	global_load_lds_dwordx4 v[184:185], off
	v_lshl_add_u64 v[184:185], v[226:227], 0, s[18:19]
	s_mov_b32 m0, s56
	s_nop 0
	global_load_lds_dwordx4 v[184:185], off
	s_waitcnt vmcnt(8)
	s_waitcnt lgkmcnt(0)
	s_setprio 1
	s_waitcnt lgkmcnt(0)
	v_mfma_i32_16x16x64_i8 v[62:65], v[148:151], v[180:183], v[62:65]
	v_mfma_i32_16x16x64_i8 v[58:61], v[156:159], v[180:183], v[58:61]
	s_barrier
	v_mfma_i32_16x16x64_i8 v[54:57], v[148:151], v[194:197], v[54:57]
	v_mfma_i32_16x16x64_i8 v[50:53], v[156:159], v[194:197], v[50:53]
	v_mfma_i32_16x16x64_i8 v[42:45], v[148:151], v[202:205], v[42:45]
	v_mfma_i32_16x16x64_i8 v[34:37], v[156:159], v[202:205], v[34:37]
	v_mfma_i32_16x16x64_i8 v[26:29], v[148:151], v[210:213], v[26:29]
	v_mfma_i32_16x16x64_i8 v[18:21], v[156:159], v[210:213], v[18:21]
	v_mfma_i32_16x16x64_i8 v[62:65], v[152:155], v[190:193], v[62:65]
	v_mfma_i32_16x16x64_i8 v[58:61], v[160:163], v[190:193], v[58:61]
	v_mfma_i32_16x16x64_i8 v[54:57], v[152:155], v[198:201], v[54:57]
	v_mfma_i32_16x16x64_i8 v[50:53], v[160:163], v[198:201], v[50:53]
	v_mfma_i32_16x16x64_i8 v[42:45], v[152:155], v[206:209], v[42:45]
	v_mfma_i32_16x16x64_i8 v[34:37], v[160:163], v[206:209], v[34:37]
	v_mfma_i32_16x16x64_i8 v[26:29], v[152:155], v[214:217], v[26:29]
	v_mfma_i32_16x16x64_i8 v[18:21], v[160:163], v[214:217], v[18:21]
	s_setprio 0
	s_setprio 1
	v_mfma_i32_16x16x64_i8 v[46:49], v[164:167], v[180:183], v[46:49]
	v_mfma_i32_16x16x64_i8 v[38:41], v[172:175], v[180:183], v[38:41]
	v_mfma_i32_16x16x64_i8 v[30:33], v[164:167], v[194:197], v[30:33]
	v_mfma_i32_16x16x64_i8 v[22:25], v[172:175], v[194:197], v[22:25]
	v_mfma_i32_16x16x64_i8 v[14:17], v[164:167], v[202:205], v[14:17]
	v_mfma_i32_16x16x64_i8 v[10:13], v[172:175], v[202:205], v[10:13]
	v_mfma_i32_16x16x64_i8 v[6:9], v[164:167], v[210:213], v[6:9]
	v_mfma_i32_16x16x64_i8 v[2:5], v[172:175], v[210:213], v[2:5]
	v_mfma_i32_16x16x64_i8 v[46:49], v[168:171], v[190:193], v[46:49]
	v_mfma_i32_16x16x64_i8 v[38:41], v[176:179], v[190:193], v[38:41]
	v_mfma_i32_16x16x64_i8 v[30:33], v[168:171], v[198:201], v[30:33]
	v_mfma_i32_16x16x64_i8 v[22:25], v[176:179], v[198:201], v[22:25]
	v_mfma_i32_16x16x64_i8 v[14:17], v[168:171], v[206:209], v[14:17]
	v_mfma_i32_16x16x64_i8 v[10:13], v[176:179], v[206:209], v[10:13]
	v_mfma_i32_16x16x64_i8 v[6:9], v[168:171], v[214:217], v[6:9]
	v_mfma_i32_16x16x64_i8 v[2:5], v[176:179], v[214:217], v[2:5]
	s_setprio 0
	s_barrier
	s_add_u32 s26, s26, 0x100
	s_addc_u32 s27, s27, 0
	s_add_u32 s34, s34, 0x100
	s_addc_u32 s35, s35, 0
	s_cmp_ge_i32 s66, s57
	s_mov_b32 s28, s66
	s_cbranch_scc0 .LBB0_1939
	v_cvt_f32_i32_e32 v172, v126
	v_cvt_f32_i32_e32 v173, v127
	v_cvt_f32_i32_e32 v170, v128
	v_cvt_f32_i32_e32 v171, v129
	v_cvt_f32_i32_e32 v174, v122
	v_cvt_f32_i32_e32 v175, v123
	v_cvt_f32_i32_e32 v176, v124
	v_cvt_f32_i32_e32 v177, v125
	v_cvt_f32_i32_e32 v180, v110
	v_cvt_f32_i32_e32 v181, v111
	v_cvt_f32_i32_e32 v182, v112
	v_cvt_f32_i32_e32 v183, v113
	v_cvt_f32_i32_e32 v178, v102
	v_cvt_f32_i32_e32 v179, v103
	v_cvt_f32_i32_e32 v184, v104
	v_cvt_f32_i32_e32 v185, v105
	v_cvt_f32_i32_e32 v152, v118
	v_cvt_f32_i32_e32 v153, v119
	v_cvt_f32_i32_e32 v154, v120
	v_cvt_f32_i32_e32 v155, v121
	v_cvt_f32_i32_e32 v156, v114
	v_cvt_f32_i32_e32 v157, v115
	v_cvt_f32_i32_e32 v158, v116
	v_cvt_f32_i32_e32 v159, v117
	v_cvt_f32_i32_e32 v160, v94
	v_cvt_f32_i32_e32 v161, v95
	v_cvt_f32_i32_e32 v162, v96
	v_cvt_f32_i32_e32 v163, v97
	v_cvt_f32_i32_e32 v164, v86
	v_cvt_f32_i32_e32 v165, v87
	v_cvt_f32_i32_e32 v166, v88
	v_cvt_f32_i32_e32 v167, v89
	v_cvt_f32_i32_e32 v118, v106
	v_cvt_f32_i32_e32 v119, v107
	v_cvt_f32_i32_e32 v120, v108
	v_cvt_f32_i32_e32 v121, v109
	v_cvt_f32_i32_e32 v122, v98
	v_cvt_f32_i32_e32 v123, v99
	v_cvt_f32_i32_e32 v124, v100
	v_cvt_f32_i32_e32 v125, v101
	v_cvt_f32_i32_e32 v126, v78
	v_cvt_f32_i32_e32 v127, v79
	v_cvt_f32_i32_e32 v128, v80
	v_cvt_f32_i32_e32 v129, v81
	v_cvt_f32_i32_e32 v148, v74
	v_cvt_f32_i32_e32 v149, v75
	v_cvt_f32_i32_e32 v150, v76
	v_cvt_f32_i32_e32 v151, v77
	v_cvt_f32_i32_e32 v102, v90
	v_cvt_f32_i32_e32 v103, v91
	v_cvt_f32_i32_e32 v104, v92
	v_cvt_f32_i32_e32 v105, v93
	v_cvt_f32_i32_e32 v106, v82
	v_cvt_f32_i32_e32 v107, v83
	v_cvt_f32_i32_e32 v108, v84
	v_cvt_f32_i32_e32 v109, v85
	v_cvt_f32_i32_e32 v110, v70
	v_cvt_f32_i32_e32 v111, v71
	v_cvt_f32_i32_e32 v112, v72
	v_cvt_f32_i32_e32 v113, v73
	v_cvt_f32_i32_e32 v114, v66
	v_cvt_f32_i32_e32 v115, v67
	v_cvt_f32_i32_e32 v116, v68
	v_cvt_f32_i32_e32 v117, v69
	v_cvt_f32_i32_e32 v82, v62
	v_cvt_f32_i32_e32 v83, v63
	v_cvt_f32_i32_e32 v84, v64
	v_cvt_f32_i32_e32 v85, v65
	v_cvt_f32_i32_e32 v86, v58
	v_cvt_f32_i32_e32 v87, v59
	v_cvt_f32_i32_e32 v88, v60
	v_cvt_f32_i32_e32 v89, v61
	v_cvt_f32_i32_e32 v92, v46
	v_cvt_f32_i32_e32 v93, v47
	v_cvt_f32_i32_e32 v94, v48
	v_cvt_f32_i32_e32 v95, v49
	v_cvt_f32_i32_e32 v96, v38
	v_cvt_f32_i32_e32 v97, v39
	v_cvt_f32_i32_e32 v98, v40
	v_cvt_f32_i32_e32 v99, v41
	v_cvt_f32_i32_e32 v66, v54
	v_cvt_f32_i32_e32 v67, v55
	v_cvt_f32_i32_e32 v68, v56
	v_cvt_f32_i32_e32 v69, v57
	v_cvt_f32_i32_e32 v70, v50
	v_cvt_f32_i32_e32 v71, v51
	v_cvt_f32_i32_e32 v72, v52
	v_cvt_f32_i32_e32 v73, v53
	v_cvt_f32_i32_e32 v74, v30
	v_cvt_f32_i32_e32 v75, v31
	v_cvt_f32_i32_e32 v76, v32
	v_cvt_f32_i32_e32 v77, v33
	v_cvt_f32_i32_e32 v78, v22
	v_cvt_f32_i32_e32 v79, v23
	v_cvt_f32_i32_e32 v80, v24
	v_cvt_f32_i32_e32 v81, v25
	v_cvt_f32_i32_e32 v50, v42
	v_cvt_f32_i32_e32 v51, v43
	v_cvt_f32_i32_e32 v52, v44
	v_cvt_f32_i32_e32 v53, v45
	v_cvt_f32_i32_e32 v54, v34
	v_cvt_f32_i32_e32 v55, v35
	v_cvt_f32_i32_e32 v56, v36
	v_cvt_f32_i32_e32 v57, v37
	v_cvt_f32_i32_e32 v58, v14
	v_cvt_f32_i32_e32 v59, v15
	v_cvt_f32_i32_e32 v60, v16
	v_cvt_f32_i32_e32 v61, v17
	v_cvt_f32_i32_e32 v62, v10
	v_cvt_f32_i32_e32 v63, v11
	v_cvt_f32_i32_e32 v64, v12
	v_cvt_f32_i32_e32 v65, v13
	v_cvt_f32_i32_e32 v34, v26
	v_cvt_f32_i32_e32 v35, v27
	v_cvt_f32_i32_e32 v36, v28
	v_cvt_f32_i32_e32 v37, v29
	v_cvt_f32_i32_e32 v38, v18
	v_cvt_f32_i32_e32 v39, v19
	v_cvt_f32_i32_e32 v40, v20
	v_cvt_f32_i32_e32 v41, v21
	v_cvt_f32_i32_e32 v42, v6
	v_cvt_f32_i32_e32 v43, v7
	v_cvt_f32_i32_e32 v44, v8
	v_cvt_f32_i32_e32 v45, v9
	v_cvt_f32_i32_e32 v46, v2
	v_cvt_f32_i32_e32 v47, v3
	v_cvt_f32_i32_e32 v48, v4
	v_cvt_f32_i32_e32 v49, v5

.LBB0_2022:
	ds_read_b128 v[114:117], v209
	ds_read_b128 v[118:121], v209 offset:1024
	ds_read_b128 v[122:125], v209 offset:2048
	ds_read_b128 v[126:129], v209 offset:3072
	ds_read_b128 v[146:149], v210
	ds_read_b128 v[150:153], v210 offset:1024
	ds_read_b128 v[154:157], v210 offset:2048
	ds_read_b128 v[158:161], v210 offset:3072
	s_add_i32 s84, s36, 2
	s_add_u32 s37, s34, 0x4000
	s_addc_u32 s38, s35, 0
	s_cmp_eq_u32 s63, s36
	s_cselect_b32 s39, s5, s38
	s_cselect_b32 s38, s4, s37
	s_cselect_b32 s86, s30, s82
	s_cselect_b32 s87, s31, s83
	s_add_u32 s36, s38, 0x8000
	s_addc_u32 s37, s39, 0
	v_lshl_add_u64 v[218:219], s[34:35], 0, v[170:171]
	s_add_i32 m0, s47, 0xc000
	ds_read_b128 v[178:181], v211
	ds_read_b128 v[182:185], v211 offset:1024
	ds_read_b128 v[186:189], v211 offset:2048
	ds_read_b128 v[190:193], v211 offset:3072
	ds_read_b128 v[194:197], v211 offset:4096
	ds_read_b128 v[198:201], v211 offset:5120
	ds_read_b128 v[202:205], v211 offset:6144
	ds_read_b128 v[214:217], v211 offset:7168
	global_load_lds_dwordx4 v[218:219], off
	v_lshl_add_u64 v[218:219], s[34:35], 0, v[172:173]
	s_add_i32 m0, s47, 0xe000
	s_nop 0
	global_load_lds_dwordx4 v[218:219], off
	s_waitcnt vmcnt(8)
	s_waitcnt lgkmcnt(0)
	s_setprio 1
	s_waitcnt lgkmcnt(0)
	v_mfma_f32_16x16x32_bf16 v[142:145], v[114:117], v[178:181], v[142:145]
	v_mfma_f32_16x16x32_bf16 v[138:141], v[122:125], v[178:181], v[138:141]
	s_barrier
	v_mfma_f32_16x16x32_bf16 v[110:113], v[114:117], v[186:189], v[110:113]
	v_mfma_f32_16x16x32_bf16 v[106:109], v[122:125], v[186:189], v[106:109]
	v_mfma_f32_16x16x32_bf16 v[94:97], v[114:117], v[194:197], v[94:97]
	v_mfma_f32_16x16x32_bf16 v[90:93], v[122:125], v[194:197], v[90:93]
	v_mfma_f32_16x16x32_bf16 v[78:81], v[114:117], v[202:205], v[78:81]
	v_mfma_f32_16x16x32_bf16 v[74:77], v[122:125], v[202:205], v[74:77]
	v_mfma_f32_16x16x32_bf16 v[142:145], v[118:121], v[182:185], v[142:145]
	v_mfma_f32_16x16x32_bf16 v[138:141], v[126:129], v[182:185], v[138:141]
	v_mfma_f32_16x16x32_bf16 v[110:113], v[118:121], v[190:193], v[110:113]
	v_mfma_f32_16x16x32_bf16 v[106:109], v[126:129], v[190:193], v[106:109]
	v_mfma_f32_16x16x32_bf16 v[94:97], v[118:121], v[198:201], v[94:97]
	v_mfma_f32_16x16x32_bf16 v[90:93], v[126:129], v[198:201], v[90:93]
	v_mfma_f32_16x16x32_bf16 v[78:81], v[118:121], v[214:217], v[78:81]
	v_mfma_f32_16x16x32_bf16 v[74:77], v[126:129], v[214:217], v[74:77]
	s_setprio 0
	s_setprio 1
	v_mfma_f32_16x16x32_bf16 v[134:137], v[146:149], v[178:181], v[134:137]
	v_mfma_f32_16x16x32_bf16 v[130:133], v[154:157], v[178:181], v[130:133]
	v_mfma_f32_16x16x32_bf16 v[102:105], v[146:149], v[186:189], v[102:105]
	v_mfma_f32_16x16x32_bf16 v[98:101], v[154:157], v[186:189], v[98:101]
	v_mfma_f32_16x16x32_bf16 v[86:89], v[146:149], v[194:197], v[86:89]
	v_mfma_f32_16x16x32_bf16 v[82:85], v[154:157], v[194:197], v[82:85]
	v_mfma_f32_16x16x32_bf16 v[70:73], v[146:149], v[202:205], v[70:73]
	v_mfma_f32_16x16x32_bf16 v[66:69], v[154:157], v[202:205], v[66:69]
	v_mfma_f32_16x16x32_bf16 v[134:137], v[150:153], v[182:185], v[134:137]
	v_mfma_f32_16x16x32_bf16 v[130:133], v[158:161], v[182:185], v[130:133]
	v_mfma_f32_16x16x32_bf16 v[102:105], v[150:153], v[190:193], v[102:105]
	v_mfma_f32_16x16x32_bf16 v[98:101], v[158:161], v[190:193], v[98:101]
	v_mfma_f32_16x16x32_bf16 v[86:89], v[150:153], v[198:201], v[86:89]
	v_mfma_f32_16x16x32_bf16 v[82:85], v[158:161], v[198:201], v[82:85]
	v_mfma_f32_16x16x32_bf16 v[70:73], v[150:153], v[214:217], v[70:73]
	v_mfma_f32_16x16x32_bf16 v[66:69], v[158:161], v[214:217], v[66:69]
	s_setprio 0
	s_barrier
	s_add_i32 s85, s66, s46
	v_lshl_add_u64 v[218:219], s[86:87], 0, v[164:165]
	s_mov_b32 m0, s85
	ds_read_b128 v[178:181], v211 offset:16384
	ds_read_b128 v[182:185], v211 offset:17408
	ds_read_b128 v[186:189], v211 offset:18432
	ds_read_b128 v[190:193], v211 offset:19456
	ds_read_b128 v[194:197], v211 offset:20480
	ds_read_b128 v[198:201], v211 offset:21504
	ds_read_b128 v[202:205], v211 offset:22528
	ds_read_b128 v[214:217], v211 offset:23552
	global_load_lds_dwordx4 v[218:219], off
	s_add_i32 m0, s85, 0x2000
	v_lshl_add_u64 v[220:221], s[86:87], 0, v[168:169]
	s_add_u32 s86, s86, s8
	s_addc_u32 s87, s87, s9
	s_add_i32 s85, s67, s46
	global_load_lds_dwordx4 v[220:221], off
	v_lshl_add_u64 v[222:223], s[86:87], 0, v[164:165]
	s_mov_b32 m0, s85
	v_lshl_add_u64 v[224:225], s[86:87], 0, v[168:169]
	global_load_lds_dwordx4 v[222:223], off
	s_add_i32 m0, s85, 0x2000
	v_lshl_add_u64 v[226:227], s[38:39], 0, v[162:163]
	global_load_lds_dwordx4 v[224:225], off
	s_mov_b32 m0, s47
	s_nop 0
	global_load_lds_dwordx4 v[226:227], off
	v_lshl_add_u64 v[226:227], s[38:39], 0, v[166:167]
	s_mov_b32 m0, s50
	s_nop 0
	global_load_lds_dwordx4 v[226:227], off
	s_waitcnt vmcnt(8)
	s_waitcnt lgkmcnt(0)
	s_setprio 1
	s_waitcnt lgkmcnt(0)
	v_mfma_f32_16x16x32_bf16 v[62:65], v[114:117], v[178:181], v[62:65]
	v_mfma_f32_16x16x32_bf16 v[58:61], v[122:125], v[178:181], v[58:61]
	s_barrier
	v_mfma_f32_16x16x32_bf16 v[46:49], v[114:117], v[186:189], v[46:49]
	v_mfma_f32_16x16x32_bf16 v[42:45], v[122:125], v[186:189], v[42:45]
	v_mfma_f32_16x16x32_bf16 v[30:33], v[114:117], v[194:197], v[30:33]
	v_mfma_f32_16x16x32_bf16 v[26:29], v[122:125], v[194:197], v[26:29]
	v_mfma_f32_16x16x32_bf16 v[14:17], v[114:117], v[202:205], v[14:17]
	v_mfma_f32_16x16x32_bf16 v[10:13], v[122:125], v[202:205], v[10:13]
	v_mfma_f32_16x16x32_bf16 v[62:65], v[118:121], v[182:185], v[62:65]
	v_mfma_f32_16x16x32_bf16 v[58:61], v[126:129], v[182:185], v[58:61]
	v_mfma_f32_16x16x32_bf16 v[46:49], v[118:121], v[190:193], v[46:49]
	v_mfma_f32_16x16x32_bf16 v[42:45], v[126:129], v[190:193], v[42:45]
	v_mfma_f32_16x16x32_bf16 v[30:33], v[118:121], v[198:201], v[30:33]
	v_mfma_f32_16x16x32_bf16 v[26:29], v[126:129], v[198:201], v[26:29]
	v_mfma_f32_16x16x32_bf16 v[14:17], v[118:121], v[214:217], v[14:17]
	v_mfma_f32_16x16x32_bf16 v[10:13], v[126:129], v[214:217], v[10:13]
	s_setprio 0
	s_setprio 1
	v_mfma_f32_16x16x32_bf16 v[54:57], v[146:149], v[178:181], v[54:57]
	v_mfma_f32_16x16x32_bf16 v[50:53], v[154:157], v[178:181], v[50:53]
	v_mfma_f32_16x16x32_bf16 v[38:41], v[146:149], v[186:189], v[38:41]
	v_mfma_f32_16x16x32_bf16 v[34:37], v[154:157], v[186:189], v[34:37]
	v_mfma_f32_16x16x32_bf16 v[22:25], v[146:149], v[194:197], v[22:25]
	v_mfma_f32_16x16x32_bf16 v[18:21], v[154:157], v[194:197], v[18:21]
	v_mfma_f32_16x16x32_bf16 v[6:9], v[146:149], v[202:205], v[6:9]
	v_mfma_f32_16x16x32_bf16 v[2:5], v[154:157], v[202:205], v[2:5]
	v_mfma_f32_16x16x32_bf16 v[54:57], v[150:153], v[182:185], v[54:57]
	v_mfma_f32_16x16x32_bf16 v[50:53], v[158:161], v[182:185], v[50:53]
	v_mfma_f32_16x16x32_bf16 v[38:41], v[150:153], v[190:193], v[38:41]
	v_mfma_f32_16x16x32_bf16 v[34:37], v[158:161], v[190:193], v[34:37]
	v_mfma_f32_16x16x32_bf16 v[22:25], v[150:153], v[198:201], v[22:25]
	v_mfma_f32_16x16x32_bf16 v[18:21], v[158:161], v[198:201], v[18:21]
	v_mfma_f32_16x16x32_bf16 v[6:9], v[150:153], v[214:217], v[6:9]
	v_mfma_f32_16x16x32_bf16 v[2:5], v[158:161], v[214:217], v[2:5]
	s_setprio 0
	s_barrier
	s_add_i32 s85, 0, 0x18000
	s_add_i32 s86, 0, 0x1c000
	v_add_u32_e32 v126, s85, v207
	v_add_u32_e32 v158, s86, v207
	ds_read_b128 v[114:117], v126
	ds_read_b128 v[118:121], v126 offset:1024
	ds_read_b128 v[122:125], v126 offset:2048
	ds_read_b128 v[126:129], v126 offset:3072
	ds_read_b128 v[146:149], v158
	ds_read_b128 v[150:153], v158 offset:1024
	ds_read_b128 v[154:157], v158 offset:2048
	ds_read_b128 v[158:161], v158 offset:3072
	s_add_u32 s38, s38, 0x4000
	s_addc_u32 s39, s39, 0
	s_mov_b32 m0, s51
	v_lshl_add_u64 v[226:227], s[38:39], 0, v[162:163]
	ds_read_b128 v[178:181], v211 offset:32768
	ds_read_b128 v[182:185], v211 offset:33792
	ds_read_b128 v[186:189], v211 offset:34816
	ds_read_b128 v[190:193], v211 offset:35840
	ds_read_b128 v[194:197], v211 offset:36864
	ds_read_b128 v[198:201], v211 offset:37888
	ds_read_b128 v[202:205], v211 offset:38912
	ds_read_b128 v[214:217], v211 offset:39936
	global_load_lds_dwordx4 v[226:227], off
	v_lshl_add_u64 v[226:227], s[38:39], 0, v[166:167]
	s_mov_b32 m0, s54
	s_nop 0
	global_load_lds_dwordx4 v[226:227], off
	s_waitcnt vmcnt(8)
	s_waitcnt lgkmcnt(0)
	s_setprio 1
	s_waitcnt lgkmcnt(0)
	v_mfma_f32_16x16x32_bf16 v[142:145], v[114:117], v[178:181], v[142:145]
	v_mfma_f32_16x16x32_bf16 v[138:141], v[122:125], v[178:181], v[138:141]
	s_barrier
	v_mfma_f32_16x16x32_bf16 v[110:113], v[114:117], v[186:189], v[110:113]
	v_mfma_f32_16x16x32_bf16 v[106:109], v[122:125], v[186:189], v[106:109]
	v_mfma_f32_16x16x32_bf16 v[94:97], v[114:117], v[194:197], v[94:97]
	v_mfma_f32_16x16x32_bf16 v[90:93], v[122:125], v[194:197], v[90:93]
	v_mfma_f32_16x16x32_bf16 v[78:81], v[114:117], v[202:205], v[78:81]
	v_mfma_f32_16x16x32_bf16 v[74:77], v[122:125], v[202:205], v[74:77]
	v_mfma_f32_16x16x32_bf16 v[142:145], v[118:121], v[182:185], v[142:145]
	v_mfma_f32_16x16x32_bf16 v[138:141], v[126:129], v[182:185], v[138:141]
	v_mfma_f32_16x16x32_bf16 v[110:113], v[118:121], v[190:193], v[110:113]
	v_mfma_f32_16x16x32_bf16 v[106:109], v[126:129], v[190:193], v[106:109]
	v_mfma_f32_16x16x32_bf16 v[94:97], v[118:121], v[198:201], v[94:97]
	v_mfma_f32_16x16x32_bf16 v[90:93], v[126:129], v[198:201], v[90:93]
	v_mfma_f32_16x16x32_bf16 v[78:81], v[118:121], v[214:217], v[78:81]
	v_mfma_f32_16x16x32_bf16 v[74:77], v[126:129], v[214:217], v[74:77]
	s_setprio 0
	s_setprio 1
	v_mfma_f32_16x16x32_bf16 v[134:137], v[146:149], v[178:181], v[134:137]
	v_mfma_f32_16x16x32_bf16 v[130:133], v[154:157], v[178:181], v[130:133]
	v_mfma_f32_16x16x32_bf16 v[102:105], v[146:149], v[186:189], v[102:105]
	v_mfma_f32_16x16x32_bf16 v[98:101], v[154:157], v[186:189], v[98:101]
	v_mfma_f32_16x16x32_bf16 v[86:89], v[146:149], v[194:197], v[86:89]
	v_mfma_f32_16x16x32_bf16 v[82:85], v[154:157], v[194:197], v[82:85]
	v_mfma_f32_16x16x32_bf16 v[70:73], v[146:149], v[202:205], v[70:73]
	v_mfma_f32_16x16x32_bf16 v[66:69], v[154:157], v[202:205], v[66:69]
	v_mfma_f32_16x16x32_bf16 v[134:137], v[150:153], v[182:185], v[134:137]
	v_mfma_f32_16x16x32_bf16 v[130:133], v[158:161], v[182:185], v[130:133]
	v_mfma_f32_16x16x32_bf16 v[102:105], v[150:153], v[190:193], v[102:105]
	v_mfma_f32_16x16x32_bf16 v[98:101], v[158:161], v[190:193], v[98:101]
	v_mfma_f32_16x16x32_bf16 v[86:89], v[150:153], v[198:201], v[86:89]
	v_mfma_f32_16x16x32_bf16 v[82:85], v[158:161], v[198:201], v[82:85]
	v_mfma_f32_16x16x32_bf16 v[70:73], v[150:153], v[214:217], v[70:73]
	v_mfma_f32_16x16x32_bf16 v[66:69], v[158:161], v[214:217], v[66:69]
	s_setprio 0
	s_barrier
	s_add_i32 s38, s85, s46
	v_lshl_add_u64 v[218:219], v[218:219], 0, s[24:25]
	s_mov_b32 m0, s38
	ds_read_b128 v[178:181], v211 offset:49152
	ds_read_b128 v[182:185], v211 offset:50176
	ds_read_b128 v[186:189], v211 offset:51200
	ds_read_b128 v[190:193], v211 offset:52224
	ds_read_b128 v[194:197], v211 offset:53248
	ds_read_b128 v[198:201], v211 offset:54272
	ds_read_b128 v[202:205], v211 offset:55296
	ds_read_b128 v[214:217], v211 offset:56320
	global_load_lds_dwordx4 v[218:219], off
	v_lshl_add_u64 v[218:219], v[220:221], 0, s[24:25]
	s_add_i32 m0, s38, 0x2000
	s_add_i32 s38, s86, s46
	global_load_lds_dwordx4 v[218:219], off
	v_lshl_add_u64 v[218:219], v[222:223], 0, s[24:25]
	s_mov_b32 m0, s38
	s_nop 0
	global_load_lds_dwordx4 v[218:219], off
	v_lshl_add_u64 v[218:219], v[224:225], 0, s[24:25]
	s_add_i32 m0, s38, 0x2000
	s_nop 0
	global_load_lds_dwordx4 v[218:219], off
	v_lshl_add_u64 v[218:219], s[36:37], 0, v[162:163]
	s_mov_b32 m0, s61
	s_nop 0
	global_load_lds_dwordx4 v[218:219], off
	v_lshl_add_u64 v[218:219], s[36:37], 0, v[166:167]
	s_mov_b32 m0, s62
	s_nop 0
	global_load_lds_dwordx4 v[218:219], off
	s_waitcnt vmcnt(8)
	s_waitcnt lgkmcnt(0)
	s_setprio 1
	s_waitcnt lgkmcnt(0)
	v_mfma_f32_16x16x32_bf16 v[62:65], v[114:117], v[178:181], v[62:65]
	v_mfma_f32_16x16x32_bf16 v[58:61], v[122:125], v[178:181], v[58:61]
	s_barrier
	v_mfma_f32_16x16x32_bf16 v[46:49], v[114:117], v[186:189], v[46:49]
	v_mfma_f32_16x16x32_bf16 v[42:45], v[122:125], v[186:189], v[42:45]
	v_mfma_f32_16x16x32_bf16 v[30:33], v[114:117], v[194:197], v[30:33]
	v_mfma_f32_16x16x32_bf16 v[26:29], v[122:125], v[194:197], v[26:29]
	v_mfma_f32_16x16x32_bf16 v[14:17], v[114:117], v[202:205], v[14:17]
	v_mfma_f32_16x16x32_bf16 v[10:13], v[122:125], v[202:205], v[10:13]
	v_mfma_f32_16x16x32_bf16 v[62:65], v[118:121], v[182:185], v[62:65]
	v_mfma_f32_16x16x32_bf16 v[58:61], v[126:129], v[182:185], v[58:61]
	v_mfma_f32_16x16x32_bf16 v[46:49], v[118:121], v[190:193], v[46:49]
	v_mfma_f32_16x16x32_bf16 v[42:45], v[126:129], v[190:193], v[42:45]
	v_mfma_f32_16x16x32_bf16 v[30:33], v[118:121], v[198:201], v[30:33]
	v_mfma_f32_16x16x32_bf16 v[26:29], v[126:129], v[198:201], v[26:29]
	v_mfma_f32_16x16x32_bf16 v[14:17], v[118:121], v[214:217], v[14:17]
	v_mfma_f32_16x16x32_bf16 v[10:13], v[126:129], v[214:217], v[10:13]
	s_setprio 0
	s_setprio 1
	v_mfma_f32_16x16x32_bf16 v[54:57], v[146:149], v[178:181], v[54:57]
	v_mfma_f32_16x16x32_bf16 v[50:53], v[154:157], v[178:181], v[50:53]
	v_mfma_f32_16x16x32_bf16 v[38:41], v[146:149], v[186:189], v[38:41]
	v_mfma_f32_16x16x32_bf16 v[34:37], v[154:157], v[186:189], v[34:37]
	v_mfma_f32_16x16x32_bf16 v[22:25], v[146:149], v[194:197], v[22:25]
	v_mfma_f32_16x16x32_bf16 v[18:21], v[154:157], v[194:197], v[18:21]
	v_mfma_f32_16x16x32_bf16 v[6:9], v[146:149], v[202:205], v[6:9]
	v_mfma_f32_16x16x32_bf16 v[2:5], v[154:157], v[202:205], v[2:5]
	v_mfma_f32_16x16x32_bf16 v[54:57], v[150:153], v[182:185], v[54:57]
	v_mfma_f32_16x16x32_bf16 v[50:53], v[158:161], v[182:185], v[50:53]
	v_mfma_f32_16x16x32_bf16 v[38:41], v[150:153], v[190:193], v[38:41]
	v_mfma_f32_16x16x32_bf16 v[34:37], v[158:161], v[190:193], v[34:37]
	v_mfma_f32_16x16x32_bf16 v[22:25], v[150:153], v[198:201], v[22:25]
	v_mfma_f32_16x16x32_bf16 v[18:21], v[158:161], v[198:201], v[18:21]
	v_mfma_f32_16x16x32_bf16 v[6:9], v[150:153], v[214:217], v[6:9]
	v_mfma_f32_16x16x32_bf16 v[2:5], v[158:161], v[214:217], v[2:5]
	s_setprio 0
	s_barrier
	s_add_u32 s82, s82, 0x100
	s_addc_u32 s83, s83, 0
	s_add_u32 s34, s34, 0x10000
	s_addc_u32 s35, s35, 0
	s_cmp_ge_i32 s84, s60
	s_mov_b32 s36, s84
	s_cbranch_scc0 .LBB0_2022

.LBB0_2116:
	ds_read_b128 v[34:37], v186
	ds_read_b128 v[38:41], v186 offset:1024
	ds_read_b128 v[50:53], v186 offset:2048
	ds_read_b128 v[54:57], v186 offset:3072
	ds_read_b128 v[168:171], v187
	ds_read_b128 v[172:175], v187 offset:1024
	ds_read_b128 v[176:179], v187 offset:2048
	ds_read_b128 v[192:195], v187 offset:3072
	s_add_i32 s47, s4, 2
	s_add_u32 s50, s2, 0x80
	s_addc_u32 s5, s3, 0
	s_cmp_eq_u32 s85, s4
	s_cselect_b32 s4, s42, s50
	s_cselect_b32 s5, s43, s5
	s_cselect_b32 s51, s45, s7
	s_cselect_b32 s50, s44, s6
	v_lshl_add_u64 v[228:229], s[2:3], 0, v[160:161]
	s_add_i32 m0, s65, 0xc000
	ds_read_b128 v[196:199], v188
	ds_read_b128 v[200:203], v188 offset:1024
	ds_read_b128 v[204:207], v188 offset:2048
	ds_read_b128 v[208:211], v188 offset:3072
	ds_read_b128 v[212:215], v188 offset:4096
	ds_read_b128 v[216:219], v188 offset:5120
	ds_read_b128 v[220:223], v188 offset:6144
	ds_read_b128 v[224:227], v188 offset:7168
	global_load_lds_dwordx4 v[228:229], off
	v_lshl_add_u64 v[228:229], s[2:3], 0, v[162:163]
	s_add_i32 m0, s65, 0xe000
	s_nop 0
	global_load_lds_dwordx4 v[228:229], off
	s_waitcnt vmcnt(8)
	s_waitcnt lgkmcnt(0)
	s_setprio 1
	s_waitcnt lgkmcnt(0)
	v_mfma_f32_16x16x32_bf16 v[142:145], v[34:37], v[196:199], v[142:145]
	v_mfma_f32_16x16x32_bf16 v[138:141], v[50:53], v[196:199], v[138:141]
	s_barrier
	v_mfma_f32_16x16x32_bf16 v[126:129], v[34:37], v[204:207], v[126:129]
	v_mfma_f32_16x16x32_bf16 v[122:125], v[50:53], v[204:207], v[122:125]
	v_mfma_f32_16x16x32_bf16 v[110:113], v[34:37], v[212:215], v[110:113]
	v_mfma_f32_16x16x32_bf16 v[106:109], v[50:53], v[212:215], v[106:109]
	v_mfma_f32_16x16x32_bf16 v[94:97], v[34:37], v[220:223], v[94:97]
	v_mfma_f32_16x16x32_bf16 v[90:93], v[50:53], v[220:223], v[90:93]
	v_mfma_f32_16x16x32_bf16 v[142:145], v[38:41], v[200:203], v[142:145]
	v_mfma_f32_16x16x32_bf16 v[138:141], v[54:57], v[200:203], v[138:141]
	v_mfma_f32_16x16x32_bf16 v[126:129], v[38:41], v[208:211], v[126:129]
	v_mfma_f32_16x16x32_bf16 v[122:125], v[54:57], v[208:211], v[122:125]
	v_mfma_f32_16x16x32_bf16 v[110:113], v[38:41], v[216:219], v[110:113]
	v_mfma_f32_16x16x32_bf16 v[106:109], v[54:57], v[216:219], v[106:109]
	v_mfma_f32_16x16x32_bf16 v[94:97], v[38:41], v[224:227], v[94:97]
	v_mfma_f32_16x16x32_bf16 v[90:93], v[54:57], v[224:227], v[90:93]
	s_setprio 0
	s_setprio 1
	v_mfma_f32_16x16x32_bf16 v[134:137], v[168:171], v[196:199], v[134:137]
	v_mfma_f32_16x16x32_bf16 v[130:133], v[176:179], v[196:199], v[130:133]
	v_mfma_f32_16x16x32_bf16 v[118:121], v[168:171], v[204:207], v[118:121]
	v_mfma_f32_16x16x32_bf16 v[114:117], v[176:179], v[204:207], v[114:117]
	v_mfma_f32_16x16x32_bf16 v[102:105], v[168:171], v[212:215], v[102:105]
	v_mfma_f32_16x16x32_bf16 v[98:101], v[176:179], v[212:215], v[98:101]
	v_mfma_f32_16x16x32_bf16 v[86:89], v[168:171], v[220:223], v[86:89]
	v_mfma_f32_16x16x32_bf16 v[82:85], v[176:179], v[220:223], v[82:85]
	v_mfma_f32_16x16x32_bf16 v[134:137], v[172:175], v[200:203], v[134:137]
	v_mfma_f32_16x16x32_bf16 v[130:133], v[192:195], v[200:203], v[130:133]
	v_mfma_f32_16x16x32_bf16 v[118:121], v[172:175], v[208:211], v[118:121]
	v_mfma_f32_16x16x32_bf16 v[114:117], v[192:195], v[208:211], v[114:117]
	v_mfma_f32_16x16x32_bf16 v[102:105], v[172:175], v[216:219], v[102:105]
	v_mfma_f32_16x16x32_bf16 v[98:101], v[192:195], v[216:219], v[98:101]
	v_mfma_f32_16x16x32_bf16 v[86:89], v[172:175], v[224:227], v[86:89]
	v_mfma_f32_16x16x32_bf16 v[82:85], v[192:195], v[224:227], v[82:85]
	s_setprio 0
	s_barrier
	s_add_i32 s55, s88, s62
	v_lshl_add_u64 v[228:229], s[50:51], 0, v[148:149]
	s_mov_b32 m0, s55
	ds_read_b128 v[196:199], v188 offset:16384
	ds_read_b128 v[200:203], v188 offset:17408
	ds_read_b128 v[204:207], v188 offset:18432
	ds_read_b128 v[208:211], v188 offset:19456
	ds_read_b128 v[212:215], v188 offset:20480
	ds_read_b128 v[216:219], v188 offset:21504
	ds_read_b128 v[220:223], v188 offset:22528
	ds_read_b128 v[224:227], v188 offset:23552
	global_load_lds_dwordx4 v[228:229], off
	s_add_i32 m0, s55, 0x2000
	v_lshl_add_u64 v[230:231], s[50:51], 0, v[152:153]
	s_add_u32 s50, s50, s14
	s_addc_u32 s51, s51, s15
	s_add_i32 s55, s89, s62
	global_load_lds_dwordx4 v[230:231], off
	v_lshl_add_u64 v[232:233], s[50:51], 0, v[148:149]
	s_mov_b32 m0, s55
	v_lshl_add_u64 v[234:235], s[50:51], 0, v[152:153]
	global_load_lds_dwordx4 v[232:233], off
	s_add_i32 m0, s55, 0x2000
	v_lshl_add_u64 v[236:237], s[4:5], 0, v[146:147]
	global_load_lds_dwordx4 v[234:235], off
	s_mov_b32 m0, s65
	v_lshl_add_u64 v[238:239], s[4:5], 0, v[150:151]
	global_load_lds_dwordx4 v[236:237], off
	s_mov_b32 m0, s66
	s_nop 0
	global_load_lds_dwordx4 v[238:239], off
	s_waitcnt vmcnt(8)
	s_waitcnt lgkmcnt(0)
	s_setprio 1
	s_waitcnt lgkmcnt(0)
	v_mfma_f32_16x16x32_bf16 v[78:81], v[34:37], v[196:199], v[78:81]
	v_mfma_f32_16x16x32_bf16 v[74:77], v[50:53], v[196:199], v[74:77]
	s_barrier
	v_mfma_f32_16x16x32_bf16 v[62:65], v[34:37], v[204:207], v[62:65]
	v_mfma_f32_16x16x32_bf16 v[58:61], v[50:53], v[204:207], v[58:61]
	v_mfma_f32_16x16x32_bf16 v[30:33], v[34:37], v[212:215], v[30:33]
	v_mfma_f32_16x16x32_bf16 v[26:29], v[50:53], v[212:215], v[26:29]
	v_mfma_f32_16x16x32_bf16 v[14:17], v[34:37], v[220:223], v[14:17]
	v_mfma_f32_16x16x32_bf16 v[10:13], v[50:53], v[220:223], v[10:13]
	v_mfma_f32_16x16x32_bf16 v[78:81], v[38:41], v[200:203], v[78:81]
	v_mfma_f32_16x16x32_bf16 v[74:77], v[54:57], v[200:203], v[74:77]
	v_mfma_f32_16x16x32_bf16 v[62:65], v[38:41], v[208:211], v[62:65]
	v_mfma_f32_16x16x32_bf16 v[58:61], v[54:57], v[208:211], v[58:61]
	v_mfma_f32_16x16x32_bf16 v[30:33], v[38:41], v[216:219], v[30:33]
	v_mfma_f32_16x16x32_bf16 v[26:29], v[54:57], v[216:219], v[26:29]
	v_mfma_f32_16x16x32_bf16 v[14:17], v[38:41], v[224:227], v[14:17]
	v_mfma_f32_16x16x32_bf16 v[10:13], v[54:57], v[224:227], v[10:13]
	s_setprio 0
	s_setprio 1
	v_mfma_f32_16x16x32_bf16 v[46:49], v[168:171], v[204:207], v[46:49]
	v_mfma_f32_16x16x32_bf16 v[42:45], v[176:179], v[204:207], v[42:45]
	v_mfma_f32_16x16x32_bf16 v[22:25], v[168:171], v[212:215], v[22:25]
	v_mfma_f32_16x16x32_bf16 v[18:21], v[176:179], v[212:215], v[18:21]
	v_mfma_f32_16x16x32_bf16 v[6:9], v[168:171], v[220:223], v[6:9]
	v_mfma_f32_16x16x32_bf16 v[2:5], v[176:179], v[220:223], v[2:5]
	v_mfma_f32_16x16x32_bf16 v[34:37], v[168:171], v[196:199], v[70:73]
	v_mfma_f32_16x16x32_bf16 v[38:41], v[176:179], v[196:199], v[66:69]
	v_mfma_f32_16x16x32_bf16 v[46:49], v[172:175], v[208:211], v[46:49]
	v_mfma_f32_16x16x32_bf16 v[42:45], v[192:195], v[208:211], v[42:45]
	v_mfma_f32_16x16x32_bf16 v[22:25], v[172:175], v[216:219], v[22:25]
	v_mfma_f32_16x16x32_bf16 v[18:21], v[192:195], v[216:219], v[18:21]
	v_mfma_f32_16x16x32_bf16 v[6:9], v[172:175], v[224:227], v[6:9]
	v_mfma_f32_16x16x32_bf16 v[2:5], v[192:195], v[224:227], v[2:5]
	v_mfma_f32_16x16x32_bf16 v[34:37], v[172:175], v[200:203], v[34:37]
	v_mfma_f32_16x16x32_bf16 v[38:41], v[192:195], v[200:203], v[38:41]
	s_setprio 0
	s_barrier
	s_add_i32 s50, 0, 0x18000
	s_add_i32 s51, 0, 0x1c000
	v_add_u32_e32 v70, s50, v184
	v_add_u32_e32 v154, s51, v184
	ds_read_b128 v[50:53], v70
	ds_read_b128 v[54:57], v70 offset:1024
	ds_read_b128 v[66:69], v70 offset:2048
	ds_read_b128 v[70:73], v70 offset:3072
	ds_read_b128 v[168:171], v154
	ds_read_b128 v[172:175], v154 offset:1024
	ds_read_b128 v[176:179], v154 offset:2048
	ds_read_b128 v[192:195], v154 offset:3072
	s_add_u32 s4, s4, s14
	s_addc_u32 s5, s5, s15
	s_mov_b32 m0, s67
	v_lshl_add_u64 v[240:241], s[4:5], 0, v[146:147]
	ds_read_b128 v[196:199], v188 offset:32768
	ds_read_b128 v[200:203], v188 offset:33792
	ds_read_b128 v[204:207], v188 offset:34816
	ds_read_b128 v[208:211], v188 offset:35840
	ds_read_b128 v[212:215], v188 offset:36864
	ds_read_b128 v[216:219], v188 offset:37888
	ds_read_b128 v[220:223], v188 offset:38912
	ds_read_b128 v[224:227], v188 offset:39936
	global_load_lds_dwordx4 v[240:241], off
	v_lshl_add_u64 v[240:241], s[4:5], 0, v[150:151]
	s_mov_b32 m0, s68
	s_nop 0
	global_load_lds_dwordx4 v[240:241], off
	s_waitcnt vmcnt(8)
	s_waitcnt lgkmcnt(0)
	s_setprio 1
	s_waitcnt lgkmcnt(0)
	v_mfma_f32_16x16x32_bf16 v[142:145], v[50:53], v[196:199], v[142:145]
	v_mfma_f32_16x16x32_bf16 v[138:141], v[66:69], v[196:199], v[138:141]
	s_barrier
	v_mfma_f32_16x16x32_bf16 v[126:129], v[50:53], v[204:207], v[126:129]
	v_mfma_f32_16x16x32_bf16 v[122:125], v[66:69], v[204:207], v[122:125]
	v_mfma_f32_16x16x32_bf16 v[110:113], v[50:53], v[212:215], v[110:113]
	v_mfma_f32_16x16x32_bf16 v[106:109], v[66:69], v[212:215], v[106:109]
	v_mfma_f32_16x16x32_bf16 v[94:97], v[50:53], v[220:223], v[94:97]
	v_mfma_f32_16x16x32_bf16 v[90:93], v[66:69], v[220:223], v[90:93]
	v_mfma_f32_16x16x32_bf16 v[142:145], v[54:57], v[200:203], v[142:145]
	v_mfma_f32_16x16x32_bf16 v[138:141], v[70:73], v[200:203], v[138:141]
	v_mfma_f32_16x16x32_bf16 v[126:129], v[54:57], v[208:211], v[126:129]
	v_mfma_f32_16x16x32_bf16 v[122:125], v[70:73], v[208:211], v[122:125]
	v_mfma_f32_16x16x32_bf16 v[110:113], v[54:57], v[216:219], v[110:113]
	v_mfma_f32_16x16x32_bf16 v[106:109], v[70:73], v[216:219], v[106:109]
	v_mfma_f32_16x16x32_bf16 v[94:97], v[54:57], v[224:227], v[94:97]
	v_mfma_f32_16x16x32_bf16 v[90:93], v[70:73], v[224:227], v[90:93]
	s_setprio 0
	s_setprio 1
	v_mfma_f32_16x16x32_bf16 v[134:137], v[168:171], v[196:199], v[134:137]
	v_mfma_f32_16x16x32_bf16 v[130:133], v[176:179], v[196:199], v[130:133]
	v_mfma_f32_16x16x32_bf16 v[118:121], v[168:171], v[204:207], v[118:121]
	v_mfma_f32_16x16x32_bf16 v[114:117], v[176:179], v[204:207], v[114:117]
	v_mfma_f32_16x16x32_bf16 v[102:105], v[168:171], v[212:215], v[102:105]
	v_mfma_f32_16x16x32_bf16 v[98:101], v[176:179], v[212:215], v[98:101]
	v_mfma_f32_16x16x32_bf16 v[86:89], v[168:171], v[220:223], v[86:89]
	v_mfma_f32_16x16x32_bf16 v[82:85], v[176:179], v[220:223], v[82:85]
	v_mfma_f32_16x16x32_bf16 v[134:137], v[172:175], v[200:203], v[134:137]
	v_mfma_f32_16x16x32_bf16 v[130:133], v[192:195], v[200:203], v[130:133]
	v_mfma_f32_16x16x32_bf16 v[118:121], v[172:175], v[208:211], v[118:121]
	v_mfma_f32_16x16x32_bf16 v[114:117], v[192:195], v[208:211], v[114:117]
	v_mfma_f32_16x16x32_bf16 v[102:105], v[172:175], v[216:219], v[102:105]
	v_mfma_f32_16x16x32_bf16 v[98:101], v[192:195], v[216:219], v[98:101]
	v_mfma_f32_16x16x32_bf16 v[86:89], v[172:175], v[224:227], v[86:89]
	v_mfma_f32_16x16x32_bf16 v[82:85], v[192:195], v[224:227], v[82:85]
	s_setprio 0
	s_barrier
	s_add_i32 s4, s50, s62
	v_lshl_add_u64 v[228:229], v[228:229], 0, s[28:29]
	s_mov_b32 m0, s4
	ds_read_b128 v[196:199], v188 offset:49152
	ds_read_b128 v[200:203], v188 offset:50176
	ds_read_b128 v[204:207], v188 offset:51200
	ds_read_b128 v[208:211], v188 offset:52224
	ds_read_b128 v[212:215], v188 offset:53248
	ds_read_b128 v[216:219], v188 offset:54272
	ds_read_b128 v[220:223], v188 offset:55296
	ds_read_b128 v[224:227], v188 offset:56320
	global_load_lds_dwordx4 v[228:229], off
	v_lshl_add_u64 v[228:229], v[230:231], 0, s[28:29]
	s_add_i32 m0, s4, 0x2000
	s_add_i32 s4, s51, s62
	global_load_lds_dwordx4 v[228:229], off
	v_lshl_add_u64 v[228:229], v[232:233], 0, s[28:29]
	s_mov_b32 m0, s4
	s_nop 0
	global_load_lds_dwordx4 v[228:229], off
	v_lshl_add_u64 v[228:229], v[234:235], 0, s[28:29]
	s_add_i32 m0, s4, 0x2000
	s_nop 0
	global_load_lds_dwordx4 v[228:229], off
	v_lshl_add_u64 v[228:229], v[236:237], 0, s[28:29]
	s_mov_b32 m0, s82
	s_nop 0
	global_load_lds_dwordx4 v[228:229], off
	v_lshl_add_u64 v[228:229], v[238:239], 0, s[28:29]
	s_mov_b32 m0, s83
	s_nop 0
	global_load_lds_dwordx4 v[228:229], off
	s_waitcnt vmcnt(8)
	s_waitcnt lgkmcnt(0)
	s_setprio 1
	s_waitcnt lgkmcnt(0)
	v_mfma_f32_16x16x32_bf16 v[78:81], v[50:53], v[196:199], v[78:81]
	v_mfma_f32_16x16x32_bf16 v[74:77], v[66:69], v[196:199], v[74:77]
	s_barrier
	v_mfma_f32_16x16x32_bf16 v[62:65], v[50:53], v[204:207], v[62:65]
	v_mfma_f32_16x16x32_bf16 v[58:61], v[66:69], v[204:207], v[58:61]
	v_mfma_f32_16x16x32_bf16 v[30:33], v[50:53], v[212:215], v[30:33]
	v_mfma_f32_16x16x32_bf16 v[26:29], v[66:69], v[212:215], v[26:29]
	v_mfma_f32_16x16x32_bf16 v[14:17], v[50:53], v[220:223], v[14:17]
	v_mfma_f32_16x16x32_bf16 v[10:13], v[66:69], v[220:223], v[10:13]
	v_mfma_f32_16x16x32_bf16 v[78:81], v[54:57], v[200:203], v[78:81]
	v_mfma_f32_16x16x32_bf16 v[74:77], v[70:73], v[200:203], v[74:77]
	v_mfma_f32_16x16x32_bf16 v[62:65], v[54:57], v[208:211], v[62:65]
	v_mfma_f32_16x16x32_bf16 v[58:61], v[70:73], v[208:211], v[58:61]
	v_mfma_f32_16x16x32_bf16 v[30:33], v[54:57], v[216:219], v[30:33]
	v_mfma_f32_16x16x32_bf16 v[26:29], v[70:73], v[216:219], v[26:29]
	v_mfma_f32_16x16x32_bf16 v[14:17], v[54:57], v[224:227], v[14:17]
	v_mfma_f32_16x16x32_bf16 v[10:13], v[70:73], v[224:227], v[10:13]
	s_setprio 0
	s_setprio 1
	v_mfma_f32_16x16x32_bf16 v[34:37], v[168:171], v[196:199], v[34:37]
	v_mfma_f32_16x16x32_bf16 v[70:73], v[172:175], v[200:203], v[34:37]
	v_mfma_f32_16x16x32_bf16 v[34:37], v[176:179], v[196:199], v[38:41]
	v_mfma_f32_16x16x32_bf16 v[66:69], v[192:195], v[200:203], v[34:37]
	v_mfma_f32_16x16x32_bf16 v[34:37], v[168:171], v[204:207], v[46:49]
	v_mfma_f32_16x16x32_bf16 v[46:49], v[172:175], v[208:211], v[34:37]
	v_mfma_f32_16x16x32_bf16 v[34:37], v[176:179], v[204:207], v[42:45]
	v_mfma_f32_16x16x32_bf16 v[22:25], v[168:171], v[212:215], v[22:25]
	v_mfma_f32_16x16x32_bf16 v[18:21], v[176:179], v[212:215], v[18:21]
	v_mfma_f32_16x16x32_bf16 v[6:9], v[168:171], v[220:223], v[6:9]
	v_mfma_f32_16x16x32_bf16 v[2:5], v[176:179], v[220:223], v[2:5]
	v_mfma_f32_16x16x32_bf16 v[42:45], v[192:195], v[208:211], v[34:37]
	v_mfma_f32_16x16x32_bf16 v[22:25], v[172:175], v[216:219], v[22:25]
	v_mfma_f32_16x16x32_bf16 v[18:21], v[192:195], v[216:219], v[18:21]
	v_mfma_f32_16x16x32_bf16 v[6:9], v[172:175], v[224:227], v[6:9]
	v_mfma_f32_16x16x32_bf16 v[2:5], v[192:195], v[224:227], v[2:5]
	s_setprio 0
	s_barrier
	s_add_u32 s2, s2, 0x100
	s_addc_u32 s3, s3, 0
	s_add_u32 s6, s6, 0x100
	s_addc_u32 s7, s7, 0
	s_cmp_ge_i32 s47, s84
	s_mov_b32 s4, s47
	s_cbranch_scc0 .LBB0_2116

.LBB0_2764:
	v_add_u32_e32 v158, s68, v229
	v_add_u32_e32 v174, s69, v229
	ds_read_b128 v[146:149], v158
	ds_read_b128 v[150:153], v158 offset:1024
	ds_read_b128 v[154:157], v158 offset:2048
	ds_read_b128 v[158:161], v158 offset:3072
	ds_read_b128 v[162:165], v174
	ds_read_b128 v[166:169], v174 offset:1024
	ds_read_b128 v[170:173], v174 offset:2048
	ds_read_b128 v[174:177], v174 offset:3072
	s_add_i32 s84, s42, 2
	s_add_u32 s85, s40, 0x80
	s_addc_u32 s43, s41, 0
	s_cmp_eq_u32 s65, s42
	s_cselect_b32 s42, s4, s85
	s_cselect_b32 s43, s5, s43
	s_cselect_b32 s87, s39, s83
	s_cselect_b32 s86, s38, s82
	v_lshl_add_u64 v[210:211], s[40:41], 0, v[138:139]
	s_add_i32 m0, s51, 0xc000
	ds_read_b128 v[178:181], v231
	ds_read_b128 v[182:185], v231 offset:1024
	ds_read_b128 v[186:189], v231 offset:2048
	ds_read_b128 v[190:193], v231 offset:3072
	ds_read_b128 v[194:197], v231 offset:4096
	ds_read_b128 v[198:201], v231 offset:5120
	ds_read_b128 v[202:205], v231 offset:6144
	ds_read_b128 v[206:209], v231 offset:7168
	global_load_lds_dwordx4 v[210:211], off
	v_lshl_add_u64 v[210:211], s[40:41], 0, v[140:141]
	s_add_i32 m0, s51, 0xe000
	s_nop 0
	global_load_lds_dwordx4 v[210:211], off
	s_waitcnt vmcnt(8)
	s_waitcnt lgkmcnt(0)
	s_setprio 1
	s_waitcnt lgkmcnt(0)
	v_mfma_i32_16x16x64_i8 v[126:129], v[146:149], v[178:181], v[126:129]
	v_mfma_i32_16x16x64_i8 v[122:125], v[154:157], v[178:181], v[122:125]
	s_barrier
	v_mfma_i32_16x16x64_i8 v[118:121], v[146:149], v[186:189], v[118:121]
	v_mfma_i32_16x16x64_i8 v[114:117], v[154:157], v[186:189], v[114:117]
	v_mfma_i32_16x16x64_i8 v[106:109], v[146:149], v[194:197], v[106:109]
	v_mfma_i32_16x16x64_i8 v[98:101], v[154:157], v[194:197], v[98:101]
	v_mfma_i32_16x16x64_i8 v[90:93], v[146:149], v[202:205], v[90:93]
	v_mfma_i32_16x16x64_i8 v[82:85], v[154:157], v[202:205], v[82:85]
	v_mfma_i32_16x16x64_i8 v[126:129], v[150:153], v[182:185], v[126:129]
	v_mfma_i32_16x16x64_i8 v[122:125], v[158:161], v[182:185], v[122:125]
	v_mfma_i32_16x16x64_i8 v[118:121], v[150:153], v[190:193], v[118:121]
	v_mfma_i32_16x16x64_i8 v[114:117], v[158:161], v[190:193], v[114:117]
	v_mfma_i32_16x16x64_i8 v[106:109], v[150:153], v[198:201], v[106:109]
	v_mfma_i32_16x16x64_i8 v[98:101], v[158:161], v[198:201], v[98:101]
	v_mfma_i32_16x16x64_i8 v[90:93], v[150:153], v[206:209], v[90:93]
	v_mfma_i32_16x16x64_i8 v[82:85], v[158:161], v[206:209], v[82:85]
	s_setprio 0
	s_setprio 1
	v_mfma_i32_16x16x64_i8 v[110:113], v[162:165], v[178:181], v[110:113]
	v_mfma_i32_16x16x64_i8 v[102:105], v[170:173], v[178:181], v[102:105]
	v_mfma_i32_16x16x64_i8 v[94:97], v[162:165], v[186:189], v[94:97]
	v_mfma_i32_16x16x64_i8 v[86:89], v[170:173], v[186:189], v[86:89]
	v_mfma_i32_16x16x64_i8 v[78:81], v[162:165], v[194:197], v[78:81]
	v_mfma_i32_16x16x64_i8 v[74:77], v[170:173], v[194:197], v[74:77]
	v_mfma_i32_16x16x64_i8 v[70:73], v[162:165], v[202:205], v[70:73]
	v_mfma_i32_16x16x64_i8 v[66:69], v[170:173], v[202:205], v[66:69]
	v_mfma_i32_16x16x64_i8 v[110:113], v[166:169], v[182:185], v[110:113]
	v_mfma_i32_16x16x64_i8 v[102:105], v[174:177], v[182:185], v[102:105]
	v_mfma_i32_16x16x64_i8 v[94:97], v[166:169], v[190:193], v[94:97]
	v_mfma_i32_16x16x64_i8 v[86:89], v[174:177], v[190:193], v[86:89]
	v_mfma_i32_16x16x64_i8 v[78:81], v[166:169], v[198:201], v[78:81]
	v_mfma_i32_16x16x64_i8 v[74:77], v[174:177], v[198:201], v[74:77]
	v_mfma_i32_16x16x64_i8 v[70:73], v[166:169], v[206:209], v[70:73]
	v_mfma_i32_16x16x64_i8 v[66:69], v[174:177], v[206:209], v[66:69]
	s_setprio 0
	s_barrier
	s_add_i32 s85, s68, s50
	v_lshl_add_u64 v[210:211], s[86:87], 0, v[132:133]
	s_mov_b32 m0, s85
	ds_read_b128 v[178:181], v231 offset:16384
	ds_read_b128 v[182:185], v231 offset:17408
	ds_read_b128 v[186:189], v231 offset:18432
	ds_read_b128 v[190:193], v231 offset:19456
	ds_read_b128 v[194:197], v231 offset:20480
	ds_read_b128 v[198:201], v231 offset:21504
	ds_read_b128 v[202:205], v231 offset:22528
	ds_read_b128 v[206:209], v231 offset:23552
	global_load_lds_dwordx4 v[210:211], off
	s_add_i32 m0, s85, 0x2000
	v_lshl_add_u64 v[212:213], s[86:87], 0, v[136:137]
	s_add_u32 s86, s86, s8
	s_addc_u32 s87, s87, s9
	s_add_i32 s85, s69, s50
	global_load_lds_dwordx4 v[212:213], off
	v_lshl_add_u64 v[214:215], s[86:87], 0, v[132:133]
	s_mov_b32 m0, s85
	v_lshl_add_u64 v[216:217], s[86:87], 0, v[136:137]
	global_load_lds_dwordx4 v[214:215], off
	s_add_i32 m0, s85, 0x2000
	v_lshl_add_u64 v[218:219], s[42:43], 0, v[130:131]
	global_load_lds_dwordx4 v[216:217], off
	s_mov_b32 m0, s51
	v_lshl_add_u64 v[220:221], s[42:43], 0, v[134:135]
	global_load_lds_dwordx4 v[218:219], off
	s_mov_b32 m0, s54
	s_nop 0
	global_load_lds_dwordx4 v[220:221], off
	s_waitcnt vmcnt(8)
	s_waitcnt lgkmcnt(0)
	s_setprio 1
	s_waitcnt lgkmcnt(0)
	v_mfma_i32_16x16x64_i8 v[62:65], v[146:149], v[178:181], v[62:65]
	v_mfma_i32_16x16x64_i8 v[58:61], v[154:157], v[178:181], v[58:61]
	s_barrier
	v_mfma_i32_16x16x64_i8 v[54:57], v[146:149], v[186:189], v[54:57]
	v_mfma_i32_16x16x64_i8 v[50:53], v[154:157], v[186:189], v[50:53]
	v_mfma_i32_16x16x64_i8 v[42:45], v[146:149], v[194:197], v[42:45]
	v_mfma_i32_16x16x64_i8 v[34:37], v[154:157], v[194:197], v[34:37]
	v_mfma_i32_16x16x64_i8 v[26:29], v[146:149], v[202:205], v[26:29]
	v_mfma_i32_16x16x64_i8 v[18:21], v[154:157], v[202:205], v[18:21]
	v_mfma_i32_16x16x64_i8 v[62:65], v[150:153], v[182:185], v[62:65]
	v_mfma_i32_16x16x64_i8 v[58:61], v[158:161], v[182:185], v[58:61]
	v_mfma_i32_16x16x64_i8 v[54:57], v[150:153], v[190:193], v[54:57]
	v_mfma_i32_16x16x64_i8 v[50:53], v[158:161], v[190:193], v[50:53]
	v_mfma_i32_16x16x64_i8 v[42:45], v[150:153], v[198:201], v[42:45]
	v_mfma_i32_16x16x64_i8 v[34:37], v[158:161], v[198:201], v[34:37]
	v_mfma_i32_16x16x64_i8 v[26:29], v[150:153], v[206:209], v[26:29]
	v_mfma_i32_16x16x64_i8 v[18:21], v[158:161], v[206:209], v[18:21]
	s_setprio 0
	s_setprio 1
	v_mfma_i32_16x16x64_i8 v[46:49], v[162:165], v[178:181], v[46:49]
	v_mfma_i32_16x16x64_i8 v[38:41], v[170:173], v[178:181], v[38:41]
	v_mfma_i32_16x16x64_i8 v[30:33], v[162:165], v[186:189], v[30:33]
	v_mfma_i32_16x16x64_i8 v[22:25], v[170:173], v[186:189], v[22:25]
	v_mfma_i32_16x16x64_i8 v[14:17], v[162:165], v[194:197], v[14:17]
	v_mfma_i32_16x16x64_i8 v[10:13], v[170:173], v[194:197], v[10:13]
	v_mfma_i32_16x16x64_i8 v[6:9], v[162:165], v[202:205], v[6:9]
	v_mfma_i32_16x16x64_i8 v[2:5], v[170:173], v[202:205], v[2:5]
	v_mfma_i32_16x16x64_i8 v[46:49], v[166:169], v[182:185], v[46:49]
	v_mfma_i32_16x16x64_i8 v[38:41], v[174:177], v[182:185], v[38:41]
	v_mfma_i32_16x16x64_i8 v[30:33], v[166:169], v[190:193], v[30:33]
	v_mfma_i32_16x16x64_i8 v[22:25], v[174:177], v[190:193], v[22:25]
	v_mfma_i32_16x16x64_i8 v[14:17], v[166:169], v[198:201], v[14:17]
	v_mfma_i32_16x16x64_i8 v[10:13], v[174:177], v[198:201], v[10:13]
	v_mfma_i32_16x16x64_i8 v[6:9], v[166:169], v[206:209], v[6:9]
	v_mfma_i32_16x16x64_i8 v[2:5], v[174:177], v[206:209], v[2:5]
	s_setprio 0
	s_barrier
	s_add_i32 s85, 0, 0x18000
	s_add_i32 s86, 0, 0x1c000
	v_add_u32_e32 v158, s85, v229
	v_add_u32_e32 v174, s86, v229
	ds_read_b128 v[146:149], v158
	ds_read_b128 v[150:153], v158 offset:1024
	ds_read_b128 v[154:157], v158 offset:2048
	ds_read_b128 v[158:161], v158 offset:3072
	ds_read_b128 v[162:165], v174
	ds_read_b128 v[166:169], v174 offset:1024
	ds_read_b128 v[170:173], v174 offset:2048
	ds_read_b128 v[174:177], v174 offset:3072
	s_add_u32 s42, s42, s8
	s_addc_u32 s43, s43, s9
	s_mov_b32 m0, s55
	v_lshl_add_u64 v[222:223], s[42:43], 0, v[130:131]
	ds_read_b128 v[178:181], v231 offset:32768
	ds_read_b128 v[182:185], v231 offset:33792
	ds_read_b128 v[186:189], v231 offset:34816
	ds_read_b128 v[190:193], v231 offset:35840
	ds_read_b128 v[194:197], v231 offset:36864
	ds_read_b128 v[198:201], v231 offset:37888
	ds_read_b128 v[202:205], v231 offset:38912
	ds_read_b128 v[206:209], v231 offset:39936
	global_load_lds_dwordx4 v[222:223], off
	v_lshl_add_u64 v[222:223], s[42:43], 0, v[134:135]
	s_mov_b32 m0, s56
	s_nop 0
	global_load_lds_dwordx4 v[222:223], off
	s_waitcnt vmcnt(8)
	s_waitcnt lgkmcnt(0)
	s_setprio 1
	s_waitcnt lgkmcnt(0)
	v_mfma_i32_16x16x64_i8 v[126:129], v[146:149], v[178:181], v[126:129]
	v_mfma_i32_16x16x64_i8 v[122:125], v[154:157], v[178:181], v[122:125]
	s_barrier
	v_mfma_i32_16x16x64_i8 v[118:121], v[146:149], v[186:189], v[118:121]
	v_mfma_i32_16x16x64_i8 v[114:117], v[154:157], v[186:189], v[114:117]
	v_mfma_i32_16x16x64_i8 v[106:109], v[146:149], v[194:197], v[106:109]
	v_mfma_i32_16x16x64_i8 v[98:101], v[154:157], v[194:197], v[98:101]
	v_mfma_i32_16x16x64_i8 v[90:93], v[146:149], v[202:205], v[90:93]
	v_mfma_i32_16x16x64_i8 v[82:85], v[154:157], v[202:205], v[82:85]
	v_mfma_i32_16x16x64_i8 v[126:129], v[150:153], v[182:185], v[126:129]
	v_mfma_i32_16x16x64_i8 v[122:125], v[158:161], v[182:185], v[122:125]
	v_mfma_i32_16x16x64_i8 v[118:121], v[150:153], v[190:193], v[118:121]
	v_mfma_i32_16x16x64_i8 v[114:117], v[158:161], v[190:193], v[114:117]
	v_mfma_i32_16x16x64_i8 v[106:109], v[150:153], v[198:201], v[106:109]
	v_mfma_i32_16x16x64_i8 v[98:101], v[158:161], v[198:201], v[98:101]
	v_mfma_i32_16x16x64_i8 v[90:93], v[150:153], v[206:209], v[90:93]
	v_mfma_i32_16x16x64_i8 v[82:85], v[158:161], v[206:209], v[82:85]
	s_setprio 0
	s_setprio 1
	v_mfma_i32_16x16x64_i8 v[110:113], v[162:165], v[178:181], v[110:113]
	v_mfma_i32_16x16x64_i8 v[102:105], v[170:173], v[178:181], v[102:105]
	v_mfma_i32_16x16x64_i8 v[94:97], v[162:165], v[186:189], v[94:97]
	v_mfma_i32_16x16x64_i8 v[86:89], v[170:173], v[186:189], v[86:89]
	v_mfma_i32_16x16x64_i8 v[78:81], v[162:165], v[194:197], v[78:81]
	v_mfma_i32_16x16x64_i8 v[74:77], v[170:173], v[194:197], v[74:77]
	v_mfma_i32_16x16x64_i8 v[70:73], v[162:165], v[202:205], v[70:73]
	v_mfma_i32_16x16x64_i8 v[66:69], v[170:173], v[202:205], v[66:69]
	v_mfma_i32_16x16x64_i8 v[110:113], v[166:169], v[182:185], v[110:113]
	v_mfma_i32_16x16x64_i8 v[102:105], v[174:177], v[182:185], v[102:105]
	v_mfma_i32_16x16x64_i8 v[94:97], v[166:169], v[190:193], v[94:97]
	v_mfma_i32_16x16x64_i8 v[86:89], v[174:177], v[190:193], v[86:89]
	v_mfma_i32_16x16x64_i8 v[78:81], v[166:169], v[198:201], v[78:81]
	v_mfma_i32_16x16x64_i8 v[74:77], v[174:177], v[198:201], v[74:77]
	v_mfma_i32_16x16x64_i8 v[70:73], v[166:169], v[206:209], v[70:73]
	v_mfma_i32_16x16x64_i8 v[66:69], v[174:177], v[206:209], v[66:69]
	s_setprio 0
	s_barrier
	s_add_i32 s42, s85, s50
	v_lshl_add_u64 v[210:211], v[210:211], 0, s[30:31]
	s_mov_b32 m0, s42
	ds_read_b128 v[178:181], v231 offset:49152
	ds_read_b128 v[182:185], v231 offset:50176
	ds_read_b128 v[186:189], v231 offset:51200
	ds_read_b128 v[190:193], v231 offset:52224
	ds_read_b128 v[194:197], v231 offset:53248
	ds_read_b128 v[198:201], v231 offset:54272
	ds_read_b128 v[202:205], v231 offset:55296
	ds_read_b128 v[206:209], v231 offset:56320
	global_load_lds_dwordx4 v[210:211], off
	v_lshl_add_u64 v[210:211], v[212:213], 0, s[30:31]
	s_add_i32 m0, s42, 0x2000
	s_add_i32 s42, s86, s50
	global_load_lds_dwordx4 v[210:211], off
	v_lshl_add_u64 v[210:211], v[214:215], 0, s[30:31]
	s_mov_b32 m0, s42
	s_nop 0
	global_load_lds_dwordx4 v[210:211], off
	v_lshl_add_u64 v[210:211], v[216:217], 0, s[30:31]
	s_add_i32 m0, s42, 0x2000
	s_nop 0
	global_load_lds_dwordx4 v[210:211], off
	v_lshl_add_u64 v[210:211], v[218:219], 0, s[30:31]
	s_mov_b32 m0, s61
	s_nop 0
	global_load_lds_dwordx4 v[210:211], off
	v_lshl_add_u64 v[210:211], v[220:221], 0, s[30:31]
	s_mov_b32 m0, s62
	s_nop 0
	global_load_lds_dwordx4 v[210:211], off
	s_waitcnt vmcnt(8)
	s_waitcnt lgkmcnt(0)
	s_setprio 1
	s_waitcnt lgkmcnt(0)
	v_mfma_i32_16x16x64_i8 v[62:65], v[146:149], v[178:181], v[62:65]
	v_mfma_i32_16x16x64_i8 v[58:61], v[154:157], v[178:181], v[58:61]
	s_barrier
	v_mfma_i32_16x16x64_i8 v[54:57], v[146:149], v[186:189], v[54:57]
	v_mfma_i32_16x16x64_i8 v[50:53], v[154:157], v[186:189], v[50:53]
	v_mfma_i32_16x16x64_i8 v[42:45], v[146:149], v[194:197], v[42:45]
	v_mfma_i32_16x16x64_i8 v[34:37], v[154:157], v[194:197], v[34:37]
	v_mfma_i32_16x16x64_i8 v[26:29], v[146:149], v[202:205], v[26:29]
	v_mfma_i32_16x16x64_i8 v[18:21], v[154:157], v[202:205], v[18:21]
	v_mfma_i32_16x16x64_i8 v[62:65], v[150:153], v[182:185], v[62:65]
	v_mfma_i32_16x16x64_i8 v[58:61], v[158:161], v[182:185], v[58:61]
	v_mfma_i32_16x16x64_i8 v[54:57], v[150:153], v[190:193], v[54:57]
	v_mfma_i32_16x16x64_i8 v[50:53], v[158:161], v[190:193], v[50:53]
	v_mfma_i32_16x16x64_i8 v[42:45], v[150:153], v[198:201], v[42:45]
	v_mfma_i32_16x16x64_i8 v[34:37], v[158:161], v[198:201], v[34:37]
	v_mfma_i32_16x16x64_i8 v[26:29], v[150:153], v[206:209], v[26:29]
	v_mfma_i32_16x16x64_i8 v[18:21], v[158:161], v[206:209], v[18:21]
	s_setprio 0
	s_setprio 1
	v_mfma_i32_16x16x64_i8 v[46:49], v[162:165], v[178:181], v[46:49]
	v_mfma_i32_16x16x64_i8 v[38:41], v[170:173], v[178:181], v[38:41]
	v_mfma_i32_16x16x64_i8 v[30:33], v[162:165], v[186:189], v[30:33]
	v_mfma_i32_16x16x64_i8 v[22:25], v[170:173], v[186:189], v[22:25]
	v_mfma_i32_16x16x64_i8 v[14:17], v[162:165], v[194:197], v[14:17]
	v_mfma_i32_16x16x64_i8 v[10:13], v[170:173], v[194:197], v[10:13]
	v_mfma_i32_16x16x64_i8 v[6:9], v[162:165], v[202:205], v[6:9]
	v_mfma_i32_16x16x64_i8 v[2:5], v[170:173], v[202:205], v[2:5]
	v_mfma_i32_16x16x64_i8 v[46:49], v[166:169], v[182:185], v[46:49]
	v_mfma_i32_16x16x64_i8 v[38:41], v[174:177], v[182:185], v[38:41]
	v_mfma_i32_16x16x64_i8 v[30:33], v[166:169], v[190:193], v[30:33]
	v_mfma_i32_16x16x64_i8 v[22:25], v[174:177], v[190:193], v[22:25]
	v_mfma_i32_16x16x64_i8 v[14:17], v[166:169], v[198:201], v[14:17]
	v_mfma_i32_16x16x64_i8 v[10:13], v[174:177], v[198:201], v[10:13]
	v_mfma_i32_16x16x64_i8 v[6:9], v[166:169], v[206:209], v[6:9]
	v_mfma_i32_16x16x64_i8 v[2:5], v[174:177], v[206:209], v[2:5]
	s_setprio 0
	s_barrier
	s_add_u32 s40, s40, 0x100
	s_addc_u32 s41, s41, 0
	s_add_u32 s82, s82, 0x100
	s_addc_u32 s83, s83, 0
	s_cmp_ge_i32 s84, s64
	s_mov_b32 s42, s84
	s_cbranch_scc0 .LBB0_2764
	v_cvt_f32_i32_e32 v214, v126
	v_cvt_f32_i32_e32 v215, v127
	v_cvt_f32_i32_e32 v212, v128
	v_cvt_f32_i32_e32 v213, v129
	v_cvt_f32_i32_e32 v218, v122
	v_cvt_f32_i32_e32 v219, v123
	v_cvt_f32_i32_e32 v216, v124
	v_cvt_f32_i32_e32 v217, v125
	v_cvt_f32_i32_e32 v222, v110
	v_cvt_f32_i32_e32 v223, v111
	v_cvt_f32_i32_e32 v220, v112
	v_cvt_f32_i32_e32 v221, v113
	v_cvt_f32_i32_e32 v226, v102
	v_cvt_f32_i32_e32 v227, v103
	v_cvt_f32_i32_e32 v224, v104
	v_cvt_f32_i32_e32 v225, v105
	v_cvt_f32_i32_e32 v194, v118
	v_cvt_f32_i32_e32 v195, v119
	v_cvt_f32_i32_e32 v192, v120
	v_cvt_f32_i32_e32 v193, v121
	v_cvt_f32_i32_e32 v200, v114
	v_cvt_f32_i32_e32 v201, v115
	v_cvt_f32_i32_e32 v198, v116
	v_cvt_f32_i32_e32 v199, v117
	v_cvt_f32_i32_e32 v206, v94
	v_cvt_f32_i32_e32 v207, v95
	v_cvt_f32_i32_e32 v202, v96
	v_cvt_f32_i32_e32 v203, v97
	v_cvt_f32_i32_e32 v208, v86
	v_cvt_f32_i32_e32 v209, v87
	v_cvt_f32_i32_e32 v204, v88
	v_cvt_f32_i32_e32 v205, v89
	v_cvt_f32_i32_e32 v178, v106
	v_cvt_f32_i32_e32 v179, v107
	v_cvt_f32_i32_e32 v176, v108
	v_cvt_f32_i32_e32 v177, v109
	v_cvt_f32_i32_e32 v182, v98
	v_cvt_f32_i32_e32 v183, v99
	v_cvt_f32_i32_e32 v180, v100
	v_cvt_f32_i32_e32 v181, v101
	v_cvt_f32_i32_e32 v188, v78
	v_cvt_f32_i32_e32 v189, v79
	v_cvt_f32_i32_e32 v184, v80
	v_cvt_f32_i32_e32 v185, v81
	v_cvt_f32_i32_e32 v190, v74
	v_cvt_f32_i32_e32 v191, v75
	v_cvt_f32_i32_e32 v186, v76
	v_cvt_f32_i32_e32 v187, v77
	v_cvt_f32_i32_e32 v162, v90
	v_cvt_f32_i32_e32 v163, v91
	v_cvt_f32_i32_e32 v160, v92
	v_cvt_f32_i32_e32 v161, v93
	v_cvt_f32_i32_e32 v166, v82
	v_cvt_f32_i32_e32 v167, v83
	v_cvt_f32_i32_e32 v164, v84
	v_cvt_f32_i32_e32 v165, v85
	v_cvt_f32_i32_e32 v172, v70
	v_cvt_f32_i32_e32 v173, v71
	v_cvt_f32_i32_e32 v168, v72
	v_cvt_f32_i32_e32 v169, v73
	v_cvt_f32_i32_e32 v174, v66
	v_cvt_f32_i32_e32 v175, v67
	v_cvt_f32_i32_e32 v170, v68
	v_cvt_f32_i32_e32 v171, v69
	v_cvt_f32_i32_e32 v146, v62
	v_cvt_f32_i32_e32 v147, v63
	v_cvt_f32_i32_e32 v128, v64
	v_cvt_f32_i32_e32 v129, v65
	v_cvt_f32_i32_e32 v150, v58
	v_cvt_f32_i32_e32 v151, v59
	v_cvt_f32_i32_e32 v148, v60
	v_cvt_f32_i32_e32 v149, v61
	v_cvt_f32_i32_e32 v156, v46
	v_cvt_f32_i32_e32 v157, v47
	v_cvt_f32_i32_e32 v152, v48
	v_cvt_f32_i32_e32 v153, v49
	v_cvt_f32_i32_e32 v158, v38
	v_cvt_f32_i32_e32 v159, v39
	v_cvt_f32_i32_e32 v154, v40
	v_cvt_f32_i32_e32 v155, v41
	v_cvt_f32_i32_e32 v114, v54
	v_cvt_f32_i32_e32 v115, v55
	v_cvt_f32_i32_e32 v112, v56
	v_cvt_f32_i32_e32 v113, v57
	v_cvt_f32_i32_e32 v118, v50
	v_cvt_f32_i32_e32 v119, v51
	v_cvt_f32_i32_e32 v116, v52
	v_cvt_f32_i32_e32 v117, v53
	v_cvt_f32_i32_e32 v124, v30
	v_cvt_f32_i32_e32 v125, v31
	v_cvt_f32_i32_e32 v120, v32
	v_cvt_f32_i32_e32 v121, v33
	v_cvt_f32_i32_e32 v126, v22
	v_cvt_f32_i32_e32 v127, v23
	v_cvt_f32_i32_e32 v122, v24
	v_cvt_f32_i32_e32 v123, v25
	v_cvt_f32_i32_e32 v64, v42
	v_cvt_f32_i32_e32 v65, v43
	v_cvt_f32_i32_e32 v62, v44
	v_cvt_f32_i32_e32 v63, v45
	v_cvt_f32_i32_e32 v68, v34
	v_cvt_f32_i32_e32 v69, v35
	v_cvt_f32_i32_e32 v66, v36
	v_cvt_f32_i32_e32 v67, v37
	v_cvt_f32_i32_e32 v74, v14
	v_cvt_f32_i32_e32 v75, v15
	v_cvt_f32_i32_e32 v70, v16
	v_cvt_f32_i32_e32 v71, v17
	v_cvt_f32_i32_e32 v76, v10
	v_cvt_f32_i32_e32 v77, v11
	v_cvt_f32_i32_e32 v72, v12
	v_cvt_f32_i32_e32 v73, v13
	v_cvt_f32_i32_e32 v48, v26
	v_cvt_f32_i32_e32 v49, v27
	v_cvt_f32_i32_e32 v46, v28
	v_cvt_f32_i32_e32 v47, v29
	v_cvt_f32_i32_e32 v52, v18
	v_cvt_f32_i32_e32 v53, v19
	v_cvt_f32_i32_e32 v50, v20
	v_cvt_f32_i32_e32 v51, v21
	v_cvt_f32_i32_e32 v58, v6
	v_cvt_f32_i32_e32 v59, v7
	v_cvt_f32_i32_e32 v54, v8
	v_cvt_f32_i32_e32 v55, v9
	v_cvt_f32_i32_e32 v60, v2
	v_cvt_f32_i32_e32 v61, v3
	v_cvt_f32_i32_e32 v56, v4
	v_cvt_f32_i32_e32 v57, v5

.LBB0_2949:
	v_add_u32_e32 v138, s60, v188
	ds_read_b128 v[148:151], v138
	ds_read_b128 v[152:155], v138 offset:1024
	ds_read_b128 v[156:159], v138 offset:2048
	ds_read_b128 v[160:163], v138 offset:3072
	v_add_u32_e32 v138, s61, v188
	ds_read_b128 v[164:167], v138
	ds_read_b128 v[168:171], v138 offset:1024
	ds_read_b128 v[172:175], v138 offset:2048
	ds_read_b128 v[176:179], v138 offset:3072
	s_add_i32 s64, s28, 2
	s_add_u32 s65, s26, 0x80
	s_addc_u32 s29, s27, 0
	s_cmp_eq_u32 s58, s28
	s_cselect_b32 s28, s2, s65
	s_cselect_b32 s29, s3, s29
	s_cselect_b32 s67, s25, s35
	s_cselect_b32 s66, s24, s34
	v_lshl_add_u64 v[184:185], s[26:27], 0, v[140:141]
	s_add_i32 m0, s42, 0xc000
	ds_read_b128 v[180:183], v189
	ds_read_b128 v[190:193], v189 offset:1024
	ds_read_b128 v[194:197], v189 offset:2048
	ds_read_b128 v[198:201], v189 offset:3072
	ds_read_b128 v[202:205], v189 offset:4096
	ds_read_b128 v[206:209], v189 offset:5120
	ds_read_b128 v[210:213], v189 offset:6144
	ds_read_b128 v[214:217], v189 offset:7168
	global_load_lds_dwordx4 v[184:185], off
	v_lshl_add_u64 v[184:185], s[26:27], 0, v[142:143]
	s_add_i32 m0, s42, 0xe000
	s_nop 0
	global_load_lds_dwordx4 v[184:185], off
	s_waitcnt vmcnt(8)
	s_waitcnt lgkmcnt(0)
	s_setprio 1
	s_waitcnt lgkmcnt(0)
	v_mfma_i32_16x16x64_i8 v[126:129], v[148:151], v[180:183], v[126:129]
	v_mfma_i32_16x16x64_i8 v[122:125], v[156:159], v[180:183], v[122:125]
	s_barrier
	v_mfma_i32_16x16x64_i8 v[118:121], v[148:151], v[194:197], v[118:121]
	v_mfma_i32_16x16x64_i8 v[114:117], v[156:159], v[194:197], v[114:117]
	v_mfma_i32_16x16x64_i8 v[106:109], v[148:151], v[202:205], v[106:109]
	v_mfma_i32_16x16x64_i8 v[98:101], v[156:159], v[202:205], v[98:101]
	v_mfma_i32_16x16x64_i8 v[90:93], v[148:151], v[210:213], v[90:93]
	v_mfma_i32_16x16x64_i8 v[82:85], v[156:159], v[210:213], v[82:85]
	v_mfma_i32_16x16x64_i8 v[126:129], v[152:155], v[190:193], v[126:129]
	v_mfma_i32_16x16x64_i8 v[122:125], v[160:163], v[190:193], v[122:125]
	v_mfma_i32_16x16x64_i8 v[118:121], v[152:155], v[198:201], v[118:121]
	v_mfma_i32_16x16x64_i8 v[114:117], v[160:163], v[198:201], v[114:117]
	v_mfma_i32_16x16x64_i8 v[106:109], v[152:155], v[206:209], v[106:109]
	v_mfma_i32_16x16x64_i8 v[98:101], v[160:163], v[206:209], v[98:101]
	v_mfma_i32_16x16x64_i8 v[90:93], v[152:155], v[214:217], v[90:93]
	v_mfma_i32_16x16x64_i8 v[82:85], v[160:163], v[214:217], v[82:85]
	s_setprio 0
	s_setprio 1
	v_mfma_i32_16x16x64_i8 v[110:113], v[164:167], v[180:183], v[110:113]
	v_mfma_i32_16x16x64_i8 v[102:105], v[172:175], v[180:183], v[102:105]
	v_mfma_i32_16x16x64_i8 v[94:97], v[164:167], v[194:197], v[94:97]
	v_mfma_i32_16x16x64_i8 v[86:89], v[172:175], v[194:197], v[86:89]
	v_mfma_i32_16x16x64_i8 v[78:81], v[164:167], v[202:205], v[78:81]
	v_mfma_i32_16x16x64_i8 v[74:77], v[172:175], v[202:205], v[74:77]
	v_mfma_i32_16x16x64_i8 v[70:73], v[164:167], v[210:213], v[70:73]
	v_mfma_i32_16x16x64_i8 v[66:69], v[172:175], v[210:213], v[66:69]
	v_mfma_i32_16x16x64_i8 v[110:113], v[168:171], v[190:193], v[110:113]
	v_mfma_i32_16x16x64_i8 v[102:105], v[176:179], v[190:193], v[102:105]
	v_mfma_i32_16x16x64_i8 v[94:97], v[168:171], v[198:201], v[94:97]
	v_mfma_i32_16x16x64_i8 v[86:89], v[176:179], v[198:201], v[86:89]
	v_mfma_i32_16x16x64_i8 v[78:81], v[168:171], v[206:209], v[78:81]
	v_mfma_i32_16x16x64_i8 v[74:77], v[176:179], v[206:209], v[74:77]
	v_mfma_i32_16x16x64_i8 v[70:73], v[168:171], v[214:217], v[70:73]
	v_mfma_i32_16x16x64_i8 v[66:69], v[176:179], v[214:217], v[66:69]
	s_setprio 0
	s_barrier
	s_add_i32 s65, s60, s41
	v_lshl_add_u64 v[184:185], s[66:67], 0, v[132:133]
	s_mov_b32 m0, s65
	ds_read_b128 v[180:183], v189 offset:16384
	ds_read_b128 v[190:193], v189 offset:17408
	ds_read_b128 v[194:197], v189 offset:18432
	ds_read_b128 v[198:201], v189 offset:19456
	ds_read_b128 v[202:205], v189 offset:20480
	ds_read_b128 v[206:209], v189 offset:21504
	ds_read_b128 v[210:213], v189 offset:22528
	ds_read_b128 v[214:217], v189 offset:23552
	global_load_lds_dwordx4 v[184:185], off
	s_add_i32 m0, s65, 0x2000
	v_lshl_add_u64 v[218:219], s[66:67], 0, v[136:137]
	s_add_u32 s66, s66, s6
	s_addc_u32 s67, s67, s7
	s_add_i32 s65, s61, s41
	global_load_lds_dwordx4 v[218:219], off
	v_lshl_add_u64 v[220:221], s[66:67], 0, v[132:133]
	s_mov_b32 m0, s65
	v_lshl_add_u64 v[222:223], s[66:67], 0, v[136:137]
	global_load_lds_dwordx4 v[220:221], off
	s_add_i32 m0, s65, 0x2000
	v_lshl_add_u64 v[224:225], s[28:29], 0, v[130:131]
	global_load_lds_dwordx4 v[222:223], off
	s_mov_b32 m0, s42
	v_lshl_add_u64 v[226:227], s[28:29], 0, v[134:135]
	global_load_lds_dwordx4 v[224:225], off
	s_mov_b32 m0, s43
	s_nop 0
	global_load_lds_dwordx4 v[226:227], off
	s_waitcnt vmcnt(8)
	s_waitcnt lgkmcnt(0)
	s_setprio 1
	s_waitcnt lgkmcnt(0)
	v_mfma_i32_16x16x64_i8 v[62:65], v[148:151], v[180:183], v[62:65]
	v_mfma_i32_16x16x64_i8 v[58:61], v[156:159], v[180:183], v[58:61]
	s_barrier
	v_mfma_i32_16x16x64_i8 v[54:57], v[148:151], v[194:197], v[54:57]
	v_mfma_i32_16x16x64_i8 v[50:53], v[156:159], v[194:197], v[50:53]
	v_mfma_i32_16x16x64_i8 v[42:45], v[148:151], v[202:205], v[42:45]
	v_mfma_i32_16x16x64_i8 v[34:37], v[156:159], v[202:205], v[34:37]
	v_mfma_i32_16x16x64_i8 v[26:29], v[148:151], v[210:213], v[26:29]
	v_mfma_i32_16x16x64_i8 v[18:21], v[156:159], v[210:213], v[18:21]
	v_mfma_i32_16x16x64_i8 v[62:65], v[152:155], v[190:193], v[62:65]
	v_mfma_i32_16x16x64_i8 v[58:61], v[160:163], v[190:193], v[58:61]
	v_mfma_i32_16x16x64_i8 v[54:57], v[152:155], v[198:201], v[54:57]
	v_mfma_i32_16x16x64_i8 v[50:53], v[160:163], v[198:201], v[50:53]
	v_mfma_i32_16x16x64_i8 v[42:45], v[152:155], v[206:209], v[42:45]
	v_mfma_i32_16x16x64_i8 v[34:37], v[160:163], v[206:209], v[34:37]
	v_mfma_i32_16x16x64_i8 v[26:29], v[152:155], v[214:217], v[26:29]
	v_mfma_i32_16x16x64_i8 v[18:21], v[160:163], v[214:217], v[18:21]
	s_setprio 0
	s_setprio 1
	v_mfma_i32_16x16x64_i8 v[46:49], v[164:167], v[180:183], v[46:49]
	v_mfma_i32_16x16x64_i8 v[38:41], v[172:175], v[180:183], v[38:41]
	v_mfma_i32_16x16x64_i8 v[30:33], v[164:167], v[194:197], v[30:33]
	v_mfma_i32_16x16x64_i8 v[22:25], v[172:175], v[194:197], v[22:25]
	v_mfma_i32_16x16x64_i8 v[14:17], v[164:167], v[202:205], v[14:17]
	v_mfma_i32_16x16x64_i8 v[10:13], v[172:175], v[202:205], v[10:13]
	v_mfma_i32_16x16x64_i8 v[6:9], v[164:167], v[210:213], v[6:9]
	v_mfma_i32_16x16x64_i8 v[2:5], v[172:175], v[210:213], v[2:5]
	v_mfma_i32_16x16x64_i8 v[46:49], v[168:171], v[190:193], v[46:49]
	v_mfma_i32_16x16x64_i8 v[38:41], v[176:179], v[190:193], v[38:41]
	v_mfma_i32_16x16x64_i8 v[30:33], v[168:171], v[198:201], v[30:33]
	v_mfma_i32_16x16x64_i8 v[22:25], v[176:179], v[198:201], v[22:25]
	v_mfma_i32_16x16x64_i8 v[14:17], v[168:171], v[206:209], v[14:17]
	v_mfma_i32_16x16x64_i8 v[10:13], v[176:179], v[206:209], v[10:13]
	v_mfma_i32_16x16x64_i8 v[6:9], v[168:171], v[214:217], v[6:9]
	v_mfma_i32_16x16x64_i8 v[2:5], v[176:179], v[214:217], v[2:5]
	s_setprio 0
	s_barrier
	s_add_i32 s65, 0, 0x18000
	v_add_u32_e32 v138, s65, v188
	s_add_i32 s66, 0, 0x1c000
	ds_read_b128 v[148:151], v138
	ds_read_b128 v[152:155], v138 offset:1024
	ds_read_b128 v[156:159], v138 offset:2048
	ds_read_b128 v[160:163], v138 offset:3072
	v_add_u32_e32 v138, s66, v188
	ds_read_b128 v[164:167], v138
	ds_read_b128 v[168:171], v138 offset:1024
	ds_read_b128 v[172:175], v138 offset:2048
	ds_read_b128 v[176:179], v138 offset:3072
	s_add_u32 s28, s28, s6
	s_addc_u32 s29, s29, s7
	s_mov_b32 m0, s44
	v_lshl_add_u64 v[228:229], s[28:29], 0, v[130:131]
	ds_read_b128 v[180:183], v189 offset:32768
	ds_read_b128 v[190:193], v189 offset:33792
	ds_read_b128 v[194:197], v189 offset:34816
	ds_read_b128 v[198:201], v189 offset:35840
	ds_read_b128 v[202:205], v189 offset:36864
	ds_read_b128 v[206:209], v189 offset:37888
	ds_read_b128 v[210:213], v189 offset:38912
	ds_read_b128 v[214:217], v189 offset:39936
	global_load_lds_dwordx4 v[228:229], off
	v_lshl_add_u64 v[228:229], s[28:29], 0, v[134:135]
	s_mov_b32 m0, s45
	s_nop 0
	global_load_lds_dwordx4 v[228:229], off
	s_waitcnt vmcnt(8)
	s_waitcnt lgkmcnt(0)
	s_setprio 1
	s_waitcnt lgkmcnt(0)
	v_mfma_i32_16x16x64_i8 v[126:129], v[148:151], v[180:183], v[126:129]
	v_mfma_i32_16x16x64_i8 v[122:125], v[156:159], v[180:183], v[122:125]
	s_barrier
	v_mfma_i32_16x16x64_i8 v[118:121], v[148:151], v[194:197], v[118:121]
	v_mfma_i32_16x16x64_i8 v[114:117], v[156:159], v[194:197], v[114:117]
	v_mfma_i32_16x16x64_i8 v[106:109], v[148:151], v[202:205], v[106:109]
	v_mfma_i32_16x16x64_i8 v[98:101], v[156:159], v[202:205], v[98:101]
	v_mfma_i32_16x16x64_i8 v[90:93], v[148:151], v[210:213], v[90:93]
	v_mfma_i32_16x16x64_i8 v[82:85], v[156:159], v[210:213], v[82:85]
	v_mfma_i32_16x16x64_i8 v[126:129], v[152:155], v[190:193], v[126:129]
	v_mfma_i32_16x16x64_i8 v[122:125], v[160:163], v[190:193], v[122:125]
	v_mfma_i32_16x16x64_i8 v[118:121], v[152:155], v[198:201], v[118:121]
	v_mfma_i32_16x16x64_i8 v[114:117], v[160:163], v[198:201], v[114:117]
	v_mfma_i32_16x16x64_i8 v[106:109], v[152:155], v[206:209], v[106:109]
	v_mfma_i32_16x16x64_i8 v[98:101], v[160:163], v[206:209], v[98:101]
	v_mfma_i32_16x16x64_i8 v[90:93], v[152:155], v[214:217], v[90:93]
	v_mfma_i32_16x16x64_i8 v[82:85], v[160:163], v[214:217], v[82:85]
	s_setprio 0
	s_setprio 1
	v_mfma_i32_16x16x64_i8 v[110:113], v[164:167], v[180:183], v[110:113]
	v_mfma_i32_16x16x64_i8 v[102:105], v[172:175], v[180:183], v[102:105]
	v_mfma_i32_16x16x64_i8 v[94:97], v[164:167], v[194:197], v[94:97]
	v_mfma_i32_16x16x64_i8 v[86:89], v[172:175], v[194:197], v[86:89]
	v_mfma_i32_16x16x64_i8 v[78:81], v[164:167], v[202:205], v[78:81]
	v_mfma_i32_16x16x64_i8 v[74:77], v[172:175], v[202:205], v[74:77]
	v_mfma_i32_16x16x64_i8 v[70:73], v[164:167], v[210:213], v[70:73]
	v_mfma_i32_16x16x64_i8 v[66:69], v[172:175], v[210:213], v[66:69]
	v_mfma_i32_16x16x64_i8 v[110:113], v[168:171], v[190:193], v[110:113]
	v_mfma_i32_16x16x64_i8 v[102:105], v[176:179], v[190:193], v[102:105]
	v_mfma_i32_16x16x64_i8 v[94:97], v[168:171], v[198:201], v[94:97]
	v_mfma_i32_16x16x64_i8 v[86:89], v[176:179], v[198:201], v[86:89]
	v_mfma_i32_16x16x64_i8 v[78:81], v[168:171], v[206:209], v[78:81]
	v_mfma_i32_16x16x64_i8 v[74:77], v[176:179], v[206:209], v[74:77]
	v_mfma_i32_16x16x64_i8 v[70:73], v[168:171], v[214:217], v[70:73]
	v_mfma_i32_16x16x64_i8 v[66:69], v[176:179], v[214:217], v[66:69]
	s_setprio 0
	s_barrier
	s_add_i32 s28, s65, s41
	v_lshl_add_u64 v[184:185], v[184:185], 0, s[18:19]
	s_mov_b32 m0, s28
	ds_read_b128 v[180:183], v189 offset:49152
	ds_read_b128 v[190:193], v189 offset:50176
	ds_read_b128 v[194:197], v189 offset:51200
	ds_read_b128 v[198:201], v189 offset:52224
	ds_read_b128 v[202:205], v189 offset:53248
	ds_read_b128 v[206:209], v189 offset:54272
	ds_read_b128 v[210:213], v189 offset:55296
	ds_read_b128 v[214:217], v189 offset:56320
	global_load_lds_dwordx4 v[184:185], off
	v_lshl_add_u64 v[184:185], v[218:219], 0, s[18:19]
	s_add_i32 m0, s28, 0x2000
	s_add_i32 s28, s66, s41
	global_load_lds_dwordx4 v[184:185], off
	v_lshl_add_u64 v[184:185], v[220:221], 0, s[18:19]
	s_mov_b32 m0, s28
	s_nop 0
	global_load_lds_dwordx4 v[184:185], off
	v_lshl_add_u64 v[184:185], v[222:223], 0, s[18:19]
	s_add_i32 m0, s28, 0x2000
	s_nop 0
	global_load_lds_dwordx4 v[184:185], off
	v_lshl_add_u64 v[184:185], v[224:225], 0, s[18:19]
	s_mov_b32 m0, s51
	s_nop 0
	global_load_lds_dwordx4 v[184:185], off
	v_lshl_add_u64 v[184:185], v[226:227], 0, s[18:19]
	s_mov_b32 m0, s54
	s_nop 0
	global_load_lds_dwordx4 v[184:185], off
	s_waitcnt vmcnt(8)
	s_waitcnt lgkmcnt(0)
	s_setprio 1
	s_waitcnt lgkmcnt(0)
	v_mfma_i32_16x16x64_i8 v[62:65], v[148:151], v[180:183], v[62:65]
	v_mfma_i32_16x16x64_i8 v[58:61], v[156:159], v[180:183], v[58:61]
	s_barrier
	v_mfma_i32_16x16x64_i8 v[54:57], v[148:151], v[194:197], v[54:57]
	v_mfma_i32_16x16x64_i8 v[50:53], v[156:159], v[194:197], v[50:53]
	v_mfma_i32_16x16x64_i8 v[42:45], v[148:151], v[202:205], v[42:45]
	v_mfma_i32_16x16x64_i8 v[34:37], v[156:159], v[202:205], v[34:37]
	v_mfma_i32_16x16x64_i8 v[26:29], v[148:151], v[210:213], v[26:29]
	v_mfma_i32_16x16x64_i8 v[18:21], v[156:159], v[210:213], v[18:21]
	v_mfma_i32_16x16x64_i8 v[62:65], v[152:155], v[190:193], v[62:65]
	v_mfma_i32_16x16x64_i8 v[58:61], v[160:163], v[190:193], v[58:61]
	v_mfma_i32_16x16x64_i8 v[54:57], v[152:155], v[198:201], v[54:57]
	v_mfma_i32_16x16x64_i8 v[50:53], v[160:163], v[198:201], v[50:53]
	v_mfma_i32_16x16x64_i8 v[42:45], v[152:155], v[206:209], v[42:45]
	v_mfma_i32_16x16x64_i8 v[34:37], v[160:163], v[206:209], v[34:37]
	v_mfma_i32_16x16x64_i8 v[26:29], v[152:155], v[214:217], v[26:29]
	v_mfma_i32_16x16x64_i8 v[18:21], v[160:163], v[214:217], v[18:21]
	s_setprio 0
	s_setprio 1
	v_mfma_i32_16x16x64_i8 v[46:49], v[164:167], v[180:183], v[46:49]
	v_mfma_i32_16x16x64_i8 v[38:41], v[172:175], v[180:183], v[38:41]
	v_mfma_i32_16x16x64_i8 v[30:33], v[164:167], v[194:197], v[30:33]
	v_mfma_i32_16x16x64_i8 v[22:25], v[172:175], v[194:197], v[22:25]
	v_mfma_i32_16x16x64_i8 v[14:17], v[164:167], v[202:205], v[14:17]
	v_mfma_i32_16x16x64_i8 v[10:13], v[172:175], v[202:205], v[10:13]
	v_mfma_i32_16x16x64_i8 v[6:9], v[164:167], v[210:213], v[6:9]
	v_mfma_i32_16x16x64_i8 v[2:5], v[172:175], v[210:213], v[2:5]
	v_mfma_i32_16x16x64_i8 v[46:49], v[168:171], v[190:193], v[46:49]
	v_mfma_i32_16x16x64_i8 v[38:41], v[176:179], v[190:193], v[38:41]
	v_mfma_i32_16x16x64_i8 v[30:33], v[168:171], v[198:201], v[30:33]
	v_mfma_i32_16x16x64_i8 v[22:25], v[176:179], v[198:201], v[22:25]
	v_mfma_i32_16x16x64_i8 v[14:17], v[168:171], v[206:209], v[14:17]
	v_mfma_i32_16x16x64_i8 v[10:13], v[176:179], v[206:209], v[10:13]
	v_mfma_i32_16x16x64_i8 v[6:9], v[168:171], v[214:217], v[6:9]
	v_mfma_i32_16x16x64_i8 v[2:5], v[176:179], v[214:217], v[2:5]
	s_setprio 0
	s_barrier
	s_add_u32 s26, s26, 0x100
	s_addc_u32 s27, s27, 0
	s_add_u32 s34, s34, 0x100
	s_addc_u32 s35, s35, 0
	s_cmp_ge_i32 s64, s55
	s_mov_b32 s28, s64
	s_cbranch_scc0 .LBB0_2949
	v_cvt_f32_i32_e32 v172, v126
	v_cvt_f32_i32_e32 v173, v127
	v_cvt_f32_i32_e32 v170, v128
	v_cvt_f32_i32_e32 v171, v129
	v_cvt_f32_i32_e32 v174, v122
	v_cvt_f32_i32_e32 v175, v123
	v_cvt_f32_i32_e32 v176, v124
	v_cvt_f32_i32_e32 v177, v125
	v_cvt_f32_i32_e32 v180, v110
	v_cvt_f32_i32_e32 v181, v111
	v_cvt_f32_i32_e32 v182, v112
	v_cvt_f32_i32_e32 v183, v113
	v_cvt_f32_i32_e32 v178, v102
	v_cvt_f32_i32_e32 v179, v103
	v_cvt_f32_i32_e32 v184, v104
	v_cvt_f32_i32_e32 v185, v105
	v_cvt_f32_i32_e32 v152, v118
	v_cvt_f32_i32_e32 v153, v119
	v_cvt_f32_i32_e32 v154, v120
	v_cvt_f32_i32_e32 v155, v121
	v_cvt_f32_i32_e32 v156, v114
	v_cvt_f32_i32_e32 v157, v115
	v_cvt_f32_i32_e32 v158, v116
	v_cvt_f32_i32_e32 v159, v117
	v_cvt_f32_i32_e32 v160, v94
	v_cvt_f32_i32_e32 v161, v95
	v_cvt_f32_i32_e32 v162, v96
	v_cvt_f32_i32_e32 v163, v97
	v_cvt_f32_i32_e32 v164, v86
	v_cvt_f32_i32_e32 v165, v87
	v_cvt_f32_i32_e32 v166, v88
	v_cvt_f32_i32_e32 v167, v89
	v_cvt_f32_i32_e32 v118, v106
	v_cvt_f32_i32_e32 v119, v107
	v_cvt_f32_i32_e32 v120, v108
	v_cvt_f32_i32_e32 v121, v109
	v_cvt_f32_i32_e32 v122, v98
	v_cvt_f32_i32_e32 v123, v99
	v_cvt_f32_i32_e32 v124, v100
	v_cvt_f32_i32_e32 v125, v101
	v_cvt_f32_i32_e32 v126, v78
	v_cvt_f32_i32_e32 v127, v79
	v_cvt_f32_i32_e32 v128, v80
	v_cvt_f32_i32_e32 v129, v81
	v_cvt_f32_i32_e32 v148, v74
	v_cvt_f32_i32_e32 v149, v75
	v_cvt_f32_i32_e32 v150, v76
	v_cvt_f32_i32_e32 v151, v77
	v_cvt_f32_i32_e32 v102, v90
	v_cvt_f32_i32_e32 v103, v91
	v_cvt_f32_i32_e32 v104, v92
	v_cvt_f32_i32_e32 v105, v93
	v_cvt_f32_i32_e32 v106, v82
	v_cvt_f32_i32_e32 v107, v83
	v_cvt_f32_i32_e32 v108, v84
	v_cvt_f32_i32_e32 v109, v85
	v_cvt_f32_i32_e32 v110, v70
	v_cvt_f32_i32_e32 v111, v71
	v_cvt_f32_i32_e32 v112, v72
	v_cvt_f32_i32_e32 v113, v73
	v_cvt_f32_i32_e32 v114, v66
	v_cvt_f32_i32_e32 v115, v67
	v_cvt_f32_i32_e32 v116, v68
	v_cvt_f32_i32_e32 v117, v69
	v_cvt_f32_i32_e32 v82, v62
	v_cvt_f32_i32_e32 v83, v63
	v_cvt_f32_i32_e32 v84, v64
	v_cvt_f32_i32_e32 v85, v65
	v_cvt_f32_i32_e32 v86, v58
	v_cvt_f32_i32_e32 v87, v59
	v_cvt_f32_i32_e32 v88, v60
	v_cvt_f32_i32_e32 v89, v61
	v_cvt_f32_i32_e32 v92, v46
	v_cvt_f32_i32_e32 v93, v47
	v_cvt_f32_i32_e32 v94, v48
	v_cvt_f32_i32_e32 v95, v49
	v_cvt_f32_i32_e32 v96, v38
	v_cvt_f32_i32_e32 v97, v39
	v_cvt_f32_i32_e32 v98, v40
	v_cvt_f32_i32_e32 v99, v41
	v_cvt_f32_i32_e32 v66, v54
	v_cvt_f32_i32_e32 v67, v55
	v_cvt_f32_i32_e32 v68, v56
	v_cvt_f32_i32_e32 v69, v57
	v_cvt_f32_i32_e32 v70, v50
	v_cvt_f32_i32_e32 v71, v51
	v_cvt_f32_i32_e32 v72, v52
	v_cvt_f32_i32_e32 v73, v53
	v_cvt_f32_i32_e32 v74, v30
	v_cvt_f32_i32_e32 v75, v31
	v_cvt_f32_i32_e32 v76, v32
	v_cvt_f32_i32_e32 v77, v33
	v_cvt_f32_i32_e32 v78, v22
	v_cvt_f32_i32_e32 v79, v23
	v_cvt_f32_i32_e32 v80, v24
	v_cvt_f32_i32_e32 v81, v25
	v_cvt_f32_i32_e32 v50, v42
	v_cvt_f32_i32_e32 v51, v43
	v_cvt_f32_i32_e32 v52, v44
	v_cvt_f32_i32_e32 v53, v45
	v_cvt_f32_i32_e32 v54, v34
	v_cvt_f32_i32_e32 v55, v35
	v_cvt_f32_i32_e32 v56, v36
	v_cvt_f32_i32_e32 v57, v37
	v_cvt_f32_i32_e32 v58, v14
	v_cvt_f32_i32_e32 v59, v15
	v_cvt_f32_i32_e32 v60, v16
	v_cvt_f32_i32_e32 v61, v17
	v_cvt_f32_i32_e32 v62, v10
	v_cvt_f32_i32_e32 v63, v11
	v_cvt_f32_i32_e32 v64, v12
	v_cvt_f32_i32_e32 v65, v13
	v_cvt_f32_i32_e32 v34, v26
	v_cvt_f32_i32_e32 v35, v27
	v_cvt_f32_i32_e32 v36, v28
	v_cvt_f32_i32_e32 v37, v29
	v_cvt_f32_i32_e32 v38, v18
	v_cvt_f32_i32_e32 v39, v19
	v_cvt_f32_i32_e32 v40, v20
	v_cvt_f32_i32_e32 v41, v21
	v_cvt_f32_i32_e32 v42, v6
	v_cvt_f32_i32_e32 v43, v7
	v_cvt_f32_i32_e32 v44, v8
	v_cvt_f32_i32_e32 v45, v9
	v_cvt_f32_i32_e32 v46, v2
	v_cvt_f32_i32_e32 v47, v3
	v_cvt_f32_i32_e32 v48, v4
	v_cvt_f32_i32_e32 v49, v5

.LBB0_3032:
	ds_read_b128 v[114:117], v209
	ds_read_b128 v[118:121], v209 offset:1024
	ds_read_b128 v[122:125], v209 offset:2048
	ds_read_b128 v[126:129], v209 offset:3072
	ds_read_b128 v[146:149], v210
	ds_read_b128 v[150:153], v210 offset:1024
	ds_read_b128 v[154:157], v210 offset:2048
	ds_read_b128 v[158:161], v210 offset:3072
	s_add_i32 s80, s36, 2
	s_add_u32 s37, s34, 0x4000
	s_addc_u32 s38, s35, 0
	s_cmp_eq_u32 s61, s36
	s_cselect_b32 s39, s5, s38
	s_cselect_b32 s38, s4, s37
	s_cselect_b32 s82, s30, s70
	s_cselect_b32 s83, s31, s71
	s_add_u32 s36, s38, 0x8000
	s_addc_u32 s37, s39, 0
	v_lshl_add_u64 v[218:219], s[34:35], 0, v[170:171]
	s_add_i32 m0, s45, 0xc000
	ds_read_b128 v[178:181], v211
	ds_read_b128 v[182:185], v211 offset:1024
	ds_read_b128 v[186:189], v211 offset:2048
	ds_read_b128 v[190:193], v211 offset:3072
	ds_read_b128 v[194:197], v211 offset:4096
	ds_read_b128 v[198:201], v211 offset:5120
	ds_read_b128 v[202:205], v211 offset:6144
	ds_read_b128 v[214:217], v211 offset:7168
	global_load_lds_dwordx4 v[218:219], off
	v_lshl_add_u64 v[218:219], s[34:35], 0, v[172:173]
	s_add_i32 m0, s45, 0xe000
	s_nop 0
	global_load_lds_dwordx4 v[218:219], off
	s_waitcnt vmcnt(8)
	s_waitcnt lgkmcnt(0)
	s_setprio 1
	s_waitcnt lgkmcnt(0)
	v_mfma_f32_16x16x32_bf16 v[142:145], v[114:117], v[178:181], v[142:145]
	v_mfma_f32_16x16x32_bf16 v[138:141], v[122:125], v[178:181], v[138:141]
	s_barrier
	v_mfma_f32_16x16x32_bf16 v[110:113], v[114:117], v[186:189], v[110:113]
	v_mfma_f32_16x16x32_bf16 v[106:109], v[122:125], v[186:189], v[106:109]
	v_mfma_f32_16x16x32_bf16 v[94:97], v[114:117], v[194:197], v[94:97]
	v_mfma_f32_16x16x32_bf16 v[90:93], v[122:125], v[194:197], v[90:93]
	v_mfma_f32_16x16x32_bf16 v[78:81], v[114:117], v[202:205], v[78:81]
	v_mfma_f32_16x16x32_bf16 v[74:77], v[122:125], v[202:205], v[74:77]
	v_mfma_f32_16x16x32_bf16 v[142:145], v[118:121], v[182:185], v[142:145]
	v_mfma_f32_16x16x32_bf16 v[138:141], v[126:129], v[182:185], v[138:141]
	v_mfma_f32_16x16x32_bf16 v[110:113], v[118:121], v[190:193], v[110:113]
	v_mfma_f32_16x16x32_bf16 v[106:109], v[126:129], v[190:193], v[106:109]
	v_mfma_f32_16x16x32_bf16 v[94:97], v[118:121], v[198:201], v[94:97]
	v_mfma_f32_16x16x32_bf16 v[90:93], v[126:129], v[198:201], v[90:93]
	v_mfma_f32_16x16x32_bf16 v[78:81], v[118:121], v[214:217], v[78:81]
	v_mfma_f32_16x16x32_bf16 v[74:77], v[126:129], v[214:217], v[74:77]
	s_setprio 0
	s_setprio 1
	v_mfma_f32_16x16x32_bf16 v[134:137], v[146:149], v[178:181], v[134:137]
	v_mfma_f32_16x16x32_bf16 v[130:133], v[154:157], v[178:181], v[130:133]
	v_mfma_f32_16x16x32_bf16 v[102:105], v[146:149], v[186:189], v[102:105]
	v_mfma_f32_16x16x32_bf16 v[98:101], v[154:157], v[186:189], v[98:101]
	v_mfma_f32_16x16x32_bf16 v[86:89], v[146:149], v[194:197], v[86:89]
	v_mfma_f32_16x16x32_bf16 v[82:85], v[154:157], v[194:197], v[82:85]
	v_mfma_f32_16x16x32_bf16 v[70:73], v[146:149], v[202:205], v[70:73]
	v_mfma_f32_16x16x32_bf16 v[66:69], v[154:157], v[202:205], v[66:69]
	v_mfma_f32_16x16x32_bf16 v[134:137], v[150:153], v[182:185], v[134:137]
	v_mfma_f32_16x16x32_bf16 v[130:133], v[158:161], v[182:185], v[130:133]
	v_mfma_f32_16x16x32_bf16 v[102:105], v[150:153], v[190:193], v[102:105]
	v_mfma_f32_16x16x32_bf16 v[98:101], v[158:161], v[190:193], v[98:101]
	v_mfma_f32_16x16x32_bf16 v[86:89], v[150:153], v[198:201], v[86:89]
	v_mfma_f32_16x16x32_bf16 v[82:85], v[158:161], v[198:201], v[82:85]
	v_mfma_f32_16x16x32_bf16 v[70:73], v[150:153], v[214:217], v[70:73]
	v_mfma_f32_16x16x32_bf16 v[66:69], v[158:161], v[214:217], v[66:69]
	s_setprio 0
	s_barrier
	s_add_i32 s81, s64, s44
	v_lshl_add_u64 v[218:219], s[82:83], 0, v[164:165]
	s_mov_b32 m0, s81
	ds_read_b128 v[178:181], v211 offset:16384
	ds_read_b128 v[182:185], v211 offset:17408
	ds_read_b128 v[186:189], v211 offset:18432
	ds_read_b128 v[190:193], v211 offset:19456
	ds_read_b128 v[194:197], v211 offset:20480
	ds_read_b128 v[198:201], v211 offset:21504
	ds_read_b128 v[202:205], v211 offset:22528
	ds_read_b128 v[214:217], v211 offset:23552
	global_load_lds_dwordx4 v[218:219], off
	s_add_i32 m0, s81, 0x2000
	v_lshl_add_u64 v[220:221], s[82:83], 0, v[168:169]
	s_add_u32 s82, s82, s8
	s_addc_u32 s83, s83, s9
	s_add_i32 s81, s65, s44
	global_load_lds_dwordx4 v[220:221], off
	v_lshl_add_u64 v[222:223], s[82:83], 0, v[164:165]
	s_mov_b32 m0, s81
	v_lshl_add_u64 v[224:225], s[82:83], 0, v[168:169]
	global_load_lds_dwordx4 v[222:223], off
	s_add_i32 m0, s81, 0x2000
	v_lshl_add_u64 v[226:227], s[38:39], 0, v[162:163]
	global_load_lds_dwordx4 v[224:225], off
	s_mov_b32 m0, s45
	s_nop 0
	global_load_lds_dwordx4 v[226:227], off
	v_lshl_add_u64 v[226:227], s[38:39], 0, v[166:167]
	s_mov_b32 m0, s46
	s_nop 0
	global_load_lds_dwordx4 v[226:227], off
	s_waitcnt vmcnt(8)
	s_waitcnt lgkmcnt(0)
	s_setprio 1
	s_waitcnt lgkmcnt(0)
	v_mfma_f32_16x16x32_bf16 v[62:65], v[114:117], v[178:181], v[62:65]
	v_mfma_f32_16x16x32_bf16 v[58:61], v[122:125], v[178:181], v[58:61]
	s_barrier
	v_mfma_f32_16x16x32_bf16 v[46:49], v[114:117], v[186:189], v[46:49]
	v_mfma_f32_16x16x32_bf16 v[42:45], v[122:125], v[186:189], v[42:45]
	v_mfma_f32_16x16x32_bf16 v[30:33], v[114:117], v[194:197], v[30:33]
	v_mfma_f32_16x16x32_bf16 v[26:29], v[122:125], v[194:197], v[26:29]
	v_mfma_f32_16x16x32_bf16 v[14:17], v[114:117], v[202:205], v[14:17]
	v_mfma_f32_16x16x32_bf16 v[10:13], v[122:125], v[202:205], v[10:13]
	v_mfma_f32_16x16x32_bf16 v[62:65], v[118:121], v[182:185], v[62:65]
	v_mfma_f32_16x16x32_bf16 v[58:61], v[126:129], v[182:185], v[58:61]
	v_mfma_f32_16x16x32_bf16 v[46:49], v[118:121], v[190:193], v[46:49]
	v_mfma_f32_16x16x32_bf16 v[42:45], v[126:129], v[190:193], v[42:45]
	v_mfma_f32_16x16x32_bf16 v[30:33], v[118:121], v[198:201], v[30:33]
	v_mfma_f32_16x16x32_bf16 v[26:29], v[126:129], v[198:201], v[26:29]
	v_mfma_f32_16x16x32_bf16 v[14:17], v[118:121], v[214:217], v[14:17]
	v_mfma_f32_16x16x32_bf16 v[10:13], v[126:129], v[214:217], v[10:13]
	s_setprio 0
	s_setprio 1
	v_mfma_f32_16x16x32_bf16 v[54:57], v[146:149], v[178:181], v[54:57]
	v_mfma_f32_16x16x32_bf16 v[50:53], v[154:157], v[178:181], v[50:53]
	v_mfma_f32_16x16x32_bf16 v[38:41], v[146:149], v[186:189], v[38:41]
	v_mfma_f32_16x16x32_bf16 v[34:37], v[154:157], v[186:189], v[34:37]
	v_mfma_f32_16x16x32_bf16 v[22:25], v[146:149], v[194:197], v[22:25]
	v_mfma_f32_16x16x32_bf16 v[18:21], v[154:157], v[194:197], v[18:21]
	v_mfma_f32_16x16x32_bf16 v[6:9], v[146:149], v[202:205], v[6:9]
	v_mfma_f32_16x16x32_bf16 v[2:5], v[154:157], v[202:205], v[2:5]
	v_mfma_f32_16x16x32_bf16 v[54:57], v[150:153], v[182:185], v[54:57]
	v_mfma_f32_16x16x32_bf16 v[50:53], v[158:161], v[182:185], v[50:53]
	v_mfma_f32_16x16x32_bf16 v[38:41], v[150:153], v[190:193], v[38:41]
	v_mfma_f32_16x16x32_bf16 v[34:37], v[158:161], v[190:193], v[34:37]
	v_mfma_f32_16x16x32_bf16 v[22:25], v[150:153], v[198:201], v[22:25]
	v_mfma_f32_16x16x32_bf16 v[18:21], v[158:161], v[198:201], v[18:21]
	v_mfma_f32_16x16x32_bf16 v[6:9], v[150:153], v[214:217], v[6:9]
	v_mfma_f32_16x16x32_bf16 v[2:5], v[158:161], v[214:217], v[2:5]
	s_setprio 0
	s_barrier
	s_add_i32 s81, 0, 0x18000
	s_add_i32 s82, 0, 0x1c000
	v_add_u32_e32 v126, s81, v207
	v_add_u32_e32 v158, s82, v207
	ds_read_b128 v[114:117], v126
	ds_read_b128 v[118:121], v126 offset:1024
	ds_read_b128 v[122:125], v126 offset:2048
	ds_read_b128 v[126:129], v126 offset:3072
	ds_read_b128 v[146:149], v158
	ds_read_b128 v[150:153], v158 offset:1024
	ds_read_b128 v[154:157], v158 offset:2048
	ds_read_b128 v[158:161], v158 offset:3072
	s_add_u32 s38, s38, 0x4000
	s_addc_u32 s39, s39, 0
	s_mov_b32 m0, s47
	v_lshl_add_u64 v[226:227], s[38:39], 0, v[162:163]
	ds_read_b128 v[178:181], v211 offset:32768
	ds_read_b128 v[182:185], v211 offset:33792
	ds_read_b128 v[186:189], v211 offset:34816
	ds_read_b128 v[190:193], v211 offset:35840
	ds_read_b128 v[194:197], v211 offset:36864
	ds_read_b128 v[198:201], v211 offset:37888
	ds_read_b128 v[202:205], v211 offset:38912
	ds_read_b128 v[214:217], v211 offset:39936
	global_load_lds_dwordx4 v[226:227], off
	v_lshl_add_u64 v[226:227], s[38:39], 0, v[166:167]
	s_mov_b32 m0, s50
	s_nop 0
	global_load_lds_dwordx4 v[226:227], off
	s_waitcnt vmcnt(8)
	s_waitcnt lgkmcnt(0)
	s_setprio 1
	s_waitcnt lgkmcnt(0)
	v_mfma_f32_16x16x32_bf16 v[142:145], v[114:117], v[178:181], v[142:145]
	v_mfma_f32_16x16x32_bf16 v[138:141], v[122:125], v[178:181], v[138:141]
	s_barrier
	v_mfma_f32_16x16x32_bf16 v[110:113], v[114:117], v[186:189], v[110:113]
	v_mfma_f32_16x16x32_bf16 v[106:109], v[122:125], v[186:189], v[106:109]
	v_mfma_f32_16x16x32_bf16 v[94:97], v[114:117], v[194:197], v[94:97]
	v_mfma_f32_16x16x32_bf16 v[90:93], v[122:125], v[194:197], v[90:93]
	v_mfma_f32_16x16x32_bf16 v[78:81], v[114:117], v[202:205], v[78:81]
	v_mfma_f32_16x16x32_bf16 v[74:77], v[122:125], v[202:205], v[74:77]
	v_mfma_f32_16x16x32_bf16 v[142:145], v[118:121], v[182:185], v[142:145]
	v_mfma_f32_16x16x32_bf16 v[138:141], v[126:129], v[182:185], v[138:141]
	v_mfma_f32_16x16x32_bf16 v[110:113], v[118:121], v[190:193], v[110:113]
	v_mfma_f32_16x16x32_bf16 v[106:109], v[126:129], v[190:193], v[106:109]
	v_mfma_f32_16x16x32_bf16 v[94:97], v[118:121], v[198:201], v[94:97]
	v_mfma_f32_16x16x32_bf16 v[90:93], v[126:129], v[198:201], v[90:93]
	v_mfma_f32_16x16x32_bf16 v[78:81], v[118:121], v[214:217], v[78:81]
	v_mfma_f32_16x16x32_bf16 v[74:77], v[126:129], v[214:217], v[74:77]
	s_setprio 0
	s_setprio 1
	v_mfma_f32_16x16x32_bf16 v[134:137], v[146:149], v[178:181], v[134:137]
	v_mfma_f32_16x16x32_bf16 v[130:133], v[154:157], v[178:181], v[130:133]
	v_mfma_f32_16x16x32_bf16 v[102:105], v[146:149], v[186:189], v[102:105]
	v_mfma_f32_16x16x32_bf16 v[98:101], v[154:157], v[186:189], v[98:101]
	v_mfma_f32_16x16x32_bf16 v[86:89], v[146:149], v[194:197], v[86:89]
	v_mfma_f32_16x16x32_bf16 v[82:85], v[154:157], v[194:197], v[82:85]
	v_mfma_f32_16x16x32_bf16 v[70:73], v[146:149], v[202:205], v[70:73]
	v_mfma_f32_16x16x32_bf16 v[66:69], v[154:157], v[202:205], v[66:69]
	v_mfma_f32_16x16x32_bf16 v[134:137], v[150:153], v[182:185], v[134:137]
	v_mfma_f32_16x16x32_bf16 v[130:133], v[158:161], v[182:185], v[130:133]
	v_mfma_f32_16x16x32_bf16 v[102:105], v[150:153], v[190:193], v[102:105]
	v_mfma_f32_16x16x32_bf16 v[98:101], v[158:161], v[190:193], v[98:101]
	v_mfma_f32_16x16x32_bf16 v[86:89], v[150:153], v[198:201], v[86:89]
	v_mfma_f32_16x16x32_bf16 v[82:85], v[158:161], v[198:201], v[82:85]
	v_mfma_f32_16x16x32_bf16 v[70:73], v[150:153], v[214:217], v[70:73]
	v_mfma_f32_16x16x32_bf16 v[66:69], v[158:161], v[214:217], v[66:69]
	s_setprio 0
	s_barrier
	s_add_i32 s38, s81, s44
	v_lshl_add_u64 v[218:219], v[218:219], 0, s[24:25]
	s_mov_b32 m0, s38
	ds_read_b128 v[178:181], v211 offset:49152
	ds_read_b128 v[182:185], v211 offset:50176
	ds_read_b128 v[186:189], v211 offset:51200
	ds_read_b128 v[190:193], v211 offset:52224
	ds_read_b128 v[194:197], v211 offset:53248
	ds_read_b128 v[198:201], v211 offset:54272
	ds_read_b128 v[202:205], v211 offset:55296
	ds_read_b128 v[214:217], v211 offset:56320
	global_load_lds_dwordx4 v[218:219], off
	v_lshl_add_u64 v[218:219], v[220:221], 0, s[24:25]
	s_add_i32 m0, s38, 0x2000
	s_add_i32 s38, s82, s44
	global_load_lds_dwordx4 v[218:219], off
	v_lshl_add_u64 v[218:219], v[222:223], 0, s[24:25]
	s_mov_b32 m0, s38
	s_nop 0
	global_load_lds_dwordx4 v[218:219], off
	v_lshl_add_u64 v[218:219], v[224:225], 0, s[24:25]
	s_add_i32 m0, s38, 0x2000
	s_nop 0
	global_load_lds_dwordx4 v[218:219], off
	v_lshl_add_u64 v[218:219], s[36:37], 0, v[162:163]
	s_mov_b32 m0, s59
	s_nop 0
	global_load_lds_dwordx4 v[218:219], off
	v_lshl_add_u64 v[218:219], s[36:37], 0, v[166:167]
	s_mov_b32 m0, s60
	s_nop 0
	global_load_lds_dwordx4 v[218:219], off
	s_waitcnt vmcnt(8)
	s_waitcnt lgkmcnt(0)
	s_setprio 1
	s_waitcnt lgkmcnt(0)
	v_mfma_f32_16x16x32_bf16 v[62:65], v[114:117], v[178:181], v[62:65]
	v_mfma_f32_16x16x32_bf16 v[58:61], v[122:125], v[178:181], v[58:61]
	s_barrier
	v_mfma_f32_16x16x32_bf16 v[46:49], v[114:117], v[186:189], v[46:49]
	v_mfma_f32_16x16x32_bf16 v[42:45], v[122:125], v[186:189], v[42:45]
	v_mfma_f32_16x16x32_bf16 v[30:33], v[114:117], v[194:197], v[30:33]
	v_mfma_f32_16x16x32_bf16 v[26:29], v[122:125], v[194:197], v[26:29]
	v_mfma_f32_16x16x32_bf16 v[14:17], v[114:117], v[202:205], v[14:17]
	v_mfma_f32_16x16x32_bf16 v[10:13], v[122:125], v[202:205], v[10:13]
	v_mfma_f32_16x16x32_bf16 v[62:65], v[118:121], v[182:185], v[62:65]
	v_mfma_f32_16x16x32_bf16 v[58:61], v[126:129], v[182:185], v[58:61]
	v_mfma_f32_16x16x32_bf16 v[46:49], v[118:121], v[190:193], v[46:49]
	v_mfma_f32_16x16x32_bf16 v[42:45], v[126:129], v[190:193], v[42:45]
	v_mfma_f32_16x16x32_bf16 v[30:33], v[118:121], v[198:201], v[30:33]
	v_mfma_f32_16x16x32_bf16 v[26:29], v[126:129], v[198:201], v[26:29]
	v_mfma_f32_16x16x32_bf16 v[14:17], v[118:121], v[214:217], v[14:17]
	v_mfma_f32_16x16x32_bf16 v[10:13], v[126:129], v[214:217], v[10:13]
	s_setprio 0
	s_setprio 1
	v_mfma_f32_16x16x32_bf16 v[54:57], v[146:149], v[178:181], v[54:57]
	v_mfma_f32_16x16x32_bf16 v[50:53], v[154:157], v[178:181], v[50:53]
	v_mfma_f32_16x16x32_bf16 v[38:41], v[146:149], v[186:189], v[38:41]
	v_mfma_f32_16x16x32_bf16 v[34:37], v[154:157], v[186:189], v[34:37]
	v_mfma_f32_16x16x32_bf16 v[22:25], v[146:149], v[194:197], v[22:25]
	v_mfma_f32_16x16x32_bf16 v[18:21], v[154:157], v[194:197], v[18:21]
	v_mfma_f32_16x16x32_bf16 v[6:9], v[146:149], v[202:205], v[6:9]
	v_mfma_f32_16x16x32_bf16 v[2:5], v[154:157], v[202:205], v[2:5]
	v_mfma_f32_16x16x32_bf16 v[54:57], v[150:153], v[182:185], v[54:57]
	v_mfma_f32_16x16x32_bf16 v[50:53], v[158:161], v[182:185], v[50:53]
	v_mfma_f32_16x16x32_bf16 v[38:41], v[150:153], v[190:193], v[38:41]
	v_mfma_f32_16x16x32_bf16 v[34:37], v[158:161], v[190:193], v[34:37]
	v_mfma_f32_16x16x32_bf16 v[22:25], v[150:153], v[198:201], v[22:25]
	v_mfma_f32_16x16x32_bf16 v[18:21], v[158:161], v[198:201], v[18:21]
	v_mfma_f32_16x16x32_bf16 v[6:9], v[150:153], v[214:217], v[6:9]
	v_mfma_f32_16x16x32_bf16 v[2:5], v[158:161], v[214:217], v[2:5]
	s_setprio 0
	s_barrier
	s_add_u32 s70, s70, 0x100
	s_addc_u32 s71, s71, 0
	s_add_u32 s34, s34, 0x10000
	s_addc_u32 s35, s35, 0
	s_cmp_ge_i32 s80, s58
	s_mov_b32 s36, s80
	s_cbranch_scc0 .LBB0_3032

.LBB0_3126:
	ds_read_b128 v[34:37], v196
	ds_read_b128 v[38:41], v196 offset:1024
	ds_read_b128 v[50:53], v196 offset:2048
	ds_read_b128 v[54:57], v196 offset:3072
	ds_read_b128 v[146:149], v197
	ds_read_b128 v[150:153], v197 offset:1024
	ds_read_b128 v[184:187], v197 offset:2048
	ds_read_b128 v[188:191], v197 offset:3072
	s_add_i32 s11, s6, 2
	s_add_u32 s12, s4, 0x80
	s_addc_u32 s7, s5, 0
	s_cmp_eq_u32 s84, s6
	s_cselect_b32 s6, s44, s12
	s_cselect_b32 s7, s45, s7
	s_cselect_b32 s13, s47, s9
	s_cselect_b32 s12, s46, s8
	v_lshl_add_u64 v[192:193], s[4:5], 0, v[174:175]
	s_add_i32 m0, s66, 0xc000
	ds_read_b128 v[200:203], v198
	ds_read_b128 v[204:207], v198 offset:1024
	ds_read_b128 v[208:211], v198 offset:2048
	ds_read_b128 v[212:215], v198 offset:3072
	ds_read_b128 v[216:219], v198 offset:4096
	ds_read_b128 v[220:223], v198 offset:5120
	ds_read_b128 v[224:227], v198 offset:6144
	ds_read_b128 v[228:231], v198 offset:7168
	global_load_lds_dwordx4 v[192:193], off
	v_lshl_add_u64 v[192:193], s[4:5], 0, v[176:177]
	s_add_i32 m0, s66, 0xe000
	s_nop 0
	global_load_lds_dwordx4 v[192:193], off
	s_waitcnt vmcnt(8)
	s_waitcnt lgkmcnt(0)
	s_setprio 1
	s_waitcnt lgkmcnt(0)
	v_mfma_f32_16x16x32_bf16 v[142:145], v[34:37], v[200:203], v[142:145]
	v_mfma_f32_16x16x32_bf16 v[138:141], v[50:53], v[200:203], v[138:141]
	s_barrier
	v_mfma_f32_16x16x32_bf16 v[126:129], v[34:37], v[208:211], v[126:129]
	v_mfma_f32_16x16x32_bf16 v[122:125], v[50:53], v[208:211], v[122:125]
	v_mfma_f32_16x16x32_bf16 v[110:113], v[34:37], v[216:219], v[110:113]
	v_mfma_f32_16x16x32_bf16 v[106:109], v[50:53], v[216:219], v[106:109]
	v_mfma_f32_16x16x32_bf16 v[94:97], v[34:37], v[224:227], v[94:97]
	v_mfma_f32_16x16x32_bf16 v[90:93], v[50:53], v[224:227], v[90:93]
	v_mfma_f32_16x16x32_bf16 v[142:145], v[38:41], v[204:207], v[142:145]
	v_mfma_f32_16x16x32_bf16 v[138:141], v[54:57], v[204:207], v[138:141]
	v_mfma_f32_16x16x32_bf16 v[126:129], v[38:41], v[212:215], v[126:129]
	v_mfma_f32_16x16x32_bf16 v[122:125], v[54:57], v[212:215], v[122:125]
	v_mfma_f32_16x16x32_bf16 v[110:113], v[38:41], v[220:223], v[110:113]
	v_mfma_f32_16x16x32_bf16 v[106:109], v[54:57], v[220:223], v[106:109]
	v_mfma_f32_16x16x32_bf16 v[94:97], v[38:41], v[228:231], v[94:97]
	v_mfma_f32_16x16x32_bf16 v[90:93], v[54:57], v[228:231], v[90:93]
	s_setprio 0
	s_setprio 1
	v_mfma_f32_16x16x32_bf16 v[134:137], v[146:149], v[200:203], v[134:137]
	v_mfma_f32_16x16x32_bf16 v[130:133], v[184:187], v[200:203], v[130:133]
	v_mfma_f32_16x16x32_bf16 v[118:121], v[146:149], v[208:211], v[118:121]
	v_mfma_f32_16x16x32_bf16 v[114:117], v[184:187], v[208:211], v[114:117]
	v_mfma_f32_16x16x32_bf16 v[102:105], v[146:149], v[216:219], v[102:105]
	v_mfma_f32_16x16x32_bf16 v[98:101], v[184:187], v[216:219], v[98:101]
	v_mfma_f32_16x16x32_bf16 v[86:89], v[146:149], v[224:227], v[86:89]
	v_mfma_f32_16x16x32_bf16 v[82:85], v[184:187], v[224:227], v[82:85]
	v_mfma_f32_16x16x32_bf16 v[134:137], v[150:153], v[204:207], v[134:137]
	v_mfma_f32_16x16x32_bf16 v[130:133], v[188:191], v[204:207], v[130:133]
	v_mfma_f32_16x16x32_bf16 v[118:121], v[150:153], v[212:215], v[118:121]
	v_mfma_f32_16x16x32_bf16 v[114:117], v[188:191], v[212:215], v[114:117]
	v_mfma_f32_16x16x32_bf16 v[102:105], v[150:153], v[220:223], v[102:105]
	v_mfma_f32_16x16x32_bf16 v[98:101], v[188:191], v[220:223], v[98:101]
	v_mfma_f32_16x16x32_bf16 v[86:89], v[150:153], v[228:231], v[86:89]
	v_mfma_f32_16x16x32_bf16 v[82:85], v[188:191], v[228:231], v[82:85]
	s_setprio 0
	s_barrier
	s_add_i32 s20, s88, s61
	v_lshl_add_u64 v[192:193], s[12:13], 0, v[156:157]
	s_mov_b32 m0, s20
	ds_read_b128 v[200:203], v198 offset:16384
	ds_read_b128 v[204:207], v198 offset:17408
	ds_read_b128 v[208:211], v198 offset:18432
	ds_read_b128 v[212:215], v198 offset:19456
	ds_read_b128 v[216:219], v198 offset:20480
	ds_read_b128 v[220:223], v198 offset:21504
	ds_read_b128 v[224:227], v198 offset:22528
	ds_read_b128 v[228:231], v198 offset:23552
	global_load_lds_dwordx4 v[192:193], off
	s_add_i32 m0, s20, 0x2000
	v_lshl_add_u64 v[232:233], s[12:13], 0, v[160:161]
	s_add_u32 s12, s12, s16
	s_addc_u32 s13, s13, s17
	s_add_i32 s20, s89, s61
	global_load_lds_dwordx4 v[232:233], off
	v_lshl_add_u64 v[234:235], s[12:13], 0, v[156:157]
	s_mov_b32 m0, s20
	v_lshl_add_u64 v[236:237], s[12:13], 0, v[160:161]
	global_load_lds_dwordx4 v[234:235], off
	s_add_i32 m0, s20, 0x2000
	v_lshl_add_u64 v[238:239], s[6:7], 0, v[154:155]
	global_load_lds_dwordx4 v[236:237], off
	s_mov_b32 m0, s66
	v_lshl_add_u64 v[240:241], s[6:7], 0, v[158:159]
	global_load_lds_dwordx4 v[238:239], off
	s_mov_b32 m0, s68
	s_nop 0
	global_load_lds_dwordx4 v[240:241], off
	s_waitcnt vmcnt(8)
	s_waitcnt lgkmcnt(0)
	s_setprio 1
	s_waitcnt lgkmcnt(0)
	v_mfma_f32_16x16x32_bf16 v[78:81], v[34:37], v[200:203], v[78:81]
	v_mfma_f32_16x16x32_bf16 v[74:77], v[50:53], v[200:203], v[74:77]
	s_barrier
	v_mfma_f32_16x16x32_bf16 v[62:65], v[34:37], v[208:211], v[62:65]
	v_mfma_f32_16x16x32_bf16 v[58:61], v[50:53], v[208:211], v[58:61]
	v_mfma_f32_16x16x32_bf16 v[30:33], v[34:37], v[216:219], v[30:33]
	v_mfma_f32_16x16x32_bf16 v[26:29], v[50:53], v[216:219], v[26:29]
	v_mfma_f32_16x16x32_bf16 v[14:17], v[34:37], v[224:227], v[14:17]
	v_mfma_f32_16x16x32_bf16 v[10:13], v[50:53], v[224:227], v[10:13]
	v_mfma_f32_16x16x32_bf16 v[78:81], v[38:41], v[204:207], v[78:81]
	v_mfma_f32_16x16x32_bf16 v[74:77], v[54:57], v[204:207], v[74:77]
	v_mfma_f32_16x16x32_bf16 v[62:65], v[38:41], v[212:215], v[62:65]
	v_mfma_f32_16x16x32_bf16 v[58:61], v[54:57], v[212:215], v[58:61]
	v_mfma_f32_16x16x32_bf16 v[30:33], v[38:41], v[220:223], v[30:33]
	v_mfma_f32_16x16x32_bf16 v[26:29], v[54:57], v[220:223], v[26:29]
	v_mfma_f32_16x16x32_bf16 v[14:17], v[38:41], v[228:231], v[14:17]
	v_mfma_f32_16x16x32_bf16 v[10:13], v[54:57], v[228:231], v[10:13]
	s_setprio 0
	s_setprio 1
	v_mfma_f32_16x16x32_bf16 v[46:49], v[146:149], v[208:211], v[46:49]
	v_mfma_f32_16x16x32_bf16 v[42:45], v[184:187], v[208:211], v[42:45]
	v_mfma_f32_16x16x32_bf16 v[22:25], v[146:149], v[216:219], v[22:25]
	v_mfma_f32_16x16x32_bf16 v[18:21], v[184:187], v[216:219], v[18:21]
	v_mfma_f32_16x16x32_bf16 v[6:9], v[146:149], v[224:227], v[6:9]
	v_mfma_f32_16x16x32_bf16 v[2:5], v[184:187], v[224:227], v[2:5]
	v_mfma_f32_16x16x32_bf16 v[34:37], v[146:149], v[200:203], v[70:73]
	v_mfma_f32_16x16x32_bf16 v[38:41], v[184:187], v[200:203], v[66:69]
	v_mfma_f32_16x16x32_bf16 v[46:49], v[150:153], v[212:215], v[46:49]
	v_mfma_f32_16x16x32_bf16 v[42:45], v[188:191], v[212:215], v[42:45]
	v_mfma_f32_16x16x32_bf16 v[22:25], v[150:153], v[220:223], v[22:25]
	v_mfma_f32_16x16x32_bf16 v[18:21], v[188:191], v[220:223], v[18:21]
	v_mfma_f32_16x16x32_bf16 v[6:9], v[150:153], v[228:231], v[6:9]
	v_mfma_f32_16x16x32_bf16 v[2:5], v[188:191], v[228:231], v[2:5]
	v_mfma_f32_16x16x32_bf16 v[34:37], v[150:153], v[204:207], v[34:37]
	v_mfma_f32_16x16x32_bf16 v[38:41], v[188:191], v[204:207], v[38:41]
	s_setprio 0
	s_barrier
	s_add_i32 s12, 0, 0x18000
	s_add_i32 s13, 0, 0x1c000
	v_add_u32_e32 v70, s12, v194
	v_add_u32_e32 v162, s13, v194
	ds_read_b128 v[50:53], v70
	ds_read_b128 v[54:57], v70 offset:1024
	ds_read_b128 v[66:69], v70 offset:2048
	ds_read_b128 v[70:73], v70 offset:3072
	ds_read_b128 v[146:149], v162
	ds_read_b128 v[150:153], v162 offset:1024
	ds_read_b128 v[184:187], v162 offset:2048
	ds_read_b128 v[188:191], v162 offset:3072
	s_add_u32 s6, s6, s16
	s_addc_u32 s7, s7, s17
	s_mov_b32 m0, s69
	v_lshl_add_u64 v[242:243], s[6:7], 0, v[154:155]
	ds_read_b128 v[200:203], v198 offset:32768
	ds_read_b128 v[204:207], v198 offset:33792
	ds_read_b128 v[208:211], v198 offset:34816
	ds_read_b128 v[212:215], v198 offset:35840
	ds_read_b128 v[216:219], v198 offset:36864
	ds_read_b128 v[220:223], v198 offset:37888
	ds_read_b128 v[224:227], v198 offset:38912
	ds_read_b128 v[228:231], v198 offset:39936
	global_load_lds_dwordx4 v[242:243], off
	v_lshl_add_u64 v[242:243], s[6:7], 0, v[158:159]
	s_mov_b32 m0, s70
	s_nop 0
	global_load_lds_dwordx4 v[242:243], off
	s_waitcnt vmcnt(8)
	s_waitcnt lgkmcnt(0)
	s_setprio 1
	s_waitcnt lgkmcnt(0)
	v_mfma_f32_16x16x32_bf16 v[142:145], v[50:53], v[200:203], v[142:145]
	v_mfma_f32_16x16x32_bf16 v[138:141], v[66:69], v[200:203], v[138:141]
	s_barrier
	v_mfma_f32_16x16x32_bf16 v[126:129], v[50:53], v[208:211], v[126:129]
	v_mfma_f32_16x16x32_bf16 v[122:125], v[66:69], v[208:211], v[122:125]
	v_mfma_f32_16x16x32_bf16 v[110:113], v[50:53], v[216:219], v[110:113]
	v_mfma_f32_16x16x32_bf16 v[106:109], v[66:69], v[216:219], v[106:109]
	v_mfma_f32_16x16x32_bf16 v[94:97], v[50:53], v[224:227], v[94:97]
	v_mfma_f32_16x16x32_bf16 v[90:93], v[66:69], v[224:227], v[90:93]
	v_mfma_f32_16x16x32_bf16 v[142:145], v[54:57], v[204:207], v[142:145]
	v_mfma_f32_16x16x32_bf16 v[138:141], v[70:73], v[204:207], v[138:141]
	v_mfma_f32_16x16x32_bf16 v[126:129], v[54:57], v[212:215], v[126:129]
	v_mfma_f32_16x16x32_bf16 v[122:125], v[70:73], v[212:215], v[122:125]
	v_mfma_f32_16x16x32_bf16 v[110:113], v[54:57], v[220:223], v[110:113]
	v_mfma_f32_16x16x32_bf16 v[106:109], v[70:73], v[220:223], v[106:109]
	v_mfma_f32_16x16x32_bf16 v[94:97], v[54:57], v[228:231], v[94:97]
	v_mfma_f32_16x16x32_bf16 v[90:93], v[70:73], v[228:231], v[90:93]
	s_setprio 0
	s_setprio 1
	v_mfma_f32_16x16x32_bf16 v[134:137], v[146:149], v[200:203], v[134:137]
	v_mfma_f32_16x16x32_bf16 v[130:133], v[184:187], v[200:203], v[130:133]
	v_mfma_f32_16x16x32_bf16 v[118:121], v[146:149], v[208:211], v[118:121]
	v_mfma_f32_16x16x32_bf16 v[114:117], v[184:187], v[208:211], v[114:117]
	v_mfma_f32_16x16x32_bf16 v[102:105], v[146:149], v[216:219], v[102:105]
	v_mfma_f32_16x16x32_bf16 v[98:101], v[184:187], v[216:219], v[98:101]
	v_mfma_f32_16x16x32_bf16 v[86:89], v[146:149], v[224:227], v[86:89]
	v_mfma_f32_16x16x32_bf16 v[82:85], v[184:187], v[224:227], v[82:85]
	v_mfma_f32_16x16x32_bf16 v[134:137], v[150:153], v[204:207], v[134:137]
	v_mfma_f32_16x16x32_bf16 v[130:133], v[188:191], v[204:207], v[130:133]
	v_mfma_f32_16x16x32_bf16 v[118:121], v[150:153], v[212:215], v[118:121]
	v_mfma_f32_16x16x32_bf16 v[114:117], v[188:191], v[212:215], v[114:117]
	v_mfma_f32_16x16x32_bf16 v[102:105], v[150:153], v[220:223], v[102:105]
	v_mfma_f32_16x16x32_bf16 v[98:101], v[188:191], v[220:223], v[98:101]
	v_mfma_f32_16x16x32_bf16 v[86:89], v[150:153], v[228:231], v[86:89]
	v_mfma_f32_16x16x32_bf16 v[82:85], v[188:191], v[228:231], v[82:85]
	s_setprio 0
	s_barrier
	s_add_i32 s6, s12, s61
	v_lshl_add_u64 v[192:193], v[192:193], 0, s[38:39]
	s_mov_b32 m0, s6
	ds_read_b128 v[200:203], v198 offset:49152
	ds_read_b128 v[204:207], v198 offset:50176
	ds_read_b128 v[208:211], v198 offset:51200
	ds_read_b128 v[212:215], v198 offset:52224
	ds_read_b128 v[216:219], v198 offset:53248
	ds_read_b128 v[220:223], v198 offset:54272
	ds_read_b128 v[224:227], v198 offset:55296
	ds_read_b128 v[228:231], v198 offset:56320
	global_load_lds_dwordx4 v[192:193], off
	v_lshl_add_u64 v[192:193], v[232:233], 0, s[38:39]
	s_add_i32 m0, s6, 0x2000
	s_add_i32 s6, s13, s61
	global_load_lds_dwordx4 v[192:193], off
	v_lshl_add_u64 v[192:193], v[234:235], 0, s[38:39]
	s_mov_b32 m0, s6
	s_nop 0
	global_load_lds_dwordx4 v[192:193], off
	v_lshl_add_u64 v[192:193], v[236:237], 0, s[38:39]
	s_add_i32 m0, s6, 0x2000
	s_nop 0
	global_load_lds_dwordx4 v[192:193], off
	v_lshl_add_u64 v[192:193], v[238:239], 0, s[38:39]
	s_mov_b32 m0, s81
	s_nop 0
	global_load_lds_dwordx4 v[192:193], off
	v_lshl_add_u64 v[192:193], v[240:241], 0, s[38:39]
	s_mov_b32 m0, s82
	s_nop 0
	global_load_lds_dwordx4 v[192:193], off
	s_waitcnt vmcnt(8)
	s_waitcnt lgkmcnt(0)
	s_setprio 1
	s_waitcnt lgkmcnt(0)
	v_mfma_f32_16x16x32_bf16 v[78:81], v[50:53], v[200:203], v[78:81]
	v_mfma_f32_16x16x32_bf16 v[74:77], v[66:69], v[200:203], v[74:77]
	s_barrier
	v_mfma_f32_16x16x32_bf16 v[62:65], v[50:53], v[208:211], v[62:65]
	v_mfma_f32_16x16x32_bf16 v[58:61], v[66:69], v[208:211], v[58:61]
	v_mfma_f32_16x16x32_bf16 v[30:33], v[50:53], v[216:219], v[30:33]
	v_mfma_f32_16x16x32_bf16 v[26:29], v[66:69], v[216:219], v[26:29]
	v_mfma_f32_16x16x32_bf16 v[14:17], v[50:53], v[224:227], v[14:17]
	v_mfma_f32_16x16x32_bf16 v[10:13], v[66:69], v[224:227], v[10:13]
	v_mfma_f32_16x16x32_bf16 v[78:81], v[54:57], v[204:207], v[78:81]
	v_mfma_f32_16x16x32_bf16 v[74:77], v[70:73], v[204:207], v[74:77]
	v_mfma_f32_16x16x32_bf16 v[62:65], v[54:57], v[212:215], v[62:65]
	v_mfma_f32_16x16x32_bf16 v[58:61], v[70:73], v[212:215], v[58:61]
	v_mfma_f32_16x16x32_bf16 v[30:33], v[54:57], v[220:223], v[30:33]
	v_mfma_f32_16x16x32_bf16 v[26:29], v[70:73], v[220:223], v[26:29]
	v_mfma_f32_16x16x32_bf16 v[14:17], v[54:57], v[228:231], v[14:17]
	v_mfma_f32_16x16x32_bf16 v[10:13], v[70:73], v[228:231], v[10:13]
	s_setprio 0
	s_setprio 1
	v_mfma_f32_16x16x32_bf16 v[34:37], v[146:149], v[200:203], v[34:37]
	v_mfma_f32_16x16x32_bf16 v[70:73], v[150:153], v[204:207], v[34:37]
	v_mfma_f32_16x16x32_bf16 v[34:37], v[184:187], v[200:203], v[38:41]
	v_mfma_f32_16x16x32_bf16 v[66:69], v[188:191], v[204:207], v[34:37]
	v_mfma_f32_16x16x32_bf16 v[34:37], v[146:149], v[208:211], v[46:49]
	v_mfma_f32_16x16x32_bf16 v[46:49], v[150:153], v[212:215], v[34:37]
	v_mfma_f32_16x16x32_bf16 v[34:37], v[184:187], v[208:211], v[42:45]
	v_mfma_f32_16x16x32_bf16 v[22:25], v[146:149], v[216:219], v[22:25]
	v_mfma_f32_16x16x32_bf16 v[18:21], v[184:187], v[216:219], v[18:21]
	v_mfma_f32_16x16x32_bf16 v[6:9], v[146:149], v[224:227], v[6:9]
	v_mfma_f32_16x16x32_bf16 v[2:5], v[184:187], v[224:227], v[2:5]
	v_mfma_f32_16x16x32_bf16 v[42:45], v[188:191], v[212:215], v[34:37]
	v_mfma_f32_16x16x32_bf16 v[22:25], v[150:153], v[220:223], v[22:25]
	v_mfma_f32_16x16x32_bf16 v[18:21], v[188:191], v[220:223], v[18:21]
	v_mfma_f32_16x16x32_bf16 v[6:9], v[150:153], v[228:231], v[6:9]
	v_mfma_f32_16x16x32_bf16 v[2:5], v[188:191], v[228:231], v[2:5]
	s_setprio 0
	s_barrier
	s_add_u32 s4, s4, 0x100
	s_addc_u32 s5, s5, 0
	s_add_u32 s8, s8, 0x100
	s_addc_u32 s9, s9, 0
	s_cmp_ge_i32 s11, s83
	s_mov_b32 s6, s11
	s_cbranch_scc0 .LBB0_3126

.LBB0_3613:
	v_add_u32_e32 v158, s64, v229
	v_add_u32_e32 v174, s65, v229
	ds_read_b128 v[146:149], v158
	ds_read_b128 v[150:153], v158 offset:1024
	ds_read_b128 v[154:157], v158 offset:2048
	ds_read_b128 v[158:161], v158 offset:3072
	ds_read_b128 v[162:165], v174
	ds_read_b128 v[166:169], v174 offset:1024
	ds_read_b128 v[170:173], v174 offset:2048
	ds_read_b128 v[174:177], v174 offset:3072
	s_add_i32 s80, s42, 2
	s_add_u32 s81, s40, 0x80
	s_addc_u32 s43, s41, 0
	s_cmp_eq_u32 s61, s42
	s_cselect_b32 s42, s4, s81
	s_cselect_b32 s43, s5, s43
	s_cselect_b32 s83, s39, s71
	s_cselect_b32 s82, s38, s70
	v_lshl_add_u64 v[210:211], s[40:41], 0, v[138:139]
	s_add_i32 m0, s51, 0xc000
	ds_read_b128 v[178:181], v231
	ds_read_b128 v[182:185], v231 offset:1024
	ds_read_b128 v[186:189], v231 offset:2048
	ds_read_b128 v[190:193], v231 offset:3072
	ds_read_b128 v[194:197], v231 offset:4096
	ds_read_b128 v[198:201], v231 offset:5120
	ds_read_b128 v[202:205], v231 offset:6144
	ds_read_b128 v[206:209], v231 offset:7168
	global_load_lds_dwordx4 v[210:211], off
	v_lshl_add_u64 v[210:211], s[40:41], 0, v[140:141]
	s_add_i32 m0, s51, 0xe000
	s_nop 0
	global_load_lds_dwordx4 v[210:211], off
	s_waitcnt vmcnt(8)
	s_waitcnt lgkmcnt(0)
	s_setprio 1
	s_waitcnt lgkmcnt(0)
	v_mfma_i32_16x16x64_i8 v[126:129], v[146:149], v[178:181], v[126:129]
	v_mfma_i32_16x16x64_i8 v[122:125], v[154:157], v[178:181], v[122:125]
	s_barrier
	v_mfma_i32_16x16x64_i8 v[118:121], v[146:149], v[186:189], v[118:121]
	v_mfma_i32_16x16x64_i8 v[114:117], v[154:157], v[186:189], v[114:117]
	v_mfma_i32_16x16x64_i8 v[106:109], v[146:149], v[194:197], v[106:109]
	v_mfma_i32_16x16x64_i8 v[98:101], v[154:157], v[194:197], v[98:101]
	v_mfma_i32_16x16x64_i8 v[90:93], v[146:149], v[202:205], v[90:93]
	v_mfma_i32_16x16x64_i8 v[82:85], v[154:157], v[202:205], v[82:85]
	v_mfma_i32_16x16x64_i8 v[126:129], v[150:153], v[182:185], v[126:129]
	v_mfma_i32_16x16x64_i8 v[122:125], v[158:161], v[182:185], v[122:125]
	v_mfma_i32_16x16x64_i8 v[118:121], v[150:153], v[190:193], v[118:121]
	v_mfma_i32_16x16x64_i8 v[114:117], v[158:161], v[190:193], v[114:117]
	v_mfma_i32_16x16x64_i8 v[106:109], v[150:153], v[198:201], v[106:109]
	v_mfma_i32_16x16x64_i8 v[98:101], v[158:161], v[198:201], v[98:101]
	v_mfma_i32_16x16x64_i8 v[90:93], v[150:153], v[206:209], v[90:93]
	v_mfma_i32_16x16x64_i8 v[82:85], v[158:161], v[206:209], v[82:85]
	s_setprio 0
	s_setprio 1
	v_mfma_i32_16x16x64_i8 v[110:113], v[162:165], v[178:181], v[110:113]
	v_mfma_i32_16x16x64_i8 v[102:105], v[170:173], v[178:181], v[102:105]
	v_mfma_i32_16x16x64_i8 v[94:97], v[162:165], v[186:189], v[94:97]
	v_mfma_i32_16x16x64_i8 v[86:89], v[170:173], v[186:189], v[86:89]
	v_mfma_i32_16x16x64_i8 v[78:81], v[162:165], v[194:197], v[78:81]
	v_mfma_i32_16x16x64_i8 v[74:77], v[170:173], v[194:197], v[74:77]
	v_mfma_i32_16x16x64_i8 v[70:73], v[162:165], v[202:205], v[70:73]
	v_mfma_i32_16x16x64_i8 v[66:69], v[170:173], v[202:205], v[66:69]
	v_mfma_i32_16x16x64_i8 v[110:113], v[166:169], v[182:185], v[110:113]
	v_mfma_i32_16x16x64_i8 v[102:105], v[174:177], v[182:185], v[102:105]
	v_mfma_i32_16x16x64_i8 v[94:97], v[166:169], v[190:193], v[94:97]
	v_mfma_i32_16x16x64_i8 v[86:89], v[174:177], v[190:193], v[86:89]
	v_mfma_i32_16x16x64_i8 v[78:81], v[166:169], v[198:201], v[78:81]
	v_mfma_i32_16x16x64_i8 v[74:77], v[174:177], v[198:201], v[74:77]
	v_mfma_i32_16x16x64_i8 v[70:73], v[166:169], v[206:209], v[70:73]
	v_mfma_i32_16x16x64_i8 v[66:69], v[174:177], v[206:209], v[66:69]
	s_setprio 0
	s_barrier
	s_add_i32 s81, s64, s50
	v_lshl_add_u64 v[210:211], s[82:83], 0, v[132:133]
	s_mov_b32 m0, s81
	ds_read_b128 v[178:181], v231 offset:16384
	ds_read_b128 v[182:185], v231 offset:17408
	ds_read_b128 v[186:189], v231 offset:18432
	ds_read_b128 v[190:193], v231 offset:19456
	ds_read_b128 v[194:197], v231 offset:20480
	ds_read_b128 v[198:201], v231 offset:21504
	ds_read_b128 v[202:205], v231 offset:22528
	ds_read_b128 v[206:209], v231 offset:23552
	global_load_lds_dwordx4 v[210:211], off
	s_add_i32 m0, s81, 0x2000
	v_lshl_add_u64 v[212:213], s[82:83], 0, v[136:137]
	s_add_u32 s82, s82, s8
	s_addc_u32 s83, s83, s9
	s_add_i32 s81, s65, s50
	global_load_lds_dwordx4 v[212:213], off
	v_lshl_add_u64 v[214:215], s[82:83], 0, v[132:133]
	s_mov_b32 m0, s81
	v_lshl_add_u64 v[216:217], s[82:83], 0, v[136:137]
	global_load_lds_dwordx4 v[214:215], off
	s_add_i32 m0, s81, 0x2000
	v_lshl_add_u64 v[218:219], s[42:43], 0, v[130:131]
	global_load_lds_dwordx4 v[216:217], off
	s_mov_b32 m0, s51
	v_lshl_add_u64 v[220:221], s[42:43], 0, v[134:135]
	global_load_lds_dwordx4 v[218:219], off
	s_mov_b32 m0, s52
	s_nop 0
	global_load_lds_dwordx4 v[220:221], off
	s_waitcnt vmcnt(8)
	s_waitcnt lgkmcnt(0)
	s_setprio 1
	s_waitcnt lgkmcnt(0)
	v_mfma_i32_16x16x64_i8 v[62:65], v[146:149], v[178:181], v[62:65]
	v_mfma_i32_16x16x64_i8 v[58:61], v[154:157], v[178:181], v[58:61]
	s_barrier
	v_mfma_i32_16x16x64_i8 v[54:57], v[146:149], v[186:189], v[54:57]
	v_mfma_i32_16x16x64_i8 v[50:53], v[154:157], v[186:189], v[50:53]
	v_mfma_i32_16x16x64_i8 v[42:45], v[146:149], v[194:197], v[42:45]
	v_mfma_i32_16x16x64_i8 v[34:37], v[154:157], v[194:197], v[34:37]
	v_mfma_i32_16x16x64_i8 v[26:29], v[146:149], v[202:205], v[26:29]
	v_mfma_i32_16x16x64_i8 v[18:21], v[154:157], v[202:205], v[18:21]
	v_mfma_i32_16x16x64_i8 v[62:65], v[150:153], v[182:185], v[62:65]
	v_mfma_i32_16x16x64_i8 v[58:61], v[158:161], v[182:185], v[58:61]
	v_mfma_i32_16x16x64_i8 v[54:57], v[150:153], v[190:193], v[54:57]
	v_mfma_i32_16x16x64_i8 v[50:53], v[158:161], v[190:193], v[50:53]
	v_mfma_i32_16x16x64_i8 v[42:45], v[150:153], v[198:201], v[42:45]
	v_mfma_i32_16x16x64_i8 v[34:37], v[158:161], v[198:201], v[34:37]
	v_mfma_i32_16x16x64_i8 v[26:29], v[150:153], v[206:209], v[26:29]
	v_mfma_i32_16x16x64_i8 v[18:21], v[158:161], v[206:209], v[18:21]
	s_setprio 0
	s_setprio 1
	v_mfma_i32_16x16x64_i8 v[46:49], v[162:165], v[178:181], v[46:49]
	v_mfma_i32_16x16x64_i8 v[38:41], v[170:173], v[178:181], v[38:41]
	v_mfma_i32_16x16x64_i8 v[30:33], v[162:165], v[186:189], v[30:33]
	v_mfma_i32_16x16x64_i8 v[22:25], v[170:173], v[186:189], v[22:25]
	v_mfma_i32_16x16x64_i8 v[14:17], v[162:165], v[194:197], v[14:17]
	v_mfma_i32_16x16x64_i8 v[10:13], v[170:173], v[194:197], v[10:13]
	v_mfma_i32_16x16x64_i8 v[6:9], v[162:165], v[202:205], v[6:9]
	v_mfma_i32_16x16x64_i8 v[2:5], v[170:173], v[202:205], v[2:5]
	v_mfma_i32_16x16x64_i8 v[46:49], v[166:169], v[182:185], v[46:49]
	v_mfma_i32_16x16x64_i8 v[38:41], v[174:177], v[182:185], v[38:41]
	v_mfma_i32_16x16x64_i8 v[30:33], v[166:169], v[190:193], v[30:33]
	v_mfma_i32_16x16x64_i8 v[22:25], v[174:177], v[190:193], v[22:25]
	v_mfma_i32_16x16x64_i8 v[14:17], v[166:169], v[198:201], v[14:17]
	v_mfma_i32_16x16x64_i8 v[10:13], v[174:177], v[198:201], v[10:13]
	v_mfma_i32_16x16x64_i8 v[6:9], v[166:169], v[206:209], v[6:9]
	v_mfma_i32_16x16x64_i8 v[2:5], v[174:177], v[206:209], v[2:5]
	s_setprio 0
	s_barrier
	s_add_i32 s81, 0, 0x18000
	s_add_i32 s82, 0, 0x1c000
	v_add_u32_e32 v158, s81, v229
	v_add_u32_e32 v174, s82, v229
	ds_read_b128 v[146:149], v158
	ds_read_b128 v[150:153], v158 offset:1024
	ds_read_b128 v[154:157], v158 offset:2048
	ds_read_b128 v[158:161], v158 offset:3072
	ds_read_b128 v[162:165], v174
	ds_read_b128 v[166:169], v174 offset:1024
	ds_read_b128 v[170:173], v174 offset:2048
	ds_read_b128 v[174:177], v174 offset:3072
	s_add_u32 s42, s42, s8
	s_addc_u32 s43, s43, s9
	s_mov_b32 m0, s53
	v_lshl_add_u64 v[222:223], s[42:43], 0, v[130:131]
	ds_read_b128 v[178:181], v231 offset:32768
	ds_read_b128 v[182:185], v231 offset:33792
	ds_read_b128 v[186:189], v231 offset:34816
	ds_read_b128 v[190:193], v231 offset:35840
	ds_read_b128 v[194:197], v231 offset:36864
	ds_read_b128 v[198:201], v231 offset:37888
	ds_read_b128 v[202:205], v231 offset:38912
	ds_read_b128 v[206:209], v231 offset:39936
	global_load_lds_dwordx4 v[222:223], off
	v_lshl_add_u64 v[222:223], s[42:43], 0, v[134:135]
	s_mov_b32 m0, s54
	s_nop 0
	global_load_lds_dwordx4 v[222:223], off
	s_waitcnt vmcnt(8)
	s_waitcnt lgkmcnt(0)
	s_setprio 1
	s_waitcnt lgkmcnt(0)
	v_mfma_i32_16x16x64_i8 v[126:129], v[146:149], v[178:181], v[126:129]
	v_mfma_i32_16x16x64_i8 v[122:125], v[154:157], v[178:181], v[122:125]
	s_barrier
	v_mfma_i32_16x16x64_i8 v[118:121], v[146:149], v[186:189], v[118:121]
	v_mfma_i32_16x16x64_i8 v[114:117], v[154:157], v[186:189], v[114:117]
	v_mfma_i32_16x16x64_i8 v[106:109], v[146:149], v[194:197], v[106:109]
	v_mfma_i32_16x16x64_i8 v[98:101], v[154:157], v[194:197], v[98:101]
	v_mfma_i32_16x16x64_i8 v[90:93], v[146:149], v[202:205], v[90:93]
	v_mfma_i32_16x16x64_i8 v[82:85], v[154:157], v[202:205], v[82:85]
	v_mfma_i32_16x16x64_i8 v[126:129], v[150:153], v[182:185], v[126:129]
	v_mfma_i32_16x16x64_i8 v[122:125], v[158:161], v[182:185], v[122:125]
	v_mfma_i32_16x16x64_i8 v[118:121], v[150:153], v[190:193], v[118:121]
	v_mfma_i32_16x16x64_i8 v[114:117], v[158:161], v[190:193], v[114:117]
	v_mfma_i32_16x16x64_i8 v[106:109], v[150:153], v[198:201], v[106:109]
	v_mfma_i32_16x16x64_i8 v[98:101], v[158:161], v[198:201], v[98:101]
	v_mfma_i32_16x16x64_i8 v[90:93], v[150:153], v[206:209], v[90:93]
	v_mfma_i32_16x16x64_i8 v[82:85], v[158:161], v[206:209], v[82:85]
	s_setprio 0
	s_setprio 1
	v_mfma_i32_16x16x64_i8 v[110:113], v[162:165], v[178:181], v[110:113]
	v_mfma_i32_16x16x64_i8 v[102:105], v[170:173], v[178:181], v[102:105]
	v_mfma_i32_16x16x64_i8 v[94:97], v[162:165], v[186:189], v[94:97]
	v_mfma_i32_16x16x64_i8 v[86:89], v[170:173], v[186:189], v[86:89]
	v_mfma_i32_16x16x64_i8 v[78:81], v[162:165], v[194:197], v[78:81]
	v_mfma_i32_16x16x64_i8 v[74:77], v[170:173], v[194:197], v[74:77]
	v_mfma_i32_16x16x64_i8 v[70:73], v[162:165], v[202:205], v[70:73]
	v_mfma_i32_16x16x64_i8 v[66:69], v[170:173], v[202:205], v[66:69]
	v_mfma_i32_16x16x64_i8 v[110:113], v[166:169], v[182:185], v[110:113]
	v_mfma_i32_16x16x64_i8 v[102:105], v[174:177], v[182:185], v[102:105]
	v_mfma_i32_16x16x64_i8 v[94:97], v[166:169], v[190:193], v[94:97]
	v_mfma_i32_16x16x64_i8 v[86:89], v[174:177], v[190:193], v[86:89]
	v_mfma_i32_16x16x64_i8 v[78:81], v[166:169], v[198:201], v[78:81]
	v_mfma_i32_16x16x64_i8 v[74:77], v[174:177], v[198:201], v[74:77]
	v_mfma_i32_16x16x64_i8 v[70:73], v[166:169], v[206:209], v[70:73]
	v_mfma_i32_16x16x64_i8 v[66:69], v[174:177], v[206:209], v[66:69]
	s_setprio 0
	s_barrier
	s_add_i32 s42, s81, s50
	v_lshl_add_u64 v[210:211], v[210:211], 0, s[30:31]
	s_mov_b32 m0, s42
	ds_read_b128 v[178:181], v231 offset:49152
	ds_read_b128 v[182:185], v231 offset:50176
	ds_read_b128 v[186:189], v231 offset:51200
	ds_read_b128 v[190:193], v231 offset:52224
	ds_read_b128 v[194:197], v231 offset:53248
	ds_read_b128 v[198:201], v231 offset:54272
	ds_read_b128 v[202:205], v231 offset:55296
	ds_read_b128 v[206:209], v231 offset:56320
	global_load_lds_dwordx4 v[210:211], off
	v_lshl_add_u64 v[210:211], v[212:213], 0, s[30:31]
	s_add_i32 m0, s42, 0x2000
	s_add_i32 s42, s82, s50
	global_load_lds_dwordx4 v[210:211], off
	v_lshl_add_u64 v[210:211], v[214:215], 0, s[30:31]
	s_mov_b32 m0, s42
	s_nop 0
	global_load_lds_dwordx4 v[210:211], off
	v_lshl_add_u64 v[210:211], v[216:217], 0, s[30:31]
	s_add_i32 m0, s42, 0x2000
	s_nop 0
	global_load_lds_dwordx4 v[210:211], off
	v_lshl_add_u64 v[210:211], v[218:219], 0, s[30:31]
	s_mov_b32 m0, s57
	s_nop 0
	global_load_lds_dwordx4 v[210:211], off
	v_lshl_add_u64 v[210:211], v[220:221], 0, s[30:31]
	s_mov_b32 m0, s58
	s_nop 0
	global_load_lds_dwordx4 v[210:211], off
	s_waitcnt vmcnt(8)
	s_waitcnt lgkmcnt(0)
	s_setprio 1
	s_waitcnt lgkmcnt(0)
	v_mfma_i32_16x16x64_i8 v[62:65], v[146:149], v[178:181], v[62:65]
	v_mfma_i32_16x16x64_i8 v[58:61], v[154:157], v[178:181], v[58:61]
	s_barrier
	v_mfma_i32_16x16x64_i8 v[54:57], v[146:149], v[186:189], v[54:57]
	v_mfma_i32_16x16x64_i8 v[50:53], v[154:157], v[186:189], v[50:53]
	v_mfma_i32_16x16x64_i8 v[42:45], v[146:149], v[194:197], v[42:45]
	v_mfma_i32_16x16x64_i8 v[34:37], v[154:157], v[194:197], v[34:37]
	v_mfma_i32_16x16x64_i8 v[26:29], v[146:149], v[202:205], v[26:29]
	v_mfma_i32_16x16x64_i8 v[18:21], v[154:157], v[202:205], v[18:21]
	v_mfma_i32_16x16x64_i8 v[62:65], v[150:153], v[182:185], v[62:65]
	v_mfma_i32_16x16x64_i8 v[58:61], v[158:161], v[182:185], v[58:61]
	v_mfma_i32_16x16x64_i8 v[54:57], v[150:153], v[190:193], v[54:57]
	v_mfma_i32_16x16x64_i8 v[50:53], v[158:161], v[190:193], v[50:53]
	v_mfma_i32_16x16x64_i8 v[42:45], v[150:153], v[198:201], v[42:45]
	v_mfma_i32_16x16x64_i8 v[34:37], v[158:161], v[198:201], v[34:37]
	v_mfma_i32_16x16x64_i8 v[26:29], v[150:153], v[206:209], v[26:29]
	v_mfma_i32_16x16x64_i8 v[18:21], v[158:161], v[206:209], v[18:21]
	s_setprio 0
	s_setprio 1
	v_mfma_i32_16x16x64_i8 v[46:49], v[162:165], v[178:181], v[46:49]
	v_mfma_i32_16x16x64_i8 v[38:41], v[170:173], v[178:181], v[38:41]
	v_mfma_i32_16x16x64_i8 v[30:33], v[162:165], v[186:189], v[30:33]
	v_mfma_i32_16x16x64_i8 v[22:25], v[170:173], v[186:189], v[22:25]
	v_mfma_i32_16x16x64_i8 v[14:17], v[162:165], v[194:197], v[14:17]
	v_mfma_i32_16x16x64_i8 v[10:13], v[170:173], v[194:197], v[10:13]
	v_mfma_i32_16x16x64_i8 v[6:9], v[162:165], v[202:205], v[6:9]
	v_mfma_i32_16x16x64_i8 v[2:5], v[170:173], v[202:205], v[2:5]
	v_mfma_i32_16x16x64_i8 v[46:49], v[166:169], v[182:185], v[46:49]
	v_mfma_i32_16x16x64_i8 v[38:41], v[174:177], v[182:185], v[38:41]
	v_mfma_i32_16x16x64_i8 v[30:33], v[166:169], v[190:193], v[30:33]
	v_mfma_i32_16x16x64_i8 v[22:25], v[174:177], v[190:193], v[22:25]
	v_mfma_i32_16x16x64_i8 v[14:17], v[166:169], v[198:201], v[14:17]
	v_mfma_i32_16x16x64_i8 v[10:13], v[174:177], v[198:201], v[10:13]
	v_mfma_i32_16x16x64_i8 v[6:9], v[166:169], v[206:209], v[6:9]
	v_mfma_i32_16x16x64_i8 v[2:5], v[174:177], v[206:209], v[2:5]
	s_setprio 0
	s_barrier
	s_add_u32 s40, s40, 0x100
	s_addc_u32 s41, s41, 0
	s_add_u32 s70, s70, 0x100
	s_addc_u32 s71, s71, 0
	s_cmp_ge_i32 s80, s60
	s_mov_b32 s42, s80
	s_cbranch_scc0 .LBB0_3613
	v_cvt_f32_i32_e32 v214, v126
	v_cvt_f32_i32_e32 v215, v127
	v_cvt_f32_i32_e32 v212, v128
	v_cvt_f32_i32_e32 v213, v129
	v_cvt_f32_i32_e32 v218, v122
	v_cvt_f32_i32_e32 v219, v123
	v_cvt_f32_i32_e32 v216, v124
	v_cvt_f32_i32_e32 v217, v125
	v_cvt_f32_i32_e32 v222, v110
	v_cvt_f32_i32_e32 v223, v111
	v_cvt_f32_i32_e32 v220, v112
	v_cvt_f32_i32_e32 v221, v113
	v_cvt_f32_i32_e32 v226, v102
	v_cvt_f32_i32_e32 v227, v103
	v_cvt_f32_i32_e32 v224, v104
	v_cvt_f32_i32_e32 v225, v105
	v_cvt_f32_i32_e32 v194, v118
	v_cvt_f32_i32_e32 v195, v119
	v_cvt_f32_i32_e32 v192, v120
	v_cvt_f32_i32_e32 v193, v121
	v_cvt_f32_i32_e32 v200, v114
	v_cvt_f32_i32_e32 v201, v115
	v_cvt_f32_i32_e32 v198, v116
	v_cvt_f32_i32_e32 v199, v117
	v_cvt_f32_i32_e32 v206, v94
	v_cvt_f32_i32_e32 v207, v95
	v_cvt_f32_i32_e32 v202, v96
	v_cvt_f32_i32_e32 v203, v97
	v_cvt_f32_i32_e32 v208, v86
	v_cvt_f32_i32_e32 v209, v87
	v_cvt_f32_i32_e32 v204, v88
	v_cvt_f32_i32_e32 v205, v89
	v_cvt_f32_i32_e32 v178, v106
	v_cvt_f32_i32_e32 v179, v107
	v_cvt_f32_i32_e32 v176, v108
	v_cvt_f32_i32_e32 v177, v109
	v_cvt_f32_i32_e32 v182, v98
	v_cvt_f32_i32_e32 v183, v99
	v_cvt_f32_i32_e32 v180, v100
	v_cvt_f32_i32_e32 v181, v101
	v_cvt_f32_i32_e32 v188, v78
	v_cvt_f32_i32_e32 v189, v79
	v_cvt_f32_i32_e32 v184, v80
	v_cvt_f32_i32_e32 v185, v81
	v_cvt_f32_i32_e32 v190, v74
	v_cvt_f32_i32_e32 v191, v75
	v_cvt_f32_i32_e32 v186, v76
	v_cvt_f32_i32_e32 v187, v77
	v_cvt_f32_i32_e32 v162, v90
	v_cvt_f32_i32_e32 v163, v91
	v_cvt_f32_i32_e32 v160, v92
	v_cvt_f32_i32_e32 v161, v93
	v_cvt_f32_i32_e32 v166, v82
	v_cvt_f32_i32_e32 v167, v83
	v_cvt_f32_i32_e32 v164, v84
	v_cvt_f32_i32_e32 v165, v85
	v_cvt_f32_i32_e32 v172, v70
	v_cvt_f32_i32_e32 v173, v71
	v_cvt_f32_i32_e32 v168, v72
	v_cvt_f32_i32_e32 v169, v73
	v_cvt_f32_i32_e32 v174, v66
	v_cvt_f32_i32_e32 v175, v67
	v_cvt_f32_i32_e32 v170, v68
	v_cvt_f32_i32_e32 v171, v69
	v_cvt_f32_i32_e32 v146, v62
	v_cvt_f32_i32_e32 v147, v63
	v_cvt_f32_i32_e32 v128, v64
	v_cvt_f32_i32_e32 v129, v65
	v_cvt_f32_i32_e32 v150, v58
	v_cvt_f32_i32_e32 v151, v59
	v_cvt_f32_i32_e32 v148, v60
	v_cvt_f32_i32_e32 v149, v61
	v_cvt_f32_i32_e32 v156, v46
	v_cvt_f32_i32_e32 v157, v47
	v_cvt_f32_i32_e32 v152, v48
	v_cvt_f32_i32_e32 v153, v49
	v_cvt_f32_i32_e32 v158, v38
	v_cvt_f32_i32_e32 v159, v39
	v_cvt_f32_i32_e32 v154, v40
	v_cvt_f32_i32_e32 v155, v41
	v_cvt_f32_i32_e32 v114, v54
	v_cvt_f32_i32_e32 v115, v55
	v_cvt_f32_i32_e32 v112, v56
	v_cvt_f32_i32_e32 v113, v57
	v_cvt_f32_i32_e32 v118, v50
	v_cvt_f32_i32_e32 v119, v51
	v_cvt_f32_i32_e32 v116, v52
	v_cvt_f32_i32_e32 v117, v53
	v_cvt_f32_i32_e32 v124, v30
	v_cvt_f32_i32_e32 v125, v31
	v_cvt_f32_i32_e32 v120, v32
	v_cvt_f32_i32_e32 v121, v33
	v_cvt_f32_i32_e32 v126, v22
	v_cvt_f32_i32_e32 v127, v23
	v_cvt_f32_i32_e32 v122, v24
	v_cvt_f32_i32_e32 v123, v25
	v_cvt_f32_i32_e32 v64, v42
	v_cvt_f32_i32_e32 v65, v43
	v_cvt_f32_i32_e32 v62, v44
	v_cvt_f32_i32_e32 v63, v45
	v_cvt_f32_i32_e32 v68, v34
	v_cvt_f32_i32_e32 v69, v35
	v_cvt_f32_i32_e32 v66, v36
	v_cvt_f32_i32_e32 v67, v37
	v_cvt_f32_i32_e32 v74, v14
	v_cvt_f32_i32_e32 v75, v15
	v_cvt_f32_i32_e32 v70, v16
	v_cvt_f32_i32_e32 v71, v17
	v_cvt_f32_i32_e32 v76, v10
	v_cvt_f32_i32_e32 v77, v11
	v_cvt_f32_i32_e32 v72, v12
	v_cvt_f32_i32_e32 v73, v13
	v_cvt_f32_i32_e32 v48, v26
	v_cvt_f32_i32_e32 v49, v27
	v_cvt_f32_i32_e32 v46, v28
	v_cvt_f32_i32_e32 v47, v29
	v_cvt_f32_i32_e32 v52, v18
	v_cvt_f32_i32_e32 v53, v19
	v_cvt_f32_i32_e32 v50, v20
	v_cvt_f32_i32_e32 v51, v21
	v_cvt_f32_i32_e32 v58, v6
	v_cvt_f32_i32_e32 v59, v7
	v_cvt_f32_i32_e32 v54, v8
	v_cvt_f32_i32_e32 v55, v9
	v_cvt_f32_i32_e32 v60, v2
	v_cvt_f32_i32_e32 v61, v3
	v_cvt_f32_i32_e32 v56, v4
	v_cvt_f32_i32_e32 v57, v5

.LBB0_3798:
	v_add_u32_e32 v138, s56, v188
	ds_read_b128 v[148:151], v138
	ds_read_b128 v[152:155], v138 offset:1024
	ds_read_b128 v[156:159], v138 offset:2048
	ds_read_b128 v[160:163], v138 offset:3072
	v_add_u32_e32 v138, s57, v188
	ds_read_b128 v[164:167], v138
	ds_read_b128 v[168:171], v138 offset:1024
	ds_read_b128 v[172:175], v138 offset:2048
	ds_read_b128 v[176:179], v138 offset:3072
	s_add_i32 s60, s28, 2
	s_add_u32 s61, s26, 0x80
	s_addc_u32 s29, s27, 0
	s_cmp_eq_u32 s54, s28
	s_cselect_b32 s28, s2, s61
	s_cselect_b32 s29, s3, s29
	s_cselect_b32 s63, s25, s35
	s_cselect_b32 s62, s24, s34
	v_lshl_add_u64 v[184:185], s[26:27], 0, v[140:141]
	s_add_i32 m0, s42, 0xc000
	ds_read_b128 v[180:183], v189
	ds_read_b128 v[190:193], v189 offset:1024
	ds_read_b128 v[194:197], v189 offset:2048
	ds_read_b128 v[198:201], v189 offset:3072
	ds_read_b128 v[202:205], v189 offset:4096
	ds_read_b128 v[206:209], v189 offset:5120
	ds_read_b128 v[210:213], v189 offset:6144
	ds_read_b128 v[214:217], v189 offset:7168
	global_load_lds_dwordx4 v[184:185], off
	v_lshl_add_u64 v[184:185], s[26:27], 0, v[142:143]
	s_add_i32 m0, s42, 0xe000
	s_nop 0
	global_load_lds_dwordx4 v[184:185], off
	s_waitcnt vmcnt(8)
	s_waitcnt lgkmcnt(0)
	s_setprio 1
	s_waitcnt lgkmcnt(0)
	v_mfma_i32_16x16x64_i8 v[126:129], v[148:151], v[180:183], v[126:129]
	v_mfma_i32_16x16x64_i8 v[122:125], v[156:159], v[180:183], v[122:125]
	s_barrier
	v_mfma_i32_16x16x64_i8 v[118:121], v[148:151], v[194:197], v[118:121]
	v_mfma_i32_16x16x64_i8 v[114:117], v[156:159], v[194:197], v[114:117]
	v_mfma_i32_16x16x64_i8 v[106:109], v[148:151], v[202:205], v[106:109]
	v_mfma_i32_16x16x64_i8 v[98:101], v[156:159], v[202:205], v[98:101]
	v_mfma_i32_16x16x64_i8 v[90:93], v[148:151], v[210:213], v[90:93]
	v_mfma_i32_16x16x64_i8 v[82:85], v[156:159], v[210:213], v[82:85]
	v_mfma_i32_16x16x64_i8 v[126:129], v[152:155], v[190:193], v[126:129]
	v_mfma_i32_16x16x64_i8 v[122:125], v[160:163], v[190:193], v[122:125]
	v_mfma_i32_16x16x64_i8 v[118:121], v[152:155], v[198:201], v[118:121]
	v_mfma_i32_16x16x64_i8 v[114:117], v[160:163], v[198:201], v[114:117]
	v_mfma_i32_16x16x64_i8 v[106:109], v[152:155], v[206:209], v[106:109]
	v_mfma_i32_16x16x64_i8 v[98:101], v[160:163], v[206:209], v[98:101]
	v_mfma_i32_16x16x64_i8 v[90:93], v[152:155], v[214:217], v[90:93]
	v_mfma_i32_16x16x64_i8 v[82:85], v[160:163], v[214:217], v[82:85]
	s_setprio 0
	s_setprio 1
	v_mfma_i32_16x16x64_i8 v[110:113], v[164:167], v[180:183], v[110:113]
	v_mfma_i32_16x16x64_i8 v[102:105], v[172:175], v[180:183], v[102:105]
	v_mfma_i32_16x16x64_i8 v[94:97], v[164:167], v[194:197], v[94:97]
	v_mfma_i32_16x16x64_i8 v[86:89], v[172:175], v[194:197], v[86:89]
	v_mfma_i32_16x16x64_i8 v[78:81], v[164:167], v[202:205], v[78:81]
	v_mfma_i32_16x16x64_i8 v[74:77], v[172:175], v[202:205], v[74:77]
	v_mfma_i32_16x16x64_i8 v[70:73], v[164:167], v[210:213], v[70:73]
	v_mfma_i32_16x16x64_i8 v[66:69], v[172:175], v[210:213], v[66:69]
	v_mfma_i32_16x16x64_i8 v[110:113], v[168:171], v[190:193], v[110:113]
	v_mfma_i32_16x16x64_i8 v[102:105], v[176:179], v[190:193], v[102:105]
	v_mfma_i32_16x16x64_i8 v[94:97], v[168:171], v[198:201], v[94:97]
	v_mfma_i32_16x16x64_i8 v[86:89], v[176:179], v[198:201], v[86:89]
	v_mfma_i32_16x16x64_i8 v[78:81], v[168:171], v[206:209], v[78:81]
	v_mfma_i32_16x16x64_i8 v[74:77], v[176:179], v[206:209], v[74:77]
	v_mfma_i32_16x16x64_i8 v[70:73], v[168:171], v[214:217], v[70:73]
	v_mfma_i32_16x16x64_i8 v[66:69], v[176:179], v[214:217], v[66:69]
	s_setprio 0
	s_barrier
	s_add_i32 s61, s56, s41
	v_lshl_add_u64 v[184:185], s[62:63], 0, v[132:133]
	s_mov_b32 m0, s61
	ds_read_b128 v[180:183], v189 offset:16384
	ds_read_b128 v[190:193], v189 offset:17408
	ds_read_b128 v[194:197], v189 offset:18432
	ds_read_b128 v[198:201], v189 offset:19456
	ds_read_b128 v[202:205], v189 offset:20480
	ds_read_b128 v[206:209], v189 offset:21504
	ds_read_b128 v[210:213], v189 offset:22528
	ds_read_b128 v[214:217], v189 offset:23552
	global_load_lds_dwordx4 v[184:185], off
	s_add_i32 m0, s61, 0x2000
	v_lshl_add_u64 v[218:219], s[62:63], 0, v[136:137]
	s_add_u32 s62, s62, s6
	s_addc_u32 s63, s63, s7
	s_add_i32 s61, s57, s41
	global_load_lds_dwordx4 v[218:219], off
	v_lshl_add_u64 v[220:221], s[62:63], 0, v[132:133]
	s_mov_b32 m0, s61
	v_lshl_add_u64 v[222:223], s[62:63], 0, v[136:137]
	global_load_lds_dwordx4 v[220:221], off
	s_add_i32 m0, s61, 0x2000
	v_lshl_add_u64 v[224:225], s[28:29], 0, v[130:131]
	global_load_lds_dwordx4 v[222:223], off
	s_mov_b32 m0, s42
	v_lshl_add_u64 v[226:227], s[28:29], 0, v[134:135]
	global_load_lds_dwordx4 v[224:225], off
	s_mov_b32 m0, s43
	s_nop 0
	global_load_lds_dwordx4 v[226:227], off
	s_waitcnt vmcnt(8)
	s_waitcnt lgkmcnt(0)
	s_setprio 1
	s_waitcnt lgkmcnt(0)
	v_mfma_i32_16x16x64_i8 v[62:65], v[148:151], v[180:183], v[62:65]
	v_mfma_i32_16x16x64_i8 v[58:61], v[156:159], v[180:183], v[58:61]
	s_barrier
	v_mfma_i32_16x16x64_i8 v[54:57], v[148:151], v[194:197], v[54:57]
	v_mfma_i32_16x16x64_i8 v[50:53], v[156:159], v[194:197], v[50:53]
	v_mfma_i32_16x16x64_i8 v[42:45], v[148:151], v[202:205], v[42:45]
	v_mfma_i32_16x16x64_i8 v[34:37], v[156:159], v[202:205], v[34:37]
	v_mfma_i32_16x16x64_i8 v[26:29], v[148:151], v[210:213], v[26:29]
	v_mfma_i32_16x16x64_i8 v[18:21], v[156:159], v[210:213], v[18:21]
	v_mfma_i32_16x16x64_i8 v[62:65], v[152:155], v[190:193], v[62:65]
	v_mfma_i32_16x16x64_i8 v[58:61], v[160:163], v[190:193], v[58:61]
	v_mfma_i32_16x16x64_i8 v[54:57], v[152:155], v[198:201], v[54:57]
	v_mfma_i32_16x16x64_i8 v[50:53], v[160:163], v[198:201], v[50:53]
	v_mfma_i32_16x16x64_i8 v[42:45], v[152:155], v[206:209], v[42:45]
	v_mfma_i32_16x16x64_i8 v[34:37], v[160:163], v[206:209], v[34:37]
	v_mfma_i32_16x16x64_i8 v[26:29], v[152:155], v[214:217], v[26:29]
	v_mfma_i32_16x16x64_i8 v[18:21], v[160:163], v[214:217], v[18:21]
	s_setprio 0
	s_setprio 1
	v_mfma_i32_16x16x64_i8 v[46:49], v[164:167], v[180:183], v[46:49]
	v_mfma_i32_16x16x64_i8 v[38:41], v[172:175], v[180:183], v[38:41]
	v_mfma_i32_16x16x64_i8 v[30:33], v[164:167], v[194:197], v[30:33]
	v_mfma_i32_16x16x64_i8 v[22:25], v[172:175], v[194:197], v[22:25]
	v_mfma_i32_16x16x64_i8 v[14:17], v[164:167], v[202:205], v[14:17]
	v_mfma_i32_16x16x64_i8 v[10:13], v[172:175], v[202:205], v[10:13]
	v_mfma_i32_16x16x64_i8 v[6:9], v[164:167], v[210:213], v[6:9]
	v_mfma_i32_16x16x64_i8 v[2:5], v[172:175], v[210:213], v[2:5]
	v_mfma_i32_16x16x64_i8 v[46:49], v[168:171], v[190:193], v[46:49]
	v_mfma_i32_16x16x64_i8 v[38:41], v[176:179], v[190:193], v[38:41]
	v_mfma_i32_16x16x64_i8 v[30:33], v[168:171], v[198:201], v[30:33]
	v_mfma_i32_16x16x64_i8 v[22:25], v[176:179], v[198:201], v[22:25]
	v_mfma_i32_16x16x64_i8 v[14:17], v[168:171], v[206:209], v[14:17]
	v_mfma_i32_16x16x64_i8 v[10:13], v[176:179], v[206:209], v[10:13]
	v_mfma_i32_16x16x64_i8 v[6:9], v[168:171], v[214:217], v[6:9]
	v_mfma_i32_16x16x64_i8 v[2:5], v[176:179], v[214:217], v[2:5]
	s_setprio 0
	s_barrier
	s_add_i32 s61, 0, 0x18000
	v_add_u32_e32 v138, s61, v188
	s_add_i32 s62, 0, 0x1c000
	ds_read_b128 v[148:151], v138
	ds_read_b128 v[152:155], v138 offset:1024
	ds_read_b128 v[156:159], v138 offset:2048
	ds_read_b128 v[160:163], v138 offset:3072
	v_add_u32_e32 v138, s62, v188
	ds_read_b128 v[164:167], v138
	ds_read_b128 v[168:171], v138 offset:1024
	ds_read_b128 v[172:175], v138 offset:2048
	ds_read_b128 v[176:179], v138 offset:3072
	s_add_u32 s28, s28, s6
	s_addc_u32 s29, s29, s7
	s_mov_b32 m0, s44
	v_lshl_add_u64 v[228:229], s[28:29], 0, v[130:131]
	ds_read_b128 v[180:183], v189 offset:32768
	ds_read_b128 v[190:193], v189 offset:33792
	ds_read_b128 v[194:197], v189 offset:34816
	ds_read_b128 v[198:201], v189 offset:35840
	ds_read_b128 v[202:205], v189 offset:36864
	ds_read_b128 v[206:209], v189 offset:37888
	ds_read_b128 v[210:213], v189 offset:38912
	ds_read_b128 v[214:217], v189 offset:39936
	global_load_lds_dwordx4 v[228:229], off
	v_lshl_add_u64 v[228:229], s[28:29], 0, v[134:135]
	s_mov_b32 m0, s45
	s_nop 0
	global_load_lds_dwordx4 v[228:229], off
	s_waitcnt vmcnt(8)
	s_waitcnt lgkmcnt(0)
	s_setprio 1
	s_waitcnt lgkmcnt(0)
	v_mfma_i32_16x16x64_i8 v[126:129], v[148:151], v[180:183], v[126:129]
	v_mfma_i32_16x16x64_i8 v[122:125], v[156:159], v[180:183], v[122:125]
	s_barrier
	v_mfma_i32_16x16x64_i8 v[118:121], v[148:151], v[194:197], v[118:121]
	v_mfma_i32_16x16x64_i8 v[114:117], v[156:159], v[194:197], v[114:117]
	v_mfma_i32_16x16x64_i8 v[106:109], v[148:151], v[202:205], v[106:109]
	v_mfma_i32_16x16x64_i8 v[98:101], v[156:159], v[202:205], v[98:101]
	v_mfma_i32_16x16x64_i8 v[90:93], v[148:151], v[210:213], v[90:93]
	v_mfma_i32_16x16x64_i8 v[82:85], v[156:159], v[210:213], v[82:85]
	v_mfma_i32_16x16x64_i8 v[126:129], v[152:155], v[190:193], v[126:129]
	v_mfma_i32_16x16x64_i8 v[122:125], v[160:163], v[190:193], v[122:125]
	v_mfma_i32_16x16x64_i8 v[118:121], v[152:155], v[198:201], v[118:121]
	v_mfma_i32_16x16x64_i8 v[114:117], v[160:163], v[198:201], v[114:117]
	v_mfma_i32_16x16x64_i8 v[106:109], v[152:155], v[206:209], v[106:109]
	v_mfma_i32_16x16x64_i8 v[98:101], v[160:163], v[206:209], v[98:101]
	v_mfma_i32_16x16x64_i8 v[90:93], v[152:155], v[214:217], v[90:93]
	v_mfma_i32_16x16x64_i8 v[82:85], v[160:163], v[214:217], v[82:85]
	s_setprio 0
	s_setprio 1
	v_mfma_i32_16x16x64_i8 v[110:113], v[164:167], v[180:183], v[110:113]
	v_mfma_i32_16x16x64_i8 v[102:105], v[172:175], v[180:183], v[102:105]
	v_mfma_i32_16x16x64_i8 v[94:97], v[164:167], v[194:197], v[94:97]
	v_mfma_i32_16x16x64_i8 v[86:89], v[172:175], v[194:197], v[86:89]
	v_mfma_i32_16x16x64_i8 v[78:81], v[164:167], v[202:205], v[78:81]
	v_mfma_i32_16x16x64_i8 v[74:77], v[172:175], v[202:205], v[74:77]
	v_mfma_i32_16x16x64_i8 v[70:73], v[164:167], v[210:213], v[70:73]
	v_mfma_i32_16x16x64_i8 v[66:69], v[172:175], v[210:213], v[66:69]
	v_mfma_i32_16x16x64_i8 v[110:113], v[168:171], v[190:193], v[110:113]
	v_mfma_i32_16x16x64_i8 v[102:105], v[176:179], v[190:193], v[102:105]
	v_mfma_i32_16x16x64_i8 v[94:97], v[168:171], v[198:201], v[94:97]
	v_mfma_i32_16x16x64_i8 v[86:89], v[176:179], v[198:201], v[86:89]
	v_mfma_i32_16x16x64_i8 v[78:81], v[168:171], v[206:209], v[78:81]
	v_mfma_i32_16x16x64_i8 v[74:77], v[176:179], v[206:209], v[74:77]
	v_mfma_i32_16x16x64_i8 v[70:73], v[168:171], v[214:217], v[70:73]
	v_mfma_i32_16x16x64_i8 v[66:69], v[176:179], v[214:217], v[66:69]
	s_setprio 0
	s_barrier
	s_add_i32 s28, s61, s41
	v_lshl_add_u64 v[184:185], v[184:185], 0, s[18:19]
	s_mov_b32 m0, s28
	ds_read_b128 v[180:183], v189 offset:49152
	ds_read_b128 v[190:193], v189 offset:50176
	ds_read_b128 v[194:197], v189 offset:51200
	ds_read_b128 v[198:201], v189 offset:52224
	ds_read_b128 v[202:205], v189 offset:53248
	ds_read_b128 v[206:209], v189 offset:54272
	ds_read_b128 v[210:213], v189 offset:55296
	ds_read_b128 v[214:217], v189 offset:56320
	global_load_lds_dwordx4 v[184:185], off
	v_lshl_add_u64 v[184:185], v[218:219], 0, s[18:19]
	s_add_i32 m0, s28, 0x2000
	s_add_i32 s28, s62, s41
	global_load_lds_dwordx4 v[184:185], off
	v_lshl_add_u64 v[184:185], v[220:221], 0, s[18:19]
	s_mov_b32 m0, s28
	s_nop 0
	global_load_lds_dwordx4 v[184:185], off
	v_lshl_add_u64 v[184:185], v[222:223], 0, s[18:19]
	s_add_i32 m0, s28, 0x2000
	s_nop 0
	global_load_lds_dwordx4 v[184:185], off
	v_lshl_add_u64 v[184:185], v[224:225], 0, s[18:19]
	s_mov_b32 m0, s49
	s_nop 0
	global_load_lds_dwordx4 v[184:185], off
	v_lshl_add_u64 v[184:185], v[226:227], 0, s[18:19]
	s_mov_b32 m0, s50
	s_nop 0
	global_load_lds_dwordx4 v[184:185], off
	s_waitcnt vmcnt(8)
	s_waitcnt lgkmcnt(0)
	s_setprio 1
	s_waitcnt lgkmcnt(0)
	v_mfma_i32_16x16x64_i8 v[62:65], v[148:151], v[180:183], v[62:65]
	v_mfma_i32_16x16x64_i8 v[58:61], v[156:159], v[180:183], v[58:61]
	s_barrier
	v_mfma_i32_16x16x64_i8 v[54:57], v[148:151], v[194:197], v[54:57]
	v_mfma_i32_16x16x64_i8 v[50:53], v[156:159], v[194:197], v[50:53]
	v_mfma_i32_16x16x64_i8 v[42:45], v[148:151], v[202:205], v[42:45]
	v_mfma_i32_16x16x64_i8 v[34:37], v[156:159], v[202:205], v[34:37]
	v_mfma_i32_16x16x64_i8 v[26:29], v[148:151], v[210:213], v[26:29]
	v_mfma_i32_16x16x64_i8 v[18:21], v[156:159], v[210:213], v[18:21]
	v_mfma_i32_16x16x64_i8 v[62:65], v[152:155], v[190:193], v[62:65]
	v_mfma_i32_16x16x64_i8 v[58:61], v[160:163], v[190:193], v[58:61]
	v_mfma_i32_16x16x64_i8 v[54:57], v[152:155], v[198:201], v[54:57]
	v_mfma_i32_16x16x64_i8 v[50:53], v[160:163], v[198:201], v[50:53]
	v_mfma_i32_16x16x64_i8 v[42:45], v[152:155], v[206:209], v[42:45]
	v_mfma_i32_16x16x64_i8 v[34:37], v[160:163], v[206:209], v[34:37]
	v_mfma_i32_16x16x64_i8 v[26:29], v[152:155], v[214:217], v[26:29]
	v_mfma_i32_16x16x64_i8 v[18:21], v[160:163], v[214:217], v[18:21]
	s_setprio 0
	s_setprio 1
	v_mfma_i32_16x16x64_i8 v[46:49], v[164:167], v[180:183], v[46:49]
	v_mfma_i32_16x16x64_i8 v[38:41], v[172:175], v[180:183], v[38:41]
	v_mfma_i32_16x16x64_i8 v[30:33], v[164:167], v[194:197], v[30:33]
	v_mfma_i32_16x16x64_i8 v[22:25], v[172:175], v[194:197], v[22:25]
	v_mfma_i32_16x16x64_i8 v[14:17], v[164:167], v[202:205], v[14:17]
	v_mfma_i32_16x16x64_i8 v[10:13], v[172:175], v[202:205], v[10:13]
	v_mfma_i32_16x16x64_i8 v[6:9], v[164:167], v[210:213], v[6:9]
	v_mfma_i32_16x16x64_i8 v[2:5], v[172:175], v[210:213], v[2:5]
	v_mfma_i32_16x16x64_i8 v[46:49], v[168:171], v[190:193], v[46:49]
	v_mfma_i32_16x16x64_i8 v[38:41], v[176:179], v[190:193], v[38:41]
	v_mfma_i32_16x16x64_i8 v[30:33], v[168:171], v[198:201], v[30:33]
	v_mfma_i32_16x16x64_i8 v[22:25], v[176:179], v[198:201], v[22:25]
	v_mfma_i32_16x16x64_i8 v[14:17], v[168:171], v[206:209], v[14:17]
	v_mfma_i32_16x16x64_i8 v[10:13], v[176:179], v[206:209], v[10:13]
	v_mfma_i32_16x16x64_i8 v[6:9], v[168:171], v[214:217], v[6:9]
	v_mfma_i32_16x16x64_i8 v[2:5], v[176:179], v[214:217], v[2:5]
	s_setprio 0
	s_barrier
	s_add_u32 s26, s26, 0x100
	s_addc_u32 s27, s27, 0
	s_add_u32 s34, s34, 0x100
	s_addc_u32 s35, s35, 0
	s_cmp_ge_i32 s60, s51
	s_mov_b32 s28, s60
	s_cbranch_scc0 .LBB0_3798
	v_cvt_f32_i32_e32 v172, v126
	v_cvt_f32_i32_e32 v173, v127
	v_cvt_f32_i32_e32 v170, v128
	v_cvt_f32_i32_e32 v171, v129
	v_cvt_f32_i32_e32 v174, v122
	v_cvt_f32_i32_e32 v175, v123
	v_cvt_f32_i32_e32 v176, v124
	v_cvt_f32_i32_e32 v177, v125
	v_cvt_f32_i32_e32 v180, v110
	v_cvt_f32_i32_e32 v181, v111
	v_cvt_f32_i32_e32 v182, v112
	v_cvt_f32_i32_e32 v183, v113
	v_cvt_f32_i32_e32 v178, v102
	v_cvt_f32_i32_e32 v179, v103
	v_cvt_f32_i32_e32 v184, v104
	v_cvt_f32_i32_e32 v185, v105
	v_cvt_f32_i32_e32 v152, v118
	v_cvt_f32_i32_e32 v153, v119
	v_cvt_f32_i32_e32 v154, v120
	v_cvt_f32_i32_e32 v155, v121
	v_cvt_f32_i32_e32 v156, v114
	v_cvt_f32_i32_e32 v157, v115
	v_cvt_f32_i32_e32 v158, v116
	v_cvt_f32_i32_e32 v159, v117
	v_cvt_f32_i32_e32 v160, v94
	v_cvt_f32_i32_e32 v161, v95
	v_cvt_f32_i32_e32 v162, v96
	v_cvt_f32_i32_e32 v163, v97
	v_cvt_f32_i32_e32 v164, v86
	v_cvt_f32_i32_e32 v165, v87
	v_cvt_f32_i32_e32 v166, v88
	v_cvt_f32_i32_e32 v167, v89
	v_cvt_f32_i32_e32 v118, v106
	v_cvt_f32_i32_e32 v119, v107
	v_cvt_f32_i32_e32 v120, v108
	v_cvt_f32_i32_e32 v121, v109
	v_cvt_f32_i32_e32 v122, v98
	v_cvt_f32_i32_e32 v123, v99
	v_cvt_f32_i32_e32 v124, v100
	v_cvt_f32_i32_e32 v125, v101
	v_cvt_f32_i32_e32 v126, v78
	v_cvt_f32_i32_e32 v127, v79
	v_cvt_f32_i32_e32 v128, v80
	v_cvt_f32_i32_e32 v129, v81
	v_cvt_f32_i32_e32 v148, v74
	v_cvt_f32_i32_e32 v149, v75
	v_cvt_f32_i32_e32 v150, v76
	v_cvt_f32_i32_e32 v151, v77
	v_cvt_f32_i32_e32 v102, v90
	v_cvt_f32_i32_e32 v103, v91
	v_cvt_f32_i32_e32 v104, v92
	v_cvt_f32_i32_e32 v105, v93
	v_cvt_f32_i32_e32 v106, v82
	v_cvt_f32_i32_e32 v107, v83
	v_cvt_f32_i32_e32 v108, v84
	v_cvt_f32_i32_e32 v109, v85
	v_cvt_f32_i32_e32 v110, v70
	v_cvt_f32_i32_e32 v111, v71
	v_cvt_f32_i32_e32 v112, v72
	v_cvt_f32_i32_e32 v113, v73
	v_cvt_f32_i32_e32 v114, v66
	v_cvt_f32_i32_e32 v115, v67
	v_cvt_f32_i32_e32 v116, v68
	v_cvt_f32_i32_e32 v117, v69
	v_cvt_f32_i32_e32 v82, v62
	v_cvt_f32_i32_e32 v83, v63
	v_cvt_f32_i32_e32 v84, v64
	v_cvt_f32_i32_e32 v85, v65
	v_cvt_f32_i32_e32 v86, v58
	v_cvt_f32_i32_e32 v87, v59
	v_cvt_f32_i32_e32 v88, v60
	v_cvt_f32_i32_e32 v89, v61
	v_cvt_f32_i32_e32 v92, v46
	v_cvt_f32_i32_e32 v93, v47
	v_cvt_f32_i32_e32 v94, v48
	v_cvt_f32_i32_e32 v95, v49
	v_cvt_f32_i32_e32 v96, v38
	v_cvt_f32_i32_e32 v97, v39
	v_cvt_f32_i32_e32 v98, v40
	v_cvt_f32_i32_e32 v99, v41
	v_cvt_f32_i32_e32 v66, v54
	v_cvt_f32_i32_e32 v67, v55
	v_cvt_f32_i32_e32 v68, v56
	v_cvt_f32_i32_e32 v69, v57
	v_cvt_f32_i32_e32 v70, v50
	v_cvt_f32_i32_e32 v71, v51
	v_cvt_f32_i32_e32 v72, v52
	v_cvt_f32_i32_e32 v73, v53
	v_cvt_f32_i32_e32 v74, v30
	v_cvt_f32_i32_e32 v75, v31
	v_cvt_f32_i32_e32 v76, v32
	v_cvt_f32_i32_e32 v77, v33
	v_cvt_f32_i32_e32 v78, v22
	v_cvt_f32_i32_e32 v79, v23
	v_cvt_f32_i32_e32 v80, v24
	v_cvt_f32_i32_e32 v81, v25
	v_cvt_f32_i32_e32 v50, v42
	v_cvt_f32_i32_e32 v51, v43
	v_cvt_f32_i32_e32 v52, v44
	v_cvt_f32_i32_e32 v53, v45
	v_cvt_f32_i32_e32 v54, v34
	v_cvt_f32_i32_e32 v55, v35
	v_cvt_f32_i32_e32 v56, v36
	v_cvt_f32_i32_e32 v57, v37
	v_cvt_f32_i32_e32 v58, v14
	v_cvt_f32_i32_e32 v59, v15
	v_cvt_f32_i32_e32 v60, v16
	v_cvt_f32_i32_e32 v61, v17
	v_cvt_f32_i32_e32 v62, v10
	v_cvt_f32_i32_e32 v63, v11
	v_cvt_f32_i32_e32 v64, v12
	v_cvt_f32_i32_e32 v65, v13
	v_cvt_f32_i32_e32 v34, v26
	v_cvt_f32_i32_e32 v35, v27
	v_cvt_f32_i32_e32 v36, v28
	v_cvt_f32_i32_e32 v37, v29
	v_cvt_f32_i32_e32 v38, v18
	v_cvt_f32_i32_e32 v39, v19
	v_cvt_f32_i32_e32 v40, v20
	v_cvt_f32_i32_e32 v41, v21
	v_cvt_f32_i32_e32 v42, v6
	v_cvt_f32_i32_e32 v43, v7
	v_cvt_f32_i32_e32 v44, v8
	v_cvt_f32_i32_e32 v45, v9
	v_cvt_f32_i32_e32 v46, v2
	v_cvt_f32_i32_e32 v47, v3
	v_cvt_f32_i32_e32 v48, v4
	v_cvt_f32_i32_e32 v49, v5

.LBB0_3879:
	ds_read_b128 v[130:133], v169
	ds_read_b128 v[134:137], v169 offset:1024
	ds_read_b128 v[138:141], v169 offset:2048
	ds_read_b128 v[142:145], v169 offset:3072
	ds_read_b128 v[162:165], v170
	ds_read_b128 v[172:175], v170 offset:1024
	ds_read_b128 v[176:179], v170 offset:2048
	ds_read_b128 v[180:183], v170 offset:3072
	s_add_i32 s59, s26, 2
	s_add_u32 s27, s24, 0x4000
	s_addc_u32 s28, s25, 0
	s_cmp_eq_u32 s48, s26
	s_cselect_b32 s29, s3, s28
	s_cselect_b32 s28, s2, s27
	s_cselect_b32 s60, s22, s57
	s_cselect_b32 s61, s23, s58
	s_add_u32 s26, s28, 0x8000
	s_addc_u32 s27, s29, 0
	v_lshl_add_u64 v[216:217], s[24:25], 0, v[154:155]
	s_add_i32 m0, s38, 0xc000
	ds_read_b128 v[184:187], v171
	ds_read_b128 v[188:191], v171 offset:1024
	ds_read_b128 v[192:195], v171 offset:2048
	ds_read_b128 v[196:199], v171 offset:3072
	ds_read_b128 v[200:203], v171 offset:4096
	ds_read_b128 v[204:207], v171 offset:5120
	ds_read_b128 v[208:211], v171 offset:6144
	ds_read_b128 v[212:215], v171 offset:7168
	global_load_lds_dwordx4 v[216:217], off
	v_lshl_add_u64 v[216:217], s[24:25], 0, v[156:157]
	s_add_i32 m0, s38, 0xe000
	s_nop 0
	global_load_lds_dwordx4 v[216:217], off
	s_waitcnt vmcnt(8)
	s_waitcnt lgkmcnt(0)
	s_setprio 1
	s_waitcnt lgkmcnt(0)
	v_mfma_f32_16x16x32_bf16 v[126:129], v[130:133], v[184:187], v[126:129]
	v_mfma_f32_16x16x32_bf16 v[122:125], v[138:141], v[184:187], v[122:125]
	s_barrier
	v_mfma_f32_16x16x32_bf16 v[110:113], v[130:133], v[192:195], v[110:113]
	v_mfma_f32_16x16x32_bf16 v[106:109], v[138:141], v[192:195], v[106:109]
	v_mfma_f32_16x16x32_bf16 v[94:97], v[130:133], v[200:203], v[94:97]
	v_mfma_f32_16x16x32_bf16 v[90:93], v[138:141], v[200:203], v[90:93]
	v_mfma_f32_16x16x32_bf16 v[78:81], v[130:133], v[208:211], v[78:81]
	v_mfma_f32_16x16x32_bf16 v[74:77], v[138:141], v[208:211], v[74:77]
	v_mfma_f32_16x16x32_bf16 v[126:129], v[134:137], v[188:191], v[126:129]
	v_mfma_f32_16x16x32_bf16 v[122:125], v[142:145], v[188:191], v[122:125]
	v_mfma_f32_16x16x32_bf16 v[110:113], v[134:137], v[196:199], v[110:113]
	v_mfma_f32_16x16x32_bf16 v[106:109], v[142:145], v[196:199], v[106:109]
	v_mfma_f32_16x16x32_bf16 v[94:97], v[134:137], v[204:207], v[94:97]
	v_mfma_f32_16x16x32_bf16 v[90:93], v[142:145], v[204:207], v[90:93]
	v_mfma_f32_16x16x32_bf16 v[78:81], v[134:137], v[212:215], v[78:81]
	v_mfma_f32_16x16x32_bf16 v[74:77], v[142:145], v[212:215], v[74:77]
	s_setprio 0
	s_setprio 1
	v_mfma_f32_16x16x32_bf16 v[118:121], v[162:165], v[184:187], v[118:121]
	v_mfma_f32_16x16x32_bf16 v[114:117], v[176:179], v[184:187], v[114:117]
	v_mfma_f32_16x16x32_bf16 v[102:105], v[162:165], v[192:195], v[102:105]
	v_mfma_f32_16x16x32_bf16 v[98:101], v[176:179], v[192:195], v[98:101]
	v_mfma_f32_16x16x32_bf16 v[86:89], v[162:165], v[200:203], v[86:89]
	v_mfma_f32_16x16x32_bf16 v[82:85], v[176:179], v[200:203], v[82:85]
	v_mfma_f32_16x16x32_bf16 v[70:73], v[162:165], v[208:211], v[70:73]
	v_mfma_f32_16x16x32_bf16 v[66:69], v[176:179], v[208:211], v[66:69]
	v_mfma_f32_16x16x32_bf16 v[118:121], v[172:175], v[188:191], v[118:121]
	v_mfma_f32_16x16x32_bf16 v[114:117], v[180:183], v[188:191], v[114:117]
	v_mfma_f32_16x16x32_bf16 v[102:105], v[172:175], v[196:199], v[102:105]
	v_mfma_f32_16x16x32_bf16 v[98:101], v[180:183], v[196:199], v[98:101]
	v_mfma_f32_16x16x32_bf16 v[86:89], v[172:175], v[204:207], v[86:89]
	v_mfma_f32_16x16x32_bf16 v[82:85], v[180:183], v[204:207], v[82:85]
	v_mfma_f32_16x16x32_bf16 v[70:73], v[172:175], v[212:215], v[70:73]
	v_mfma_f32_16x16x32_bf16 v[66:69], v[180:183], v[212:215], v[66:69]
	s_setprio 0
	s_barrier
	s_add_i32 s62, s50, s37
	v_lshl_add_u64 v[216:217], s[60:61], 0, v[148:149]
	s_mov_b32 m0, s62
	ds_read_b128 v[184:187], v171 offset:16384
	ds_read_b128 v[188:191], v171 offset:17408
	ds_read_b128 v[192:195], v171 offset:18432
	ds_read_b128 v[196:199], v171 offset:19456
	ds_read_b128 v[200:203], v171 offset:20480
	ds_read_b128 v[204:207], v171 offset:21504
	ds_read_b128 v[208:211], v171 offset:22528
	ds_read_b128 v[212:215], v171 offset:23552
	global_load_lds_dwordx4 v[216:217], off
	s_add_i32 m0, s62, 0x2000
	v_lshl_add_u64 v[218:219], s[60:61], 0, v[152:153]
	s_add_u32 s60, s60, s6
	s_addc_u32 s61, s61, s7
	s_add_i32 s62, s51, s37
	global_load_lds_dwordx4 v[218:219], off
	v_lshl_add_u64 v[220:221], s[60:61], 0, v[148:149]
	s_mov_b32 m0, s62
	v_lshl_add_u64 v[222:223], s[60:61], 0, v[152:153]
	global_load_lds_dwordx4 v[220:221], off
	s_add_i32 m0, s62, 0x2000
	v_lshl_add_u64 v[224:225], s[28:29], 0, v[146:147]
	global_load_lds_dwordx4 v[222:223], off
	s_mov_b32 m0, s38
	s_nop 0
	global_load_lds_dwordx4 v[224:225], off
	v_lshl_add_u64 v[224:225], s[28:29], 0, v[150:151]
	s_mov_b32 m0, s39
	s_nop 0
	global_load_lds_dwordx4 v[224:225], off
	s_waitcnt vmcnt(8)
	s_waitcnt lgkmcnt(0)
	s_setprio 1
	s_waitcnt lgkmcnt(0)
	v_mfma_f32_16x16x32_bf16 v[62:65], v[130:133], v[184:187], v[62:65]
	v_mfma_f32_16x16x32_bf16 v[58:61], v[138:141], v[184:187], v[58:61]
	s_barrier
	v_mfma_f32_16x16x32_bf16 v[46:49], v[130:133], v[192:195], v[46:49]
	v_mfma_f32_16x16x32_bf16 v[42:45], v[138:141], v[192:195], v[42:45]
	v_mfma_f32_16x16x32_bf16 v[30:33], v[130:133], v[200:203], v[30:33]
	v_mfma_f32_16x16x32_bf16 v[26:29], v[138:141], v[200:203], v[26:29]
	v_mfma_f32_16x16x32_bf16 v[14:17], v[130:133], v[208:211], v[14:17]
	v_mfma_f32_16x16x32_bf16 v[10:13], v[138:141], v[208:211], v[10:13]
	v_mfma_f32_16x16x32_bf16 v[62:65], v[134:137], v[188:191], v[62:65]
	v_mfma_f32_16x16x32_bf16 v[58:61], v[142:145], v[188:191], v[58:61]
	v_mfma_f32_16x16x32_bf16 v[46:49], v[134:137], v[196:199], v[46:49]
	v_mfma_f32_16x16x32_bf16 v[42:45], v[142:145], v[196:199], v[42:45]
	v_mfma_f32_16x16x32_bf16 v[30:33], v[134:137], v[204:207], v[30:33]
	v_mfma_f32_16x16x32_bf16 v[26:29], v[142:145], v[204:207], v[26:29]
	v_mfma_f32_16x16x32_bf16 v[14:17], v[134:137], v[212:215], v[14:17]
	v_mfma_f32_16x16x32_bf16 v[10:13], v[142:145], v[212:215], v[10:13]
	s_setprio 0
	s_setprio 1
	v_mfma_f32_16x16x32_bf16 v[54:57], v[162:165], v[184:187], v[54:57]
	v_mfma_f32_16x16x32_bf16 v[50:53], v[176:179], v[184:187], v[50:53]
	v_mfma_f32_16x16x32_bf16 v[38:41], v[162:165], v[192:195], v[38:41]
	v_mfma_f32_16x16x32_bf16 v[34:37], v[176:179], v[192:195], v[34:37]
	v_mfma_f32_16x16x32_bf16 v[22:25], v[162:165], v[200:203], v[22:25]
	v_mfma_f32_16x16x32_bf16 v[18:21], v[176:179], v[200:203], v[18:21]
	v_mfma_f32_16x16x32_bf16 v[6:9], v[162:165], v[208:211], v[6:9]
	v_mfma_f32_16x16x32_bf16 v[2:5], v[176:179], v[208:211], v[2:5]
	v_mfma_f32_16x16x32_bf16 v[54:57], v[172:175], v[188:191], v[54:57]
	v_mfma_f32_16x16x32_bf16 v[50:53], v[180:183], v[188:191], v[50:53]
	v_mfma_f32_16x16x32_bf16 v[38:41], v[172:175], v[196:199], v[38:41]
	v_mfma_f32_16x16x32_bf16 v[34:37], v[180:183], v[196:199], v[34:37]
	v_mfma_f32_16x16x32_bf16 v[22:25], v[172:175], v[204:207], v[22:25]
	v_mfma_f32_16x16x32_bf16 v[18:21], v[180:183], v[204:207], v[18:21]
	v_mfma_f32_16x16x32_bf16 v[6:9], v[172:175], v[212:215], v[6:9]
	v_mfma_f32_16x16x32_bf16 v[2:5], v[180:183], v[212:215], v[2:5]
	s_setprio 0
	s_barrier
	s_add_i32 s60, 0, 0x18000
	s_add_i32 s61, 0, 0x1c000
	v_add_u32_e32 v142, s60, v167
	v_add_u32_e32 v180, s61, v167
	ds_read_b128 v[130:133], v142
	ds_read_b128 v[134:137], v142 offset:1024
	ds_read_b128 v[138:141], v142 offset:2048
	ds_read_b128 v[142:145], v142 offset:3072
	ds_read_b128 v[162:165], v180
	ds_read_b128 v[172:175], v180 offset:1024
	ds_read_b128 v[176:179], v180 offset:2048
	ds_read_b128 v[180:183], v180 offset:3072
	s_add_u32 s28, s28, 0x4000
	s_addc_u32 s29, s29, 0
	s_mov_b32 m0, s40
	v_lshl_add_u64 v[224:225], s[28:29], 0, v[146:147]
	ds_read_b128 v[184:187], v171 offset:32768
	ds_read_b128 v[188:191], v171 offset:33792
	ds_read_b128 v[192:195], v171 offset:34816
	ds_read_b128 v[196:199], v171 offset:35840
	ds_read_b128 v[200:203], v171 offset:36864
	ds_read_b128 v[204:207], v171 offset:37888
	ds_read_b128 v[208:211], v171 offset:38912
	ds_read_b128 v[212:215], v171 offset:39936
	global_load_lds_dwordx4 v[224:225], off
	v_lshl_add_u64 v[224:225], s[28:29], 0, v[150:151]
	s_mov_b32 m0, s41
	s_nop 0
	global_load_lds_dwordx4 v[224:225], off
	s_waitcnt vmcnt(8)
	s_waitcnt lgkmcnt(0)
	s_setprio 1
	s_waitcnt lgkmcnt(0)
	v_mfma_f32_16x16x32_bf16 v[126:129], v[130:133], v[184:187], v[126:129]
	v_mfma_f32_16x16x32_bf16 v[122:125], v[138:141], v[184:187], v[122:125]
	s_barrier
	v_mfma_f32_16x16x32_bf16 v[110:113], v[130:133], v[192:195], v[110:113]
	v_mfma_f32_16x16x32_bf16 v[106:109], v[138:141], v[192:195], v[106:109]
	v_mfma_f32_16x16x32_bf16 v[94:97], v[130:133], v[200:203], v[94:97]
	v_mfma_f32_16x16x32_bf16 v[90:93], v[138:141], v[200:203], v[90:93]
	v_mfma_f32_16x16x32_bf16 v[78:81], v[130:133], v[208:211], v[78:81]
	v_mfma_f32_16x16x32_bf16 v[74:77], v[138:141], v[208:211], v[74:77]
	v_mfma_f32_16x16x32_bf16 v[126:129], v[134:137], v[188:191], v[126:129]
	v_mfma_f32_16x16x32_bf16 v[122:125], v[142:145], v[188:191], v[122:125]
	v_mfma_f32_16x16x32_bf16 v[110:113], v[134:137], v[196:199], v[110:113]
	v_mfma_f32_16x16x32_bf16 v[106:109], v[142:145], v[196:199], v[106:109]
	v_mfma_f32_16x16x32_bf16 v[94:97], v[134:137], v[204:207], v[94:97]
	v_mfma_f32_16x16x32_bf16 v[90:93], v[142:145], v[204:207], v[90:93]
	v_mfma_f32_16x16x32_bf16 v[78:81], v[134:137], v[212:215], v[78:81]
	v_mfma_f32_16x16x32_bf16 v[74:77], v[142:145], v[212:215], v[74:77]
	s_setprio 0
	s_setprio 1
	v_mfma_f32_16x16x32_bf16 v[118:121], v[162:165], v[184:187], v[118:121]
	v_mfma_f32_16x16x32_bf16 v[114:117], v[176:179], v[184:187], v[114:117]
	v_mfma_f32_16x16x32_bf16 v[102:105], v[162:165], v[192:195], v[102:105]
	v_mfma_f32_16x16x32_bf16 v[98:101], v[176:179], v[192:195], v[98:101]
	v_mfma_f32_16x16x32_bf16 v[86:89], v[162:165], v[200:203], v[86:89]
	v_mfma_f32_16x16x32_bf16 v[82:85], v[176:179], v[200:203], v[82:85]
	v_mfma_f32_16x16x32_bf16 v[70:73], v[162:165], v[208:211], v[70:73]
	v_mfma_f32_16x16x32_bf16 v[66:69], v[176:179], v[208:211], v[66:69]
	v_mfma_f32_16x16x32_bf16 v[118:121], v[172:175], v[188:191], v[118:121]
	v_mfma_f32_16x16x32_bf16 v[114:117], v[180:183], v[188:191], v[114:117]
	v_mfma_f32_16x16x32_bf16 v[102:105], v[172:175], v[196:199], v[102:105]
	v_mfma_f32_16x16x32_bf16 v[98:101], v[180:183], v[196:199], v[98:101]
	v_mfma_f32_16x16x32_bf16 v[86:89], v[172:175], v[204:207], v[86:89]
	v_mfma_f32_16x16x32_bf16 v[82:85], v[180:183], v[204:207], v[82:85]
	v_mfma_f32_16x16x32_bf16 v[70:73], v[172:175], v[212:215], v[70:73]
	v_mfma_f32_16x16x32_bf16 v[66:69], v[180:183], v[212:215], v[66:69]
	s_setprio 0
	s_barrier
	s_add_i32 s28, s60, s37
	v_lshl_add_u64 v[216:217], v[216:217], 0, s[14:15]
	s_mov_b32 m0, s28
	ds_read_b128 v[184:187], v171 offset:49152
	ds_read_b128 v[188:191], v171 offset:50176
	ds_read_b128 v[192:195], v171 offset:51200
	ds_read_b128 v[196:199], v171 offset:52224
	ds_read_b128 v[200:203], v171 offset:53248
	ds_read_b128 v[204:207], v171 offset:54272
	ds_read_b128 v[208:211], v171 offset:55296
	ds_read_b128 v[212:215], v171 offset:56320
	global_load_lds_dwordx4 v[216:217], off
	v_lshl_add_u64 v[216:217], v[218:219], 0, s[14:15]
	s_add_i32 m0, s28, 0x2000
	s_add_i32 s28, s61, s37
	global_load_lds_dwordx4 v[216:217], off
	v_lshl_add_u64 v[216:217], v[220:221], 0, s[14:15]
	s_mov_b32 m0, s28
	s_nop 0
	global_load_lds_dwordx4 v[216:217], off
	v_lshl_add_u64 v[216:217], v[222:223], 0, s[14:15]
	s_add_i32 m0, s28, 0x2000
	s_nop 0
	global_load_lds_dwordx4 v[216:217], off
	v_lshl_add_u64 v[216:217], s[26:27], 0, v[146:147]
	s_mov_b32 m0, s46
	s_nop 0
	global_load_lds_dwordx4 v[216:217], off
	v_lshl_add_u64 v[216:217], s[26:27], 0, v[150:151]
	s_mov_b32 m0, s47
	s_nop 0
	global_load_lds_dwordx4 v[216:217], off
	s_waitcnt vmcnt(8)
	s_waitcnt lgkmcnt(0)
	s_setprio 1
	s_waitcnt lgkmcnt(0)
	v_mfma_f32_16x16x32_bf16 v[62:65], v[130:133], v[184:187], v[62:65]
	v_mfma_f32_16x16x32_bf16 v[58:61], v[138:141], v[184:187], v[58:61]
	s_barrier
	v_mfma_f32_16x16x32_bf16 v[46:49], v[130:133], v[192:195], v[46:49]
	v_mfma_f32_16x16x32_bf16 v[42:45], v[138:141], v[192:195], v[42:45]
	v_mfma_f32_16x16x32_bf16 v[30:33], v[130:133], v[200:203], v[30:33]
	v_mfma_f32_16x16x32_bf16 v[26:29], v[138:141], v[200:203], v[26:29]
	v_mfma_f32_16x16x32_bf16 v[14:17], v[130:133], v[208:211], v[14:17]
	v_mfma_f32_16x16x32_bf16 v[10:13], v[138:141], v[208:211], v[10:13]
	v_mfma_f32_16x16x32_bf16 v[62:65], v[134:137], v[188:191], v[62:65]
	v_mfma_f32_16x16x32_bf16 v[58:61], v[142:145], v[188:191], v[58:61]
	v_mfma_f32_16x16x32_bf16 v[46:49], v[134:137], v[196:199], v[46:49]
	v_mfma_f32_16x16x32_bf16 v[42:45], v[142:145], v[196:199], v[42:45]
	v_mfma_f32_16x16x32_bf16 v[30:33], v[134:137], v[204:207], v[30:33]
	v_mfma_f32_16x16x32_bf16 v[26:29], v[142:145], v[204:207], v[26:29]
	v_mfma_f32_16x16x32_bf16 v[14:17], v[134:137], v[212:215], v[14:17]
	v_mfma_f32_16x16x32_bf16 v[10:13], v[142:145], v[212:215], v[10:13]
	s_setprio 0
	s_setprio 1
	v_mfma_f32_16x16x32_bf16 v[54:57], v[162:165], v[184:187], v[54:57]
	v_mfma_f32_16x16x32_bf16 v[50:53], v[176:179], v[184:187], v[50:53]
	v_mfma_f32_16x16x32_bf16 v[38:41], v[162:165], v[192:195], v[38:41]
	v_mfma_f32_16x16x32_bf16 v[34:37], v[176:179], v[192:195], v[34:37]
	v_mfma_f32_16x16x32_bf16 v[22:25], v[162:165], v[200:203], v[22:25]
	v_mfma_f32_16x16x32_bf16 v[18:21], v[176:179], v[200:203], v[18:21]
	v_mfma_f32_16x16x32_bf16 v[6:9], v[162:165], v[208:211], v[6:9]
	v_mfma_f32_16x16x32_bf16 v[2:5], v[176:179], v[208:211], v[2:5]
	v_mfma_f32_16x16x32_bf16 v[54:57], v[172:175], v[188:191], v[54:57]
	v_mfma_f32_16x16x32_bf16 v[50:53], v[180:183], v[188:191], v[50:53]
	v_mfma_f32_16x16x32_bf16 v[38:41], v[172:175], v[196:199], v[38:41]
	v_mfma_f32_16x16x32_bf16 v[34:37], v[180:183], v[196:199], v[34:37]
	v_mfma_f32_16x16x32_bf16 v[22:25], v[172:175], v[204:207], v[22:25]
	v_mfma_f32_16x16x32_bf16 v[18:21], v[180:183], v[204:207], v[18:21]
	v_mfma_f32_16x16x32_bf16 v[6:9], v[172:175], v[212:215], v[6:9]
	v_mfma_f32_16x16x32_bf16 v[2:5], v[180:183], v[212:215], v[2:5]
	s_setprio 0
	s_barrier
	s_add_u32 s57, s57, 0x100
	s_addc_u32 s58, s58, 0
	s_add_u32 s24, s24, 0x10000
	s_addc_u32 s25, s25, 0
	s_cmp_ge_i32 s59, s45
	s_mov_b32 s26, s59
	s_cbranch_scc0 .LBB0_3879
